# v5_ntst
# baseline (speedup 1.0000x reference)
; #define LAS __attribute__((address_space(3)))
; #define LDS_WAIT() asm volatile("s_waitcnt lgkmcnt(0)" ::: "memory")
; __device__ __forceinline__ void transpose_item_f8(const float* W, int N, unsigned char* WT, int nkt, int k0, int n0, int r0, int kt8, int koff, LAS float* scr, int lane) {
;     const size_t dst_off = ((size_t)(r0 >> 8) * nkt + kt8) * 32768 + (size_t)(r0 & 255) * 128 + koff;
;     const int l15 = lane & 15, lq = lane >> 4;
;     f32x4 v[16];
; #pragma unroll
;     for (int i = 0; i < 16; ++i) v[i] = *(const f32x4*)(W + (size_t)(k0 + 4 * i + lq) * N + n0 + 4 * l15);
; #pragma unroll
;     for (int i = 0; i < 16; ++i) { LAS float* d = scr + (4 * i + lq) * 65 + 4 * l15; d[0] = v[i][0]; d[1] = v[i][1]; d[2] = v[i][2]; d[3] = v[i][3]; }
;     LDS_WAIT();
; __device__ __forceinline__ void phase0(const Params& p, LAS unsigned char* lds, int gw, int NGW, int wave, int lane, int G) {
;     ...
;     for (int it = gw; it < I0; it += NGW) {
;         const int nb = it % 192, kb = it / 192;
;         if (nb < 64) transpose_item(p.in[2], DIN, (bf16_t*)(ws + WS_W_IN), 64, kb * 64, nb * 64, nb * 64, kb, scr, lane);
;         else transpose_item_f8(p.in[2], DIN, ws + WS_W_IN + ((size_t)32 << 20), 32, kb * 64, nb * 64, (nb - 64) * 64, kb >> 1, (kb & 1) * 64, scr, lane);
.LBB0_23:
	s_mul_hi_i32 s4, s64, 0x2aaaaaab
	s_lshr_b32 s5, s4, 31
	s_ashr_i32 s4, s4, 5
	s_add_i32 s4, s4, s5
	s_mul_i32 s5, s4, 0xffffff40
	s_lshl_b32 s65, s4, 6
	s_mul_i32 s6, s4, 0xffffd000
	s_add_i32 s5, s64, s5
	s_add_i32 s6, s16, s6
	v_or_b32_e32 v71, s65, v30
	s_cmp_gt_i32 s5, 63
	s_mov_b64 s[10:11], -1
	v_or_b32_e32 v70, 4, v71
	v_or_b32_e32 v69, 8, v71
	v_or_b32_e32 v68, 12, v71
	v_or_b32_e32 v67, 16, v71
	v_or_b32_e32 v66, 20, v71
	v_or_b32_e32 v65, 24, v71
	v_or_b32_e32 v64, 28, v71
	v_or_b32_e32 v63, 32, v71
	v_or_b32_e32 v62, 36, v71
	v_or_b32_e32 v25, 40, v71
	v_or_b32_e32 v27, 44, v71
	v_or_b32_e32 v29, 48, v71
	v_or_b32_e32 v23, 52, v71
	v_or_b32_e32 v21, 56, v71
	v_or_b32_e32 v19, 60, v71
	v_add_u32_e32 v15, 0x3cf0, v33
	v_add_u32_e32 v17, 0x3cf8, v33
	s_cbranch_scc0 .LBB0_25
	s_mov_b32 s7, s3
	v_lshl_add_u64 v[132:133], s[6:7], 2, v[12:13]
	v_mad_i64_i32 v[72:73], s[10:11], v71, s63, v[132:133]
	v_mad_i64_i32 v[76:77], s[10:11], v70, s63, v[132:133]
	v_mad_i64_i32 v[80:81], s[10:11], v69, s63, v[132:133]
	v_mad_i64_i32 v[84:85], s[10:11], v68, s63, v[132:133]
	v_mad_i64_i32 v[88:89], s[10:11], v67, s63, v[132:133]
	v_mad_i64_i32 v[92:93], s[10:11], v66, s63, v[132:133]
	v_mad_i64_i32 v[96:97], s[10:11], v65, s63, v[132:133]
	v_mad_i64_i32 v[100:101], s[10:11], v64, s63, v[132:133]
	v_mad_i64_i32 v[104:105], s[10:11], v63, s63, v[132:133]
	v_mad_i64_i32 v[108:109], s[10:11], v62, s63, v[132:133]
	v_mad_i64_i32 v[112:113], s[10:11], v25, s63, v[132:133]
	v_mad_i64_i32 v[116:117], s[10:11], v27, s63, v[132:133]
	v_mad_i64_i32 v[120:121], s[10:11], v29, s63, v[132:133]
	v_mad_i64_i32 v[124:125], s[10:11], v23, s63, v[132:133]
	v_mad_i64_i32 v[128:129], s[10:11], v21, s63, v[132:133]
	global_load_dwordx4 v[72:75], v[72:73], off nt
	s_nop 0
	global_load_dwordx4 v[76:79], v[76:77], off nt
	s_nop 0
	global_load_dwordx4 v[80:83], v[80:81], off nt
	s_nop 0
	global_load_dwordx4 v[84:87], v[84:85], off nt
	s_nop 0
	global_load_dwordx4 v[88:91], v[88:89], off nt
	s_nop 0
	global_load_dwordx4 v[92:95], v[92:93], off nt
	s_nop 0
	global_load_dwordx4 v[96:99], v[96:97], off nt
	s_nop 0
	global_load_dwordx4 v[100:103], v[100:101], off nt
	v_mad_i64_i32 v[132:133], s[10:11], v19, s63, v[132:133]
	global_load_dwordx4 v[104:107], v[104:105], off nt
	s_nop 0
	global_load_dwordx4 v[108:111], v[108:109], off nt
	s_nop 0
	global_load_dwordx4 v[112:115], v[112:113], off nt
	s_nop 0
	global_load_dwordx4 v[116:119], v[116:117], off nt
	s_nop 0
	global_load_dwordx4 v[120:123], v[120:121], off nt
	s_nop 0
	global_load_dwordx4 v[124:127], v[124:125], off nt
	s_nop 0
	global_load_dwordx4 v[128:131], v[128:129], off nt
	v_mov_b32_e32 v136, v1
	global_load_dwordx4 v[132:135], v[132:133], off nt
	v_mov_b32_e32 v137, v1
	v_mov_b32_e32 v138, v1
	v_mov_b32_e32 v139, v1
	s_add_i32 s7, s6, 0xfffff000
	s_ashr_i32 s10, s4, 1
	s_lshr_b32 s7, s7, 3
	s_and_b32 s65, s65, 64
	s_and_b32 s7, s7, 0x3e0
	s_ashr_i32 s11, s10, 31
	s_add_u32 s10, s7, s10
	s_addc_u32 s11, 0, s11
	s_and_b32 s7, s33, 0x6000
	s_lshl_b64 s[10:11], s[10:11], 15
	s_add_u32 s10, s8, s10
	s_addc_u32 s11, s9, s11
	s_add_u32 s7, s10, s7
	s_addc_u32 s11, s11, 0
	s_add_u32 s10, s7, s65
	s_addc_u32 s11, s11, 0
	s_waitcnt vmcnt(15)
	ds_write2_b32 v33, v72, v73 offset1:1
	ds_write2_b32 v33, v74, v75 offset0:2 offset1:3
	s_waitcnt vmcnt(14)
	ds_write2_b32 v34, v76, v77 offset1:1
	ds_write2_b32 v35, v78, v79 offset1:1
	s_waitcnt vmcnt(13)
	ds_write2_b32 v36, v80, v81 offset1:1
	ds_write2_b32 v37, v82, v83 offset1:1
	s_waitcnt vmcnt(12)
	ds_write2_b32 v38, v84, v85 offset1:1
	ds_write2_b32 v39, v86, v87 offset1:1
	s_waitcnt vmcnt(11)
	ds_write2_b32 v40, v88, v89 offset1:1
	ds_write2_b32 v41, v90, v91 offset1:1
	s_waitcnt vmcnt(10)
	ds_write2_b32 v42, v92, v93 offset1:1
	ds_write2_b32 v43, v94, v95 offset1:1
	s_waitcnt vmcnt(9)
	ds_write2_b32 v44, v96, v97 offset1:1
	ds_write2_b32 v45, v98, v99 offset1:1
	s_waitcnt vmcnt(8)
	ds_write2_b32 v46, v100, v101 offset1:1
	ds_write2_b32 v47, v102, v103 offset1:1
	s_waitcnt vmcnt(7)
	ds_write2_b32 v48, v104, v105 offset1:1
	ds_write2_b32 v49, v106, v107 offset1:1
	s_waitcnt vmcnt(6)
	ds_write2_b32 v50, v108, v109 offset1:1
	ds_write2_b32 v51, v110, v111 offset1:1
	s_waitcnt vmcnt(5)
	ds_write2_b32 v52, v112, v113 offset1:1
	ds_write2_b32 v53, v114, v115 offset1:1
	s_waitcnt vmcnt(4)
	ds_write2_b32 v54, v116, v117 offset1:1
	ds_write2_b32 v55, v118, v119 offset1:1
	s_waitcnt vmcnt(3)
	ds_write2_b32 v56, v120, v121 offset1:1
	ds_write2_b32 v57, v122, v123 offset1:1
	s_waitcnt vmcnt(2)
	ds_write2_b32 v58, v124, v125 offset1:1
	ds_write2_b32 v59, v126, v127 offset1:1
	s_waitcnt vmcnt(1)
	ds_write2_b32 v60, v128, v129 offset1:1
	ds_write2_b32 v61, v130, v131 offset1:1
	s_waitcnt vmcnt(0)
	ds_write2_b32 v15, v132, v133 offset1:1
	ds_write2_b32 v17, v134, v135 offset1:1
	s_waitcnt lgkmcnt(0)
	ds_read2_b32 v[72:73], v31 offset1:16
	ds_read2_b32 v[74:75], v31 offset0:65 offset1:81
	v_add_u32_e32 v104, 0x400, v31
	ds_read2_b32 v[76:77], v31 offset0:130 offset1:146
	ds_read2_b32 v[78:79], v31 offset0:195 offset1:211
	ds_read2_b32 v[80:81], v104 offset0:4 offset1:20
	ds_read2_b32 v[82:83], v104 offset0:69 offset1:85
	s_waitcnt lgkmcnt(5)
	v_mul_f32_e32 v72, 0x44800000, v72
	s_waitcnt lgkmcnt(4)
	v_mul_f32_e32 v74, 0x44800000, v74
	v_cvt_pk_fp8_f32 v136, v72, v74
	s_waitcnt lgkmcnt(3)
	v_mul_f32_e32 v72, 0x44800000, v76
	s_waitcnt lgkmcnt(2)
	v_mul_f32_e32 v74, 0x44800000, v78
	ds_read2_b32 v[84:85], v104 offset0:134 offset1:150
	ds_read2_b32 v[86:87], v104 offset0:199 offset1:215
	v_add_u32_e32 v105, 0x800, v31
	v_cvt_pk_fp8_f32 v136, v72, v74 op_sel:[0,0,1]
	s_waitcnt lgkmcnt(3)
; #define LAS __attribute__((address_space(3)))
; #define LDS_WAIT() asm volatile("s_waitcnt lgkmcnt(0)" ::: "memory")
; __device__ __forceinline__ void transpose_item_f8(const float* W, int N, unsigned char* WT, int nkt, int k0, int n0, int r0, int kt8, int koff, LAS float* scr, int lane) {
;     ...
;     LDS_WAIT();
;     const int c = lane & 3;
; #pragma unroll
;     for (int j = 0; j < 4; ++j) { const int n = (lane >> 2) + 16 * j; const LAS float* s = scr + (16 * c) * 65 + n; u32x4 o;
; #pragma unroll
;         for (int q = 0; q < 4; ++q) { int w = __builtin_amdgcn_cvt_pk_fp8_f32(s[(4 * q) * 65] * 1024.f, s[(4 * q + 1) * 65] * 1024.f, 0, false);
;             w = __builtin_amdgcn_cvt_pk_fp8_f32(s[(4 * q + 2) * 65] * 1024.f, s[(4 * q + 3) * 65] * 1024.f, w, true); o[q] = (unsigned)w; }
;         *(u32x4*)(WT + dst_off + (size_t)n * 128 + 16 * c) = o; }
;     LDS_WAIT();
	v_mul_f32_e32 v72, 0x44800000, v80
	s_waitcnt lgkmcnt(2)
	v_mul_f32_e32 v74, 0x44800000, v82
	ds_read2_b32 v[88:89], v105 offset0:8 offset1:24
	ds_read2_b32 v[90:91], v105 offset0:73 offset1:89
	v_cvt_pk_fp8_f32 v137, v72, v74
	s_waitcnt lgkmcnt(3)
	v_mul_f32_e32 v72, 0x44800000, v84
	s_waitcnt lgkmcnt(2)
	v_mul_f32_e32 v74, 0x44800000, v86
	ds_read2_b32 v[92:93], v105 offset0:138 offset1:154
	ds_read2_b32 v[94:95], v105 offset0:203 offset1:219
	v_add_u32_e32 v108, 0xc00, v31
	v_cvt_pk_fp8_f32 v137, v72, v74 op_sel:[0,0,1]
	s_waitcnt lgkmcnt(3)
	v_mul_f32_e32 v72, 0x44800000, v88
	s_waitcnt lgkmcnt(2)
	v_mul_f32_e32 v74, 0x44800000, v90
	ds_read2_b32 v[96:97], v108 offset0:12 offset1:28
	ds_read2_b32 v[98:99], v108 offset0:77 offset1:93
	v_cvt_pk_fp8_f32 v138, v72, v74
	s_waitcnt lgkmcnt(3)
	v_mul_f32_e32 v72, 0x44800000, v92
	s_waitcnt lgkmcnt(2)
	v_mul_f32_e32 v74, 0x44800000, v94
	ds_read2_b32 v[100:101], v108 offset0:142 offset1:158
	ds_read2_b32 v[102:103], v108 offset0:207 offset1:223
	v_cvt_pk_fp8_f32 v138, v72, v74 op_sel:[0,0,1]
	s_waitcnt lgkmcnt(3)
	v_mul_f32_e32 v72, 0x44800000, v96
	s_waitcnt lgkmcnt(2)
	v_mul_f32_e32 v74, 0x44800000, v98
	v_cvt_pk_fp8_f32 v139, v72, v74
	v_mul_f32_e32 v73, 0x44800000, v73
	v_mul_f32_e32 v74, 0x44800000, v75
	v_mov_b32_e32 v72, v1
	v_cvt_pk_fp8_f32 v72, v73, v74
	s_waitcnt lgkmcnt(1)
	v_mul_f32_e32 v73, 0x44800000, v100
	s_waitcnt lgkmcnt(0)
	v_mul_f32_e32 v74, 0x44800000, v102
	v_cvt_pk_fp8_f32 v139, v73, v74 op_sel:[0,0,1]
	v_mul_f32_e32 v73, 0x44800000, v77
	v_mul_f32_e32 v74, 0x44800000, v79
	v_cvt_pk_fp8_f32 v72, v73, v74 op_sel:[0,0,1]
	v_mul_f32_e32 v74, 0x44800000, v81
	v_mul_f32_e32 v75, 0x44800000, v83
	v_mov_b32_e32 v73, v1
	v_cvt_pk_fp8_f32 v73, v74, v75
	v_mul_f32_e32 v74, 0x44800000, v85
	v_mul_f32_e32 v75, 0x44800000, v87
	v_mul_f32_e32 v78, 0x44800000, v91
	v_cvt_pk_fp8_f32 v73, v74, v75 op_sel:[0,0,1]
	v_mul_f32_e32 v75, 0x44800000, v89
	v_mov_b32_e32 v74, v1
	v_cvt_pk_fp8_f32 v74, v75, v78
	v_mul_f32_e32 v82, 0x44800000, v97
	v_mul_f32_e32 v83, 0x44800000, v99
	v_mov_b32_e32 v75, v1
	v_cvt_pk_fp8_f32 v75, v82, v83
	v_mul_f32_e32 v78, 0x44800000, v93
	v_mul_f32_e32 v79, 0x44800000, v95
	v_cvt_pk_fp8_f32 v74, v78, v79 op_sel:[0,0,1]
	v_mul_f32_e32 v78, 0x44800000, v101
	v_mul_f32_e32 v79, 0x44800000, v103
	v_cvt_pk_fp8_f32 v75, v78, v79 op_sel:[0,0,1]
	v_lshl_add_u64 v[80:81], s[10:11], 0, v[2:3]
	ds_read2_b32 v[78:79], v31 offset0:32 offset1:48
	ds_read2_b32 v[82:83], v31 offset0:97 offset1:113
	v_lshl_add_u64 v[76:77], v[80:81], 0, v[4:5]
	global_store_dwordx4 v[76:77], v[136:139], off nt
	v_lshl_add_u64 v[76:77], v[80:81], 0, v[6:7]
	global_store_dwordx4 v[76:77], v[72:75], off nt
	ds_read2_b32 v[84:85], v31 offset0:162 offset1:178
	ds_read2_b32 v[86:87], v31 offset0:227 offset1:243
	s_waitcnt lgkmcnt(3)
	v_mul_f32_e32 v73, 0x44800000, v78
	s_waitcnt lgkmcnt(2)
	v_mul_f32_e32 v74, 0x44800000, v82
	v_mov_b32_e32 v72, v1
	ds_read2_b32 v[76:77], v104 offset0:36 offset1:52
	ds_read2_b32 v[88:89], v104 offset0:101 offset1:117
	v_cvt_pk_fp8_f32 v72, v73, v74
	s_waitcnt lgkmcnt(3)
	v_mul_f32_e32 v73, 0x44800000, v84
	s_waitcnt lgkmcnt(2)
	v_mul_f32_e32 v74, 0x44800000, v86
	ds_read2_b32 v[90:91], v104 offset0:166 offset1:182
	ds_read2_b32 v[92:93], v104 offset0:231 offset1:247
	v_cvt_pk_fp8_f32 v72, v73, v74 op_sel:[0,0,1]
	s_waitcnt lgkmcnt(3)
	v_mul_f32_e32 v74, 0x44800000, v76
	s_waitcnt lgkmcnt(2)
	v_mul_f32_e32 v75, 0x44800000, v88
	v_mov_b32_e32 v73, v1
	ds_read2_b32 v[94:95], v105 offset0:40 offset1:56
	ds_read2_b32 v[96:97], v105 offset0:105 offset1:121
	v_cvt_pk_fp8_f32 v73, v74, v75
	ds_read2_b32 v[98:99], v105 offset0:170 offset1:186
	ds_read2_b32 v[100:101], v105 offset0:235 offset1:251
	ds_read2_b32 v[102:103], v108 offset0:44 offset1:60
	ds_read2_b32 v[104:105], v108 offset0:109 offset1:125
	s_waitcnt lgkmcnt(7)
	v_mul_f32_e32 v74, 0x44800000, v90
	s_waitcnt lgkmcnt(6)
	v_mul_f32_e32 v75, 0x44800000, v92
	v_cvt_pk_fp8_f32 v73, v74, v75 op_sel:[0,0,1]
	s_waitcnt lgkmcnt(5)
	v_mul_f32_e32 v75, 0x44800000, v94
	s_waitcnt lgkmcnt(4)
	v_mul_f32_e32 v76, 0x44800000, v96
	v_mov_b32_e32 v74, v1
	ds_read2_b32 v[106:107], v108 offset0:174 offset1:190
	ds_read2_b32 v[108:109], v108 offset0:239 offset1:255
	v_cvt_pk_fp8_f32 v74, v75, v76
	v_mov_b32_e32 v75, v1
	s_waitcnt lgkmcnt(3)
	v_mul_f32_e32 v82, 0x44800000, v102
	s_waitcnt lgkmcnt(2)
	v_mul_f32_e32 v84, 0x44800000, v104
	v_cvt_pk_fp8_f32 v75, v82, v84
	v_mul_f32_e32 v76, 0x44800000, v98
	v_mul_f32_e32 v78, 0x44800000, v100
	v_cvt_pk_fp8_f32 v74, v76, v78 op_sel:[0,0,1]
	s_waitcnt lgkmcnt(1)
	v_mul_f32_e32 v76, 0x44800000, v106
	s_waitcnt lgkmcnt(0)
	v_mul_f32_e32 v78, 0x44800000, v108
	v_cvt_pk_fp8_f32 v75, v76, v78 op_sel:[0,0,1]
	v_mul_f32_e32 v78, 0x44800000, v79
	v_mul_f32_e32 v79, 0x44800000, v83
	v_mov_b32_e32 v76, v1
	v_cvt_pk_fp8_f32 v76, v78, v79
	v_mul_f32_e32 v78, 0x44800000, v77
	v_mul_f32_e32 v79, 0x44800000, v89
	v_mov_b32_e32 v77, v1
	v_cvt_pk_fp8_f32 v77, v78, v79
	v_mul_f32_e32 v78, 0x44800000, v85
	v_mul_f32_e32 v79, 0x44800000, v87
	v_cvt_pk_fp8_f32 v76, v78, v79 op_sel:[0,0,1]
	v_mul_f32_e32 v78, 0x44800000, v91
	v_mul_f32_e32 v79, 0x44800000, v93
	v_cvt_pk_fp8_f32 v77, v78, v79 op_sel:[0,0,1]
	v_mul_f32_e32 v79, 0x44800000, v95
	v_mul_f32_e32 v82, 0x44800000, v97
	v_mov_b32_e32 v78, v1
	v_cvt_pk_fp8_f32 v78, v79, v82
	v_mul_f32_e32 v84, 0x44800000, v103
	v_mul_f32_e32 v85, 0x44800000, v105
	v_mov_b32_e32 v79, v1
	v_cvt_pk_fp8_f32 v79, v84, v85
	v_mul_f32_e32 v82, 0x44800000, v99
	v_mul_f32_e32 v83, 0x44800000, v101
	v_cvt_pk_fp8_f32 v78, v82, v83 op_sel:[0,0,1]
	v_mul_f32_e32 v82, 0x44800000, v107
	v_mul_f32_e32 v83, 0x44800000, v109
	v_cvt_pk_fp8_f32 v79, v82, v83 op_sel:[0,0,1]
	v_lshl_add_u64 v[82:83], v[80:81], 0, v[8:9]
	global_store_dwordx4 v[82:83], v[72:75], off nt
	s_mov_b64 s[10:11], 0
	s_nop 0
	v_lshl_add_u64 v[72:73], v[80:81], 0, v[10:11]
	global_store_dwordx4 v[72:73], v[76:79], off nt
	s_waitcnt lgkmcnt(0)
; #define LAS __attribute__((address_space(3)))
; #define LDS_WAIT() asm volatile("s_waitcnt lgkmcnt(0)" ::: "memory")
; __device__ __forceinline__ void transpose_item(const float* W, int N, bf16_t* WT, int nkt, int k0, int n0, int r0, int kbd, LAS float* scr, int lane) {
;     const size_t dst_off = ((size_t)(r0 >> 8) * nkt + kbd) * 16384 + (size_t)(r0 & 255) * 64;
;     const int l15 = lane & 15, lq = lane >> 4;
;     f32x4 v[16];
; #pragma unroll
;     for (int i = 0; i < 16; ++i) v[i] = *(const f32x4*)(W + (size_t)(k0 + 4 * i + lq) * N + n0 + 4 * l15);
; #pragma unroll
;     for (int i = 0; i < 16; ++i) { LAS float* d = scr + (4 * i + lq) * 65 + 4 * l15; d[0] = v[i][0]; d[1] = v[i][1]; d[2] = v[i][2]; d[3] = v[i][3]; }
;     LDS_WAIT();
; __device__ __forceinline__ void phase0(const Params& p, LAS unsigned char* lds, int gw, int NGW, int wave, int lane, int G) {
;     ...
;     for (int it = gw; it < I0; it += NGW) {
;         const int nb = it % 192, kb = it / 192;
;         if (nb < 64) transpose_item(p.in[2], DIN, (bf16_t*)(ws + WS_W_IN), 64, kb * 64, nb * 64, nb * 64, kb, scr, lane);
.LBB0_25:
	s_andn2_b64 vcc, exec, s[10:11]
	s_cbranch_vccnz .LBB0_22
	s_ashr_i32 s7, s6, 31
	v_lshl_add_u64 v[122:123], s[6:7], 2, v[12:13]
	v_mad_i64_i32 v[72:73], s[6:7], v71, s63, v[122:123]
	v_mad_i64_i32 v[74:75], s[6:7], v70, s63, v[122:123]
	v_mad_i64_i32 v[78:79], s[6:7], v69, s63, v[122:123]
	v_mad_i64_i32 v[68:69], s[6:7], v68, s63, v[122:123]
	global_load_dwordx4 v[70:73], v[72:73], off nt
	s_nop 0
	global_load_dwordx4 v[74:77], v[74:75], off nt
	s_nop 0
	global_load_dwordx4 v[78:81], v[78:79], off nt
	s_nop 0
	global_load_dwordx4 v[82:85], v[68:69], off nt
	v_mad_i64_i32 v[68:69], s[6:7], v67, s63, v[122:123]
	v_mad_i64_i32 v[86:87], s[6:7], v66, s63, v[122:123]
	v_mad_i64_i32 v[90:91], s[6:7], v65, s63, v[122:123]
	v_mad_i64_i32 v[64:65], s[6:7], v64, s63, v[122:123]
	global_load_dwordx4 v[66:69], v[68:69], off nt
	s_nop 0
	global_load_dwordx4 v[86:89], v[86:87], off nt
	s_nop 0
	global_load_dwordx4 v[90:93], v[90:91], off nt
	s_nop 0
	global_load_dwordx4 v[94:97], v[64:65], off nt
	v_mad_i64_i32 v[64:65], s[6:7], v63, s63, v[122:123]
	v_mad_i64_i32 v[98:99], s[6:7], v62, s63, v[122:123]
	v_mad_i64_i32 v[102:103], s[6:7], v25, s63, v[122:123]
	v_mad_i64_i32 v[106:107], s[6:7], v27, s63, v[122:123]
	v_mad_i64_i32 v[110:111], s[6:7], v29, s63, v[122:123]
	v_mad_i64_i32 v[114:115], s[6:7], v23, s63, v[122:123]
	v_mad_i64_i32 v[118:119], s[6:7], v21, s63, v[122:123]
	global_load_dwordx4 v[62:65], v[64:65], off nt
	s_nop 0
	global_load_dwordx4 v[98:101], v[98:99], off nt
	v_mad_i64_i32 v[122:123], s[6:7], v19, s63, v[122:123]
	global_load_dwordx4 v[102:105], v[102:103], off nt
	s_nop 0
	global_load_dwordx4 v[106:109], v[106:107], off nt
	s_nop 0
	global_load_dwordx4 v[110:113], v[110:111], off nt
	s_nop 0
	global_load_dwordx4 v[114:117], v[114:115], off nt
	s_nop 0
	global_load_dwordx4 v[118:121], v[118:119], off nt
	s_ashr_i32 s6, s5, 2
	global_load_dwordx4 v[122:125], v[122:123], off nt
	s_and_b32 s10, s61, 0x3000
	s_ashr_i32 s5, s4, 31
	s_ashr_i32 s7, s6, 31
	s_lshl_b32 s10, s10, 1
	s_add_u32 s10, s30, s10
	s_addc_u32 s11, s31, 0
	s_lshl_b64 s[6:7], s[6:7], 21
	s_lshl_b64 s[4:5], s[4:5], 15
	s_add_u32 s6, s10, s6
	s_addc_u32 s7, s11, s7
	s_add_u32 s4, s6, s4
	v_add_u32_e32 v29, 0x400, v32
	s_addc_u32 s5, s7, s5
	v_mov_b32_e32 v19, v1
	v_mov_b32_e32 v21, v1
	v_mov_b32_e32 v23, v1
	v_mov_b32_e32 v25, v1
	v_mov_b32_e32 v27, v1
	s_waitcnt vmcnt(15)
	ds_write2_b32 v33, v70, v71 offset1:1
	ds_write2_b32 v33, v72, v73 offset0:2 offset1:3
	s_waitcnt vmcnt(14)
	ds_write2_b32 v34, v74, v75 offset1:1
	ds_write2_b32 v35, v76, v77 offset1:1
	s_waitcnt vmcnt(13)
	ds_write2_b32 v36, v78, v79 offset1:1
	ds_write2_b32 v37, v80, v81 offset1:1
	s_waitcnt vmcnt(12)
	ds_write2_b32 v38, v82, v83 offset1:1
	ds_write2_b32 v39, v84, v85 offset1:1
	s_waitcnt vmcnt(11)
	ds_write2_b32 v40, v66, v67 offset1:1
	ds_write2_b32 v41, v68, v69 offset1:1
	s_waitcnt vmcnt(10)
	ds_write2_b32 v42, v86, v87 offset1:1
	ds_write2_b32 v43, v88, v89 offset1:1
	s_waitcnt vmcnt(9)
	ds_write2_b32 v44, v90, v91 offset1:1
	ds_write2_b32 v45, v92, v93 offset1:1
	s_waitcnt vmcnt(8)
	ds_write2_b32 v46, v94, v95 offset1:1
	ds_write2_b32 v47, v96, v97 offset1:1
	s_waitcnt vmcnt(7)
	ds_write2_b32 v48, v62, v63 offset1:1
	ds_write2_b32 v49, v64, v65 offset1:1
	s_waitcnt vmcnt(6)
	ds_write2_b32 v50, v98, v99 offset1:1
	ds_write2_b32 v51, v100, v101 offset1:1
	s_waitcnt vmcnt(5)
	ds_write2_b32 v52, v102, v103 offset1:1
	ds_write2_b32 v53, v104, v105 offset1:1
	s_waitcnt vmcnt(4)
	ds_write2_b32 v54, v106, v107 offset1:1
	ds_write2_b32 v55, v108, v109 offset1:1
	s_waitcnt vmcnt(3)
	ds_write2_b32 v56, v110, v111 offset1:1
	ds_write2_b32 v57, v112, v113 offset1:1
	s_waitcnt vmcnt(2)
	ds_write2_b32 v58, v114, v115 offset1:1
	ds_write2_b32 v59, v116, v117 offset1:1
	s_waitcnt vmcnt(1)
	ds_write2_b32 v60, v118, v119 offset1:1
	ds_write2_b32 v61, v120, v121 offset1:1
	s_waitcnt vmcnt(0)
	ds_write2_b32 v15, v122, v123 offset1:1
	ds_write2_b32 v17, v124, v125 offset1:1
	s_waitcnt lgkmcnt(0)
	ds_read2_b32 v[62:63], v32 offset1:65
	s_waitcnt lgkmcnt(0)
	v_cvt_pk_bf16_f32 v62, v62, v63
	ds_read2_b32 v[64:65], v32 offset0:130 offset1:195
	v_mov_b32_e32 v15, v1
	s_waitcnt lgkmcnt(0)
; #define LAS __attribute__((address_space(3)))
; __device__ __forceinline__ unsigned cvt_pk_bf16(float lo, float hi) { unsigned r; asm volatile("v_cvt_pk_bf16_f32 %0, %1, %2" : "=v"(r) : "v"(lo), "v"(hi)); return r; }
; #define LDS_WAIT() asm volatile("s_waitcnt lgkmcnt(0)" ::: "memory")
; __device__ __forceinline__ void transpose_item(const float* W, int N, bf16_t* WT, int nkt, int k0, int n0, int r0, int kbd, LAS float* scr, int lane) {
;     ...
;     const int c = lane & 7;
; #pragma unroll
;     for (int j = 0; j < 8; ++j) { const int n = (lane >> 3) + 8 * j; const LAS float* s = scr + (8 * c) * 65 + n;
;         u32x4 o; o.x = cvt_pk_bf16(s[0], s[65]); o.y = cvt_pk_bf16(s[2 * 65], s[3 * 65]); o.z = cvt_pk_bf16(s[4 * 65], s[5 * 65]); o.w = cvt_pk_bf16(s[6 * 65], s[7 * 65]);
;         *(u32x4*)(WT + dst_off + (size_t)n * 64 + 8 * c) = o; }
;     LDS_WAIT();
; }
	v_cvt_pk_bf16_f32 v63, v64, v65
	ds_read2_b32 v[64:65], v29 offset0:4 offset1:69
	v_lshl_add_u64 v[68:69], s[4:5], 0, v[0:1]
	s_waitcnt lgkmcnt(0)
	v_cvt_pk_bf16_f32 v64, v64, v65
	ds_read2_b32 v[66:67], v29 offset0:134 offset1:199
	s_waitcnt lgkmcnt(0)
	v_cvt_pk_bf16_f32 v65, v66, v67
	v_lshl_add_u64 v[70:71], v[68:69], 0, v[14:15]
	ds_read2_b32 v[66:67], v32 offset0:8 offset1:73
	global_store_dwordx4 v[70:71], v[62:65], off nt
	v_mov_b32_e32 v17, v1
	v_lshl_add_u64 v[70:71], v[68:69], 0, v[16:17]
	s_waitcnt lgkmcnt(0)
	v_cvt_pk_bf16_f32 v62, v66, v67
	ds_read2_b32 v[64:65], v32 offset0:138 offset1:203
	s_waitcnt lgkmcnt(0)
	v_cvt_pk_bf16_f32 v63, v64, v65
	ds_read2_b32 v[64:65], v29 offset0:12 offset1:77
	s_waitcnt lgkmcnt(0)
	v_cvt_pk_bf16_f32 v64, v64, v65
	ds_read2_b32 v[66:67], v29 offset0:142 offset1:207
	s_waitcnt lgkmcnt(0)
	v_cvt_pk_bf16_f32 v65, v66, v67
	ds_read2_b32 v[66:67], v32 offset0:16 offset1:81
	global_store_dwordx4 v[70:71], v[62:65], off nt
	v_lshl_add_u64 v[70:71], v[68:69], 0, v[18:19]
	s_waitcnt lgkmcnt(0)
	v_cvt_pk_bf16_f32 v62, v66, v67
	ds_read2_b32 v[64:65], v32 offset0:146 offset1:211
	s_waitcnt lgkmcnt(0)
	v_cvt_pk_bf16_f32 v63, v64, v65
	ds_read2_b32 v[64:65], v29 offset0:20 offset1:85
	s_waitcnt lgkmcnt(0)
	v_cvt_pk_bf16_f32 v64, v64, v65
	ds_read2_b32 v[66:67], v29 offset0:150 offset1:215
	s_waitcnt lgkmcnt(0)
	v_cvt_pk_bf16_f32 v65, v66, v67
	ds_read2_b32 v[66:67], v32 offset0:24 offset1:89
	global_store_dwordx4 v[70:71], v[62:65], off nt
	v_lshl_add_u64 v[70:71], v[68:69], 0, v[20:21]
	s_waitcnt lgkmcnt(0)
	v_cvt_pk_bf16_f32 v62, v66, v67
	ds_read2_b32 v[64:65], v32 offset0:154 offset1:219
	s_waitcnt lgkmcnt(0)
	v_cvt_pk_bf16_f32 v63, v64, v65
	ds_read2_b32 v[64:65], v29 offset0:28 offset1:93
	s_waitcnt lgkmcnt(0)
	v_cvt_pk_bf16_f32 v64, v64, v65
	ds_read2_b32 v[66:67], v29 offset0:158 offset1:223
	s_waitcnt lgkmcnt(0)
	v_cvt_pk_bf16_f32 v65, v66, v67
	ds_read2_b32 v[66:67], v32 offset0:32 offset1:97
	global_store_dwordx4 v[70:71], v[62:65], off nt
	v_lshl_add_u64 v[70:71], v[68:69], 0, v[22:23]
	s_waitcnt lgkmcnt(0)
	v_cvt_pk_bf16_f32 v62, v66, v67
	ds_read2_b32 v[64:65], v32 offset0:162 offset1:227
	s_waitcnt lgkmcnt(0)
	v_cvt_pk_bf16_f32 v63, v64, v65
	ds_read2_b32 v[64:65], v29 offset0:36 offset1:101
	s_waitcnt lgkmcnt(0)
	v_cvt_pk_bf16_f32 v64, v64, v65
	ds_read2_b32 v[66:67], v29 offset0:166 offset1:231
	s_waitcnt lgkmcnt(0)
	v_cvt_pk_bf16_f32 v65, v66, v67
	ds_read2_b32 v[66:67], v32 offset0:40 offset1:105
	global_store_dwordx4 v[70:71], v[62:65], off nt
	v_lshl_add_u64 v[70:71], v[68:69], 0, v[24:25]
	s_waitcnt lgkmcnt(0)
	v_cvt_pk_bf16_f32 v62, v66, v67
	ds_read2_b32 v[64:65], v32 offset0:170 offset1:235
	s_waitcnt lgkmcnt(0)
	v_cvt_pk_bf16_f32 v63, v64, v65
	ds_read2_b32 v[64:65], v29 offset0:44 offset1:109
	s_waitcnt lgkmcnt(0)
	v_cvt_pk_bf16_f32 v64, v64, v65
	ds_read2_b32 v[66:67], v29 offset0:174 offset1:239
	s_waitcnt lgkmcnt(0)
	v_cvt_pk_bf16_f32 v65, v66, v67
	ds_read2_b32 v[66:67], v32 offset0:48 offset1:113
	global_store_dwordx4 v[70:71], v[62:65], off nt
	v_lshl_add_u64 v[70:71], v[68:69], 0, v[26:27]
	s_waitcnt lgkmcnt(0)
	v_cvt_pk_bf16_f32 v62, v66, v67
	ds_read2_b32 v[64:65], v32 offset0:178 offset1:243
	s_waitcnt lgkmcnt(0)
	v_cvt_pk_bf16_f32 v63, v64, v65
	ds_read2_b32 v[64:65], v29 offset0:52 offset1:117
	s_waitcnt lgkmcnt(0)
	v_cvt_pk_bf16_f32 v64, v64, v65
	ds_read2_b32 v[66:67], v29 offset0:182 offset1:247
	s_waitcnt lgkmcnt(0)
	v_cvt_pk_bf16_f32 v65, v66, v67
	ds_read2_b32 v[66:67], v32 offset0:56 offset1:121
	global_store_dwordx4 v[70:71], v[62:65], off nt
	s_waitcnt lgkmcnt(0)
	s_nop 0
	v_cvt_pk_bf16_f32 v62, v66, v67
	ds_read2_b32 v[64:65], v32 offset0:186 offset1:251
	s_waitcnt lgkmcnt(0)
	v_cvt_pk_bf16_f32 v63, v64, v65
	ds_read2_b32 v[64:65], v29 offset0:60 offset1:125
	s_waitcnt lgkmcnt(0)
	v_cvt_pk_bf16_f32 v64, v64, v65
	ds_read2_b32 v[66:67], v29 offset0:190 offset1:255
	v_mov_b32_e32 v29, v1
	s_waitcnt lgkmcnt(0)
	v_cvt_pk_bf16_f32 v65, v66, v67
	v_lshl_add_u64 v[66:67], v[68:69], 0, v[28:29]
	global_store_dwordx4 v[66:67], v[62:65], off nt
	s_waitcnt lgkmcnt(0)
	s_branch .LBB0_22

; __device__ __forceinline__ float sigm(float x) { return __builtin_amdgcn_rcpf(1.f + __builtin_amdgcn_exp2f(-1.4426950409f * x)); }
; __device__ __forceinline__ u32x4 pack8s(const f32x4 v0, const f32x4 v1) { u32x4 w; w.x = cvt_pk_bf16s(v0[0], v0[1]); w.y = cvt_pk_bf16s(v0[2], v0[3]); w.z = cvt_pk_bf16s(v1[0], v1[1]); w.w = cvt_pk_bf16s(v1[2], v1[3]); return w; }
;     __device__ __forceinline__ void operator()(AccT& acc, const Unit& u, int wr, int wc, int fr, int fq) const {
;         const bool sg = u.pn >= 16;
;         const int row0 = u.pm * 256 + wr * 64 + fr, col0 = u.pn * 256 + wc * 32 + 8 * fq;
; #pragma unroll
;         for (int ai = 0; ai < 2; ++ai)
; #pragma unroll
;             for (int m = 0; m < 4; ++m) { bf16_t* rowp = O + (size_t)(row0 + ai * 128 + m * 16) * DIN + col0;
; #pragma unroll
;                 for (int bj = 0; bj < 2; ++bj) { f32x4 v0 = acc[ai][bj][m][0], v1 = acc[ai][bj][m][1];
;                     if (sg) {
; #pragma unroll
;                         for (int j = 0; j < 4; ++j) { v0[j] = sigm(v0[j]); v1[j] = sigm(v1[j]); } }
;                     *(u32x4*)(rowp + bj * 128) = pack8s(v0, v1); } }
;     }
.LBB0_121:
	s_lshl_b32 s6, s6, 8
	s_add_i32 s6, s6, s85
	v_and_or_b32 v145, v132, 15, s6
	s_lshl_b32 s6, s33, 8
	v_lshrrev_b32_e32 v132, 1, v132
	v_and_or_b32 v132, v132, 24, s6
	v_or_b32_e32 v132, s86, v132
	v_mov_b64_e32 v[134:135], s[14:15]
	v_ashrrev_i32_e32 v133, 31, v132
	v_mad_i64_i32 v[134:135], s[6:7], v145, s84, v[134:135]
	s_nop 1
	v_cvt_pk_bf16_f32 v124, v124, v125
	s_nop 1
	v_cvt_pk_bf16_f32 v125, v126, v127
	s_nop 1
	v_cvt_pk_bf16_f32 v126, v120, v121
	v_cndmask_b32_e64 v120, 0, 1, s[16:17]
	v_lshl_add_u64 v[134:135], v[132:133], 1, v[134:135]
	v_cmp_ne_u32_e64 s[6:7], 1, v120
	s_andn2_b64 vcc, exec, s[16:17]
	s_nop 1
	v_cvt_pk_bf16_f32 v127, v122, v123
	global_store_dwordx4 v[134:135], v[124:127], off nt
	s_cbranch_vccnz .LBB0_123
	v_mul_f32_e32 v116, 0xbfb8aa3b, v116
	v_mul_f32_e32 v112, 0xbfb8aa3b, v112
	v_mul_f32_e32 v117, 0xbfb8aa3b, v117
	v_mul_f32_e32 v113, 0xbfb8aa3b, v113
	v_mul_f32_e32 v118, 0xbfb8aa3b, v118
	v_mul_f32_e32 v114, 0xbfb8aa3b, v114
	v_mul_f32_e32 v119, 0xbfb8aa3b, v119
	v_mul_f32_e32 v115, 0xbfb8aa3b, v115
	v_exp_f32_e32 v116, v116
	v_exp_f32_e32 v112, v112
	v_exp_f32_e32 v117, v117
	v_exp_f32_e32 v113, v113
	v_exp_f32_e32 v118, v118
	v_exp_f32_e32 v114, v114
	v_exp_f32_e32 v119, v119
	v_exp_f32_e32 v115, v115
	v_add_f32_e32 v116, 1.0, v116
	v_add_f32_e32 v112, 1.0, v112
	v_add_f32_e32 v117, 1.0, v117
	v_add_f32_e32 v113, 1.0, v113
	v_add_f32_e32 v118, 1.0, v118
	v_add_f32_e32 v114, 1.0, v114
	v_add_f32_e32 v119, 1.0, v119
	v_add_f32_e32 v115, 1.0, v115
	v_rcp_f32_e32 v116, v116
	v_rcp_f32_e32 v112, v112
	v_rcp_f32_e32 v117, v117
	v_rcp_f32_e32 v113, v113
	v_rcp_f32_e32 v118, v118
	v_rcp_f32_e32 v114, v114
	v_rcp_f32_e32 v119, v119
	v_rcp_f32_e32 v115, v115
.LBB0_123:
	s_and_b64 vcc, exec, s[6:7]
	s_nop 1
	v_cvt_pk_bf16_f32 v116, v116, v117
	s_nop 1
	v_cvt_pk_bf16_f32 v117, v118, v119
	s_nop 1
	v_cvt_pk_bf16_f32 v118, v112, v113
	s_nop 1
	v_cvt_pk_bf16_f32 v119, v114, v115
	global_store_dwordx4 v[134:135], v[116:119], off offset:256 nt
	s_cbranch_vccnz .LBB0_125
	v_mul_f32_e32 v108, 0xbfb8aa3b, v108
	v_mul_f32_e32 v104, 0xbfb8aa3b, v104
	v_mul_f32_e32 v109, 0xbfb8aa3b, v109
	v_mul_f32_e32 v105, 0xbfb8aa3b, v105
	v_mul_f32_e32 v110, 0xbfb8aa3b, v110
	v_mul_f32_e32 v106, 0xbfb8aa3b, v106
	v_mul_f32_e32 v111, 0xbfb8aa3b, v111
	v_mul_f32_e32 v107, 0xbfb8aa3b, v107
	v_exp_f32_e32 v108, v108
	v_exp_f32_e32 v104, v104
	v_exp_f32_e32 v109, v109
	v_exp_f32_e32 v105, v105
	v_exp_f32_e32 v110, v110
	v_exp_f32_e32 v106, v106
	v_exp_f32_e32 v111, v111
	v_exp_f32_e32 v107, v107
	v_add_f32_e32 v108, 1.0, v108
	v_add_f32_e32 v104, 1.0, v104
	v_add_f32_e32 v109, 1.0, v109
	v_add_f32_e32 v105, 1.0, v105
	v_add_f32_e32 v110, 1.0, v110
	v_add_f32_e32 v106, 1.0, v106
	v_add_f32_e32 v111, 1.0, v111
	v_add_f32_e32 v107, 1.0, v107
	v_rcp_f32_e32 v108, v108
	v_rcp_f32_e32 v104, v104
	v_rcp_f32_e32 v109, v109
	v_rcp_f32_e32 v105, v105
	v_rcp_f32_e32 v110, v110
	v_rcp_f32_e32 v106, v106
	v_rcp_f32_e32 v111, v111
	v_rcp_f32_e32 v107, v107
.LBB0_125:
	v_or_b32_e32 v114, 16, v145
	v_mov_b64_e32 v[112:113], s[14:15]
	v_mad_i64_i32 v[112:113], s[16:17], v114, s84, v[112:113]
	v_lshl_add_u64 v[112:113], v[132:133], 1, v[112:113]
	s_and_b64 vcc, exec, s[6:7]
	s_nop 1
	v_cvt_pk_bf16_f32 v108, v108, v109
	s_nop 1
	v_cvt_pk_bf16_f32 v109, v110, v111
	s_nop 1
	v_cvt_pk_bf16_f32 v110, v104, v105
	s_nop 1
	v_cvt_pk_bf16_f32 v111, v106, v107
	global_store_dwordx4 v[112:113], v[108:111], off nt
	s_cbranch_vccnz .LBB0_127
	v_mul_f32_e32 v100, 0xbfb8aa3b, v100
	v_mul_f32_e32 v96, 0xbfb8aa3b, v96
	v_mul_f32_e32 v101, 0xbfb8aa3b, v101
	v_mul_f32_e32 v97, 0xbfb8aa3b, v97
	v_mul_f32_e32 v102, 0xbfb8aa3b, v102
	v_mul_f32_e32 v98, 0xbfb8aa3b, v98
	v_mul_f32_e32 v103, 0xbfb8aa3b, v103
	v_mul_f32_e32 v99, 0xbfb8aa3b, v99
	v_exp_f32_e32 v100, v100
	v_exp_f32_e32 v96, v96
	v_exp_f32_e32 v101, v101
	v_exp_f32_e32 v97, v97
	v_exp_f32_e32 v102, v102
	v_exp_f32_e32 v98, v98
	v_exp_f32_e32 v103, v103
	v_exp_f32_e32 v99, v99
	v_add_f32_e32 v100, 1.0, v100
	v_add_f32_e32 v96, 1.0, v96
	v_add_f32_e32 v101, 1.0, v101
	v_add_f32_e32 v97, 1.0, v97
	v_add_f32_e32 v102, 1.0, v102
	v_add_f32_e32 v98, 1.0, v98
	v_add_f32_e32 v103, 1.0, v103
	v_add_f32_e32 v99, 1.0, v99
	v_rcp_f32_e32 v100, v100
	v_rcp_f32_e32 v96, v96
	v_rcp_f32_e32 v101, v101
	v_rcp_f32_e32 v97, v97
	v_rcp_f32_e32 v102, v102
	v_rcp_f32_e32 v98, v98
	v_rcp_f32_e32 v103, v103
	v_rcp_f32_e32 v99, v99
.LBB0_127:
	s_and_b64 vcc, exec, s[6:7]
	s_nop 1
	v_cvt_pk_bf16_f32 v100, v100, v101
	s_nop 1
	v_cvt_pk_bf16_f32 v101, v102, v103
	s_nop 1
	v_cvt_pk_bf16_f32 v102, v96, v97
	s_nop 1
	v_cvt_pk_bf16_f32 v103, v98, v99
	global_store_dwordx4 v[112:113], v[100:103], off offset:256 nt
	s_cbranch_vccnz .LBB0_129
	v_mul_f32_e32 v92, 0xbfb8aa3b, v92
	v_mul_f32_e32 v88, 0xbfb8aa3b, v88
	v_mul_f32_e32 v93, 0xbfb8aa3b, v93
	v_mul_f32_e32 v89, 0xbfb8aa3b, v89
	v_mul_f32_e32 v94, 0xbfb8aa3b, v94
	v_mul_f32_e32 v90, 0xbfb8aa3b, v90
	v_mul_f32_e32 v95, 0xbfb8aa3b, v95
	v_mul_f32_e32 v91, 0xbfb8aa3b, v91
	v_exp_f32_e32 v92, v92
	v_exp_f32_e32 v88, v88
	v_exp_f32_e32 v93, v93
	v_exp_f32_e32 v89, v89
	v_exp_f32_e32 v94, v94
	v_exp_f32_e32 v90, v90
	v_exp_f32_e32 v95, v95
	v_exp_f32_e32 v91, v91
	v_add_f32_e32 v92, 1.0, v92
	v_add_f32_e32 v88, 1.0, v88
	v_add_f32_e32 v93, 1.0, v93
	v_add_f32_e32 v89, 1.0, v89
	v_add_f32_e32 v94, 1.0, v94
	v_add_f32_e32 v90, 1.0, v90
	v_add_f32_e32 v95, 1.0, v95
	v_add_f32_e32 v91, 1.0, v91
	v_rcp_f32_e32 v92, v92
	v_rcp_f32_e32 v88, v88
	v_rcp_f32_e32 v93, v93
	v_rcp_f32_e32 v89, v89
	v_rcp_f32_e32 v94, v94
	v_rcp_f32_e32 v90, v90
	v_rcp_f32_e32 v95, v95
	v_rcp_f32_e32 v91, v91
; __device__ __forceinline__ float sigm(float x) { return __builtin_amdgcn_rcpf(1.f + __builtin_amdgcn_exp2f(-1.4426950409f * x)); }
; __device__ __forceinline__ u32x4 pack8s(const f32x4 v0, const f32x4 v1) { u32x4 w; w.x = cvt_pk_bf16s(v0[0], v0[1]); w.y = cvt_pk_bf16s(v0[2], v0[3]); w.z = cvt_pk_bf16s(v1[0], v1[1]); w.w = cvt_pk_bf16s(v1[2], v1[3]); return w; }
;     __device__ __forceinline__ void operator()(AccT& acc, const Unit& u, int wr, int wc, int fr, int fq) const {
;         const bool sg = u.pn >= 16;
;         const int row0 = u.pm * 256 + wr * 64 + fr, col0 = u.pn * 256 + wc * 32 + 8 * fq;
; #pragma unroll
;         for (int ai = 0; ai < 2; ++ai)
; #pragma unroll
;             for (int m = 0; m < 4; ++m) { bf16_t* rowp = O + (size_t)(row0 + ai * 128 + m * 16) * DIN + col0;
; #pragma unroll
;                 for (int bj = 0; bj < 2; ++bj) { f32x4 v0 = acc[ai][bj][m][0], v1 = acc[ai][bj][m][1];
;                     if (sg) {
; #pragma unroll
;                         for (int j = 0; j < 4; ++j) { v0[j] = sigm(v0[j]); v1[j] = sigm(v1[j]); } }
;                     *(u32x4*)(rowp + bj * 128) = pack8s(v0, v1); } }
.LBB0_129:
	v_or_b32_e32 v98, 32, v145
	v_mov_b64_e32 v[96:97], s[14:15]
	v_mad_i64_i32 v[96:97], s[16:17], v98, s84, v[96:97]
	v_lshl_add_u64 v[96:97], v[132:133], 1, v[96:97]
	s_and_b64 vcc, exec, s[6:7]
	s_nop 1
	v_cvt_pk_bf16_f32 v92, v92, v93
	s_nop 1
	v_cvt_pk_bf16_f32 v93, v94, v95
	s_nop 1
	v_cvt_pk_bf16_f32 v94, v88, v89
	s_nop 1
	v_cvt_pk_bf16_f32 v95, v90, v91
	global_store_dwordx4 v[96:97], v[92:95], off nt
	s_cbranch_vccnz .LBB0_131
	v_mul_f32_e32 v84, 0xbfb8aa3b, v84
	v_mul_f32_e32 v80, 0xbfb8aa3b, v80
	v_mul_f32_e32 v85, 0xbfb8aa3b, v85
	v_mul_f32_e32 v81, 0xbfb8aa3b, v81
	v_mul_f32_e32 v86, 0xbfb8aa3b, v86
	v_mul_f32_e32 v82, 0xbfb8aa3b, v82
	v_mul_f32_e32 v87, 0xbfb8aa3b, v87
	v_mul_f32_e32 v83, 0xbfb8aa3b, v83
	v_exp_f32_e32 v84, v84
	v_exp_f32_e32 v80, v80
	v_exp_f32_e32 v85, v85
	v_exp_f32_e32 v81, v81
	v_exp_f32_e32 v86, v86
	v_exp_f32_e32 v82, v82
	v_exp_f32_e32 v87, v87
	v_exp_f32_e32 v83, v83
	v_add_f32_e32 v84, 1.0, v84
	v_add_f32_e32 v80, 1.0, v80
	v_add_f32_e32 v85, 1.0, v85
	v_add_f32_e32 v81, 1.0, v81
	v_add_f32_e32 v86, 1.0, v86
	v_add_f32_e32 v82, 1.0, v82
	v_add_f32_e32 v87, 1.0, v87
	v_add_f32_e32 v83, 1.0, v83
	v_rcp_f32_e32 v84, v84
	v_rcp_f32_e32 v80, v80
	v_rcp_f32_e32 v85, v85
	v_rcp_f32_e32 v81, v81
	v_rcp_f32_e32 v86, v86
	v_rcp_f32_e32 v82, v82
	v_rcp_f32_e32 v87, v87
	v_rcp_f32_e32 v83, v83
.LBB0_131:
	s_and_b64 vcc, exec, s[6:7]
	s_nop 1
	v_cvt_pk_bf16_f32 v84, v84, v85
	s_nop 1
	v_cvt_pk_bf16_f32 v85, v86, v87
	s_nop 1
	v_cvt_pk_bf16_f32 v86, v80, v81
	s_nop 1
	v_cvt_pk_bf16_f32 v87, v82, v83
	global_store_dwordx4 v[96:97], v[84:87], off offset:256 nt
	s_cbranch_vccnz .LBB0_133
	v_mul_f32_e32 v76, 0xbfb8aa3b, v76
	v_mul_f32_e32 v72, 0xbfb8aa3b, v72
	v_mul_f32_e32 v77, 0xbfb8aa3b, v77
	v_mul_f32_e32 v73, 0xbfb8aa3b, v73
	v_mul_f32_e32 v78, 0xbfb8aa3b, v78
	v_mul_f32_e32 v74, 0xbfb8aa3b, v74
	v_mul_f32_e32 v79, 0xbfb8aa3b, v79
	v_mul_f32_e32 v75, 0xbfb8aa3b, v75
	v_exp_f32_e32 v76, v76
	v_exp_f32_e32 v72, v72
	v_exp_f32_e32 v77, v77
	v_exp_f32_e32 v73, v73
	v_exp_f32_e32 v78, v78
	v_exp_f32_e32 v74, v74
	v_exp_f32_e32 v79, v79
	v_exp_f32_e32 v75, v75
	v_add_f32_e32 v76, 1.0, v76
	v_add_f32_e32 v72, 1.0, v72
	v_add_f32_e32 v77, 1.0, v77
	v_add_f32_e32 v73, 1.0, v73
	v_add_f32_e32 v78, 1.0, v78
	v_add_f32_e32 v74, 1.0, v74
	v_add_f32_e32 v79, 1.0, v79
	v_add_f32_e32 v75, 1.0, v75
	v_rcp_f32_e32 v76, v76
	v_rcp_f32_e32 v72, v72
	v_rcp_f32_e32 v77, v77
	v_rcp_f32_e32 v73, v73
	v_rcp_f32_e32 v78, v78
	v_rcp_f32_e32 v74, v74
	v_rcp_f32_e32 v79, v79
	v_rcp_f32_e32 v75, v75
.LBB0_133:
	v_or_b32_e32 v82, 48, v145
	v_mov_b64_e32 v[80:81], s[14:15]
	v_mad_i64_i32 v[80:81], s[16:17], v82, s84, v[80:81]
	v_lshl_add_u64 v[80:81], v[132:133], 1, v[80:81]
	s_and_b64 vcc, exec, s[6:7]
	s_nop 1
	v_cvt_pk_bf16_f32 v76, v76, v77
	s_nop 1
	v_cvt_pk_bf16_f32 v77, v78, v79
	s_nop 1
	v_cvt_pk_bf16_f32 v78, v72, v73
	s_nop 1
	v_cvt_pk_bf16_f32 v79, v74, v75
	global_store_dwordx4 v[80:81], v[76:79], off nt
	s_cbranch_vccnz .LBB0_135
	v_mul_f32_e32 v68, 0xbfb8aa3b, v68
	v_mul_f32_e32 v64, 0xbfb8aa3b, v64
	v_mul_f32_e32 v69, 0xbfb8aa3b, v69
	v_mul_f32_e32 v65, 0xbfb8aa3b, v65
	v_mul_f32_e32 v70, 0xbfb8aa3b, v70
	v_mul_f32_e32 v66, 0xbfb8aa3b, v66
	v_mul_f32_e32 v71, 0xbfb8aa3b, v71
	v_mul_f32_e32 v67, 0xbfb8aa3b, v67
	v_exp_f32_e32 v68, v68
	v_exp_f32_e32 v64, v64
	v_exp_f32_e32 v69, v69
	v_exp_f32_e32 v65, v65
	v_exp_f32_e32 v70, v70
	v_exp_f32_e32 v66, v66
	v_exp_f32_e32 v71, v71
	v_exp_f32_e32 v67, v67
	v_add_f32_e32 v68, 1.0, v68
	v_add_f32_e32 v64, 1.0, v64
	v_add_f32_e32 v69, 1.0, v69
	v_add_f32_e32 v65, 1.0, v65
	v_add_f32_e32 v70, 1.0, v70
	v_add_f32_e32 v66, 1.0, v66
	v_add_f32_e32 v71, 1.0, v71
	v_add_f32_e32 v67, 1.0, v67
	v_rcp_f32_e32 v68, v68
	v_rcp_f32_e32 v64, v64
	v_rcp_f32_e32 v69, v69
	v_rcp_f32_e32 v65, v65
	v_rcp_f32_e32 v70, v70
	v_rcp_f32_e32 v66, v66
	v_rcp_f32_e32 v71, v71
	v_rcp_f32_e32 v67, v67
.LBB0_135:
	s_and_b64 vcc, exec, s[6:7]
	s_nop 1
	v_cvt_pk_bf16_f32 v68, v68, v69
	s_nop 1
	v_cvt_pk_bf16_f32 v69, v70, v71
	s_nop 1
	v_cvt_pk_bf16_f32 v70, v64, v65
	s_nop 1
	v_cvt_pk_bf16_f32 v71, v66, v67
	global_store_dwordx4 v[80:81], v[68:71], off offset:256 nt
	s_cbranch_vccnz .LBB0_137
	v_mul_f32_e32 v60, 0xbfb8aa3b, v60
	v_mul_f32_e32 v56, 0xbfb8aa3b, v56
	v_mul_f32_e32 v61, 0xbfb8aa3b, v61
	v_mul_f32_e32 v57, 0xbfb8aa3b, v57
	v_mul_f32_e32 v62, 0xbfb8aa3b, v62
	v_mul_f32_e32 v58, 0xbfb8aa3b, v58
	v_mul_f32_e32 v63, 0xbfb8aa3b, v63
	v_mul_f32_e32 v59, 0xbfb8aa3b, v59
	v_exp_f32_e32 v60, v60
	v_exp_f32_e32 v56, v56
	v_exp_f32_e32 v61, v61
	v_exp_f32_e32 v57, v57
	v_exp_f32_e32 v62, v62
	v_exp_f32_e32 v58, v58
	v_exp_f32_e32 v63, v63
	v_exp_f32_e32 v59, v59
	v_add_f32_e32 v60, 1.0, v60
	v_add_f32_e32 v56, 1.0, v56
	v_add_f32_e32 v61, 1.0, v61
	v_add_f32_e32 v57, 1.0, v57
	v_add_f32_e32 v62, 1.0, v62
	v_add_f32_e32 v58, 1.0, v58
	v_add_f32_e32 v63, 1.0, v63
	v_add_f32_e32 v59, 1.0, v59
	v_rcp_f32_e32 v60, v60
	v_rcp_f32_e32 v56, v56
	v_rcp_f32_e32 v61, v61
	v_rcp_f32_e32 v57, v57
	v_rcp_f32_e32 v62, v62
	v_rcp_f32_e32 v58, v58
	v_rcp_f32_e32 v63, v63
	v_rcp_f32_e32 v59, v59
; __device__ __forceinline__ float sigm(float x) { return __builtin_amdgcn_rcpf(1.f + __builtin_amdgcn_exp2f(-1.4426950409f * x)); }
; __device__ __forceinline__ u32x4 pack8s(const f32x4 v0, const f32x4 v1) { u32x4 w; w.x = cvt_pk_bf16s(v0[0], v0[1]); w.y = cvt_pk_bf16s(v0[2], v0[3]); w.z = cvt_pk_bf16s(v1[0], v1[1]); w.w = cvt_pk_bf16s(v1[2], v1[3]); return w; }
;     __device__ __forceinline__ void operator()(AccT& acc, const Unit& u, int wr, int wc, int fr, int fq) const {
;         const bool sg = u.pn >= 16;
;         const int row0 = u.pm * 256 + wr * 64 + fr, col0 = u.pn * 256 + wc * 32 + 8 * fq;
; #pragma unroll
;         for (int ai = 0; ai < 2; ++ai)
; #pragma unroll
;             for (int m = 0; m < 4; ++m) { bf16_t* rowp = O + (size_t)(row0 + ai * 128 + m * 16) * DIN + col0;
; #pragma unroll
;                 for (int bj = 0; bj < 2; ++bj) { f32x4 v0 = acc[ai][bj][m][0], v1 = acc[ai][bj][m][1];
;                     if (sg) {
; #pragma unroll
;                         for (int j = 0; j < 4; ++j) { v0[j] = sigm(v0[j]); v1[j] = sigm(v1[j]); } }
;                     *(u32x4*)(rowp + bj * 128) = pack8s(v0, v1); } }
.LBB0_137:
	v_add_u32_e32 v66, 0x80, v145
	v_mov_b64_e32 v[64:65], s[14:15]
	v_mad_i64_i32 v[64:65], s[16:17], v66, s84, v[64:65]
	v_lshl_add_u64 v[64:65], v[132:133], 1, v[64:65]
	s_and_b64 vcc, exec, s[6:7]
	s_nop 1
	v_cvt_pk_bf16_f32 v60, v60, v61
	s_nop 1
	v_cvt_pk_bf16_f32 v61, v62, v63
	s_nop 1
	v_cvt_pk_bf16_f32 v62, v56, v57
	s_nop 1
	v_cvt_pk_bf16_f32 v63, v58, v59
	global_store_dwordx4 v[64:65], v[60:63], off nt
	s_cbranch_vccnz .LBB0_139
	v_mul_f32_e32 v52, 0xbfb8aa3b, v52
	v_mul_f32_e32 v48, 0xbfb8aa3b, v48
	v_mul_f32_e32 v53, 0xbfb8aa3b, v53
	v_mul_f32_e32 v49, 0xbfb8aa3b, v49
	v_mul_f32_e32 v54, 0xbfb8aa3b, v54
	v_mul_f32_e32 v50, 0xbfb8aa3b, v50
	v_mul_f32_e32 v55, 0xbfb8aa3b, v55
	v_mul_f32_e32 v51, 0xbfb8aa3b, v51
	v_exp_f32_e32 v52, v52
	v_exp_f32_e32 v48, v48
	v_exp_f32_e32 v53, v53
	v_exp_f32_e32 v49, v49
	v_exp_f32_e32 v54, v54
	v_exp_f32_e32 v50, v50
	v_exp_f32_e32 v55, v55
	v_exp_f32_e32 v51, v51
	v_add_f32_e32 v52, 1.0, v52
	v_add_f32_e32 v48, 1.0, v48
	v_add_f32_e32 v53, 1.0, v53
	v_add_f32_e32 v49, 1.0, v49
	v_add_f32_e32 v54, 1.0, v54
	v_add_f32_e32 v50, 1.0, v50
	v_add_f32_e32 v55, 1.0, v55
	v_add_f32_e32 v51, 1.0, v51
	v_rcp_f32_e32 v52, v52
	v_rcp_f32_e32 v48, v48
	v_rcp_f32_e32 v53, v53
	v_rcp_f32_e32 v49, v49
	v_rcp_f32_e32 v54, v54
	v_rcp_f32_e32 v50, v50
	v_rcp_f32_e32 v55, v55
	v_rcp_f32_e32 v51, v51
.LBB0_139:
	s_and_b64 vcc, exec, s[6:7]
	s_nop 1
	v_cvt_pk_bf16_f32 v52, v52, v53
	s_nop 1
	v_cvt_pk_bf16_f32 v53, v54, v55
	s_nop 1
	v_cvt_pk_bf16_f32 v54, v48, v49
	s_nop 1
	v_cvt_pk_bf16_f32 v55, v50, v51
	global_store_dwordx4 v[64:65], v[52:55], off offset:256 nt
	s_cbranch_vccnz .LBB0_141
	v_mul_f32_e32 v44, 0xbfb8aa3b, v44
	v_mul_f32_e32 v40, 0xbfb8aa3b, v40
	v_mul_f32_e32 v45, 0xbfb8aa3b, v45
	v_mul_f32_e32 v41, 0xbfb8aa3b, v41
	v_mul_f32_e32 v46, 0xbfb8aa3b, v46
	v_mul_f32_e32 v42, 0xbfb8aa3b, v42
	v_mul_f32_e32 v47, 0xbfb8aa3b, v47
	v_mul_f32_e32 v43, 0xbfb8aa3b, v43
	v_exp_f32_e32 v44, v44
	v_exp_f32_e32 v40, v40
	v_exp_f32_e32 v45, v45
	v_exp_f32_e32 v41, v41
	v_exp_f32_e32 v46, v46
	v_exp_f32_e32 v42, v42
	v_exp_f32_e32 v47, v47
	v_exp_f32_e32 v43, v43
	v_add_f32_e32 v44, 1.0, v44
	v_add_f32_e32 v40, 1.0, v40
	v_add_f32_e32 v45, 1.0, v45
	v_add_f32_e32 v41, 1.0, v41
	v_add_f32_e32 v46, 1.0, v46
	v_add_f32_e32 v42, 1.0, v42
	v_add_f32_e32 v47, 1.0, v47
	v_add_f32_e32 v43, 1.0, v43
	v_rcp_f32_e32 v44, v44
	v_rcp_f32_e32 v40, v40
	v_rcp_f32_e32 v45, v45
	v_rcp_f32_e32 v41, v41
	v_rcp_f32_e32 v46, v46
	v_rcp_f32_e32 v42, v42
	v_rcp_f32_e32 v47, v47
	v_rcp_f32_e32 v43, v43
.LBB0_141:
	v_add_u32_e32 v50, 0x90, v145
	v_mov_b64_e32 v[48:49], s[14:15]
	v_mad_i64_i32 v[48:49], s[16:17], v50, s84, v[48:49]
	v_lshl_add_u64 v[48:49], v[132:133], 1, v[48:49]
	s_and_b64 vcc, exec, s[6:7]
	s_nop 1
	v_cvt_pk_bf16_f32 v44, v44, v45
	s_nop 1
	v_cvt_pk_bf16_f32 v45, v46, v47
	s_nop 1
	v_cvt_pk_bf16_f32 v46, v40, v41
	s_nop 1
	v_cvt_pk_bf16_f32 v47, v42, v43
	global_store_dwordx4 v[48:49], v[44:47], off nt
	s_cbranch_vccnz .LBB0_143
	v_mul_f32_e32 v36, 0xbfb8aa3b, v36
	v_mul_f32_e32 v32, 0xbfb8aa3b, v32
	v_mul_f32_e32 v37, 0xbfb8aa3b, v37
	v_mul_f32_e32 v33, 0xbfb8aa3b, v33
	v_mul_f32_e32 v38, 0xbfb8aa3b, v38
	v_mul_f32_e32 v34, 0xbfb8aa3b, v34
	v_mul_f32_e32 v39, 0xbfb8aa3b, v39
	v_mul_f32_e32 v35, 0xbfb8aa3b, v35
	v_exp_f32_e32 v36, v36
	v_exp_f32_e32 v32, v32
	v_exp_f32_e32 v37, v37
	v_exp_f32_e32 v33, v33
	v_exp_f32_e32 v38, v38
	v_exp_f32_e32 v34, v34
	v_exp_f32_e32 v39, v39
	v_exp_f32_e32 v35, v35
	v_add_f32_e32 v36, 1.0, v36
	v_add_f32_e32 v32, 1.0, v32
	v_add_f32_e32 v37, 1.0, v37
	v_add_f32_e32 v33, 1.0, v33
	v_add_f32_e32 v38, 1.0, v38
	v_add_f32_e32 v34, 1.0, v34
	v_add_f32_e32 v39, 1.0, v39
	v_add_f32_e32 v35, 1.0, v35
	v_rcp_f32_e32 v36, v36
	v_rcp_f32_e32 v32, v32
	v_rcp_f32_e32 v37, v37
	v_rcp_f32_e32 v33, v33
	v_rcp_f32_e32 v38, v38
	v_rcp_f32_e32 v34, v34
	v_rcp_f32_e32 v39, v39
	v_rcp_f32_e32 v35, v35
.LBB0_143:
	s_and_b64 vcc, exec, s[6:7]
	s_nop 1
	v_cvt_pk_bf16_f32 v36, v36, v37
	s_nop 1
	v_cvt_pk_bf16_f32 v37, v38, v39
	s_nop 1
	v_cvt_pk_bf16_f32 v38, v32, v33
	s_nop 1
	v_cvt_pk_bf16_f32 v39, v34, v35
	global_store_dwordx4 v[48:49], v[36:39], off offset:256 nt
	s_cbranch_vccnz .LBB0_145
	v_mul_f32_e32 v28, 0xbfb8aa3b, v28
	v_mul_f32_e32 v24, 0xbfb8aa3b, v24
	v_mul_f32_e32 v29, 0xbfb8aa3b, v29
	v_mul_f32_e32 v25, 0xbfb8aa3b, v25
	v_mul_f32_e32 v30, 0xbfb8aa3b, v30
	v_mul_f32_e32 v26, 0xbfb8aa3b, v26
	v_mul_f32_e32 v31, 0xbfb8aa3b, v31
	v_mul_f32_e32 v27, 0xbfb8aa3b, v27
	v_exp_f32_e32 v28, v28
	v_exp_f32_e32 v24, v24
	v_exp_f32_e32 v29, v29
	v_exp_f32_e32 v25, v25
	v_exp_f32_e32 v30, v30
	v_exp_f32_e32 v26, v26
	v_exp_f32_e32 v31, v31
	v_exp_f32_e32 v27, v27
	v_add_f32_e32 v28, 1.0, v28
	v_add_f32_e32 v24, 1.0, v24
	v_add_f32_e32 v29, 1.0, v29
	v_add_f32_e32 v25, 1.0, v25
	v_add_f32_e32 v30, 1.0, v30
	v_add_f32_e32 v26, 1.0, v26
	v_add_f32_e32 v31, 1.0, v31
	v_add_f32_e32 v27, 1.0, v27
	v_rcp_f32_e32 v28, v28
	v_rcp_f32_e32 v24, v24
	v_rcp_f32_e32 v29, v29
	v_rcp_f32_e32 v25, v25
	v_rcp_f32_e32 v30, v30
	v_rcp_f32_e32 v26, v26
	v_rcp_f32_e32 v31, v31
	v_rcp_f32_e32 v27, v27
; __device__ __forceinline__ float sigm(float x) { return __builtin_amdgcn_rcpf(1.f + __builtin_amdgcn_exp2f(-1.4426950409f * x)); }
; #define PG8_BAR __builtin_amdgcn_s_barrier()
; __device__ __forceinline__ u32x4 pack8s(const f32x4 v0, const f32x4 v1) { u32x4 w; w.x = cvt_pk_bf16s(v0[0], v0[1]); w.y = cvt_pk_bf16s(v0[2], v0[3]); w.z = cvt_pk_bf16s(v1[0], v1[1]); w.w = cvt_pk_bf16s(v1[2], v1[3]); return w; }
; template <class Epi, class Sched, bool F8 = false>
; __device__ __forceinline__ void gemm_phase(LAS unsigned char* lds, const int lda, const int ldb, const Sched& S, const Epi& E) {
;     ...
;         if (!has_next) break;
;         if (!(Epi::KEEP && cur.kind == 0)) {
; #pragma unroll
;         for (int a = 0; a < 2; ++a)
; #pragma unroll
;             for (int b = 0; b < 2; ++b)
; #pragma unroll
;                 for (int m = 0; m < 4; ++m)
; #pragma unroll
;                     for (int n = 0; n < 2; ++n) acc[a][b][m][n] = (f32x4){0.f, 0.f, 0.f, 0.f};
;         }
;         cur = nxt; cA = nA; cB = nB; ++ui;
;         if (wr == 1) PG8_BAR;
;     __device__ __forceinline__ void operator()(AccT& acc, const Unit& u, int wr, int wc, int fr, int fq) const {
;         const bool sg = u.pn >= 16;
;         const int row0 = u.pm * 256 + wr * 64 + fr, col0 = u.pn * 256 + wc * 32 + 8 * fq;
; #pragma unroll
;         for (int ai = 0; ai < 2; ++ai)
; #pragma unroll
;             for (int m = 0; m < 4; ++m) { bf16_t* rowp = O + (size_t)(row0 + ai * 128 + m * 16) * DIN + col0;
; #pragma unroll
;                 for (int bj = 0; bj < 2; ++bj) { f32x4 v0 = acc[ai][bj][m][0], v1 = acc[ai][bj][m][1];
;                     if (sg) {
; #pragma unroll
;                         for (int j = 0; j < 4; ++j) { v0[j] = sigm(v0[j]); v1[j] = sigm(v1[j]); } }
;                     *(u32x4*)(rowp + bj * 128) = pack8s(v0, v1); } }
.LBB0_145:
	v_add_u32_e32 v34, 0xa0, v145
	v_mov_b64_e32 v[32:33], s[14:15]
	v_mad_i64_i32 v[32:33], s[16:17], v34, s84, v[32:33]
	v_lshl_add_u64 v[32:33], v[132:133], 1, v[32:33]
	s_and_b64 vcc, exec, s[6:7]
	s_nop 1
	v_cvt_pk_bf16_f32 v28, v28, v29
	s_nop 1
	v_cvt_pk_bf16_f32 v29, v30, v31
	s_nop 1
	v_cvt_pk_bf16_f32 v30, v24, v25
	s_nop 1
	v_cvt_pk_bf16_f32 v31, v26, v27
	global_store_dwordx4 v[32:33], v[28:31], off nt
	s_cbranch_vccnz .LBB0_147
	v_mul_f32_e32 v20, 0xbfb8aa3b, v20
	v_mul_f32_e32 v16, 0xbfb8aa3b, v16
	v_mul_f32_e32 v21, 0xbfb8aa3b, v21
	v_mul_f32_e32 v17, 0xbfb8aa3b, v17
	v_mul_f32_e32 v22, 0xbfb8aa3b, v22
	v_mul_f32_e32 v18, 0xbfb8aa3b, v18
	v_mul_f32_e32 v23, 0xbfb8aa3b, v23
	v_mul_f32_e32 v19, 0xbfb8aa3b, v19
	v_exp_f32_e32 v20, v20
	v_exp_f32_e32 v16, v16
	v_exp_f32_e32 v21, v21
	v_exp_f32_e32 v17, v17
	v_exp_f32_e32 v22, v22
	v_exp_f32_e32 v18, v18
	v_exp_f32_e32 v23, v23
	v_exp_f32_e32 v19, v19
	v_add_f32_e32 v20, 1.0, v20
	v_add_f32_e32 v16, 1.0, v16
	v_add_f32_e32 v21, 1.0, v21
	v_add_f32_e32 v17, 1.0, v17
	v_add_f32_e32 v22, 1.0, v22
	v_add_f32_e32 v18, 1.0, v18
	v_add_f32_e32 v23, 1.0, v23
	v_add_f32_e32 v19, 1.0, v19
	v_rcp_f32_e32 v20, v20
	v_rcp_f32_e32 v16, v16
	v_rcp_f32_e32 v21, v21
	v_rcp_f32_e32 v17, v17
	v_rcp_f32_e32 v22, v22
	v_rcp_f32_e32 v18, v18
	v_rcp_f32_e32 v23, v23
	v_rcp_f32_e32 v19, v19
.LBB0_147:
	s_and_b64 vcc, exec, s[6:7]
	s_nop 1
	v_cvt_pk_bf16_f32 v20, v20, v21
	s_nop 1
	v_cvt_pk_bf16_f32 v21, v22, v23
	s_nop 1
	v_cvt_pk_bf16_f32 v22, v16, v17
	s_nop 1
	v_cvt_pk_bf16_f32 v23, v18, v19
	global_store_dwordx4 v[32:33], v[20:23], off offset:256 nt
	s_cbranch_vccnz .LBB0_149
	v_mul_f32_e32 v12, 0xbfb8aa3b, v12
	v_mul_f32_e32 v8, 0xbfb8aa3b, v8
	v_mul_f32_e32 v13, 0xbfb8aa3b, v13
	v_mul_f32_e32 v9, 0xbfb8aa3b, v9
	v_mul_f32_e32 v14, 0xbfb8aa3b, v14
	v_mul_f32_e32 v10, 0xbfb8aa3b, v10
	v_mul_f32_e32 v15, 0xbfb8aa3b, v15
	v_mul_f32_e32 v11, 0xbfb8aa3b, v11
	v_exp_f32_e32 v12, v12
	v_exp_f32_e32 v8, v8
	v_exp_f32_e32 v13, v13
	v_exp_f32_e32 v9, v9
	v_exp_f32_e32 v14, v14
	v_exp_f32_e32 v10, v10
	v_exp_f32_e32 v15, v15
	v_exp_f32_e32 v11, v11
	v_add_f32_e32 v12, 1.0, v12
	v_add_f32_e32 v8, 1.0, v8
	v_add_f32_e32 v13, 1.0, v13
	v_add_f32_e32 v9, 1.0, v9
	v_add_f32_e32 v14, 1.0, v14
	v_add_f32_e32 v10, 1.0, v10
	v_add_f32_e32 v15, 1.0, v15
	v_add_f32_e32 v11, 1.0, v11
	v_rcp_f32_e32 v12, v12
	v_rcp_f32_e32 v8, v8
	v_rcp_f32_e32 v13, v13
	v_rcp_f32_e32 v9, v9
	v_rcp_f32_e32 v14, v14
	v_rcp_f32_e32 v10, v10
	v_rcp_f32_e32 v15, v15
	v_rcp_f32_e32 v11, v11
.LBB0_149:
	v_add_u32_e32 v18, 0xb0, v145
	v_mov_b64_e32 v[16:17], s[14:15]
	v_mad_i64_i32 v[16:17], s[16:17], v18, s84, v[16:17]
	v_lshl_add_u64 v[16:17], v[132:133], 1, v[16:17]
	s_and_b64 vcc, exec, s[6:7]
	s_nop 1
	v_cvt_pk_bf16_f32 v12, v12, v13
	s_nop 1
	v_cvt_pk_bf16_f32 v13, v14, v15
	s_nop 1
	v_cvt_pk_bf16_f32 v14, v8, v9
	s_nop 1
	v_cvt_pk_bf16_f32 v15, v10, v11
	global_store_dwordx4 v[16:17], v[12:15], off nt
	s_cbranch_vccnz .LBB0_151
	v_mul_f32_e32 v4, 0xbfb8aa3b, v4
	v_mul_f32_e32 v0, 0xbfb8aa3b, v0
	v_mul_f32_e32 v5, 0xbfb8aa3b, v5
	v_mul_f32_e32 v1, 0xbfb8aa3b, v1
	v_mul_f32_e32 v6, 0xbfb8aa3b, v6
	v_mul_f32_e32 v2, 0xbfb8aa3b, v2
	v_mul_f32_e32 v7, 0xbfb8aa3b, v7
	v_mul_f32_e32 v3, 0xbfb8aa3b, v3
	v_exp_f32_e32 v4, v4
	v_exp_f32_e32 v0, v0
	v_exp_f32_e32 v5, v5
	v_exp_f32_e32 v1, v1
	v_exp_f32_e32 v6, v6
	v_exp_f32_e32 v2, v2
	v_exp_f32_e32 v7, v7
	v_exp_f32_e32 v3, v3
	v_add_f32_e32 v4, 1.0, v4
	v_add_f32_e32 v0, 1.0, v0
	v_add_f32_e32 v5, 1.0, v5
	v_add_f32_e32 v1, 1.0, v1
	v_add_f32_e32 v6, 1.0, v6
	v_add_f32_e32 v2, 1.0, v2
	v_add_f32_e32 v7, 1.0, v7
	v_add_f32_e32 v3, 1.0, v3
	v_rcp_f32_e32 v4, v4
	v_rcp_f32_e32 v0, v0
	v_rcp_f32_e32 v5, v5
	v_rcp_f32_e32 v1, v1
	v_rcp_f32_e32 v6, v6
	v_rcp_f32_e32 v2, v2
	v_rcp_f32_e32 v7, v7
	v_rcp_f32_e32 v3, v3
.LBB0_151:
	s_andn2_b64 vcc, exec, s[4:5]
	s_mov_b64 s[4:5], -1
	s_nop 1
	v_cvt_pk_bf16_f32 v4, v4, v5
	s_nop 1
	v_cvt_pk_bf16_f32 v5, v6, v7
	s_nop 1
	v_cvt_pk_bf16_f32 v6, v0, v1
	s_nop 1
	v_cvt_pk_bf16_f32 v7, v2, v3
	global_store_dwordx4 v[16:17], v[4:7], off offset:256 nt
	s_cbranch_vccnz .LBB0_108
	s_andn2_b64 vcc, exec, s[36:37]
	s_cbranch_vccnz .LBB0_107
	s_barrier
	s_branch .LBB0_107

; __device__ __forceinline__ float sigm(float x) { return __builtin_amdgcn_rcpf(1.f + __builtin_amdgcn_exp2f(-1.4426950409f * x)); }
; __device__ __forceinline__ u32x4 pack8s(const f32x4 v0, const f32x4 v1) { u32x4 w; w.x = cvt_pk_bf16s(v0[0], v0[1]); w.y = cvt_pk_bf16s(v0[2], v0[3]); w.z = cvt_pk_bf16s(v1[0], v1[1]); w.w = cvt_pk_bf16s(v1[2], v1[3]); return w; }
;     __device__ __forceinline__ void operator()(AccT& acc, const Unit& u, int wr, int wc, int fr, int fq) const {
;         const int pn = u.pn + 16;
;         const bool sg = pn >= 16;
;         const int row0 = u.pm * 256 + wr * 64 + fr, col0 = pn * 256 + wc * 32 + 8 * fq;
; #pragma unroll
;         for (int ai = 0; ai < 2; ++ai)
; #pragma unroll
;             for (int m = 0; m < 4; ++m) { bf16_t* rowp = O + (size_t)(row0 + ai * 128 + m * 16) * DIN + col0;
; #pragma unroll
;                 for (int bj = 0; bj < 2; ++bj) { f32x4 v0 = acc[ai][bj][m][0], v1 = acc[ai][bj][m][1];
;                     if (sg) {
; #pragma unroll
;                         for (int j = 0; j < 4; ++j) { v0[j] = sigm(v0[j] * 6.103515625e-05f); v1[j] = sigm(v1[j] * 6.103515625e-05f); } }
;                     *(u32x4*)(rowp + bj * 128) = pack8s(v0, v1); } }
.LBB0_179:
	s_lshl_b32 s6, s6, 8
	s_add_i32 s6, s6, s88
	v_and_or_b32 v146, v132, 15, s6
	s_lshl_b32 s6, s33, 8
	s_addk_i32 s6, 0x1000
	v_lshrrev_b32_e32 v132, 1, v132
	v_and_or_b32 v132, v132, 24, s6
	v_or_b32_e32 v132, s89, v132
	v_mov_b64_e32 v[134:135], s[14:15]
	v_ashrrev_i32_e32 v133, 31, v132
	v_mad_i64_i32 v[134:135], s[6:7], v146, s87, v[134:135]
	s_nop 1
	v_cvt_pk_bf16_f32 v124, v124, v125
	s_nop 1
	v_cvt_pk_bf16_f32 v125, v126, v127
	s_nop 1
	v_cvt_pk_bf16_f32 v126, v120, v121
	v_cndmask_b32_e64 v120, 0, 1, s[16:17]
	v_lshl_add_u64 v[134:135], v[132:133], 1, v[134:135]
	v_cmp_ne_u32_e64 s[6:7], 1, v120
	s_andn2_b64 vcc, exec, s[16:17]
	s_nop 1
	v_cvt_pk_bf16_f32 v127, v122, v123
	global_store_dwordx4 v[134:135], v[124:127], off nt
	s_cbranch_vccnz .LBB0_181
	v_mul_f32_e32 v116, 0x38800000, v116
	v_mul_f32_e32 v112, 0x38800000, v112
	v_mul_f32_e32 v117, 0x38800000, v117
	v_mul_f32_e32 v113, 0x38800000, v113
	v_mul_f32_e32 v118, 0x38800000, v118
	v_mul_f32_e32 v114, 0x38800000, v114
	v_mul_f32_e32 v119, 0x38800000, v119
	v_mul_f32_e32 v115, 0x38800000, v115
	v_mul_f32_e32 v116, 0xbfb8aa3b, v116
	v_mul_f32_e32 v112, 0xbfb8aa3b, v112
	v_mul_f32_e32 v117, 0xbfb8aa3b, v117
	v_mul_f32_e32 v113, 0xbfb8aa3b, v113
	v_mul_f32_e32 v118, 0xbfb8aa3b, v118
	v_mul_f32_e32 v114, 0xbfb8aa3b, v114
	v_mul_f32_e32 v119, 0xbfb8aa3b, v119
	v_mul_f32_e32 v115, 0xbfb8aa3b, v115
	v_exp_f32_e32 v116, v116
	v_exp_f32_e32 v112, v112
	v_exp_f32_e32 v117, v117
	v_exp_f32_e32 v113, v113
	v_exp_f32_e32 v118, v118
	v_exp_f32_e32 v114, v114
	v_exp_f32_e32 v119, v119
	v_exp_f32_e32 v115, v115
	v_add_f32_e32 v116, 1.0, v116
	v_add_f32_e32 v112, 1.0, v112
	v_add_f32_e32 v117, 1.0, v117
	v_add_f32_e32 v113, 1.0, v113
	v_add_f32_e32 v118, 1.0, v118
	v_add_f32_e32 v114, 1.0, v114
	v_add_f32_e32 v119, 1.0, v119
	v_add_f32_e32 v115, 1.0, v115
	v_rcp_f32_e32 v116, v116
	v_rcp_f32_e32 v112, v112
	v_rcp_f32_e32 v117, v117
	v_rcp_f32_e32 v113, v113
	v_rcp_f32_e32 v118, v118
	v_rcp_f32_e32 v114, v114
	v_rcp_f32_e32 v119, v119
	v_rcp_f32_e32 v115, v115
.LBB0_181:
	s_and_b64 vcc, exec, s[6:7]
	s_nop 1
	v_cvt_pk_bf16_f32 v116, v116, v117
	s_nop 1
	v_cvt_pk_bf16_f32 v117, v118, v119
	s_nop 1
	v_cvt_pk_bf16_f32 v118, v112, v113
	s_nop 1
	v_cvt_pk_bf16_f32 v119, v114, v115
	global_store_dwordx4 v[134:135], v[116:119], off offset:256 nt
	s_cbranch_vccnz .LBB0_183
	v_mul_f32_e32 v108, 0x38800000, v108
	v_mul_f32_e32 v104, 0x38800000, v104
	v_mul_f32_e32 v109, 0x38800000, v109
	v_mul_f32_e32 v105, 0x38800000, v105
	v_mul_f32_e32 v110, 0x38800000, v110
	v_mul_f32_e32 v106, 0x38800000, v106
	v_mul_f32_e32 v111, 0x38800000, v111
	v_mul_f32_e32 v107, 0x38800000, v107
	v_mul_f32_e32 v108, 0xbfb8aa3b, v108
	v_mul_f32_e32 v104, 0xbfb8aa3b, v104
	v_mul_f32_e32 v109, 0xbfb8aa3b, v109
	v_mul_f32_e32 v105, 0xbfb8aa3b, v105
	v_mul_f32_e32 v110, 0xbfb8aa3b, v110
	v_mul_f32_e32 v106, 0xbfb8aa3b, v106
	v_mul_f32_e32 v111, 0xbfb8aa3b, v111
	v_mul_f32_e32 v107, 0xbfb8aa3b, v107
	v_exp_f32_e32 v108, v108
	v_exp_f32_e32 v104, v104
	v_exp_f32_e32 v109, v109
	v_exp_f32_e32 v105, v105
	v_exp_f32_e32 v110, v110
	v_exp_f32_e32 v106, v106
	v_exp_f32_e32 v111, v111
	v_exp_f32_e32 v107, v107
	v_add_f32_e32 v108, 1.0, v108
	v_add_f32_e32 v104, 1.0, v104
	v_add_f32_e32 v109, 1.0, v109
	v_add_f32_e32 v105, 1.0, v105
	v_add_f32_e32 v110, 1.0, v110
	v_add_f32_e32 v106, 1.0, v106
	v_add_f32_e32 v111, 1.0, v111
	v_add_f32_e32 v107, 1.0, v107
	v_rcp_f32_e32 v108, v108
	v_rcp_f32_e32 v104, v104
	v_rcp_f32_e32 v109, v109
	v_rcp_f32_e32 v105, v105
	v_rcp_f32_e32 v110, v110
	v_rcp_f32_e32 v106, v106
	v_rcp_f32_e32 v111, v111
	v_rcp_f32_e32 v107, v107
.LBB0_183:
	v_or_b32_e32 v114, 16, v146
	v_mov_b64_e32 v[112:113], s[14:15]
	v_mad_i64_i32 v[112:113], s[16:17], v114, s87, v[112:113]
	v_lshl_add_u64 v[112:113], v[132:133], 1, v[112:113]
	s_and_b64 vcc, exec, s[6:7]
	s_nop 1
	v_cvt_pk_bf16_f32 v108, v108, v109
	s_nop 1
	v_cvt_pk_bf16_f32 v109, v110, v111
	s_nop 1
	v_cvt_pk_bf16_f32 v110, v104, v105
	s_nop 1
	v_cvt_pk_bf16_f32 v111, v106, v107
	global_store_dwordx4 v[112:113], v[108:111], off nt
	s_cbranch_vccnz .LBB0_185
	v_mul_f32_e32 v100, 0x38800000, v100
	v_mul_f32_e32 v96, 0x38800000, v96
	v_mul_f32_e32 v101, 0x38800000, v101
	v_mul_f32_e32 v97, 0x38800000, v97
	v_mul_f32_e32 v102, 0x38800000, v102
	v_mul_f32_e32 v98, 0x38800000, v98
	v_mul_f32_e32 v103, 0x38800000, v103
	v_mul_f32_e32 v99, 0x38800000, v99
	v_mul_f32_e32 v100, 0xbfb8aa3b, v100
	v_mul_f32_e32 v96, 0xbfb8aa3b, v96
	v_mul_f32_e32 v101, 0xbfb8aa3b, v101
	v_mul_f32_e32 v97, 0xbfb8aa3b, v97
	v_mul_f32_e32 v102, 0xbfb8aa3b, v102
	v_mul_f32_e32 v98, 0xbfb8aa3b, v98
	v_mul_f32_e32 v103, 0xbfb8aa3b, v103
	v_mul_f32_e32 v99, 0xbfb8aa3b, v99
	v_exp_f32_e32 v100, v100
	v_exp_f32_e32 v96, v96
	v_exp_f32_e32 v101, v101
	v_exp_f32_e32 v97, v97
	v_exp_f32_e32 v102, v102
	v_exp_f32_e32 v98, v98
	v_exp_f32_e32 v103, v103
	v_exp_f32_e32 v99, v99
	v_add_f32_e32 v100, 1.0, v100
	v_add_f32_e32 v96, 1.0, v96
	v_add_f32_e32 v101, 1.0, v101
	v_add_f32_e32 v97, 1.0, v97
	v_add_f32_e32 v102, 1.0, v102
	v_add_f32_e32 v98, 1.0, v98
	v_add_f32_e32 v103, 1.0, v103
	v_add_f32_e32 v99, 1.0, v99
	v_rcp_f32_e32 v100, v100
	v_rcp_f32_e32 v96, v96
	v_rcp_f32_e32 v101, v101
	v_rcp_f32_e32 v97, v97
	v_rcp_f32_e32 v102, v102
	v_rcp_f32_e32 v98, v98
	v_rcp_f32_e32 v103, v103
	v_rcp_f32_e32 v99, v99
; __device__ __forceinline__ float sigm(float x) { return __builtin_amdgcn_rcpf(1.f + __builtin_amdgcn_exp2f(-1.4426950409f * x)); }
; __device__ __forceinline__ u32x4 pack8s(const f32x4 v0, const f32x4 v1) { u32x4 w; w.x = cvt_pk_bf16s(v0[0], v0[1]); w.y = cvt_pk_bf16s(v0[2], v0[3]); w.z = cvt_pk_bf16s(v1[0], v1[1]); w.w = cvt_pk_bf16s(v1[2], v1[3]); return w; }
;     __device__ __forceinline__ void operator()(AccT& acc, const Unit& u, int wr, int wc, int fr, int fq) const {
;         const int pn = u.pn + 16;
;         const bool sg = pn >= 16;
;         const int row0 = u.pm * 256 + wr * 64 + fr, col0 = pn * 256 + wc * 32 + 8 * fq;
; #pragma unroll
;         for (int ai = 0; ai < 2; ++ai)
; #pragma unroll
;             for (int m = 0; m < 4; ++m) { bf16_t* rowp = O + (size_t)(row0 + ai * 128 + m * 16) * DIN + col0;
; #pragma unroll
;                 for (int bj = 0; bj < 2; ++bj) { f32x4 v0 = acc[ai][bj][m][0], v1 = acc[ai][bj][m][1];
;                     if (sg) {
; #pragma unroll
;                         for (int j = 0; j < 4; ++j) { v0[j] = sigm(v0[j] * 6.103515625e-05f); v1[j] = sigm(v1[j] * 6.103515625e-05f); } }
;                     *(u32x4*)(rowp + bj * 128) = pack8s(v0, v1); } }
.LBB0_185:
	s_and_b64 vcc, exec, s[6:7]
	s_nop 1
	v_cvt_pk_bf16_f32 v100, v100, v101
	s_nop 1
	v_cvt_pk_bf16_f32 v101, v102, v103
	s_nop 1
	v_cvt_pk_bf16_f32 v102, v96, v97
	s_nop 1
	v_cvt_pk_bf16_f32 v103, v98, v99
	global_store_dwordx4 v[112:113], v[100:103], off offset:256 nt
	s_cbranch_vccnz .LBB0_187
	v_mul_f32_e32 v92, 0x38800000, v92
	v_mul_f32_e32 v88, 0x38800000, v88
	v_mul_f32_e32 v93, 0x38800000, v93
	v_mul_f32_e32 v89, 0x38800000, v89
	v_mul_f32_e32 v94, 0x38800000, v94
	v_mul_f32_e32 v90, 0x38800000, v90
	v_mul_f32_e32 v95, 0x38800000, v95
	v_mul_f32_e32 v91, 0x38800000, v91
	v_mul_f32_e32 v92, 0xbfb8aa3b, v92
	v_mul_f32_e32 v88, 0xbfb8aa3b, v88
	v_mul_f32_e32 v93, 0xbfb8aa3b, v93
	v_mul_f32_e32 v89, 0xbfb8aa3b, v89
	v_mul_f32_e32 v94, 0xbfb8aa3b, v94
	v_mul_f32_e32 v90, 0xbfb8aa3b, v90
	v_mul_f32_e32 v95, 0xbfb8aa3b, v95
	v_mul_f32_e32 v91, 0xbfb8aa3b, v91
	v_exp_f32_e32 v92, v92
	v_exp_f32_e32 v88, v88
	v_exp_f32_e32 v93, v93
	v_exp_f32_e32 v89, v89
	v_exp_f32_e32 v94, v94
	v_exp_f32_e32 v90, v90
	v_exp_f32_e32 v95, v95
	v_exp_f32_e32 v91, v91
	v_add_f32_e32 v92, 1.0, v92
	v_add_f32_e32 v88, 1.0, v88
	v_add_f32_e32 v93, 1.0, v93
	v_add_f32_e32 v89, 1.0, v89
	v_add_f32_e32 v94, 1.0, v94
	v_add_f32_e32 v90, 1.0, v90
	v_add_f32_e32 v95, 1.0, v95
	v_add_f32_e32 v91, 1.0, v91
	v_rcp_f32_e32 v92, v92
	v_rcp_f32_e32 v88, v88
	v_rcp_f32_e32 v93, v93
	v_rcp_f32_e32 v89, v89
	v_rcp_f32_e32 v94, v94
	v_rcp_f32_e32 v90, v90
	v_rcp_f32_e32 v95, v95
	v_rcp_f32_e32 v91, v91
.LBB0_187:
	v_or_b32_e32 v98, 32, v146
	v_mov_b64_e32 v[96:97], s[14:15]
	v_mad_i64_i32 v[96:97], s[16:17], v98, s87, v[96:97]
	v_lshl_add_u64 v[96:97], v[132:133], 1, v[96:97]
	s_and_b64 vcc, exec, s[6:7]
	s_nop 1
	v_cvt_pk_bf16_f32 v92, v92, v93
	s_nop 1
	v_cvt_pk_bf16_f32 v93, v94, v95
	s_nop 1
	v_cvt_pk_bf16_f32 v94, v88, v89
	s_nop 1
	v_cvt_pk_bf16_f32 v95, v90, v91
	global_store_dwordx4 v[96:97], v[92:95], off nt
	s_cbranch_vccnz .LBB0_189
	v_mul_f32_e32 v84, 0x38800000, v84
	v_mul_f32_e32 v80, 0x38800000, v80
	v_mul_f32_e32 v85, 0x38800000, v85
	v_mul_f32_e32 v81, 0x38800000, v81
	v_mul_f32_e32 v86, 0x38800000, v86
	v_mul_f32_e32 v82, 0x38800000, v82
	v_mul_f32_e32 v87, 0x38800000, v87
	v_mul_f32_e32 v83, 0x38800000, v83
	v_mul_f32_e32 v84, 0xbfb8aa3b, v84
	v_mul_f32_e32 v80, 0xbfb8aa3b, v80
	v_mul_f32_e32 v85, 0xbfb8aa3b, v85
	v_mul_f32_e32 v81, 0xbfb8aa3b, v81
	v_mul_f32_e32 v86, 0xbfb8aa3b, v86
	v_mul_f32_e32 v82, 0xbfb8aa3b, v82
	v_mul_f32_e32 v87, 0xbfb8aa3b, v87
	v_mul_f32_e32 v83, 0xbfb8aa3b, v83
	v_exp_f32_e32 v84, v84
	v_exp_f32_e32 v80, v80
	v_exp_f32_e32 v85, v85
	v_exp_f32_e32 v81, v81
	v_exp_f32_e32 v86, v86
	v_exp_f32_e32 v82, v82
	v_exp_f32_e32 v87, v87
	v_exp_f32_e32 v83, v83
	v_add_f32_e32 v84, 1.0, v84
	v_add_f32_e32 v80, 1.0, v80
	v_add_f32_e32 v85, 1.0, v85
	v_add_f32_e32 v81, 1.0, v81
	v_add_f32_e32 v86, 1.0, v86
	v_add_f32_e32 v82, 1.0, v82
	v_add_f32_e32 v87, 1.0, v87
	v_add_f32_e32 v83, 1.0, v83
	v_rcp_f32_e32 v84, v84
	v_rcp_f32_e32 v80, v80
	v_rcp_f32_e32 v85, v85
	v_rcp_f32_e32 v81, v81
	v_rcp_f32_e32 v86, v86
	v_rcp_f32_e32 v82, v82
	v_rcp_f32_e32 v87, v87
	v_rcp_f32_e32 v83, v83
.LBB0_189:
	s_and_b64 vcc, exec, s[6:7]
	s_nop 1
	v_cvt_pk_bf16_f32 v84, v84, v85
	s_nop 1
	v_cvt_pk_bf16_f32 v85, v86, v87
	s_nop 1
	v_cvt_pk_bf16_f32 v86, v80, v81
	s_nop 1
	v_cvt_pk_bf16_f32 v87, v82, v83
	global_store_dwordx4 v[96:97], v[84:87], off offset:256 nt
	s_cbranch_vccnz .LBB0_191
	v_mul_f32_e32 v76, 0x38800000, v76
	v_mul_f32_e32 v72, 0x38800000, v72
	v_mul_f32_e32 v77, 0x38800000, v77
	v_mul_f32_e32 v73, 0x38800000, v73
	v_mul_f32_e32 v78, 0x38800000, v78
	v_mul_f32_e32 v74, 0x38800000, v74
	v_mul_f32_e32 v79, 0x38800000, v79
	v_mul_f32_e32 v75, 0x38800000, v75
	v_mul_f32_e32 v76, 0xbfb8aa3b, v76
	v_mul_f32_e32 v72, 0xbfb8aa3b, v72
	v_mul_f32_e32 v77, 0xbfb8aa3b, v77
	v_mul_f32_e32 v73, 0xbfb8aa3b, v73
	v_mul_f32_e32 v78, 0xbfb8aa3b, v78
	v_mul_f32_e32 v74, 0xbfb8aa3b, v74
	v_mul_f32_e32 v79, 0xbfb8aa3b, v79
	v_mul_f32_e32 v75, 0xbfb8aa3b, v75
	v_exp_f32_e32 v76, v76
	v_exp_f32_e32 v72, v72
	v_exp_f32_e32 v77, v77
	v_exp_f32_e32 v73, v73
	v_exp_f32_e32 v78, v78
	v_exp_f32_e32 v74, v74
	v_exp_f32_e32 v79, v79
	v_exp_f32_e32 v75, v75
	v_add_f32_e32 v76, 1.0, v76
	v_add_f32_e32 v72, 1.0, v72
	v_add_f32_e32 v77, 1.0, v77
	v_add_f32_e32 v73, 1.0, v73
	v_add_f32_e32 v78, 1.0, v78
	v_add_f32_e32 v74, 1.0, v74
	v_add_f32_e32 v79, 1.0, v79
	v_add_f32_e32 v75, 1.0, v75
	v_rcp_f32_e32 v76, v76
	v_rcp_f32_e32 v72, v72
	v_rcp_f32_e32 v77, v77
	v_rcp_f32_e32 v73, v73
	v_rcp_f32_e32 v78, v78
	v_rcp_f32_e32 v74, v74
	v_rcp_f32_e32 v79, v79
	v_rcp_f32_e32 v75, v75
.LBB0_191:
	v_or_b32_e32 v82, 48, v146
	v_mov_b64_e32 v[80:81], s[14:15]
	v_mad_i64_i32 v[80:81], s[16:17], v82, s87, v[80:81]
	v_lshl_add_u64 v[80:81], v[132:133], 1, v[80:81]
	s_and_b64 vcc, exec, s[6:7]
	s_nop 1
	v_cvt_pk_bf16_f32 v76, v76, v77
	s_nop 1
	v_cvt_pk_bf16_f32 v77, v78, v79
	s_nop 1
	v_cvt_pk_bf16_f32 v78, v72, v73
	s_nop 1
	v_cvt_pk_bf16_f32 v79, v74, v75
	global_store_dwordx4 v[80:81], v[76:79], off nt
	s_cbranch_vccnz .LBB0_193
	v_mul_f32_e32 v68, 0x38800000, v68
	v_mul_f32_e32 v64, 0x38800000, v64
	v_mul_f32_e32 v69, 0x38800000, v69
	v_mul_f32_e32 v65, 0x38800000, v65
	v_mul_f32_e32 v70, 0x38800000, v70
	v_mul_f32_e32 v66, 0x38800000, v66
	v_mul_f32_e32 v71, 0x38800000, v71
	v_mul_f32_e32 v67, 0x38800000, v67
	v_mul_f32_e32 v68, 0xbfb8aa3b, v68
	v_mul_f32_e32 v64, 0xbfb8aa3b, v64
	v_mul_f32_e32 v69, 0xbfb8aa3b, v69
	v_mul_f32_e32 v65, 0xbfb8aa3b, v65
	v_mul_f32_e32 v70, 0xbfb8aa3b, v70
	v_mul_f32_e32 v66, 0xbfb8aa3b, v66
	v_mul_f32_e32 v71, 0xbfb8aa3b, v71
	v_mul_f32_e32 v67, 0xbfb8aa3b, v67
	v_exp_f32_e32 v68, v68
	v_exp_f32_e32 v64, v64
	v_exp_f32_e32 v69, v69
	v_exp_f32_e32 v65, v65
	v_exp_f32_e32 v70, v70
	v_exp_f32_e32 v66, v66
	v_exp_f32_e32 v71, v71
	v_exp_f32_e32 v67, v67
	v_add_f32_e32 v68, 1.0, v68
	v_add_f32_e32 v64, 1.0, v64
	v_add_f32_e32 v69, 1.0, v69
	v_add_f32_e32 v65, 1.0, v65
	v_add_f32_e32 v70, 1.0, v70
	v_add_f32_e32 v66, 1.0, v66
	v_add_f32_e32 v71, 1.0, v71
	v_add_f32_e32 v67, 1.0, v67
	v_rcp_f32_e32 v68, v68
	v_rcp_f32_e32 v64, v64
	v_rcp_f32_e32 v69, v69
	v_rcp_f32_e32 v65, v65
	v_rcp_f32_e32 v70, v70
	v_rcp_f32_e32 v66, v66
	v_rcp_f32_e32 v71, v71
	v_rcp_f32_e32 v67, v67
; __device__ __forceinline__ float sigm(float x) { return __builtin_amdgcn_rcpf(1.f + __builtin_amdgcn_exp2f(-1.4426950409f * x)); }
; __device__ __forceinline__ u32x4 pack8s(const f32x4 v0, const f32x4 v1) { u32x4 w; w.x = cvt_pk_bf16s(v0[0], v0[1]); w.y = cvt_pk_bf16s(v0[2], v0[3]); w.z = cvt_pk_bf16s(v1[0], v1[1]); w.w = cvt_pk_bf16s(v1[2], v1[3]); return w; }
;     __device__ __forceinline__ void operator()(AccT& acc, const Unit& u, int wr, int wc, int fr, int fq) const {
;         const int pn = u.pn + 16;
;         const bool sg = pn >= 16;
;         const int row0 = u.pm * 256 + wr * 64 + fr, col0 = pn * 256 + wc * 32 + 8 * fq;
; #pragma unroll
;         for (int ai = 0; ai < 2; ++ai)
; #pragma unroll
;             for (int m = 0; m < 4; ++m) { bf16_t* rowp = O + (size_t)(row0 + ai * 128 + m * 16) * DIN + col0;
; #pragma unroll
;                 for (int bj = 0; bj < 2; ++bj) { f32x4 v0 = acc[ai][bj][m][0], v1 = acc[ai][bj][m][1];
;                     if (sg) {
; #pragma unroll
;                         for (int j = 0; j < 4; ++j) { v0[j] = sigm(v0[j] * 6.103515625e-05f); v1[j] = sigm(v1[j] * 6.103515625e-05f); } }
;                     *(u32x4*)(rowp + bj * 128) = pack8s(v0, v1); } }
.LBB0_193:
	s_and_b64 vcc, exec, s[6:7]
	s_nop 1
	v_cvt_pk_bf16_f32 v68, v68, v69
	s_nop 1
	v_cvt_pk_bf16_f32 v69, v70, v71
	s_nop 1
	v_cvt_pk_bf16_f32 v70, v64, v65
	s_nop 1
	v_cvt_pk_bf16_f32 v71, v66, v67
	global_store_dwordx4 v[80:81], v[68:71], off offset:256 nt
	s_cbranch_vccnz .LBB0_195
	v_mul_f32_e32 v60, 0x38800000, v60
	v_mul_f32_e32 v56, 0x38800000, v56
	v_mul_f32_e32 v61, 0x38800000, v61
	v_mul_f32_e32 v57, 0x38800000, v57
	v_mul_f32_e32 v62, 0x38800000, v62
	v_mul_f32_e32 v58, 0x38800000, v58
	v_mul_f32_e32 v63, 0x38800000, v63
	v_mul_f32_e32 v59, 0x38800000, v59
	v_mul_f32_e32 v60, 0xbfb8aa3b, v60
	v_mul_f32_e32 v56, 0xbfb8aa3b, v56
	v_mul_f32_e32 v61, 0xbfb8aa3b, v61
	v_mul_f32_e32 v57, 0xbfb8aa3b, v57
	v_mul_f32_e32 v62, 0xbfb8aa3b, v62
	v_mul_f32_e32 v58, 0xbfb8aa3b, v58
	v_mul_f32_e32 v63, 0xbfb8aa3b, v63
	v_mul_f32_e32 v59, 0xbfb8aa3b, v59
	v_exp_f32_e32 v60, v60
	v_exp_f32_e32 v56, v56
	v_exp_f32_e32 v61, v61
	v_exp_f32_e32 v57, v57
	v_exp_f32_e32 v62, v62
	v_exp_f32_e32 v58, v58
	v_exp_f32_e32 v63, v63
	v_exp_f32_e32 v59, v59
	v_add_f32_e32 v60, 1.0, v60
	v_add_f32_e32 v56, 1.0, v56
	v_add_f32_e32 v61, 1.0, v61
	v_add_f32_e32 v57, 1.0, v57
	v_add_f32_e32 v62, 1.0, v62
	v_add_f32_e32 v58, 1.0, v58
	v_add_f32_e32 v63, 1.0, v63
	v_add_f32_e32 v59, 1.0, v59
	v_rcp_f32_e32 v60, v60
	v_rcp_f32_e32 v56, v56
	v_rcp_f32_e32 v61, v61
	v_rcp_f32_e32 v57, v57
	v_rcp_f32_e32 v62, v62
	v_rcp_f32_e32 v58, v58
	v_rcp_f32_e32 v63, v63
	v_rcp_f32_e32 v59, v59
.LBB0_195:
	v_add_u32_e32 v66, 0x80, v146
	v_mov_b64_e32 v[64:65], s[14:15]
	v_mad_i64_i32 v[64:65], s[16:17], v66, s87, v[64:65]
	v_lshl_add_u64 v[64:65], v[132:133], 1, v[64:65]
	s_and_b64 vcc, exec, s[6:7]
	s_nop 1
	v_cvt_pk_bf16_f32 v60, v60, v61
	s_nop 1
	v_cvt_pk_bf16_f32 v61, v62, v63
	s_nop 1
	v_cvt_pk_bf16_f32 v62, v56, v57
	s_nop 1
	v_cvt_pk_bf16_f32 v63, v58, v59
	global_store_dwordx4 v[64:65], v[60:63], off nt
	s_cbranch_vccnz .LBB0_197
	v_mul_f32_e32 v52, 0x38800000, v52
	v_mul_f32_e32 v48, 0x38800000, v48
	v_mul_f32_e32 v53, 0x38800000, v53
	v_mul_f32_e32 v49, 0x38800000, v49
	v_mul_f32_e32 v54, 0x38800000, v54
	v_mul_f32_e32 v50, 0x38800000, v50
	v_mul_f32_e32 v55, 0x38800000, v55
	v_mul_f32_e32 v51, 0x38800000, v51
	v_mul_f32_e32 v52, 0xbfb8aa3b, v52
	v_mul_f32_e32 v48, 0xbfb8aa3b, v48
	v_mul_f32_e32 v53, 0xbfb8aa3b, v53
	v_mul_f32_e32 v49, 0xbfb8aa3b, v49
	v_mul_f32_e32 v54, 0xbfb8aa3b, v54
	v_mul_f32_e32 v50, 0xbfb8aa3b, v50
	v_mul_f32_e32 v55, 0xbfb8aa3b, v55
	v_mul_f32_e32 v51, 0xbfb8aa3b, v51
	v_exp_f32_e32 v52, v52
	v_exp_f32_e32 v48, v48
	v_exp_f32_e32 v53, v53
	v_exp_f32_e32 v49, v49
	v_exp_f32_e32 v54, v54
	v_exp_f32_e32 v50, v50
	v_exp_f32_e32 v55, v55
	v_exp_f32_e32 v51, v51
	v_add_f32_e32 v52, 1.0, v52
	v_add_f32_e32 v48, 1.0, v48
	v_add_f32_e32 v53, 1.0, v53
	v_add_f32_e32 v49, 1.0, v49
	v_add_f32_e32 v54, 1.0, v54
	v_add_f32_e32 v50, 1.0, v50
	v_add_f32_e32 v55, 1.0, v55
	v_add_f32_e32 v51, 1.0, v51
	v_rcp_f32_e32 v52, v52
	v_rcp_f32_e32 v48, v48
	v_rcp_f32_e32 v53, v53
	v_rcp_f32_e32 v49, v49
	v_rcp_f32_e32 v54, v54
	v_rcp_f32_e32 v50, v50
	v_rcp_f32_e32 v55, v55
	v_rcp_f32_e32 v51, v51
.LBB0_197:
	s_and_b64 vcc, exec, s[6:7]
	s_nop 1
	v_cvt_pk_bf16_f32 v52, v52, v53
	s_nop 1
	v_cvt_pk_bf16_f32 v53, v54, v55
	s_nop 1
	v_cvt_pk_bf16_f32 v54, v48, v49
	s_nop 1
	v_cvt_pk_bf16_f32 v55, v50, v51
	global_store_dwordx4 v[64:65], v[52:55], off offset:256 nt
	s_cbranch_vccnz .LBB0_199
	v_mul_f32_e32 v44, 0x38800000, v44
	v_mul_f32_e32 v40, 0x38800000, v40
	v_mul_f32_e32 v45, 0x38800000, v45
	v_mul_f32_e32 v41, 0x38800000, v41
	v_mul_f32_e32 v46, 0x38800000, v46
	v_mul_f32_e32 v42, 0x38800000, v42
	v_mul_f32_e32 v47, 0x38800000, v47
	v_mul_f32_e32 v43, 0x38800000, v43
	v_mul_f32_e32 v44, 0xbfb8aa3b, v44
	v_mul_f32_e32 v40, 0xbfb8aa3b, v40
	v_mul_f32_e32 v45, 0xbfb8aa3b, v45
	v_mul_f32_e32 v41, 0xbfb8aa3b, v41
	v_mul_f32_e32 v46, 0xbfb8aa3b, v46
	v_mul_f32_e32 v42, 0xbfb8aa3b, v42
	v_mul_f32_e32 v47, 0xbfb8aa3b, v47
	v_mul_f32_e32 v43, 0xbfb8aa3b, v43
	v_exp_f32_e32 v44, v44
	v_exp_f32_e32 v40, v40
	v_exp_f32_e32 v45, v45
	v_exp_f32_e32 v41, v41
	v_exp_f32_e32 v46, v46
	v_exp_f32_e32 v42, v42
	v_exp_f32_e32 v47, v47
	v_exp_f32_e32 v43, v43
	v_add_f32_e32 v44, 1.0, v44
	v_add_f32_e32 v40, 1.0, v40
	v_add_f32_e32 v45, 1.0, v45
	v_add_f32_e32 v41, 1.0, v41
	v_add_f32_e32 v46, 1.0, v46
	v_add_f32_e32 v42, 1.0, v42
	v_add_f32_e32 v47, 1.0, v47
	v_add_f32_e32 v43, 1.0, v43
	v_rcp_f32_e32 v44, v44
	v_rcp_f32_e32 v40, v40
	v_rcp_f32_e32 v45, v45
	v_rcp_f32_e32 v41, v41
	v_rcp_f32_e32 v46, v46
	v_rcp_f32_e32 v42, v42
	v_rcp_f32_e32 v47, v47
	v_rcp_f32_e32 v43, v43
.LBB0_199:
	v_add_u32_e32 v50, 0x90, v146
	v_mov_b64_e32 v[48:49], s[14:15]
	v_mad_i64_i32 v[48:49], s[16:17], v50, s87, v[48:49]
	v_lshl_add_u64 v[48:49], v[132:133], 1, v[48:49]
	s_and_b64 vcc, exec, s[6:7]
	s_nop 1
	v_cvt_pk_bf16_f32 v44, v44, v45
	s_nop 1
	v_cvt_pk_bf16_f32 v45, v46, v47
	s_nop 1
	v_cvt_pk_bf16_f32 v46, v40, v41
	s_nop 1
	v_cvt_pk_bf16_f32 v47, v42, v43
	global_store_dwordx4 v[48:49], v[44:47], off nt
	s_cbranch_vccnz .LBB0_201
	v_mul_f32_e32 v36, 0x38800000, v36
	v_mul_f32_e32 v32, 0x38800000, v32
	v_mul_f32_e32 v37, 0x38800000, v37
	v_mul_f32_e32 v33, 0x38800000, v33
	v_mul_f32_e32 v38, 0x38800000, v38
	v_mul_f32_e32 v34, 0x38800000, v34
	v_mul_f32_e32 v39, 0x38800000, v39
	v_mul_f32_e32 v35, 0x38800000, v35
	v_mul_f32_e32 v36, 0xbfb8aa3b, v36
	v_mul_f32_e32 v32, 0xbfb8aa3b, v32
	v_mul_f32_e32 v37, 0xbfb8aa3b, v37
	v_mul_f32_e32 v33, 0xbfb8aa3b, v33
	v_mul_f32_e32 v38, 0xbfb8aa3b, v38
	v_mul_f32_e32 v34, 0xbfb8aa3b, v34
	v_mul_f32_e32 v39, 0xbfb8aa3b, v39
	v_mul_f32_e32 v35, 0xbfb8aa3b, v35
	v_exp_f32_e32 v36, v36
	v_exp_f32_e32 v32, v32
	v_exp_f32_e32 v37, v37
	v_exp_f32_e32 v33, v33
	v_exp_f32_e32 v38, v38
	v_exp_f32_e32 v34, v34
	v_exp_f32_e32 v39, v39
	v_exp_f32_e32 v35, v35
	v_add_f32_e32 v36, 1.0, v36
	v_add_f32_e32 v32, 1.0, v32
	v_add_f32_e32 v37, 1.0, v37
	v_add_f32_e32 v33, 1.0, v33
	v_add_f32_e32 v38, 1.0, v38
	v_add_f32_e32 v34, 1.0, v34
	v_add_f32_e32 v39, 1.0, v39
	v_add_f32_e32 v35, 1.0, v35
	v_rcp_f32_e32 v36, v36
	v_rcp_f32_e32 v32, v32
	v_rcp_f32_e32 v37, v37
	v_rcp_f32_e32 v33, v33
	v_rcp_f32_e32 v38, v38
	v_rcp_f32_e32 v34, v34
	v_rcp_f32_e32 v39, v39
	v_rcp_f32_e32 v35, v35
; __device__ __forceinline__ float sigm(float x) { return __builtin_amdgcn_rcpf(1.f + __builtin_amdgcn_exp2f(-1.4426950409f * x)); }
; __device__ __forceinline__ u32x4 pack8s(const f32x4 v0, const f32x4 v1) { u32x4 w; w.x = cvt_pk_bf16s(v0[0], v0[1]); w.y = cvt_pk_bf16s(v0[2], v0[3]); w.z = cvt_pk_bf16s(v1[0], v1[1]); w.w = cvt_pk_bf16s(v1[2], v1[3]); return w; }
;     __device__ __forceinline__ void operator()(AccT& acc, const Unit& u, int wr, int wc, int fr, int fq) const {
;         const int pn = u.pn + 16;
;         const bool sg = pn >= 16;
;         const int row0 = u.pm * 256 + wr * 64 + fr, col0 = pn * 256 + wc * 32 + 8 * fq;
; #pragma unroll
;         for (int ai = 0; ai < 2; ++ai)
; #pragma unroll
;             for (int m = 0; m < 4; ++m) { bf16_t* rowp = O + (size_t)(row0 + ai * 128 + m * 16) * DIN + col0;
; #pragma unroll
;                 for (int bj = 0; bj < 2; ++bj) { f32x4 v0 = acc[ai][bj][m][0], v1 = acc[ai][bj][m][1];
;                     if (sg) {
; #pragma unroll
;                         for (int j = 0; j < 4; ++j) { v0[j] = sigm(v0[j] * 6.103515625e-05f); v1[j] = sigm(v1[j] * 6.103515625e-05f); } }
;                     *(u32x4*)(rowp + bj * 128) = pack8s(v0, v1); } }
.LBB0_201:
	s_and_b64 vcc, exec, s[6:7]
	s_nop 1
	v_cvt_pk_bf16_f32 v36, v36, v37
	s_nop 1
	v_cvt_pk_bf16_f32 v37, v38, v39
	s_nop 1
	v_cvt_pk_bf16_f32 v38, v32, v33
	s_nop 1
	v_cvt_pk_bf16_f32 v39, v34, v35
	global_store_dwordx4 v[48:49], v[36:39], off offset:256 nt
	s_cbranch_vccnz .LBB0_203
	v_mul_f32_e32 v28, 0x38800000, v28
	v_mul_f32_e32 v24, 0x38800000, v24
	v_mul_f32_e32 v29, 0x38800000, v29
	v_mul_f32_e32 v25, 0x38800000, v25
	v_mul_f32_e32 v30, 0x38800000, v30
	v_mul_f32_e32 v26, 0x38800000, v26
	v_mul_f32_e32 v31, 0x38800000, v31
	v_mul_f32_e32 v27, 0x38800000, v27
	v_mul_f32_e32 v28, 0xbfb8aa3b, v28
	v_mul_f32_e32 v24, 0xbfb8aa3b, v24
	v_mul_f32_e32 v29, 0xbfb8aa3b, v29
	v_mul_f32_e32 v25, 0xbfb8aa3b, v25
	v_mul_f32_e32 v30, 0xbfb8aa3b, v30
	v_mul_f32_e32 v26, 0xbfb8aa3b, v26
	v_mul_f32_e32 v31, 0xbfb8aa3b, v31
	v_mul_f32_e32 v27, 0xbfb8aa3b, v27
	v_exp_f32_e32 v28, v28
	v_exp_f32_e32 v24, v24
	v_exp_f32_e32 v29, v29
	v_exp_f32_e32 v25, v25
	v_exp_f32_e32 v30, v30
	v_exp_f32_e32 v26, v26
	v_exp_f32_e32 v31, v31
	v_exp_f32_e32 v27, v27
	v_add_f32_e32 v28, 1.0, v28
	v_add_f32_e32 v24, 1.0, v24
	v_add_f32_e32 v29, 1.0, v29
	v_add_f32_e32 v25, 1.0, v25
	v_add_f32_e32 v30, 1.0, v30
	v_add_f32_e32 v26, 1.0, v26
	v_add_f32_e32 v31, 1.0, v31
	v_add_f32_e32 v27, 1.0, v27
	v_rcp_f32_e32 v28, v28
	v_rcp_f32_e32 v24, v24
	v_rcp_f32_e32 v29, v29
	v_rcp_f32_e32 v25, v25
	v_rcp_f32_e32 v30, v30
	v_rcp_f32_e32 v26, v26
	v_rcp_f32_e32 v31, v31
	v_rcp_f32_e32 v27, v27
.LBB0_203:
	v_add_u32_e32 v34, 0xa0, v146
	v_mov_b64_e32 v[32:33], s[14:15]
	v_mad_i64_i32 v[32:33], s[16:17], v34, s87, v[32:33]
	v_lshl_add_u64 v[32:33], v[132:133], 1, v[32:33]
	s_and_b64 vcc, exec, s[6:7]
	s_nop 1
	v_cvt_pk_bf16_f32 v28, v28, v29
	s_nop 1
	v_cvt_pk_bf16_f32 v29, v30, v31
	s_nop 1
	v_cvt_pk_bf16_f32 v30, v24, v25
	s_nop 1
	v_cvt_pk_bf16_f32 v31, v26, v27
	global_store_dwordx4 v[32:33], v[28:31], off nt
	s_cbranch_vccnz .LBB0_205
	v_mul_f32_e32 v20, 0x38800000, v20
	v_mul_f32_e32 v16, 0x38800000, v16
	v_mul_f32_e32 v21, 0x38800000, v21
	v_mul_f32_e32 v17, 0x38800000, v17
	v_mul_f32_e32 v22, 0x38800000, v22
	v_mul_f32_e32 v18, 0x38800000, v18
	v_mul_f32_e32 v23, 0x38800000, v23
	v_mul_f32_e32 v19, 0x38800000, v19
	v_mul_f32_e32 v20, 0xbfb8aa3b, v20
	v_mul_f32_e32 v16, 0xbfb8aa3b, v16
	v_mul_f32_e32 v21, 0xbfb8aa3b, v21
	v_mul_f32_e32 v17, 0xbfb8aa3b, v17
	v_mul_f32_e32 v22, 0xbfb8aa3b, v22
	v_mul_f32_e32 v18, 0xbfb8aa3b, v18
	v_mul_f32_e32 v23, 0xbfb8aa3b, v23
	v_mul_f32_e32 v19, 0xbfb8aa3b, v19
	v_exp_f32_e32 v20, v20
	v_exp_f32_e32 v16, v16
	v_exp_f32_e32 v21, v21
	v_exp_f32_e32 v17, v17
	v_exp_f32_e32 v22, v22
	v_exp_f32_e32 v18, v18
	v_exp_f32_e32 v23, v23
	v_exp_f32_e32 v19, v19
	v_add_f32_e32 v20, 1.0, v20
	v_add_f32_e32 v16, 1.0, v16
	v_add_f32_e32 v21, 1.0, v21
	v_add_f32_e32 v17, 1.0, v17
	v_add_f32_e32 v22, 1.0, v22
	v_add_f32_e32 v18, 1.0, v18
	v_add_f32_e32 v23, 1.0, v23
	v_add_f32_e32 v19, 1.0, v19
	v_rcp_f32_e32 v20, v20
	v_rcp_f32_e32 v16, v16
	v_rcp_f32_e32 v21, v21
	v_rcp_f32_e32 v17, v17
	v_rcp_f32_e32 v22, v22
	v_rcp_f32_e32 v18, v18
	v_rcp_f32_e32 v23, v23
	v_rcp_f32_e32 v19, v19
.LBB0_205:
	s_and_b64 vcc, exec, s[6:7]
	s_nop 1
	v_cvt_pk_bf16_f32 v20, v20, v21
	s_nop 1
	v_cvt_pk_bf16_f32 v21, v22, v23
	s_nop 1
	v_cvt_pk_bf16_f32 v22, v16, v17
	s_nop 1
	v_cvt_pk_bf16_f32 v23, v18, v19
	global_store_dwordx4 v[32:33], v[20:23], off offset:256 nt
	s_cbranch_vccnz .LBB0_207
	v_mul_f32_e32 v12, 0x38800000, v12
	v_mul_f32_e32 v8, 0x38800000, v8
	v_mul_f32_e32 v13, 0x38800000, v13
	v_mul_f32_e32 v9, 0x38800000, v9
	v_mul_f32_e32 v14, 0x38800000, v14
	v_mul_f32_e32 v10, 0x38800000, v10
	v_mul_f32_e32 v15, 0x38800000, v15
	v_mul_f32_e32 v11, 0x38800000, v11
	v_mul_f32_e32 v12, 0xbfb8aa3b, v12
	v_mul_f32_e32 v8, 0xbfb8aa3b, v8
	v_mul_f32_e32 v13, 0xbfb8aa3b, v13
	v_mul_f32_e32 v9, 0xbfb8aa3b, v9
	v_mul_f32_e32 v14, 0xbfb8aa3b, v14
	v_mul_f32_e32 v10, 0xbfb8aa3b, v10
	v_mul_f32_e32 v15, 0xbfb8aa3b, v15
	v_mul_f32_e32 v11, 0xbfb8aa3b, v11
	v_exp_f32_e32 v12, v12
	v_exp_f32_e32 v8, v8
	v_exp_f32_e32 v13, v13
	v_exp_f32_e32 v9, v9
	v_exp_f32_e32 v14, v14
	v_exp_f32_e32 v10, v10
	v_exp_f32_e32 v15, v15
	v_exp_f32_e32 v11, v11
	v_add_f32_e32 v12, 1.0, v12
	v_add_f32_e32 v8, 1.0, v8
	v_add_f32_e32 v13, 1.0, v13
	v_add_f32_e32 v9, 1.0, v9
	v_add_f32_e32 v14, 1.0, v14
	v_add_f32_e32 v10, 1.0, v10
	v_add_f32_e32 v15, 1.0, v15
	v_add_f32_e32 v11, 1.0, v11
	v_rcp_f32_e32 v12, v12
	v_rcp_f32_e32 v8, v8
	v_rcp_f32_e32 v13, v13
	v_rcp_f32_e32 v9, v9
	v_rcp_f32_e32 v14, v14
	v_rcp_f32_e32 v10, v10
	v_rcp_f32_e32 v15, v15
	v_rcp_f32_e32 v11, v11
.LBB0_207:
	v_add_u32_e32 v18, 0xb0, v146
	v_mov_b64_e32 v[16:17], s[14:15]
	v_mad_i64_i32 v[16:17], s[16:17], v18, s87, v[16:17]
	v_lshl_add_u64 v[16:17], v[132:133], 1, v[16:17]
	s_and_b64 vcc, exec, s[6:7]
	s_nop 1
	v_cvt_pk_bf16_f32 v12, v12, v13
	s_nop 1
	v_cvt_pk_bf16_f32 v13, v14, v15
	s_nop 1
	v_cvt_pk_bf16_f32 v14, v8, v9
	s_nop 1
	v_cvt_pk_bf16_f32 v15, v10, v11
	global_store_dwordx4 v[16:17], v[12:15], off nt
	s_cbranch_vccnz .LBB0_209
	v_mul_f32_e32 v4, 0x38800000, v4
	v_mul_f32_e32 v0, 0x38800000, v0
	v_mul_f32_e32 v5, 0x38800000, v5
	v_mul_f32_e32 v1, 0x38800000, v1
	v_mul_f32_e32 v6, 0x38800000, v6
	v_mul_f32_e32 v2, 0x38800000, v2
	v_mul_f32_e32 v7, 0x38800000, v7
	v_mul_f32_e32 v3, 0x38800000, v3
	v_mul_f32_e32 v4, 0xbfb8aa3b, v4
	v_mul_f32_e32 v0, 0xbfb8aa3b, v0
	v_mul_f32_e32 v5, 0xbfb8aa3b, v5
	v_mul_f32_e32 v1, 0xbfb8aa3b, v1
	v_mul_f32_e32 v6, 0xbfb8aa3b, v6
	v_mul_f32_e32 v2, 0xbfb8aa3b, v2
	v_mul_f32_e32 v7, 0xbfb8aa3b, v7
	v_mul_f32_e32 v3, 0xbfb8aa3b, v3
	v_exp_f32_e32 v4, v4
	v_exp_f32_e32 v0, v0
	v_exp_f32_e32 v5, v5
	v_exp_f32_e32 v1, v1
	v_exp_f32_e32 v6, v6
	v_exp_f32_e32 v2, v2
	v_exp_f32_e32 v7, v7
	v_exp_f32_e32 v3, v3
	v_add_f32_e32 v4, 1.0, v4
	v_add_f32_e32 v0, 1.0, v0
	v_add_f32_e32 v5, 1.0, v5
	v_add_f32_e32 v1, 1.0, v1
	v_add_f32_e32 v6, 1.0, v6
	v_add_f32_e32 v2, 1.0, v2
	v_add_f32_e32 v7, 1.0, v7
	v_add_f32_e32 v3, 1.0, v3
	v_rcp_f32_e32 v4, v4
	v_rcp_f32_e32 v0, v0
	v_rcp_f32_e32 v5, v5
	v_rcp_f32_e32 v1, v1
	v_rcp_f32_e32 v6, v6
	v_rcp_f32_e32 v2, v2
	v_rcp_f32_e32 v7, v7
	v_rcp_f32_e32 v3, v3

; __device__ __forceinline__ u32x4 pack8(const f32x4 v0, const f32x4 v1) { u32x4 w; w.x = cvt_pk_bf16(v0[0], v0[1]); w.y = cvt_pk_bf16(v0[2], v0[3]); w.z = cvt_pk_bf16(v1[0], v1[1]); w.w = cvt_pk_bf16(v1[2], v1[3]); return w; }
; __device__ __forceinline__ void unpack8(const u32x4 w, f32x4& lo, f32x4& hi) { lo = (f32x4){bf_lo(w.x), bf_hi(w.x), bf_lo(w.y), bf_hi(w.y)}; hi = (f32x4){bf_lo(w.z), bf_hi(w.z), bf_lo(w.w), bf_hi(w.w)}; }
; __device__ __forceinline__ void phase_pool(const bf16_t* PROJ, bf16_t* Z, int gw, int NGW, int lane) {
;     for (int it = gw; it < 2048; it += NGW) {
;         const int b = it >> 9, rem = it & 511, tseg = rem >> 2, gi = rem & 3, win = 2 << gi;
;         const bf16_t* vb = PROJ + (size_t)(b * SEQ) * DIN + 2048 + gi * 512 + lane * 8;
;         bf16_t* zb = Z + (size_t)(b * SEQ) * DSS + gi * 512 + lane * 8;
;         f32x4 s0 = {0.f, 0.f, 0.f, 0.f}, s1 = {0.f, 0.f, 0.f, 0.f};
;         const int t0 = tseg * 16;
;         for (int tau = (t0 - win + 1 > 0 ? t0 - win + 1 : 0); tau < t0; ++tau) { f32x4 a, c; unpack8(*(const u32x4*)(vb + (size_t)tau * DIN), a, c); s0 += a; s1 += c; }
;         for (int t = t0; t < t0 + 16; ++t) {
;             f32x4 v0, v1; unpack8(*(const u32x4*)(vb + (size_t)t * DIN), v0, v1); s0 += v0; s1 += v1;
;             if (t > t0 && t - win >= 0) { f32x4 a, c; unpack8(*(const u32x4*)(vb + (size_t)(t - win) * DIN), a, c); s0 -= a; s1 -= c; }
;             const float inv = 1.f / (float)((t + 1) < win ? (t + 1) : win);
;             *(u32x4*)(zb + (size_t)t * DSS) = pack8(s0 * inv - v0, s1 * inv - v1);
;         }
;     }
.LBB0_306:
	s_lshr_b32 s38, s33, 4
	s_ashr_i32 s37, s36, 31
	s_and_b32 s38, s38, 0x7f
	s_lshl_b32 s39, s38, 16
	s_lshl_b64 s[36:37], s[36:37], 12
	s_add_u32 s36, s39, s36
	s_addc_u32 s37, 0, s37
	s_or_b64 s[36:37], s[36:37], s[4:5]
	s_mul_i32 s38, s38, 0x60000
	s_add_u32 s38, s38, s71
	s_addc_u32 s39, 0, s70
	s_add_u32 s38, s38, s4
	s_addc_u32 s39, s39, 0
	s_and_b32 s70, s69, 0xfffff800
	s_ashr_i32 s71, s70, 31
	s_mul_i32 s69, s70, 0x6000
	s_mul_hi_i32 s4, s70, 0x6000
	s_add_u32 s69, s58, s69
	s_addc_u32 s4, s59, s4
	s_lshl_b32 s72, s68, 10
	s_add_u32 s68, s69, s72
	s_addc_u32 s69, s4, 0
	v_lshl_add_u64 v[8:9], s[68:69], 0, v[0:1]
	v_lshl_add_u64 v[8:9], v[8:9], 0, s[0:1]
	s_mul_i32 s4, s66, 0x6000
	v_lshl_add_u64 v[10:11], v[8:9], 0, s[4:5]
	global_load_dwordx4 v[22:25], v[10:11], off
	v_lshl_add_u64 v[10:11], v[4:5], 0, s[36:37]
	s_lshl_b64 s[36:37], s[70:71], 12
	s_add_u32 s4, s8, s36
	s_addc_u32 s37, s9, s37
	s_add_u32 s36, s4, s72
	v_lshl_add_u64 v[12:13], v[6:7], 0, s[38:39]
	s_addc_u32 s37, s37, 0
	s_or_b32 s38, s66, 1
	v_lshl_add_u64 v[26:27], s[36:37], 0, v[0:1]
	s_min_u32 s36, s38, s65
	v_cvt_f32_ubyte0_e32 v28, s36
	v_div_scale_f32 v29, s[36:37], v28, v28, 1.0
	v_rcp_f32_e32 v31, v29
	v_div_scale_f32 v32, vcc, 1.0, v28, 1.0
	s_lshl_b32 s4, s66, 12
	v_fma_f32 v33, -v29, v31, 1.0
	v_fmac_f32_e32 v31, v33, v31
	v_mul_f32_e32 v33, v32, v31
	v_fma_f32 v34, -v29, v33, v32
	v_fmac_f32_e32 v33, v34, v31
	v_fma_f32 v29, -v29, v33, v32
	v_div_fmas_f32 v29, v29, v31, v33
	v_div_fixup_f32 v28, v29, v28, 1.0
	v_lshl_add_u64 v[26:27], v[26:27], 0, s[4:5]
	s_mov_b32 s4, 0
	s_waitcnt vmcnt(0)
	v_lshlrev_b32_e32 v32, 16, v22
	v_and_b32_e32 v33, 0xffff0000, v22
	v_lshlrev_b32_e32 v22, 16, v23
	v_and_b32_e32 v23, 0xffff0000, v23
	v_lshlrev_b32_e32 v34, 16, v24
	v_and_b32_e32 v35, 0xffff0000, v24
	v_lshlrev_b32_e32 v24, 16, v25
	v_and_b32_e32 v25, 0xffff0000, v25
	v_pk_add_f32 v[20:21], v[20:21], v[22:23]
	v_pk_add_f32 v[18:19], v[18:19], v[32:33]
	v_pk_add_f32 v[14:15], v[14:15], v[24:25]
	v_pk_add_f32 v[16:17], v[16:17], v[34:35]
	v_xor_b32_e32 v23, 0x80000000, v23
	v_xor_b32_e32 v22, 0x80000000, v22
	v_xor_b32_e32 v33, 0x80000000, v33
	v_xor_b32_e32 v32, 0x80000000, v32
	v_xor_b32_e32 v25, 0x80000000, v25
	v_xor_b32_e32 v24, 0x80000000, v24
	v_xor_b32_e32 v35, 0x80000000, v35
	v_xor_b32_e32 v34, 0x80000000, v34
	v_pk_fma_f32 v[36:37], v[28:29], v[20:21], v[22:23] op_sel_hi:[0,1,1]
	v_pk_fma_f32 v[22:23], v[28:29], v[18:19], v[32:33] op_sel_hi:[0,1,1]
	v_pk_fma_f32 v[32:33], v[28:29], v[14:15], v[24:25] op_sel_hi:[0,1,1]
	v_pk_fma_f32 v[24:25], v[28:29], v[16:17], v[34:35] op_sel_hi:[0,1,1]
	v_cvt_pk_bf16_f32 v22, v22, v23
	v_cvt_pk_bf16_f32 v23, v36, v37
	v_cvt_pk_bf16_f32 v24, v24, v25
	v_cvt_pk_bf16_f32 v25, v32, v33
	global_store_dwordx4 v[26:27], v[22:25], off nt
	s_branch .LBB0_308
.LBB0_307:
	s_add_i32 s36, s36, 2
	s_min_u32 s36, s36, s65
	v_cvt_f32_ubyte0_e32 v31, s36
	v_div_scale_f32 v32, s[36:37], v31, v31, 1.0
	v_rcp_f32_e32 v33, v32
	v_div_scale_f32 v34, vcc, 1.0, v31, 1.0
	v_xor_b32_e32 v29, 0x80000000, v29
	v_fma_f32 v35, -v32, v33, 1.0
	v_fmac_f32_e32 v33, v35, v33
	v_mul_f32_e32 v35, v34, v33
	v_fma_f32 v36, -v32, v35, v34
	v_fmac_f32_e32 v35, v36, v33
	v_fma_f32 v32, -v32, v35, v34
	v_div_fmas_f32 v32, v32, v33, v35
	v_div_fixup_f32 v32, v32, v31, 1.0
	v_xor_b32_e32 v28, 0x80000000, v28
	v_pk_fma_f32 v[24:25], v[32:33], v[18:19], v[24:25] op_sel_hi:[0,1,1] neg_lo:[0,0,1] neg_hi:[0,0,1]
	v_xor_b32_e32 v27, 0x80000000, v27
	v_xor_b32_e32 v26, 0x80000000, v26
	s_add_i32 s4, s4, 1
	v_pk_fma_f32 v[28:29], v[32:33], v[20:21], v[28:29] op_sel_hi:[0,1,1]
	v_pk_fma_f32 v[26:27], v[32:33], v[14:15], v[26:27] op_sel_hi:[0,1,1]
	v_pk_fma_f32 v[32:33], v[32:33], v[16:17], v[22:23] op_sel_hi:[0,1,1] neg_lo:[0,0,1] neg_hi:[0,0,1]
	v_cvt_pk_bf16_f32 v22, v24, v25
	v_cvt_pk_bf16_f32 v23, v28, v29
	v_cvt_pk_bf16_f32 v24, v32, v33
	v_cvt_pk_bf16_f32 v25, v26, v27
	global_store_dwordx4 v[10:11], v[22:25], off nt
	v_lshl_add_u64 v[10:11], v[10:11], 0, s[14:15]
	s_cmp_eq_u32 s4, 15
	v_lshl_add_u64 v[12:13], v[12:13], 0, s[10:11]
	s_cbranch_scc1 .LBB0_300

; #define LAS __attribute__((address_space(3)))
; __device__ __forceinline__ void transpose_item(const float* W, int N, bf16_t* WT, int nkt, int k0, int n0, int r0, int kbd, LAS float* scr, int lane) {
;     const size_t dst_off = ((size_t)(r0 >> 8) * nkt + kbd) * 16384 + (size_t)(r0 & 255) * 64;
;     const int l15 = lane & 15, lq = lane >> 4;
;     f32x4 v[16];
; #pragma unroll
;     for (int i = 0; i < 16; ++i) v[i] = *(const f32x4*)(W + (size_t)(k0 + 4 * i + lq) * N + n0 + 4 * l15);
; #pragma unroll
;     for (int i = 0; i < 16; ++i) { LAS float* d = scr + (4 * i + lq) * 65 + 4 * l15; d[0] = v[i][0]; d[1] = v[i][1]; d[2] = v[i][2]; d[3] = v[i][3]; }
; __device__ __forceinline__ void phase_convert_late(const Params& p, LAS float* scr, int cw, int NCW, int lane) {
;     ...
;     for (int it = cw; it < I1 + I2 + I3 + I4 + I5 + I6; it += NCW) {
;         int r = it;
;         if (r < I6) { const int nb = r % 344, kb = r / 344; const int n0 = nb * 64; const int nn = n0 < FF ? n0 : n0 - FF; const int r0 = (nn >> 7) * 256 + (n0 < FF ? 0 : 128) + (nn & 127);
;             transpose_item(p.in[21], FF2, (bf16_t*)(ws + WS_W_UP), 64, kb * 64, n0, r0, kb, scr, lane); continue; } r -= I6;
;         if (r < I1) { const int nb = r % 32, kb = r / 32; transpose_item(p.in[11], 2048, (bf16_t*)(ws + WS_W_GLU), 32, kb * 64, nb * 64, nb * 64, kb, scr, lane); continue; } r -= I1;
;         if (r < I2) { const int g = r >> 6, q = r & 63, nb = q & 7, kb = q >> 3; transpose_item(p.in[13] + (size_t)g * 512 * 512, 512, (bf16_t*)(ws + WS_W_POOL), 32, kb * 64, nb * 64, nb * 64, g * 8 + kb, scr, lane); continue; } r -= I2;
;         if (r < I3) { const int nb = r % 64, kb = r / 64; transpose_item(p.in[16], 4096, (bf16_t*)(ws + WS_W_BS), 32, kb * 64, nb * 64, nb * 64, kb, scr, lane); continue; } r -= I3;
;         if (r < I4) { const int nb = r % 64, kb = r / 64; transpose_item(p.in[17], 4096, (bf16_t*)(ws + WS_W_BP), 32, kb * 64, nb * 64, nb * 64, kb, scr, lane); continue; } r -= I4;
;         { const int nb = r % 64, kb = r / 64; transpose_item(p.in[18], 4096, (bf16_t*)(ws + WS_W_OUT), 64, kb * 64, nb * 64, nb * 64, kb, scr, lane); }
.LBB0_314:
	s_cmpk_gt_i32 s35, 0x55ff
	s_mov_b64 s[4:5], -1
	s_cbranch_scc0 .LBB0_332
	s_cmpk_gt_u32 s35, 0x59ff
	s_cbranch_scc0 .LBB0_329
	s_cmpk_gt_u32 s35, 0x5aff
	s_cbranch_scc0 .LBB0_326
	s_cmpk_gt_u32 s35, 0x62ff
	s_cbranch_scc0 .LBB0_323
	s_and_b32 s33, s16, 0xfc0
	s_cmpk_gt_u32 s35, 0x6aff
	s_cbranch_scc0 .LBB0_320
	s_add_i32 s4, s35, 0xffff9500
	s_and_b32 s0, s4, 0xffffffc0
	v_or_b32_e32 v0, s0, v3
	s_lshl_b32 s0, s33, 2
	v_or_b32_e32 v50, 4, v0
	v_mov_b32_e32 v51, v1
	v_or_b32_e32 v56, 8, v0
	v_mov_b32_e32 v57, v1
	v_or_b32_e32 v58, 12, v0
	v_mov_b32_e32 v59, v1
	v_or_b32_e32 v64, 16, v0
	v_mov_b32_e32 v65, v1
	v_or_b32_e32 v66, 20, v0
	v_mov_b32_e32 v67, v1
	v_or_b32_e32 v72, 24, v0
	v_mov_b32_e32 v73, v1
	v_or_b32_e32 v74, 28, v0
	v_mov_b32_e32 v75, v1
	v_or_b32_e32 v80, 32, v0
	v_mov_b32_e32 v81, v1
	v_or_b32_e32 v82, 36, v0
	v_mov_b32_e32 v83, v1
	v_lshl_add_u64 v[108:109], v[20:21], 0, s[0:1]
	v_lshlrev_b64 v[48:49], 14, v[0:1]
	v_lshlrev_b64 v[50:51], 14, v[50:51]
	v_lshlrev_b64 v[56:57], 14, v[56:57]
	v_lshlrev_b64 v[58:59], 14, v[58:59]
	v_lshlrev_b64 v[64:65], 14, v[64:65]
	v_lshlrev_b64 v[66:67], 14, v[66:67]
	v_lshlrev_b64 v[72:73], 14, v[72:73]
	v_lshlrev_b64 v[74:75], 14, v[74:75]
	v_lshlrev_b64 v[80:81], 14, v[80:81]
	v_lshlrev_b64 v[82:83], 14, v[82:83]
	v_or_b32_e32 v88, 40, v0
	v_mov_b32_e32 v89, v1
	v_or_b32_e32 v90, 44, v0
	v_mov_b32_e32 v91, v1
	v_lshl_add_u64 v[48:49], v[108:109], 0, v[48:49]
	v_lshl_add_u64 v[52:53], v[108:109], 0, v[50:51]
	v_lshl_add_u64 v[56:57], v[108:109], 0, v[56:57]
	v_lshl_add_u64 v[60:61], v[108:109], 0, v[58:59]
	v_lshl_add_u64 v[64:65], v[108:109], 0, v[64:65]
	v_lshl_add_u64 v[68:69], v[108:109], 0, v[66:67]
	v_lshl_add_u64 v[72:73], v[108:109], 0, v[72:73]
	v_lshl_add_u64 v[76:77], v[108:109], 0, v[74:75]
	v_lshl_add_u64 v[80:81], v[108:109], 0, v[80:81]
	v_lshl_add_u64 v[84:85], v[108:109], 0, v[82:83]
	v_lshlrev_b64 v[88:89], 14, v[88:89]
	v_lshlrev_b64 v[90:91], 14, v[90:91]
	global_load_dwordx4 v[48:51], v[48:49], off nt
	s_nop 0
	global_load_dwordx4 v[52:55], v[52:53], off nt
	s_nop 0
	global_load_dwordx4 v[56:59], v[56:57], off nt
	s_nop 0
	global_load_dwordx4 v[60:63], v[60:61], off nt
	s_nop 0
	global_load_dwordx4 v[64:67], v[64:65], off nt
	s_nop 0
	global_load_dwordx4 v[68:71], v[68:69], off nt
	s_nop 0
	global_load_dwordx4 v[72:75], v[72:73], off nt
	s_nop 0
	global_load_dwordx4 v[76:79], v[76:77], off nt
	s_nop 0
	global_load_dwordx4 v[80:83], v[80:81], off nt
	s_nop 0
	global_load_dwordx4 v[84:87], v[84:85], off nt
	v_lshl_add_u64 v[88:89], v[108:109], 0, v[88:89]
	v_lshl_add_u64 v[92:93], v[108:109], 0, v[90:91]
	global_load_dwordx4 v[88:91], v[88:89], off nt
	s_nop 0
	global_load_dwordx4 v[92:95], v[92:93], off nt
	v_or_b32_e32 v96, 48, v0
	v_mov_b32_e32 v97, v1
	v_lshlrev_b64 v[96:97], 14, v[96:97]
	v_lshl_add_u64 v[96:97], v[108:109], 0, v[96:97]
	v_or_b32_e32 v100, 52, v0
	v_mov_b32_e32 v101, v1
	global_load_dwordx4 v[96:99], v[96:97], off nt
	v_lshlrev_b64 v[100:101], 14, v[100:101]
	v_lshl_add_u64 v[100:101], v[108:109], 0, v[100:101]
	v_or_b32_e32 v104, 56, v0
	v_mov_b32_e32 v105, v1
	global_load_dwordx4 v[100:103], v[100:101], off nt
	v_lshlrev_b64 v[104:105], 14, v[104:105]
	v_lshl_add_u64 v[104:105], v[108:109], 0, v[104:105]
	v_or_b32_e32 v0, 60, v0
	global_load_dwordx4 v[104:107], v[104:105], off nt
	v_lshlrev_b64 v[110:111], 14, v[0:1]
	v_lshl_add_u64 v[108:109], v[108:109], 0, v[110:111]
	global_load_dwordx4 v[108:111], v[108:109], off nt
	v_add_u32_e32 v0, 0xf0a0, v5
	s_lshr_b32 s0, s4, 6
	s_and_b32 s4, s18, 0x3c0
	s_add_i32 s0, s4, s0
	s_lshl_b32 s4, s33, 7
	s_and_b32 s4, s4, 0x6000
	s_add_u32 s62, s3, s4
	v_add_u32_e32 v31, 0xc800, v9
	s_addc_u32 s63, s8, 0
	s_lshl_b64 s[4:5], s[0:1], 15
	s_waitcnt vmcnt(15)
	ds_write2_b32 v7, v48, v49 offset1:1
	ds_write2_b32 v11, v50, v51 offset1:1
	s_waitcnt vmcnt(14)
	ds_write2_b32 v13, v52, v53 offset1:1
	ds_write2_b32 v15, v54, v55 offset1:1
	s_waitcnt vmcnt(13)
	ds_write2_b32 v17, v56, v57 offset1:1
	ds_write2_b32 v19, v58, v59 offset1:1
	s_waitcnt vmcnt(12)
	ds_write2_b32 v32, v60, v61 offset1:1
	ds_write2_b32 v33, v62, v63 offset1:1
	s_waitcnt vmcnt(11)
	ds_write2_b32 v34, v64, v65 offset1:1
	ds_write2_b32 v36, v66, v67 offset1:1
	s_waitcnt vmcnt(10)
	ds_write2_b32 v37, v68, v69 offset1:1
	ds_write2_b32 v38, v70, v71 offset1:1
	s_waitcnt vmcnt(9)
	ds_write2_b32 v39, v72, v73 offset1:1
	ds_write2_b32 v40, v74, v75 offset1:1
	s_waitcnt vmcnt(8)
	ds_write2_b32 v41, v76, v77 offset1:1
	ds_write2_b32 v42, v78, v79 offset1:1
	s_waitcnt vmcnt(7)
	ds_write2_b32 v43, v80, v81 offset1:1
	ds_write2_b32 v44, v82, v83 offset1:1
	s_waitcnt vmcnt(6)
	ds_write2_b32 v45, v84, v85 offset1:1
	ds_write2_b32 v46, v86, v87 offset1:1
	s_add_u32 s4, s62, s4
	s_waitcnt vmcnt(5)
	ds_write2_b32 v0, v88, v89 offset1:1
	v_add_u32_e32 v0, 0xf0a8, v5
	ds_write2_b32 v0, v90, v91 offset1:1
	v_add_u32_e32 v0, 0xf4b0, v5
	s_waitcnt vmcnt(4)
	ds_write2_b32 v0, v92, v93 offset1:1
	v_add_u32_e32 v0, 0xf4b8, v5
	ds_write2_b32 v0, v94, v95 offset1:1
	v_add_u32_e32 v0, 0xf8c0, v5
	s_waitcnt vmcnt(3)
	ds_write2_b32 v0, v96, v97 offset1:1
	v_add_u32_e32 v0, 0xf8c8, v5
	ds_write2_b32 v0, v98, v99 offset1:1
	v_add_u32_e32 v0, 0xfcd0, v5
	v_add_u32_e32 v47, 0xcc00, v9
	s_waitcnt vmcnt(2)
	ds_write2_b32 v0, v100, v101 offset1:1
	v_add_u32_e32 v0, 0xfcd8, v5
	ds_write2_b32 v0, v102, v103 offset1:1
	v_add_u32_e32 v0, 0x38e0, v7
	s_waitcnt vmcnt(1)
	ds_write2_b32 v0, v104, v105 offset1:1
	v_add_u32_e32 v0, 0x38e8, v7
	ds_write2_b32 v0, v106, v107 offset1:1
	v_add_u32_e32 v0, 0x3cf0, v7
	s_waitcnt vmcnt(0)
; #define LAS __attribute__((address_space(3)))
; __device__ __forceinline__ unsigned cvt_pk_bf16(float lo, float hi) { unsigned r; asm volatile("v_cvt_pk_bf16_f32 %0, %1, %2" : "=v"(r) : "v"(lo), "v"(hi)); return r; }
; #define LDS_WAIT() asm volatile("s_waitcnt lgkmcnt(0)" ::: "memory")
; __device__ __forceinline__ void transpose_item(const float* W, int N, bf16_t* WT, int nkt, int k0, int n0, int r0, int kbd, LAS float* scr, int lane) {
;     ...
;     for (int i = 0; i < 16; ++i) { LAS float* d = scr + (4 * i + lq) * 65 + 4 * l15; d[0] = v[i][0]; d[1] = v[i][1]; d[2] = v[i][2]; d[3] = v[i][3]; }
;     LDS_WAIT();
;     const int c = lane & 7;
; #pragma unroll
;     for (int j = 0; j < 8; ++j) { const int n = (lane >> 3) + 8 * j; const LAS float* s = scr + (8 * c) * 65 + n;
;         u32x4 o; o.x = cvt_pk_bf16(s[0], s[65]); o.y = cvt_pk_bf16(s[2 * 65], s[3 * 65]); o.z = cvt_pk_bf16(s[4 * 65], s[5 * 65]); o.w = cvt_pk_bf16(s[6 * 65], s[7 * 65]);
;         *(u32x4*)(WT + dst_off + (size_t)n * 64 + 8 * c) = o; }
;     LDS_WAIT();
	ds_write2_b32 v0, v108, v109 offset1:1
	v_add_u32_e32 v0, 0x3cf8, v7
	ds_write2_b32 v0, v110, v111 offset1:1
	s_waitcnt lgkmcnt(0)
	ds_read2_b32 v[48:49], v31 offset1:65
	s_waitcnt lgkmcnt(0)
	v_cvt_pk_bf16_f32 v48, v48, v49
	ds_read2_b32 v[50:51], v31 offset0:130 offset1:195
	s_addc_u32 s5, s63, s5
	v_lshlrev_b32_e32 v0, 1, v2
	s_waitcnt lgkmcnt(0)
	v_cvt_pk_bf16_f32 v49, v50, v51
	ds_read2_b32 v[50:51], v47 offset0:4 offset1:69
	v_lshl_add_u64 v[54:55], s[4:5], 0, v[0:1]
	v_lshlrev_b32_e32 v0, 1, v4
	s_waitcnt lgkmcnt(0)
	v_cvt_pk_bf16_f32 v50, v50, v51
	ds_read2_b32 v[52:53], v47 offset0:134 offset1:199
	s_waitcnt lgkmcnt(0)
	v_cvt_pk_bf16_f32 v51, v52, v53
	v_lshl_add_u64 v[56:57], v[54:55], 0, v[0:1]
	ds_read2_b32 v[52:53], v31 offset0:8 offset1:73
	global_store_dwordx4 v[56:57], v[48:51], off nt
	v_lshlrev_b32_e32 v0, 1, v6
	v_lshl_add_u64 v[56:57], v[54:55], 0, v[0:1]
	s_waitcnt lgkmcnt(0)
	v_cvt_pk_bf16_f32 v48, v52, v53
	ds_read2_b32 v[50:51], v31 offset0:138 offset1:203
	s_waitcnt lgkmcnt(0)
	v_cvt_pk_bf16_f32 v49, v50, v51
	ds_read2_b32 v[50:51], v47 offset0:12 offset1:77
	s_waitcnt lgkmcnt(0)
	v_cvt_pk_bf16_f32 v50, v50, v51
	ds_read2_b32 v[52:53], v47 offset0:142 offset1:207
	s_waitcnt lgkmcnt(0)
	v_cvt_pk_bf16_f32 v51, v52, v53
	ds_read2_b32 v[52:53], v31 offset0:16 offset1:81
	global_store_dwordx4 v[56:57], v[48:51], off nt
	v_lshlrev_b32_e32 v0, 1, v8
	v_lshl_add_u64 v[56:57], v[54:55], 0, v[0:1]
	s_waitcnt lgkmcnt(0)
	v_cvt_pk_bf16_f32 v48, v52, v53
	ds_read2_b32 v[50:51], v31 offset0:146 offset1:211
	s_waitcnt lgkmcnt(0)
	v_cvt_pk_bf16_f32 v49, v50, v51
	ds_read2_b32 v[50:51], v47 offset0:20 offset1:85
	s_waitcnt lgkmcnt(0)
	v_cvt_pk_bf16_f32 v50, v50, v51
	ds_read2_b32 v[52:53], v47 offset0:150 offset1:215
	s_waitcnt lgkmcnt(0)
	v_cvt_pk_bf16_f32 v51, v52, v53
	ds_read2_b32 v[52:53], v31 offset0:24 offset1:89
	global_store_dwordx4 v[56:57], v[48:51], off nt
	v_lshlrev_b32_e32 v0, 1, v10
	v_lshl_add_u64 v[56:57], v[54:55], 0, v[0:1]
	s_waitcnt lgkmcnt(0)
	v_cvt_pk_bf16_f32 v48, v52, v53
	ds_read2_b32 v[50:51], v31 offset0:154 offset1:219
	s_waitcnt lgkmcnt(0)
	v_cvt_pk_bf16_f32 v49, v50, v51
	ds_read2_b32 v[50:51], v47 offset0:28 offset1:93
	s_waitcnt lgkmcnt(0)
	v_cvt_pk_bf16_f32 v50, v50, v51
	ds_read2_b32 v[52:53], v47 offset0:158 offset1:223
	s_waitcnt lgkmcnt(0)
	v_cvt_pk_bf16_f32 v51, v52, v53
	ds_read2_b32 v[52:53], v31 offset0:32 offset1:97
	global_store_dwordx4 v[56:57], v[48:51], off nt
	v_lshlrev_b32_e32 v0, 1, v12
	v_lshl_add_u64 v[56:57], v[54:55], 0, v[0:1]
	s_waitcnt lgkmcnt(0)
	v_cvt_pk_bf16_f32 v48, v52, v53
	ds_read2_b32 v[50:51], v31 offset0:162 offset1:227
	s_waitcnt lgkmcnt(0)
	v_cvt_pk_bf16_f32 v49, v50, v51
	ds_read2_b32 v[50:51], v47 offset0:36 offset1:101
	s_waitcnt lgkmcnt(0)
	v_cvt_pk_bf16_f32 v50, v50, v51
	ds_read2_b32 v[52:53], v47 offset0:166 offset1:231
	s_waitcnt lgkmcnt(0)
	v_cvt_pk_bf16_f32 v51, v52, v53
	ds_read2_b32 v[52:53], v31 offset0:40 offset1:105
	global_store_dwordx4 v[56:57], v[48:51], off nt
	v_lshlrev_b32_e32 v0, 1, v14
	v_lshl_add_u64 v[56:57], v[54:55], 0, v[0:1]
	s_waitcnt lgkmcnt(0)
	v_cvt_pk_bf16_f32 v48, v52, v53
	ds_read2_b32 v[50:51], v31 offset0:170 offset1:235
	s_waitcnt lgkmcnt(0)
	v_cvt_pk_bf16_f32 v49, v50, v51
	ds_read2_b32 v[50:51], v47 offset0:44 offset1:109
	s_waitcnt lgkmcnt(0)
	v_cvt_pk_bf16_f32 v50, v50, v51
	ds_read2_b32 v[52:53], v47 offset0:174 offset1:239
	s_waitcnt lgkmcnt(0)
	v_cvt_pk_bf16_f32 v51, v52, v53
	ds_read2_b32 v[52:53], v31 offset0:48 offset1:113
	global_store_dwordx4 v[56:57], v[48:51], off nt
	v_lshlrev_b32_e32 v0, 1, v16
	v_lshl_add_u64 v[56:57], v[54:55], 0, v[0:1]
	s_waitcnt lgkmcnt(0)
	v_cvt_pk_bf16_f32 v48, v52, v53
	ds_read2_b32 v[50:51], v31 offset0:178 offset1:243
	s_waitcnt lgkmcnt(0)
	v_cvt_pk_bf16_f32 v49, v50, v51
	ds_read2_b32 v[50:51], v47 offset0:52 offset1:117
	s_waitcnt lgkmcnt(0)
	v_cvt_pk_bf16_f32 v50, v50, v51
	ds_read2_b32 v[52:53], v47 offset0:182 offset1:247
	s_waitcnt lgkmcnt(0)
	v_cvt_pk_bf16_f32 v51, v52, v53
	ds_read2_b32 v[52:53], v31 offset0:56 offset1:121
	global_store_dwordx4 v[56:57], v[48:51], off nt
	v_lshlrev_b32_e32 v0, 1, v18
	s_mov_b64 s[4:5], 0
	s_waitcnt lgkmcnt(0)
	v_cvt_pk_bf16_f32 v48, v52, v53
	ds_read2_b32 v[50:51], v31 offset0:186 offset1:251
	s_waitcnt lgkmcnt(0)
	v_cvt_pk_bf16_f32 v49, v50, v51
	ds_read2_b32 v[50:51], v47 offset0:60 offset1:125
	s_waitcnt lgkmcnt(0)
	v_cvt_pk_bf16_f32 v50, v50, v51
	ds_read2_b32 v[52:53], v47 offset0:190 offset1:255
	s_waitcnt lgkmcnt(0)
	v_cvt_pk_bf16_f32 v51, v52, v53
	v_lshl_add_u64 v[52:53], v[54:55], 0, v[0:1]
	global_store_dwordx4 v[52:53], v[48:51], off nt
	s_waitcnt lgkmcnt(0)
; #define LAS __attribute__((address_space(3)))
; __device__ __forceinline__ void transpose_item(const float* W, int N, bf16_t* WT, int nkt, int k0, int n0, int r0, int kbd, LAS float* scr, int lane) {
;     const size_t dst_off = ((size_t)(r0 >> 8) * nkt + kbd) * 16384 + (size_t)(r0 & 255) * 64;
;     const int l15 = lane & 15, lq = lane >> 4;
;     f32x4 v[16];
; #pragma unroll
;     for (int i = 0; i < 16; ++i) v[i] = *(const f32x4*)(W + (size_t)(k0 + 4 * i + lq) * N + n0 + 4 * l15);
; #pragma unroll
;     for (int i = 0; i < 16; ++i) { LAS float* d = scr + (4 * i + lq) * 65 + 4 * l15; d[0] = v[i][0]; d[1] = v[i][1]; d[2] = v[i][2]; d[3] = v[i][3]; }
; __device__ __forceinline__ void phase_convert_late(const Params& p, LAS float* scr, int cw, int NCW, int lane) {
;     ...
;         if (r < I4) { const int nb = r % 64, kb = r / 64; transpose_item(p.in[17], 4096, (bf16_t*)(ws + WS_W_BP), 32, kb * 64, nb * 64, nb * 64, kb, scr, lane); continue; } r -= I4;
.LBB0_320:
	s_andn2_b64 vcc, exec, s[4:5]
	s_cbranch_vccnz .LBB0_322
	s_add_i32 s4, s35, 0xffff9d00
	s_and_b32 s0, s4, 0xffffffc0
	v_or_b32_e32 v0, s0, v3
	s_lshl_b32 s0, s33, 2
	v_or_b32_e32 v50, 4, v0
	v_mov_b32_e32 v51, v1
	v_or_b32_e32 v56, 8, v0
	v_mov_b32_e32 v57, v1
	v_or_b32_e32 v58, 12, v0
	v_mov_b32_e32 v59, v1
	v_or_b32_e32 v64, 16, v0
	v_mov_b32_e32 v65, v1
	v_or_b32_e32 v66, 20, v0
	v_mov_b32_e32 v67, v1
	v_or_b32_e32 v72, 24, v0
	v_mov_b32_e32 v73, v1
	v_or_b32_e32 v74, 28, v0
	v_mov_b32_e32 v75, v1
	v_or_b32_e32 v80, 32, v0
	v_mov_b32_e32 v81, v1
	v_or_b32_e32 v82, 36, v0
	v_mov_b32_e32 v83, v1
	v_lshl_add_u64 v[108:109], v[22:23], 0, s[0:1]
	v_lshlrev_b64 v[48:49], 14, v[0:1]
	v_lshlrev_b64 v[50:51], 14, v[50:51]
	v_lshlrev_b64 v[56:57], 14, v[56:57]
	v_lshlrev_b64 v[58:59], 14, v[58:59]
	v_lshlrev_b64 v[64:65], 14, v[64:65]
	v_lshlrev_b64 v[66:67], 14, v[66:67]
	v_lshlrev_b64 v[72:73], 14, v[72:73]
	v_lshlrev_b64 v[74:75], 14, v[74:75]
	v_lshlrev_b64 v[80:81], 14, v[80:81]
	v_lshlrev_b64 v[82:83], 14, v[82:83]
	v_or_b32_e32 v88, 40, v0
	v_mov_b32_e32 v89, v1
	v_or_b32_e32 v90, 44, v0
	v_mov_b32_e32 v91, v1
	v_lshl_add_u64 v[48:49], v[108:109], 0, v[48:49]
	v_lshl_add_u64 v[52:53], v[108:109], 0, v[50:51]
	v_lshl_add_u64 v[56:57], v[108:109], 0, v[56:57]
	v_lshl_add_u64 v[60:61], v[108:109], 0, v[58:59]
	v_lshl_add_u64 v[64:65], v[108:109], 0, v[64:65]
	v_lshl_add_u64 v[68:69], v[108:109], 0, v[66:67]
	v_lshl_add_u64 v[72:73], v[108:109], 0, v[72:73]
	v_lshl_add_u64 v[76:77], v[108:109], 0, v[74:75]
	v_lshl_add_u64 v[80:81], v[108:109], 0, v[80:81]
	v_lshl_add_u64 v[84:85], v[108:109], 0, v[82:83]
	v_lshlrev_b64 v[88:89], 14, v[88:89]
	v_lshlrev_b64 v[90:91], 14, v[90:91]
	global_load_dwordx4 v[48:51], v[48:49], off nt
	s_nop 0
	global_load_dwordx4 v[52:55], v[52:53], off nt
	s_nop 0
	global_load_dwordx4 v[56:59], v[56:57], off nt
	s_nop 0
	global_load_dwordx4 v[60:63], v[60:61], off nt
	s_nop 0
	global_load_dwordx4 v[64:67], v[64:65], off nt
	s_nop 0
	global_load_dwordx4 v[68:71], v[68:69], off nt
	s_nop 0
	global_load_dwordx4 v[72:75], v[72:73], off nt
	s_nop 0
	global_load_dwordx4 v[76:79], v[76:77], off nt
	s_nop 0
	global_load_dwordx4 v[80:83], v[80:81], off nt
	s_nop 0
	global_load_dwordx4 v[84:87], v[84:85], off nt
	v_lshl_add_u64 v[88:89], v[108:109], 0, v[88:89]
	v_lshl_add_u64 v[92:93], v[108:109], 0, v[90:91]
	global_load_dwordx4 v[88:91], v[88:89], off nt
	s_nop 0
	global_load_dwordx4 v[92:95], v[92:93], off nt
	v_or_b32_e32 v96, 48, v0
	v_mov_b32_e32 v97, v1
	v_lshlrev_b64 v[96:97], 14, v[96:97]
	v_lshl_add_u64 v[96:97], v[108:109], 0, v[96:97]
	v_or_b32_e32 v100, 52, v0
	v_mov_b32_e32 v101, v1
	global_load_dwordx4 v[96:99], v[96:97], off nt
	v_lshlrev_b64 v[100:101], 14, v[100:101]
	v_lshl_add_u64 v[100:101], v[108:109], 0, v[100:101]
	v_or_b32_e32 v104, 56, v0
	v_mov_b32_e32 v105, v1
	global_load_dwordx4 v[100:103], v[100:101], off nt
	v_lshlrev_b64 v[104:105], 14, v[104:105]
	v_lshl_add_u64 v[104:105], v[108:109], 0, v[104:105]
	v_or_b32_e32 v0, 60, v0
	global_load_dwordx4 v[104:107], v[104:105], off nt
	v_lshlrev_b64 v[110:111], 14, v[0:1]
	v_lshl_add_u64 v[108:109], v[108:109], 0, v[110:111]
	global_load_dwordx4 v[108:111], v[108:109], off nt
	v_add_u32_e32 v0, 0xf0a0, v5
	s_lshr_b32 s0, s4, 6
	s_and_b32 s4, s20, 0x3000
	s_and_b32 s5, s26, 0x1e0
	s_add_i32 s0, s5, s0
	s_lshl_b32 s4, s4, 1
	s_add_u32 s33, s9, s4
	v_add_u32_e32 v31, 0xc800, v9
	s_addc_u32 s62, s10, 0
	s_lshl_b64 s[4:5], s[0:1], 15
	s_waitcnt vmcnt(15)
	ds_write2_b32 v7, v48, v49 offset1:1
	ds_write2_b32 v11, v50, v51 offset1:1
	s_waitcnt vmcnt(14)
	ds_write2_b32 v13, v52, v53 offset1:1
	ds_write2_b32 v15, v54, v55 offset1:1
	s_waitcnt vmcnt(13)
	ds_write2_b32 v17, v56, v57 offset1:1
	ds_write2_b32 v19, v58, v59 offset1:1
	s_waitcnt vmcnt(12)
	ds_write2_b32 v32, v60, v61 offset1:1
	ds_write2_b32 v33, v62, v63 offset1:1
	s_waitcnt vmcnt(11)
	ds_write2_b32 v34, v64, v65 offset1:1
	ds_write2_b32 v36, v66, v67 offset1:1
	s_waitcnt vmcnt(10)
	ds_write2_b32 v37, v68, v69 offset1:1
	ds_write2_b32 v38, v70, v71 offset1:1
	s_waitcnt vmcnt(9)
	ds_write2_b32 v39, v72, v73 offset1:1
	ds_write2_b32 v40, v74, v75 offset1:1
	s_waitcnt vmcnt(8)
	ds_write2_b32 v41, v76, v77 offset1:1
	ds_write2_b32 v42, v78, v79 offset1:1
	s_waitcnt vmcnt(7)
	ds_write2_b32 v43, v80, v81 offset1:1
	ds_write2_b32 v44, v82, v83 offset1:1
	s_waitcnt vmcnt(6)
	ds_write2_b32 v45, v84, v85 offset1:1
	ds_write2_b32 v46, v86, v87 offset1:1
	s_add_u32 s4, s33, s4
	s_waitcnt vmcnt(5)
	ds_write2_b32 v0, v88, v89 offset1:1
	v_add_u32_e32 v0, 0xf0a8, v5
	ds_write2_b32 v0, v90, v91 offset1:1
	v_add_u32_e32 v0, 0xf4b0, v5
	s_waitcnt vmcnt(4)
	ds_write2_b32 v0, v92, v93 offset1:1
	v_add_u32_e32 v0, 0xf4b8, v5
	ds_write2_b32 v0, v94, v95 offset1:1
	v_add_u32_e32 v0, 0xf8c0, v5
	s_waitcnt vmcnt(3)
	ds_write2_b32 v0, v96, v97 offset1:1
	v_add_u32_e32 v0, 0xf8c8, v5
	ds_write2_b32 v0, v98, v99 offset1:1
	v_add_u32_e32 v0, 0xfcd0, v5
	v_add_u32_e32 v47, 0xcc00, v9
	s_waitcnt vmcnt(2)
; #define LAS __attribute__((address_space(3)))
; __device__ __forceinline__ unsigned cvt_pk_bf16(float lo, float hi) { unsigned r; asm volatile("v_cvt_pk_bf16_f32 %0, %1, %2" : "=v"(r) : "v"(lo), "v"(hi)); return r; }
; #define LDS_WAIT() asm volatile("s_waitcnt lgkmcnt(0)" ::: "memory")
; __device__ __forceinline__ void transpose_item(const float* W, int N, bf16_t* WT, int nkt, int k0, int n0, int r0, int kbd, LAS float* scr, int lane) {
;     ...
;     for (int i = 0; i < 16; ++i) { LAS float* d = scr + (4 * i + lq) * 65 + 4 * l15; d[0] = v[i][0]; d[1] = v[i][1]; d[2] = v[i][2]; d[3] = v[i][3]; }
;     LDS_WAIT();
;     const int c = lane & 7;
; #pragma unroll
;     for (int j = 0; j < 8; ++j) { const int n = (lane >> 3) + 8 * j; const LAS float* s = scr + (8 * c) * 65 + n;
;         u32x4 o; o.x = cvt_pk_bf16(s[0], s[65]); o.y = cvt_pk_bf16(s[2 * 65], s[3 * 65]); o.z = cvt_pk_bf16(s[4 * 65], s[5 * 65]); o.w = cvt_pk_bf16(s[6 * 65], s[7 * 65]);
;         *(u32x4*)(WT + dst_off + (size_t)n * 64 + 8 * c) = o; }
;     LDS_WAIT();
	ds_write2_b32 v0, v100, v101 offset1:1
	v_add_u32_e32 v0, 0xfcd8, v5
	ds_write2_b32 v0, v102, v103 offset1:1
	v_add_u32_e32 v0, 0x38e0, v7
	s_waitcnt vmcnt(1)
	ds_write2_b32 v0, v104, v105 offset1:1
	v_add_u32_e32 v0, 0x38e8, v7
	ds_write2_b32 v0, v106, v107 offset1:1
	v_add_u32_e32 v0, 0x3cf0, v7
	s_waitcnt vmcnt(0)
	ds_write2_b32 v0, v108, v109 offset1:1
	v_add_u32_e32 v0, 0x3cf8, v7
	ds_write2_b32 v0, v110, v111 offset1:1
	s_waitcnt lgkmcnt(0)
	ds_read2_b32 v[48:49], v31 offset1:65
	s_waitcnt lgkmcnt(0)
	v_cvt_pk_bf16_f32 v48, v48, v49
	ds_read2_b32 v[50:51], v31 offset0:130 offset1:195
	s_addc_u32 s5, s62, s5
	v_lshlrev_b32_e32 v0, 1, v2
	s_waitcnt lgkmcnt(0)
	v_cvt_pk_bf16_f32 v49, v50, v51
	ds_read2_b32 v[50:51], v47 offset0:4 offset1:69
	v_lshl_add_u64 v[54:55], s[4:5], 0, v[0:1]
	v_lshlrev_b32_e32 v0, 1, v4
	s_waitcnt lgkmcnt(0)
	v_cvt_pk_bf16_f32 v50, v50, v51
	ds_read2_b32 v[52:53], v47 offset0:134 offset1:199
	s_waitcnt lgkmcnt(0)
	v_cvt_pk_bf16_f32 v51, v52, v53
	v_lshl_add_u64 v[56:57], v[54:55], 0, v[0:1]
	ds_read2_b32 v[52:53], v31 offset0:8 offset1:73
	global_store_dwordx4 v[56:57], v[48:51], off nt
	v_lshlrev_b32_e32 v0, 1, v6
	v_lshl_add_u64 v[56:57], v[54:55], 0, v[0:1]
	s_waitcnt lgkmcnt(0)
	v_cvt_pk_bf16_f32 v48, v52, v53
	ds_read2_b32 v[50:51], v31 offset0:138 offset1:203
	s_waitcnt lgkmcnt(0)
	v_cvt_pk_bf16_f32 v49, v50, v51
	ds_read2_b32 v[50:51], v47 offset0:12 offset1:77
	s_waitcnt lgkmcnt(0)
	v_cvt_pk_bf16_f32 v50, v50, v51
	ds_read2_b32 v[52:53], v47 offset0:142 offset1:207
	s_waitcnt lgkmcnt(0)
	v_cvt_pk_bf16_f32 v51, v52, v53
	ds_read2_b32 v[52:53], v31 offset0:16 offset1:81
	global_store_dwordx4 v[56:57], v[48:51], off nt
	v_lshlrev_b32_e32 v0, 1, v8
	v_lshl_add_u64 v[56:57], v[54:55], 0, v[0:1]
	s_waitcnt lgkmcnt(0)
	v_cvt_pk_bf16_f32 v48, v52, v53
	ds_read2_b32 v[50:51], v31 offset0:146 offset1:211
	s_waitcnt lgkmcnt(0)
	v_cvt_pk_bf16_f32 v49, v50, v51
	ds_read2_b32 v[50:51], v47 offset0:20 offset1:85
	s_waitcnt lgkmcnt(0)
	v_cvt_pk_bf16_f32 v50, v50, v51
	ds_read2_b32 v[52:53], v47 offset0:150 offset1:215
	s_waitcnt lgkmcnt(0)
	v_cvt_pk_bf16_f32 v51, v52, v53
	ds_read2_b32 v[52:53], v31 offset0:24 offset1:89
	global_store_dwordx4 v[56:57], v[48:51], off nt
	v_lshlrev_b32_e32 v0, 1, v10
	v_lshl_add_u64 v[56:57], v[54:55], 0, v[0:1]
	s_waitcnt lgkmcnt(0)
	v_cvt_pk_bf16_f32 v48, v52, v53
	ds_read2_b32 v[50:51], v31 offset0:154 offset1:219
	s_waitcnt lgkmcnt(0)
	v_cvt_pk_bf16_f32 v49, v50, v51
	ds_read2_b32 v[50:51], v47 offset0:28 offset1:93
	s_waitcnt lgkmcnt(0)
	v_cvt_pk_bf16_f32 v50, v50, v51
	ds_read2_b32 v[52:53], v47 offset0:158 offset1:223
	s_waitcnt lgkmcnt(0)
	v_cvt_pk_bf16_f32 v51, v52, v53
	ds_read2_b32 v[52:53], v31 offset0:32 offset1:97
	global_store_dwordx4 v[56:57], v[48:51], off nt
	v_lshlrev_b32_e32 v0, 1, v12
	v_lshl_add_u64 v[56:57], v[54:55], 0, v[0:1]
	s_waitcnt lgkmcnt(0)
	v_cvt_pk_bf16_f32 v48, v52, v53
	ds_read2_b32 v[50:51], v31 offset0:162 offset1:227
	s_waitcnt lgkmcnt(0)
	v_cvt_pk_bf16_f32 v49, v50, v51
	ds_read2_b32 v[50:51], v47 offset0:36 offset1:101
	s_waitcnt lgkmcnt(0)
	v_cvt_pk_bf16_f32 v50, v50, v51
	ds_read2_b32 v[52:53], v47 offset0:166 offset1:231
	s_waitcnt lgkmcnt(0)
	v_cvt_pk_bf16_f32 v51, v52, v53
	ds_read2_b32 v[52:53], v31 offset0:40 offset1:105
	global_store_dwordx4 v[56:57], v[48:51], off nt
	v_lshlrev_b32_e32 v0, 1, v14
	v_lshl_add_u64 v[56:57], v[54:55], 0, v[0:1]
	s_waitcnt lgkmcnt(0)
	v_cvt_pk_bf16_f32 v48, v52, v53
	ds_read2_b32 v[50:51], v31 offset0:170 offset1:235
	s_waitcnt lgkmcnt(0)
	v_cvt_pk_bf16_f32 v49, v50, v51
	ds_read2_b32 v[50:51], v47 offset0:44 offset1:109
	s_waitcnt lgkmcnt(0)
	v_cvt_pk_bf16_f32 v50, v50, v51
	ds_read2_b32 v[52:53], v47 offset0:174 offset1:239
	s_waitcnt lgkmcnt(0)
	v_cvt_pk_bf16_f32 v51, v52, v53
	ds_read2_b32 v[52:53], v31 offset0:48 offset1:113
	global_store_dwordx4 v[56:57], v[48:51], off nt
	v_lshlrev_b32_e32 v0, 1, v16
	v_lshl_add_u64 v[56:57], v[54:55], 0, v[0:1]
	s_waitcnt lgkmcnt(0)
	v_cvt_pk_bf16_f32 v48, v52, v53
	ds_read2_b32 v[50:51], v31 offset0:178 offset1:243
	s_waitcnt lgkmcnt(0)
	v_cvt_pk_bf16_f32 v49, v50, v51
	ds_read2_b32 v[50:51], v47 offset0:52 offset1:117
	s_waitcnt lgkmcnt(0)
	v_cvt_pk_bf16_f32 v50, v50, v51
	ds_read2_b32 v[52:53], v47 offset0:182 offset1:247
	s_waitcnt lgkmcnt(0)
	v_cvt_pk_bf16_f32 v51, v52, v53
	ds_read2_b32 v[52:53], v31 offset0:56 offset1:121
	global_store_dwordx4 v[56:57], v[48:51], off nt
	v_lshlrev_b32_e32 v0, 1, v18
	s_waitcnt lgkmcnt(0)
	v_cvt_pk_bf16_f32 v48, v52, v53
	ds_read2_b32 v[50:51], v31 offset0:186 offset1:251
	s_waitcnt lgkmcnt(0)
	v_cvt_pk_bf16_f32 v49, v50, v51
	ds_read2_b32 v[50:51], v47 offset0:60 offset1:125
	s_waitcnt lgkmcnt(0)
	v_cvt_pk_bf16_f32 v50, v50, v51
	ds_read2_b32 v[52:53], v47 offset0:190 offset1:255
	s_waitcnt lgkmcnt(0)
	v_cvt_pk_bf16_f32 v51, v52, v53
	v_lshl_add_u64 v[52:53], v[54:55], 0, v[0:1]
	global_store_dwordx4 v[52:53], v[48:51], off nt
	s_waitcnt lgkmcnt(0)

; #define LAS __attribute__((address_space(3)))
; __device__ __forceinline__ void transpose_item(const float* W, int N, bf16_t* WT, int nkt, int k0, int n0, int r0, int kbd, LAS float* scr, int lane) {
;     const size_t dst_off = ((size_t)(r0 >> 8) * nkt + kbd) * 16384 + (size_t)(r0 & 255) * 64;
;     const int l15 = lane & 15, lq = lane >> 4;
;     f32x4 v[16];
; #pragma unroll
;     for (int i = 0; i < 16; ++i) v[i] = *(const f32x4*)(W + (size_t)(k0 + 4 * i + lq) * N + n0 + 4 * l15);
; #pragma unroll
;     for (int i = 0; i < 16; ++i) { LAS float* d = scr + (4 * i + lq) * 65 + 4 * l15; d[0] = v[i][0]; d[1] = v[i][1]; d[2] = v[i][2]; d[3] = v[i][3]; }
; __device__ __forceinline__ void phase_convert_late(const Params& p, LAS float* scr, int cw, int NCW, int lane) {
;     ...
;         if (r < I3) { const int nb = r % 64, kb = r / 64; transpose_item(p.in[16], 4096, (bf16_t*)(ws + WS_W_BS), 32, kb * 64, nb * 64, nb * 64, kb, scr, lane); continue; } r -= I3;
.LBB0_323:
	s_andn2_b64 vcc, exec, s[4:5]
	s_cbranch_vccnz .LBB0_325
	s_add_i32 s4, s35, 0xffffa500
	s_and_b32 s0, s4, 0xffffffc0
	s_and_b32 s5, s16, 0xfc0
	v_or_b32_e32 v0, s0, v3
	s_lshl_b32 s0, s5, 2
	v_or_b32_e32 v50, 4, v0
	v_mov_b32_e32 v51, v1
	v_or_b32_e32 v56, 8, v0
	v_mov_b32_e32 v57, v1
	v_or_b32_e32 v58, 12, v0
	v_mov_b32_e32 v59, v1
	v_or_b32_e32 v64, 16, v0
	v_mov_b32_e32 v65, v1
	v_or_b32_e32 v66, 20, v0
	v_mov_b32_e32 v67, v1
	v_or_b32_e32 v72, 24, v0
	v_mov_b32_e32 v73, v1
	v_or_b32_e32 v74, 28, v0
	v_mov_b32_e32 v75, v1
	v_or_b32_e32 v80, 32, v0
	v_mov_b32_e32 v81, v1
	v_or_b32_e32 v82, 36, v0
	v_mov_b32_e32 v83, v1
	v_lshl_add_u64 v[108:109], v[24:25], 0, s[0:1]
	v_lshlrev_b64 v[48:49], 14, v[0:1]
	v_lshlrev_b64 v[50:51], 14, v[50:51]
	v_lshlrev_b64 v[56:57], 14, v[56:57]
	v_lshlrev_b64 v[58:59], 14, v[58:59]
	v_lshlrev_b64 v[64:65], 14, v[64:65]
	v_lshlrev_b64 v[66:67], 14, v[66:67]
	v_lshlrev_b64 v[72:73], 14, v[72:73]
	v_lshlrev_b64 v[74:75], 14, v[74:75]
	v_lshlrev_b64 v[80:81], 14, v[80:81]
	v_lshlrev_b64 v[82:83], 14, v[82:83]
	v_or_b32_e32 v88, 40, v0
	v_mov_b32_e32 v89, v1
	v_or_b32_e32 v90, 44, v0
	v_mov_b32_e32 v91, v1
	v_lshl_add_u64 v[48:49], v[108:109], 0, v[48:49]
	v_lshl_add_u64 v[52:53], v[108:109], 0, v[50:51]
	v_lshl_add_u64 v[56:57], v[108:109], 0, v[56:57]
	v_lshl_add_u64 v[60:61], v[108:109], 0, v[58:59]
	v_lshl_add_u64 v[64:65], v[108:109], 0, v[64:65]
	v_lshl_add_u64 v[68:69], v[108:109], 0, v[66:67]
	v_lshl_add_u64 v[72:73], v[108:109], 0, v[72:73]
	v_lshl_add_u64 v[76:77], v[108:109], 0, v[74:75]
	v_lshl_add_u64 v[80:81], v[108:109], 0, v[80:81]
	v_lshl_add_u64 v[84:85], v[108:109], 0, v[82:83]
	v_lshlrev_b64 v[88:89], 14, v[88:89]
	v_lshlrev_b64 v[90:91], 14, v[90:91]
	global_load_dwordx4 v[48:51], v[48:49], off nt
	s_nop 0
	global_load_dwordx4 v[52:55], v[52:53], off nt
	s_nop 0
	global_load_dwordx4 v[56:59], v[56:57], off nt
	s_nop 0
	global_load_dwordx4 v[60:63], v[60:61], off nt
	s_nop 0
	global_load_dwordx4 v[64:67], v[64:65], off nt
	s_nop 0
	global_load_dwordx4 v[68:71], v[68:69], off nt
	s_nop 0
	global_load_dwordx4 v[72:75], v[72:73], off nt
	s_nop 0
	global_load_dwordx4 v[76:79], v[76:77], off nt
	s_nop 0
	global_load_dwordx4 v[80:83], v[80:81], off nt
	s_nop 0
	global_load_dwordx4 v[84:87], v[84:85], off nt
	v_lshl_add_u64 v[88:89], v[108:109], 0, v[88:89]
	v_lshl_add_u64 v[92:93], v[108:109], 0, v[90:91]
	global_load_dwordx4 v[88:91], v[88:89], off nt
	s_nop 0
	global_load_dwordx4 v[92:95], v[92:93], off nt
	v_or_b32_e32 v96, 48, v0
	v_mov_b32_e32 v97, v1
	v_lshlrev_b64 v[96:97], 14, v[96:97]
	v_lshl_add_u64 v[96:97], v[108:109], 0, v[96:97]
	v_or_b32_e32 v100, 52, v0
	v_mov_b32_e32 v101, v1
	global_load_dwordx4 v[96:99], v[96:97], off nt
	v_lshlrev_b64 v[100:101], 14, v[100:101]
	v_lshl_add_u64 v[100:101], v[108:109], 0, v[100:101]
	v_or_b32_e32 v104, 56, v0
	v_mov_b32_e32 v105, v1
	global_load_dwordx4 v[100:103], v[100:101], off nt
	v_lshlrev_b64 v[104:105], 14, v[104:105]
	v_lshl_add_u64 v[104:105], v[108:109], 0, v[104:105]
	v_or_b32_e32 v0, 60, v0
	global_load_dwordx4 v[104:107], v[104:105], off nt
	v_lshlrev_b64 v[110:111], 14, v[0:1]
	v_lshl_add_u64 v[108:109], v[108:109], 0, v[110:111]
	global_load_dwordx4 v[108:111], v[108:109], off nt
	v_add_u32_e32 v0, 0xf0a0, v5
	s_lshr_b32 s0, s4, 6
	s_and_b32 s4, s20, 0x3000
	s_and_b32 s5, s26, 0x1e0
	s_add_i32 s0, s5, s0
	s_lshl_b32 s4, s4, 1
	s_add_u32 s33, s11, s4
	v_add_u32_e32 v31, 0xc800, v9
	s_addc_u32 s62, s14, 0
	s_waitcnt vmcnt(15)
	ds_write2_b32 v7, v48, v49 offset1:1
	ds_write2_b32 v11, v50, v51 offset1:1
	s_waitcnt vmcnt(14)
	ds_write2_b32 v13, v52, v53 offset1:1
	ds_write2_b32 v15, v54, v55 offset1:1
	s_waitcnt vmcnt(13)
	ds_write2_b32 v17, v56, v57 offset1:1
	ds_write2_b32 v19, v58, v59 offset1:1
	s_waitcnt vmcnt(12)
	ds_write2_b32 v32, v60, v61 offset1:1
	ds_write2_b32 v33, v62, v63 offset1:1
	s_waitcnt vmcnt(11)
	ds_write2_b32 v34, v64, v65 offset1:1
	ds_write2_b32 v36, v66, v67 offset1:1
	s_waitcnt vmcnt(10)
	ds_write2_b32 v37, v68, v69 offset1:1
	ds_write2_b32 v38, v70, v71 offset1:1
	s_waitcnt vmcnt(9)
	ds_write2_b32 v39, v72, v73 offset1:1
	ds_write2_b32 v40, v74, v75 offset1:1
	s_waitcnt vmcnt(8)
	ds_write2_b32 v41, v76, v77 offset1:1
	ds_write2_b32 v42, v78, v79 offset1:1
	s_waitcnt vmcnt(7)
	ds_write2_b32 v43, v80, v81 offset1:1
	ds_write2_b32 v44, v82, v83 offset1:1
	s_waitcnt vmcnt(6)
	ds_write2_b32 v45, v84, v85 offset1:1
	ds_write2_b32 v46, v86, v87 offset1:1
	s_lshl_b64 s[4:5], s[0:1], 15
	s_waitcnt vmcnt(5)
	ds_write2_b32 v0, v88, v89 offset1:1
	v_add_u32_e32 v0, 0xf0a8, v5
	ds_write2_b32 v0, v90, v91 offset1:1
	v_add_u32_e32 v0, 0xf4b0, v5
	s_waitcnt vmcnt(4)
	ds_write2_b32 v0, v92, v93 offset1:1
	v_add_u32_e32 v0, 0xf4b8, v5
	ds_write2_b32 v0, v94, v95 offset1:1
	v_add_u32_e32 v0, 0xf8c0, v5
	s_waitcnt vmcnt(3)
	ds_write2_b32 v0, v96, v97 offset1:1
	v_add_u32_e32 v0, 0xf8c8, v5
	ds_write2_b32 v0, v98, v99 offset1:1
	v_add_u32_e32 v0, 0xfcd0, v5
	s_add_u32 s4, s33, s4
	s_waitcnt vmcnt(2)
; #define LAS __attribute__((address_space(3)))
; __device__ __forceinline__ unsigned cvt_pk_bf16(float lo, float hi) { unsigned r; asm volatile("v_cvt_pk_bf16_f32 %0, %1, %2" : "=v"(r) : "v"(lo), "v"(hi)); return r; }
; #define LDS_WAIT() asm volatile("s_waitcnt lgkmcnt(0)" ::: "memory")
; __device__ __forceinline__ void transpose_item(const float* W, int N, bf16_t* WT, int nkt, int k0, int n0, int r0, int kbd, LAS float* scr, int lane) {
;     ...
;     for (int i = 0; i < 16; ++i) { LAS float* d = scr + (4 * i + lq) * 65 + 4 * l15; d[0] = v[i][0]; d[1] = v[i][1]; d[2] = v[i][2]; d[3] = v[i][3]; }
;     LDS_WAIT();
;     const int c = lane & 7;
; #pragma unroll
;     for (int j = 0; j < 8; ++j) { const int n = (lane >> 3) + 8 * j; const LAS float* s = scr + (8 * c) * 65 + n;
;         u32x4 o; o.x = cvt_pk_bf16(s[0], s[65]); o.y = cvt_pk_bf16(s[2 * 65], s[3 * 65]); o.z = cvt_pk_bf16(s[4 * 65], s[5 * 65]); o.w = cvt_pk_bf16(s[6 * 65], s[7 * 65]);
;         *(u32x4*)(WT + dst_off + (size_t)n * 64 + 8 * c) = o; }
;     LDS_WAIT();
	ds_write2_b32 v0, v100, v101 offset1:1
	v_add_u32_e32 v0, 0xfcd8, v5
	ds_write2_b32 v0, v102, v103 offset1:1
	v_add_u32_e32 v0, 0x38e0, v7
	s_waitcnt vmcnt(1)
	ds_write2_b32 v0, v104, v105 offset1:1
	v_add_u32_e32 v0, 0x38e8, v7
	ds_write2_b32 v0, v106, v107 offset1:1
	v_add_u32_e32 v0, 0x3cf0, v7
	s_waitcnt vmcnt(0)
	ds_write2_b32 v0, v108, v109 offset1:1
	v_add_u32_e32 v0, 0x3cf8, v7
	ds_write2_b32 v0, v110, v111 offset1:1
	s_waitcnt lgkmcnt(0)
	ds_read2_b32 v[48:49], v31 offset1:65
	s_waitcnt lgkmcnt(0)
	v_cvt_pk_bf16_f32 v48, v48, v49
	ds_read2_b32 v[50:51], v31 offset0:130 offset1:195
	v_add_u32_e32 v47, 0xcc00, v9
	s_addc_u32 s5, s62, s5
	v_lshlrev_b32_e32 v0, 1, v2
	s_waitcnt lgkmcnt(0)
	v_cvt_pk_bf16_f32 v49, v50, v51
	ds_read2_b32 v[50:51], v47 offset0:4 offset1:69
	v_lshl_add_u64 v[54:55], s[4:5], 0, v[0:1]
	v_lshlrev_b32_e32 v0, 1, v4
	s_waitcnt lgkmcnt(0)
	v_cvt_pk_bf16_f32 v50, v50, v51
	ds_read2_b32 v[52:53], v47 offset0:134 offset1:199
	s_waitcnt lgkmcnt(0)
	v_cvt_pk_bf16_f32 v51, v52, v53
	v_lshl_add_u64 v[56:57], v[54:55], 0, v[0:1]
	ds_read2_b32 v[52:53], v31 offset0:8 offset1:73
	global_store_dwordx4 v[56:57], v[48:51], off nt
	v_lshlrev_b32_e32 v0, 1, v6
	v_lshl_add_u64 v[56:57], v[54:55], 0, v[0:1]
	s_waitcnt lgkmcnt(0)
	v_cvt_pk_bf16_f32 v48, v52, v53
	ds_read2_b32 v[50:51], v31 offset0:138 offset1:203
	s_waitcnt lgkmcnt(0)
	v_cvt_pk_bf16_f32 v49, v50, v51
	ds_read2_b32 v[50:51], v47 offset0:12 offset1:77
	s_waitcnt lgkmcnt(0)
	v_cvt_pk_bf16_f32 v50, v50, v51
	ds_read2_b32 v[52:53], v47 offset0:142 offset1:207
	s_waitcnt lgkmcnt(0)
	v_cvt_pk_bf16_f32 v51, v52, v53
	ds_read2_b32 v[52:53], v31 offset0:16 offset1:81
	global_store_dwordx4 v[56:57], v[48:51], off nt
	v_lshlrev_b32_e32 v0, 1, v8
	v_lshl_add_u64 v[56:57], v[54:55], 0, v[0:1]
	s_waitcnt lgkmcnt(0)
	v_cvt_pk_bf16_f32 v48, v52, v53
	ds_read2_b32 v[50:51], v31 offset0:146 offset1:211
	s_waitcnt lgkmcnt(0)
	v_cvt_pk_bf16_f32 v49, v50, v51
	ds_read2_b32 v[50:51], v47 offset0:20 offset1:85
	s_waitcnt lgkmcnt(0)
	v_cvt_pk_bf16_f32 v50, v50, v51
	ds_read2_b32 v[52:53], v47 offset0:150 offset1:215
	s_waitcnt lgkmcnt(0)
	v_cvt_pk_bf16_f32 v51, v52, v53
	ds_read2_b32 v[52:53], v31 offset0:24 offset1:89
	global_store_dwordx4 v[56:57], v[48:51], off nt
	v_lshlrev_b32_e32 v0, 1, v10
	v_lshl_add_u64 v[56:57], v[54:55], 0, v[0:1]
	s_waitcnt lgkmcnt(0)
	v_cvt_pk_bf16_f32 v48, v52, v53
	ds_read2_b32 v[50:51], v31 offset0:154 offset1:219
	s_waitcnt lgkmcnt(0)
	v_cvt_pk_bf16_f32 v49, v50, v51
	ds_read2_b32 v[50:51], v47 offset0:28 offset1:93
	s_waitcnt lgkmcnt(0)
	v_cvt_pk_bf16_f32 v50, v50, v51
	ds_read2_b32 v[52:53], v47 offset0:158 offset1:223
	s_waitcnt lgkmcnt(0)
	v_cvt_pk_bf16_f32 v51, v52, v53
	ds_read2_b32 v[52:53], v31 offset0:32 offset1:97
	global_store_dwordx4 v[56:57], v[48:51], off nt
	v_lshlrev_b32_e32 v0, 1, v12
	v_lshl_add_u64 v[56:57], v[54:55], 0, v[0:1]
	s_waitcnt lgkmcnt(0)
	v_cvt_pk_bf16_f32 v48, v52, v53
	ds_read2_b32 v[50:51], v31 offset0:162 offset1:227
	s_waitcnt lgkmcnt(0)
	v_cvt_pk_bf16_f32 v49, v50, v51
	ds_read2_b32 v[50:51], v47 offset0:36 offset1:101
	s_waitcnt lgkmcnt(0)
	v_cvt_pk_bf16_f32 v50, v50, v51
	ds_read2_b32 v[52:53], v47 offset0:166 offset1:231
	s_waitcnt lgkmcnt(0)
	v_cvt_pk_bf16_f32 v51, v52, v53
	ds_read2_b32 v[52:53], v31 offset0:40 offset1:105
	global_store_dwordx4 v[56:57], v[48:51], off nt
	v_lshlrev_b32_e32 v0, 1, v14
	v_lshl_add_u64 v[56:57], v[54:55], 0, v[0:1]
	s_waitcnt lgkmcnt(0)
	v_cvt_pk_bf16_f32 v48, v52, v53
	ds_read2_b32 v[50:51], v31 offset0:170 offset1:235
	s_waitcnt lgkmcnt(0)
	v_cvt_pk_bf16_f32 v49, v50, v51
	ds_read2_b32 v[50:51], v47 offset0:44 offset1:109
	s_waitcnt lgkmcnt(0)
	v_cvt_pk_bf16_f32 v50, v50, v51
	ds_read2_b32 v[52:53], v47 offset0:174 offset1:239
	s_waitcnt lgkmcnt(0)
	v_cvt_pk_bf16_f32 v51, v52, v53
	ds_read2_b32 v[52:53], v31 offset0:48 offset1:113
	global_store_dwordx4 v[56:57], v[48:51], off nt
	v_lshlrev_b32_e32 v0, 1, v16
	v_lshl_add_u64 v[56:57], v[54:55], 0, v[0:1]
	s_waitcnt lgkmcnt(0)
	v_cvt_pk_bf16_f32 v48, v52, v53
	ds_read2_b32 v[50:51], v31 offset0:178 offset1:243
	s_waitcnt lgkmcnt(0)
	v_cvt_pk_bf16_f32 v49, v50, v51
	ds_read2_b32 v[50:51], v47 offset0:52 offset1:117
	s_waitcnt lgkmcnt(0)
	v_cvt_pk_bf16_f32 v50, v50, v51
	ds_read2_b32 v[52:53], v47 offset0:182 offset1:247
	s_waitcnt lgkmcnt(0)
	v_cvt_pk_bf16_f32 v51, v52, v53
	ds_read2_b32 v[52:53], v31 offset0:56 offset1:121
	global_store_dwordx4 v[56:57], v[48:51], off nt
	v_lshlrev_b32_e32 v0, 1, v18
	s_waitcnt lgkmcnt(0)
	v_cvt_pk_bf16_f32 v48, v52, v53
	ds_read2_b32 v[50:51], v31 offset0:186 offset1:251
	s_waitcnt lgkmcnt(0)
	v_cvt_pk_bf16_f32 v49, v50, v51
	ds_read2_b32 v[50:51], v47 offset0:60 offset1:125
	s_waitcnt lgkmcnt(0)
	v_cvt_pk_bf16_f32 v50, v50, v51
	ds_read2_b32 v[52:53], v47 offset0:190 offset1:255
	s_waitcnt lgkmcnt(0)
	v_cvt_pk_bf16_f32 v51, v52, v53
	v_lshl_add_u64 v[52:53], v[54:55], 0, v[0:1]
	global_store_dwordx4 v[52:53], v[48:51], off nt
	s_waitcnt lgkmcnt(0)

; #define LAS __attribute__((address_space(3)))
; __device__ __forceinline__ void transpose_item(const float* W, int N, bf16_t* WT, int nkt, int k0, int n0, int r0, int kbd, LAS float* scr, int lane) {
;     const size_t dst_off = ((size_t)(r0 >> 8) * nkt + kbd) * 16384 + (size_t)(r0 & 255) * 64;
;     const int l15 = lane & 15, lq = lane >> 4;
;     f32x4 v[16];
; #pragma unroll
;     for (int i = 0; i < 16; ++i) v[i] = *(const f32x4*)(W + (size_t)(k0 + 4 * i + lq) * N + n0 + 4 * l15);
; #pragma unroll
;     for (int i = 0; i < 16; ++i) { LAS float* d = scr + (4 * i + lq) * 65 + 4 * l15; d[0] = v[i][0]; d[1] = v[i][1]; d[2] = v[i][2]; d[3] = v[i][3]; }
; __device__ __forceinline__ void phase_convert_late(const Params& p, LAS float* scr, int cw, int NCW, int lane) {
;     ...
;         if (r < I2) { const int g = r >> 6, q = r & 63, nb = q & 7, kb = q >> 3; transpose_item(p.in[13] + (size_t)g * 512 * 512, 512, (bf16_t*)(ws + WS_W_POOL), 32, kb * 64, nb * 64, nb * 64, g * 8 + kb, scr, lane); continue; } r -= I2;
.LBB0_326:
	s_andn2_b64 vcc, exec, s[4:5]
	s_cbranch_vccnz .LBB0_328
	s_add_i32 s0, s35, 0xffffa600
	s_lshr_b32 s0, s0, 6
	s_bfe_u32 s33, s35, 0x30003
	s_lshl_b64 s[4:5], s[0:1], 20
	s_add_u32 s4, s46, s4
	s_addc_u32 s5, s47, s5
	s_and_b32 s62, s16, 0x1c0
	s_lshl_b32 s0, s0, 3
	s_and_b32 s63, s20, 0x3000
	s_lshl_b32 s62, s62, 2
	s_add_u32 s4, s4, s62
	s_addc_u32 s5, s5, 0
	v_mov_b32_e32 v31, v1
	v_lshl_add_u64 v[48:49], s[4:5], 0, v[30:31]
	v_lshl_or_b32 v0, s33, 17, v35
	v_lshl_add_u64 v[108:109], v[48:49], 0, v[0:1]
	v_add_co_u32_e32 v52, vcc, s43, v108
	v_add_u32_e32 v0, 0xf0a0, v5
	s_nop 0
	v_addc_co_u32_e32 v53, vcc, 0, v109, vcc
	v_add_co_u32_e32 v56, vcc, s61, v108
	global_load_dwordx4 v[48:51], v[108:109], off nt
	s_nop 0
	global_load_dwordx4 v[52:55], v[52:53], off nt
	v_addc_co_u32_e32 v57, vcc, 0, v109, vcc
	v_add_co_u32_e32 v60, vcc, s42, v108
	s_and_b32 s4, s26, 32
	s_nop 0
	v_addc_co_u32_e32 v61, vcc, 0, v109, vcc
	v_add_co_u32_e32 v64, vcc, s66, v108
	global_load_dwordx4 v[56:59], v[56:57], off nt
	s_nop 0
	global_load_dwordx4 v[60:63], v[60:61], off nt
	v_addc_co_u32_e32 v65, vcc, 0, v109, vcc
	v_add_co_u32_e32 v68, vcc, s67, v108
	s_or_b32 s4, s4, s33
	s_nop 0
	v_addc_co_u32_e32 v69, vcc, 0, v109, vcc
	v_add_co_u32_e32 v72, vcc, s68, v108
	global_load_dwordx4 v[64:67], v[64:65], off nt
	s_nop 0
	global_load_dwordx4 v[68:71], v[68:69], off nt
	v_addc_co_u32_e32 v73, vcc, 0, v109, vcc
	v_add_co_u32_e32 v76, vcc, s69, v108
	s_add_i32 s0, s4, s0
	s_nop 0
	v_addc_co_u32_e32 v77, vcc, 0, v109, vcc
	v_add_co_u32_e32 v80, vcc, s70, v108
	global_load_dwordx4 v[72:75], v[72:73], off nt
	s_nop 0
	global_load_dwordx4 v[76:79], v[76:77], off nt
	v_addc_co_u32_e32 v81, vcc, 0, v109, vcc
	v_add_co_u32_e32 v84, vcc, s71, v108
	s_lshl_b32 s4, s63, 1
	s_nop 0
	v_addc_co_u32_e32 v85, vcc, 0, v109, vcc
	v_add_co_u32_e32 v88, vcc, s72, v108
	global_load_dwordx4 v[80:83], v[80:81], off nt
	s_nop 0
	global_load_dwordx4 v[84:87], v[84:85], off nt
	v_addc_co_u32_e32 v89, vcc, 0, v109, vcc
	v_add_co_u32_e32 v92, vcc, s73, v108
	s_add_u32 s33, s15, s4
	s_nop 0
	v_addc_co_u32_e32 v93, vcc, 0, v109, vcc
	global_load_dwordx4 v[88:91], v[88:89], off nt
	s_nop 0
	global_load_dwordx4 v[92:95], v[92:93], off nt
	v_add_co_u32_e32 v96, vcc, s74, v108
	v_add_u32_e32 v31, 0xc800, v9
	s_nop 0
	v_addc_co_u32_e32 v97, vcc, 0, v109, vcc
	global_load_dwordx4 v[96:99], v[96:97], off nt
	v_add_co_u32_e32 v100, vcc, s75, v108
	s_addc_u32 s62, s36, 0
	s_nop 0
	v_addc_co_u32_e32 v101, vcc, 0, v109, vcc
	global_load_dwordx4 v[100:103], v[100:101], off nt
	v_add_co_u32_e32 v104, vcc, s76, v108
	s_lshl_b64 s[4:5], s[0:1], 15
	s_nop 0
	v_addc_co_u32_e32 v105, vcc, 0, v109, vcc
	global_load_dwordx4 v[104:107], v[104:105], off nt
	v_add_co_u32_e32 v108, vcc, s77, v108
	s_add_u32 s4, s33, s4
	s_nop 0
	v_addc_co_u32_e32 v109, vcc, 0, v109, vcc
	global_load_dwordx4 v[108:111], v[108:109], off nt
	v_add_u32_e32 v47, 0xcc00, v9
	s_addc_u32 s5, s62, s5
	s_waitcnt vmcnt(15)
	ds_write2_b32 v7, v48, v49 offset1:1
	ds_write2_b32 v11, v50, v51 offset1:1
	s_waitcnt vmcnt(14)
	ds_write2_b32 v13, v52, v53 offset1:1
	ds_write2_b32 v15, v54, v55 offset1:1
	s_waitcnt vmcnt(13)
	ds_write2_b32 v17, v56, v57 offset1:1
	ds_write2_b32 v19, v58, v59 offset1:1
	s_waitcnt vmcnt(12)
	ds_write2_b32 v32, v60, v61 offset1:1
	ds_write2_b32 v33, v62, v63 offset1:1
	s_waitcnt vmcnt(11)
	ds_write2_b32 v34, v64, v65 offset1:1
	ds_write2_b32 v36, v66, v67 offset1:1
	s_waitcnt vmcnt(10)
	ds_write2_b32 v37, v68, v69 offset1:1
	ds_write2_b32 v38, v70, v71 offset1:1
	s_waitcnt vmcnt(9)
	ds_write2_b32 v39, v72, v73 offset1:1
	ds_write2_b32 v40, v74, v75 offset1:1
	s_waitcnt vmcnt(8)
	ds_write2_b32 v41, v76, v77 offset1:1
	ds_write2_b32 v42, v78, v79 offset1:1
	s_waitcnt vmcnt(7)
	ds_write2_b32 v43, v80, v81 offset1:1
	ds_write2_b32 v44, v82, v83 offset1:1
	s_waitcnt vmcnt(6)
	ds_write2_b32 v45, v84, v85 offset1:1
	ds_write2_b32 v46, v86, v87 offset1:1
	s_waitcnt vmcnt(5)
	ds_write2_b32 v0, v88, v89 offset1:1
	v_add_u32_e32 v0, 0xf0a8, v5
	ds_write2_b32 v0, v90, v91 offset1:1
	v_add_u32_e32 v0, 0xf4b0, v5
	s_waitcnt vmcnt(4)
	ds_write2_b32 v0, v92, v93 offset1:1
	v_add_u32_e32 v0, 0xf4b8, v5
	ds_write2_b32 v0, v94, v95 offset1:1
	v_add_u32_e32 v0, 0xf8c0, v5
	s_waitcnt vmcnt(3)
	ds_write2_b32 v0, v96, v97 offset1:1
	v_add_u32_e32 v0, 0xf8c8, v5
	ds_write2_b32 v0, v98, v99 offset1:1
	v_add_u32_e32 v0, 0xfcd0, v5
	s_waitcnt vmcnt(2)
	ds_write2_b32 v0, v100, v101 offset1:1
	v_add_u32_e32 v0, 0xfcd8, v5
	ds_write2_b32 v0, v102, v103 offset1:1
	v_add_u32_e32 v0, 0x38e0, v7
	s_waitcnt vmcnt(1)
	ds_write2_b32 v0, v104, v105 offset1:1
	v_add_u32_e32 v0, 0x38e8, v7
	ds_write2_b32 v0, v106, v107 offset1:1
	v_add_u32_e32 v0, 0x3cf0, v7
	s_waitcnt vmcnt(0)
; #define LAS __attribute__((address_space(3)))
; __device__ __forceinline__ unsigned cvt_pk_bf16(float lo, float hi) { unsigned r; asm volatile("v_cvt_pk_bf16_f32 %0, %1, %2" : "=v"(r) : "v"(lo), "v"(hi)); return r; }
; #define LDS_WAIT() asm volatile("s_waitcnt lgkmcnt(0)" ::: "memory")
; __device__ __forceinline__ void transpose_item(const float* W, int N, bf16_t* WT, int nkt, int k0, int n0, int r0, int kbd, LAS float* scr, int lane) {
;     ...
;     for (int i = 0; i < 16; ++i) { LAS float* d = scr + (4 * i + lq) * 65 + 4 * l15; d[0] = v[i][0]; d[1] = v[i][1]; d[2] = v[i][2]; d[3] = v[i][3]; }
;     LDS_WAIT();
;     const int c = lane & 7;
; #pragma unroll
;     for (int j = 0; j < 8; ++j) { const int n = (lane >> 3) + 8 * j; const LAS float* s = scr + (8 * c) * 65 + n;
;         u32x4 o; o.x = cvt_pk_bf16(s[0], s[65]); o.y = cvt_pk_bf16(s[2 * 65], s[3 * 65]); o.z = cvt_pk_bf16(s[4 * 65], s[5 * 65]); o.w = cvt_pk_bf16(s[6 * 65], s[7 * 65]);
;         *(u32x4*)(WT + dst_off + (size_t)n * 64 + 8 * c) = o; }
;     LDS_WAIT();
	ds_write2_b32 v0, v108, v109 offset1:1
	v_add_u32_e32 v0, 0x3cf8, v7
	ds_write2_b32 v0, v110, v111 offset1:1
	s_waitcnt lgkmcnt(0)
	ds_read2_b32 v[48:49], v31 offset1:65
	s_waitcnt lgkmcnt(0)
	v_cvt_pk_bf16_f32 v48, v48, v49
	ds_read2_b32 v[50:51], v31 offset0:130 offset1:195
	v_lshlrev_b32_e32 v0, 1, v2
	s_waitcnt lgkmcnt(0)
	v_cvt_pk_bf16_f32 v49, v50, v51
	ds_read2_b32 v[50:51], v47 offset0:4 offset1:69
	v_lshl_add_u64 v[54:55], s[4:5], 0, v[0:1]
	v_lshlrev_b32_e32 v0, 1, v4
	s_waitcnt lgkmcnt(0)
	v_cvt_pk_bf16_f32 v50, v50, v51
	ds_read2_b32 v[52:53], v47 offset0:134 offset1:199
	s_waitcnt lgkmcnt(0)
	v_cvt_pk_bf16_f32 v51, v52, v53
	v_lshl_add_u64 v[56:57], v[54:55], 0, v[0:1]
	ds_read2_b32 v[52:53], v31 offset0:8 offset1:73
	global_store_dwordx4 v[56:57], v[48:51], off nt
	v_lshlrev_b32_e32 v0, 1, v6
	v_lshl_add_u64 v[56:57], v[54:55], 0, v[0:1]
	s_waitcnt lgkmcnt(0)
	v_cvt_pk_bf16_f32 v48, v52, v53
	ds_read2_b32 v[50:51], v31 offset0:138 offset1:203
	s_waitcnt lgkmcnt(0)
	v_cvt_pk_bf16_f32 v49, v50, v51
	ds_read2_b32 v[50:51], v47 offset0:12 offset1:77
	s_waitcnt lgkmcnt(0)
	v_cvt_pk_bf16_f32 v50, v50, v51
	ds_read2_b32 v[52:53], v47 offset0:142 offset1:207
	s_waitcnt lgkmcnt(0)
	v_cvt_pk_bf16_f32 v51, v52, v53
	ds_read2_b32 v[52:53], v31 offset0:16 offset1:81
	global_store_dwordx4 v[56:57], v[48:51], off nt
	v_lshlrev_b32_e32 v0, 1, v8
	v_lshl_add_u64 v[56:57], v[54:55], 0, v[0:1]
	s_waitcnt lgkmcnt(0)
	v_cvt_pk_bf16_f32 v48, v52, v53
	ds_read2_b32 v[50:51], v31 offset0:146 offset1:211
	s_waitcnt lgkmcnt(0)
	v_cvt_pk_bf16_f32 v49, v50, v51
	ds_read2_b32 v[50:51], v47 offset0:20 offset1:85
	s_waitcnt lgkmcnt(0)
	v_cvt_pk_bf16_f32 v50, v50, v51
	ds_read2_b32 v[52:53], v47 offset0:150 offset1:215
	s_waitcnt lgkmcnt(0)
	v_cvt_pk_bf16_f32 v51, v52, v53
	ds_read2_b32 v[52:53], v31 offset0:24 offset1:89
	global_store_dwordx4 v[56:57], v[48:51], off nt
	v_lshlrev_b32_e32 v0, 1, v10
	v_lshl_add_u64 v[56:57], v[54:55], 0, v[0:1]
	s_waitcnt lgkmcnt(0)
	v_cvt_pk_bf16_f32 v48, v52, v53
	ds_read2_b32 v[50:51], v31 offset0:154 offset1:219
	s_waitcnt lgkmcnt(0)
	v_cvt_pk_bf16_f32 v49, v50, v51
	ds_read2_b32 v[50:51], v47 offset0:28 offset1:93
	s_waitcnt lgkmcnt(0)
	v_cvt_pk_bf16_f32 v50, v50, v51
	ds_read2_b32 v[52:53], v47 offset0:158 offset1:223
	s_waitcnt lgkmcnt(0)
	v_cvt_pk_bf16_f32 v51, v52, v53
	ds_read2_b32 v[52:53], v31 offset0:32 offset1:97
	global_store_dwordx4 v[56:57], v[48:51], off nt
	v_lshlrev_b32_e32 v0, 1, v12
	v_lshl_add_u64 v[56:57], v[54:55], 0, v[0:1]
	s_waitcnt lgkmcnt(0)
	v_cvt_pk_bf16_f32 v48, v52, v53
	ds_read2_b32 v[50:51], v31 offset0:162 offset1:227
	s_waitcnt lgkmcnt(0)
	v_cvt_pk_bf16_f32 v49, v50, v51
	ds_read2_b32 v[50:51], v47 offset0:36 offset1:101
	s_waitcnt lgkmcnt(0)
	v_cvt_pk_bf16_f32 v50, v50, v51
	ds_read2_b32 v[52:53], v47 offset0:166 offset1:231
	s_waitcnt lgkmcnt(0)
	v_cvt_pk_bf16_f32 v51, v52, v53
	ds_read2_b32 v[52:53], v31 offset0:40 offset1:105
	global_store_dwordx4 v[56:57], v[48:51], off nt
	v_lshlrev_b32_e32 v0, 1, v14
	v_lshl_add_u64 v[56:57], v[54:55], 0, v[0:1]
	s_waitcnt lgkmcnt(0)
	v_cvt_pk_bf16_f32 v48, v52, v53
	ds_read2_b32 v[50:51], v31 offset0:170 offset1:235
	s_waitcnt lgkmcnt(0)
	v_cvt_pk_bf16_f32 v49, v50, v51
	ds_read2_b32 v[50:51], v47 offset0:44 offset1:109
	s_waitcnt lgkmcnt(0)
	v_cvt_pk_bf16_f32 v50, v50, v51
	ds_read2_b32 v[52:53], v47 offset0:174 offset1:239
	s_waitcnt lgkmcnt(0)
	v_cvt_pk_bf16_f32 v51, v52, v53
	ds_read2_b32 v[52:53], v31 offset0:48 offset1:113
	global_store_dwordx4 v[56:57], v[48:51], off nt
	v_lshlrev_b32_e32 v0, 1, v16
	v_lshl_add_u64 v[56:57], v[54:55], 0, v[0:1]
	s_waitcnt lgkmcnt(0)
	v_cvt_pk_bf16_f32 v48, v52, v53
	ds_read2_b32 v[50:51], v31 offset0:178 offset1:243
	s_waitcnt lgkmcnt(0)
	v_cvt_pk_bf16_f32 v49, v50, v51
	ds_read2_b32 v[50:51], v47 offset0:52 offset1:117
	s_waitcnt lgkmcnt(0)
	v_cvt_pk_bf16_f32 v50, v50, v51
	ds_read2_b32 v[52:53], v47 offset0:182 offset1:247
	s_waitcnt lgkmcnt(0)
	v_cvt_pk_bf16_f32 v51, v52, v53
	ds_read2_b32 v[52:53], v31 offset0:56 offset1:121
	global_store_dwordx4 v[56:57], v[48:51], off nt
	v_lshlrev_b32_e32 v0, 1, v18
	s_waitcnt lgkmcnt(0)
	v_cvt_pk_bf16_f32 v48, v52, v53
	ds_read2_b32 v[50:51], v31 offset0:186 offset1:251
	s_waitcnt lgkmcnt(0)
	v_cvt_pk_bf16_f32 v49, v50, v51
	ds_read2_b32 v[50:51], v47 offset0:60 offset1:125
	s_waitcnt lgkmcnt(0)
	v_cvt_pk_bf16_f32 v50, v50, v51
	ds_read2_b32 v[52:53], v47 offset0:190 offset1:255
	s_waitcnt lgkmcnt(0)
	v_cvt_pk_bf16_f32 v51, v52, v53
	v_lshl_add_u64 v[52:53], v[54:55], 0, v[0:1]
	global_store_dwordx4 v[52:53], v[48:51], off nt
	s_waitcnt lgkmcnt(0)

; #define LAS __attribute__((address_space(3)))
; __device__ __forceinline__ void transpose_item(const float* W, int N, bf16_t* WT, int nkt, int k0, int n0, int r0, int kbd, LAS float* scr, int lane) {
;     const size_t dst_off = ((size_t)(r0 >> 8) * nkt + kbd) * 16384 + (size_t)(r0 & 255) * 64;
;     const int l15 = lane & 15, lq = lane >> 4;
;     f32x4 v[16];
; #pragma unroll
;     for (int i = 0; i < 16; ++i) v[i] = *(const f32x4*)(W + (size_t)(k0 + 4 * i + lq) * N + n0 + 4 * l15);
; #pragma unroll
;     for (int i = 0; i < 16; ++i) { LAS float* d = scr + (4 * i + lq) * 65 + 4 * l15; d[0] = v[i][0]; d[1] = v[i][1]; d[2] = v[i][2]; d[3] = v[i][3]; }
; __device__ __forceinline__ void phase_convert_late(const Params& p, LAS float* scr, int cw, int NCW, int lane) {
;     ...
;         if (r < I1) { const int nb = r % 32, kb = r / 32; transpose_item(p.in[11], 2048, (bf16_t*)(ws + WS_W_GLU), 32, kb * 64, nb * 64, nb * 64, kb, scr, lane); continue; } r -= I1;
.LBB0_329:
	s_andn2_b64 vcc, exec, s[4:5]
	s_cbranch_vccnz .LBB0_331
	s_add_i32 s0, s35, 0xffffaa00
	s_lshr_b32 s4, s0, 5
	s_and_b32 s0, s16, 0x7c0
	v_lshl_or_b32 v0, s4, 6, v3
	s_lshl_b32 s0, s0, 2
	v_or_b32_e32 v50, 4, v0
	v_mov_b32_e32 v51, v1
	v_or_b32_e32 v56, 8, v0
	v_mov_b32_e32 v57, v1
	v_or_b32_e32 v58, 12, v0
	v_mov_b32_e32 v59, v1
	v_or_b32_e32 v64, 16, v0
	v_mov_b32_e32 v65, v1
	v_or_b32_e32 v66, 20, v0
	v_mov_b32_e32 v67, v1
	v_or_b32_e32 v72, 24, v0
	v_mov_b32_e32 v73, v1
	v_or_b32_e32 v74, 28, v0
	v_mov_b32_e32 v75, v1
	v_or_b32_e32 v80, 32, v0
	v_mov_b32_e32 v81, v1
	v_or_b32_e32 v82, 36, v0
	v_mov_b32_e32 v83, v1
	v_lshl_add_u64 v[108:109], v[26:27], 0, s[0:1]
	v_lshlrev_b64 v[48:49], 13, v[0:1]
	v_lshlrev_b64 v[50:51], 13, v[50:51]
	v_lshlrev_b64 v[56:57], 13, v[56:57]
	v_lshlrev_b64 v[58:59], 13, v[58:59]
	v_lshlrev_b64 v[64:65], 13, v[64:65]
	v_lshlrev_b64 v[66:67], 13, v[66:67]
	v_lshlrev_b64 v[72:73], 13, v[72:73]
	v_lshlrev_b64 v[74:75], 13, v[74:75]
	v_lshlrev_b64 v[80:81], 13, v[80:81]
	v_lshlrev_b64 v[82:83], 13, v[82:83]
	v_or_b32_e32 v88, 40, v0
	v_mov_b32_e32 v89, v1
	v_or_b32_e32 v90, 44, v0
	v_mov_b32_e32 v91, v1
	v_lshl_add_u64 v[48:49], v[108:109], 0, v[48:49]
	v_lshl_add_u64 v[52:53], v[108:109], 0, v[50:51]
	v_lshl_add_u64 v[56:57], v[108:109], 0, v[56:57]
	v_lshl_add_u64 v[60:61], v[108:109], 0, v[58:59]
	v_lshl_add_u64 v[64:65], v[108:109], 0, v[64:65]
	v_lshl_add_u64 v[68:69], v[108:109], 0, v[66:67]
	v_lshl_add_u64 v[72:73], v[108:109], 0, v[72:73]
	v_lshl_add_u64 v[76:77], v[108:109], 0, v[74:75]
	v_lshl_add_u64 v[80:81], v[108:109], 0, v[80:81]
	v_lshl_add_u64 v[84:85], v[108:109], 0, v[82:83]
	v_lshlrev_b64 v[88:89], 13, v[88:89]
	v_lshlrev_b64 v[90:91], 13, v[90:91]
	global_load_dwordx4 v[48:51], v[48:49], off nt
	s_nop 0
	global_load_dwordx4 v[52:55], v[52:53], off nt
	s_nop 0
	global_load_dwordx4 v[56:59], v[56:57], off nt
	s_nop 0
	global_load_dwordx4 v[60:63], v[60:61], off nt
	s_nop 0
	global_load_dwordx4 v[64:67], v[64:65], off nt
	s_nop 0
	global_load_dwordx4 v[68:71], v[68:69], off nt
	s_nop 0
	global_load_dwordx4 v[72:75], v[72:73], off nt
	s_nop 0
	global_load_dwordx4 v[76:79], v[76:77], off nt
	s_nop 0
	global_load_dwordx4 v[80:83], v[80:81], off nt
	s_nop 0
	global_load_dwordx4 v[84:87], v[84:85], off nt
	v_lshl_add_u64 v[88:89], v[108:109], 0, v[88:89]
	v_lshl_add_u64 v[92:93], v[108:109], 0, v[90:91]
	global_load_dwordx4 v[88:91], v[88:89], off nt
	s_nop 0
	global_load_dwordx4 v[92:95], v[92:93], off nt
	v_or_b32_e32 v96, 48, v0
	v_mov_b32_e32 v97, v1
	v_lshlrev_b64 v[96:97], 13, v[96:97]
	v_lshl_add_u64 v[96:97], v[108:109], 0, v[96:97]
	v_or_b32_e32 v100, 52, v0
	v_mov_b32_e32 v101, v1
	global_load_dwordx4 v[96:99], v[96:97], off nt
	v_lshlrev_b64 v[100:101], 13, v[100:101]
	v_lshl_add_u64 v[100:101], v[108:109], 0, v[100:101]
	v_or_b32_e32 v104, 56, v0
	v_mov_b32_e32 v105, v1
	global_load_dwordx4 v[100:103], v[100:101], off nt
	v_lshlrev_b64 v[104:105], 13, v[104:105]
	v_lshl_add_u64 v[104:105], v[108:109], 0, v[104:105]
	v_or_b32_e32 v0, 60, v0
	global_load_dwordx4 v[104:107], v[104:105], off nt
	v_lshlrev_b64 v[110:111], 13, v[0:1]
	v_lshl_add_u64 v[108:109], v[108:109], 0, v[110:111]
	global_load_dwordx4 v[108:111], v[108:109], off nt
	v_add_u32_e32 v0, 0xf0a0, v5
	s_and_b32 s5, s20, 0x3000
	s_and_b32 s0, s26, 0xe0
	s_add_i32 s0, s0, s4
	s_lshl_b32 s4, s5, 1
	s_add_u32 s33, s37, s4
	v_add_u32_e32 v31, 0xc800, v9
	s_addc_u32 s62, s38, 0
	s_lshl_b64 s[4:5], s[0:1], 15
	s_waitcnt vmcnt(15)
	ds_write2_b32 v7, v48, v49 offset1:1
	ds_write2_b32 v11, v50, v51 offset1:1
	s_waitcnt vmcnt(14)
	ds_write2_b32 v13, v52, v53 offset1:1
	ds_write2_b32 v15, v54, v55 offset1:1
	s_waitcnt vmcnt(13)
	ds_write2_b32 v17, v56, v57 offset1:1
	ds_write2_b32 v19, v58, v59 offset1:1
	s_waitcnt vmcnt(12)
	ds_write2_b32 v32, v60, v61 offset1:1
	ds_write2_b32 v33, v62, v63 offset1:1
	s_waitcnt vmcnt(11)
	ds_write2_b32 v34, v64, v65 offset1:1
	ds_write2_b32 v36, v66, v67 offset1:1
	s_waitcnt vmcnt(10)
	ds_write2_b32 v37, v68, v69 offset1:1
	ds_write2_b32 v38, v70, v71 offset1:1
	s_waitcnt vmcnt(9)
	ds_write2_b32 v39, v72, v73 offset1:1
	ds_write2_b32 v40, v74, v75 offset1:1
	s_waitcnt vmcnt(8)
	ds_write2_b32 v41, v76, v77 offset1:1
	ds_write2_b32 v42, v78, v79 offset1:1
	s_waitcnt vmcnt(7)
	ds_write2_b32 v43, v80, v81 offset1:1
	ds_write2_b32 v44, v82, v83 offset1:1
	s_waitcnt vmcnt(6)
	ds_write2_b32 v45, v84, v85 offset1:1
	ds_write2_b32 v46, v86, v87 offset1:1
	s_add_u32 s4, s33, s4
	s_waitcnt vmcnt(5)
	ds_write2_b32 v0, v88, v89 offset1:1
	v_add_u32_e32 v0, 0xf0a8, v5
	ds_write2_b32 v0, v90, v91 offset1:1
	v_add_u32_e32 v0, 0xf4b0, v5
	s_waitcnt vmcnt(4)
	ds_write2_b32 v0, v92, v93 offset1:1
	v_add_u32_e32 v0, 0xf4b8, v5
	ds_write2_b32 v0, v94, v95 offset1:1
	v_add_u32_e32 v0, 0xf8c0, v5
	s_waitcnt vmcnt(3)
	ds_write2_b32 v0, v96, v97 offset1:1
	v_add_u32_e32 v0, 0xf8c8, v5
	ds_write2_b32 v0, v98, v99 offset1:1
	v_add_u32_e32 v0, 0xfcd0, v5
	v_add_u32_e32 v47, 0xcc00, v9
	s_waitcnt vmcnt(2)
; #define LAS __attribute__((address_space(3)))
; __device__ __forceinline__ unsigned cvt_pk_bf16(float lo, float hi) { unsigned r; asm volatile("v_cvt_pk_bf16_f32 %0, %1, %2" : "=v"(r) : "v"(lo), "v"(hi)); return r; }
; #define LDS_WAIT() asm volatile("s_waitcnt lgkmcnt(0)" ::: "memory")
; __device__ __forceinline__ void transpose_item(const float* W, int N, bf16_t* WT, int nkt, int k0, int n0, int r0, int kbd, LAS float* scr, int lane) {
;     ...
;     for (int i = 0; i < 16; ++i) { LAS float* d = scr + (4 * i + lq) * 65 + 4 * l15; d[0] = v[i][0]; d[1] = v[i][1]; d[2] = v[i][2]; d[3] = v[i][3]; }
;     LDS_WAIT();
;     const int c = lane & 7;
; #pragma unroll
;     for (int j = 0; j < 8; ++j) { const int n = (lane >> 3) + 8 * j; const LAS float* s = scr + (8 * c) * 65 + n;
;         u32x4 o; o.x = cvt_pk_bf16(s[0], s[65]); o.y = cvt_pk_bf16(s[2 * 65], s[3 * 65]); o.z = cvt_pk_bf16(s[4 * 65], s[5 * 65]); o.w = cvt_pk_bf16(s[6 * 65], s[7 * 65]);
;         *(u32x4*)(WT + dst_off + (size_t)n * 64 + 8 * c) = o; }
;     LDS_WAIT();
	ds_write2_b32 v0, v100, v101 offset1:1
	v_add_u32_e32 v0, 0xfcd8, v5
	ds_write2_b32 v0, v102, v103 offset1:1
	v_add_u32_e32 v0, 0x38e0, v7
	s_waitcnt vmcnt(1)
	ds_write2_b32 v0, v104, v105 offset1:1
	v_add_u32_e32 v0, 0x38e8, v7
	ds_write2_b32 v0, v106, v107 offset1:1
	v_add_u32_e32 v0, 0x3cf0, v7
	s_waitcnt vmcnt(0)
	ds_write2_b32 v0, v108, v109 offset1:1
	v_add_u32_e32 v0, 0x3cf8, v7
	ds_write2_b32 v0, v110, v111 offset1:1
	s_waitcnt lgkmcnt(0)
	ds_read2_b32 v[48:49], v31 offset1:65
	s_waitcnt lgkmcnt(0)
	v_cvt_pk_bf16_f32 v48, v48, v49
	ds_read2_b32 v[50:51], v31 offset0:130 offset1:195
	s_addc_u32 s5, s62, s5
	v_lshlrev_b32_e32 v0, 1, v2
	s_waitcnt lgkmcnt(0)
	v_cvt_pk_bf16_f32 v49, v50, v51
	ds_read2_b32 v[50:51], v47 offset0:4 offset1:69
	v_lshl_add_u64 v[54:55], s[4:5], 0, v[0:1]
	v_lshlrev_b32_e32 v0, 1, v4
	s_waitcnt lgkmcnt(0)
	v_cvt_pk_bf16_f32 v50, v50, v51
	ds_read2_b32 v[52:53], v47 offset0:134 offset1:199
	s_waitcnt lgkmcnt(0)
	v_cvt_pk_bf16_f32 v51, v52, v53
	v_lshl_add_u64 v[56:57], v[54:55], 0, v[0:1]
	ds_read2_b32 v[52:53], v31 offset0:8 offset1:73
	global_store_dwordx4 v[56:57], v[48:51], off nt
	v_lshlrev_b32_e32 v0, 1, v6
	v_lshl_add_u64 v[56:57], v[54:55], 0, v[0:1]
	s_waitcnt lgkmcnt(0)
	v_cvt_pk_bf16_f32 v48, v52, v53
	ds_read2_b32 v[50:51], v31 offset0:138 offset1:203
	s_waitcnt lgkmcnt(0)
	v_cvt_pk_bf16_f32 v49, v50, v51
	ds_read2_b32 v[50:51], v47 offset0:12 offset1:77
	s_waitcnt lgkmcnt(0)
	v_cvt_pk_bf16_f32 v50, v50, v51
	ds_read2_b32 v[52:53], v47 offset0:142 offset1:207
	s_waitcnt lgkmcnt(0)
	v_cvt_pk_bf16_f32 v51, v52, v53
	ds_read2_b32 v[52:53], v31 offset0:16 offset1:81
	global_store_dwordx4 v[56:57], v[48:51], off nt
	v_lshlrev_b32_e32 v0, 1, v8
	v_lshl_add_u64 v[56:57], v[54:55], 0, v[0:1]
	s_waitcnt lgkmcnt(0)
	v_cvt_pk_bf16_f32 v48, v52, v53
	ds_read2_b32 v[50:51], v31 offset0:146 offset1:211
	s_waitcnt lgkmcnt(0)
	v_cvt_pk_bf16_f32 v49, v50, v51
	ds_read2_b32 v[50:51], v47 offset0:20 offset1:85
	s_waitcnt lgkmcnt(0)
	v_cvt_pk_bf16_f32 v50, v50, v51
	ds_read2_b32 v[52:53], v47 offset0:150 offset1:215
	s_waitcnt lgkmcnt(0)
	v_cvt_pk_bf16_f32 v51, v52, v53
	ds_read2_b32 v[52:53], v31 offset0:24 offset1:89
	global_store_dwordx4 v[56:57], v[48:51], off nt
	v_lshlrev_b32_e32 v0, 1, v10
	v_lshl_add_u64 v[56:57], v[54:55], 0, v[0:1]
	s_waitcnt lgkmcnt(0)
	v_cvt_pk_bf16_f32 v48, v52, v53
	ds_read2_b32 v[50:51], v31 offset0:154 offset1:219
	s_waitcnt lgkmcnt(0)
	v_cvt_pk_bf16_f32 v49, v50, v51
	ds_read2_b32 v[50:51], v47 offset0:28 offset1:93
	s_waitcnt lgkmcnt(0)
	v_cvt_pk_bf16_f32 v50, v50, v51
	ds_read2_b32 v[52:53], v47 offset0:158 offset1:223
	s_waitcnt lgkmcnt(0)
	v_cvt_pk_bf16_f32 v51, v52, v53
	ds_read2_b32 v[52:53], v31 offset0:32 offset1:97
	global_store_dwordx4 v[56:57], v[48:51], off nt
	v_lshlrev_b32_e32 v0, 1, v12
	v_lshl_add_u64 v[56:57], v[54:55], 0, v[0:1]
	s_waitcnt lgkmcnt(0)
	v_cvt_pk_bf16_f32 v48, v52, v53
	ds_read2_b32 v[50:51], v31 offset0:162 offset1:227
	s_waitcnt lgkmcnt(0)
	v_cvt_pk_bf16_f32 v49, v50, v51
	ds_read2_b32 v[50:51], v47 offset0:36 offset1:101
	s_waitcnt lgkmcnt(0)
	v_cvt_pk_bf16_f32 v50, v50, v51
	ds_read2_b32 v[52:53], v47 offset0:166 offset1:231
	s_waitcnt lgkmcnt(0)
	v_cvt_pk_bf16_f32 v51, v52, v53
	ds_read2_b32 v[52:53], v31 offset0:40 offset1:105
	global_store_dwordx4 v[56:57], v[48:51], off nt
	v_lshlrev_b32_e32 v0, 1, v14
	v_lshl_add_u64 v[56:57], v[54:55], 0, v[0:1]
	s_waitcnt lgkmcnt(0)
	v_cvt_pk_bf16_f32 v48, v52, v53
	ds_read2_b32 v[50:51], v31 offset0:170 offset1:235
	s_waitcnt lgkmcnt(0)
	v_cvt_pk_bf16_f32 v49, v50, v51
	ds_read2_b32 v[50:51], v47 offset0:44 offset1:109
	s_waitcnt lgkmcnt(0)
	v_cvt_pk_bf16_f32 v50, v50, v51
	ds_read2_b32 v[52:53], v47 offset0:174 offset1:239
	s_waitcnt lgkmcnt(0)
	v_cvt_pk_bf16_f32 v51, v52, v53
	ds_read2_b32 v[52:53], v31 offset0:48 offset1:113
	global_store_dwordx4 v[56:57], v[48:51], off nt
	v_lshlrev_b32_e32 v0, 1, v16
	v_lshl_add_u64 v[56:57], v[54:55], 0, v[0:1]
	s_waitcnt lgkmcnt(0)
	v_cvt_pk_bf16_f32 v48, v52, v53
	ds_read2_b32 v[50:51], v31 offset0:178 offset1:243
	s_waitcnt lgkmcnt(0)
	v_cvt_pk_bf16_f32 v49, v50, v51
	ds_read2_b32 v[50:51], v47 offset0:52 offset1:117
	s_waitcnt lgkmcnt(0)
	v_cvt_pk_bf16_f32 v50, v50, v51
	ds_read2_b32 v[52:53], v47 offset0:182 offset1:247
	s_waitcnt lgkmcnt(0)
	v_cvt_pk_bf16_f32 v51, v52, v53
	ds_read2_b32 v[52:53], v31 offset0:56 offset1:121
	global_store_dwordx4 v[56:57], v[48:51], off nt
	v_lshlrev_b32_e32 v0, 1, v18
	s_waitcnt lgkmcnt(0)
	v_cvt_pk_bf16_f32 v48, v52, v53
	ds_read2_b32 v[50:51], v31 offset0:186 offset1:251
	s_waitcnt lgkmcnt(0)
	v_cvt_pk_bf16_f32 v49, v50, v51
	ds_read2_b32 v[50:51], v47 offset0:60 offset1:125
	s_waitcnt lgkmcnt(0)
	v_cvt_pk_bf16_f32 v50, v50, v51
	ds_read2_b32 v[52:53], v47 offset0:190 offset1:255
	s_waitcnt lgkmcnt(0)
	v_cvt_pk_bf16_f32 v51, v52, v53
	v_lshl_add_u64 v[52:53], v[54:55], 0, v[0:1]
	global_store_dwordx4 v[52:53], v[48:51], off nt
	s_waitcnt lgkmcnt(0)

; #define LAS __attribute__((address_space(3)))
; __device__ __forceinline__ void transpose_item(const float* W, int N, bf16_t* WT, int nkt, int k0, int n0, int r0, int kbd, LAS float* scr, int lane) {
;     const size_t dst_off = ((size_t)(r0 >> 8) * nkt + kbd) * 16384 + (size_t)(r0 & 255) * 64;
;     const int l15 = lane & 15, lq = lane >> 4;
;     f32x4 v[16];
; #pragma unroll
;     for (int i = 0; i < 16; ++i) v[i] = *(const f32x4*)(W + (size_t)(k0 + 4 * i + lq) * N + n0 + 4 * l15);
; #pragma unroll
;     for (int i = 0; i < 16; ++i) { LAS float* d = scr + (4 * i + lq) * 65 + 4 * l15; d[0] = v[i][0]; d[1] = v[i][1]; d[2] = v[i][2]; d[3] = v[i][3]; }
; __device__ __forceinline__ void phase_convert_late(const Params& p, LAS float* scr, int cw, int NCW, int lane) {
;     ...
;         if (r < I6) { const int nb = r % 344, kb = r / 344; const int n0 = nb * 64; const int nn = n0 < FF ? n0 : n0 - FF; const int r0 = (nn >> 7) * 256 + (n0 < FF ? 0 : 128) + (nn & 127);
;             transpose_item(p.in[21], FF2, (bf16_t*)(ws + WS_W_UP), 64, kb * 64, n0, r0, kb, scr, lane); continue; } r -= I6;
.LBB0_332:
	s_andn2_b64 vcc, exec, s[4:5]
	s_cbranch_vccnz .LBB0_313
	s_mul_hi_i32 s0, s35, 0x2fa0be83
	s_lshr_b32 s4, s0, 31
	s_ashr_i32 s0, s0, 6
	s_add_i32 s4, s0, s4
	s_mul_i32 s5, s4, 0xffffaa00
	s_mul_i32 s0, s4, 0xfffffea8
	s_add_i32 s62, s16, s5
	s_add_i32 s0, s35, s0
	s_add_i32 s5, s62, 0xffffd500
	s_cmpk_lt_i32 s0, 0xac
	s_cselect_b32 s0, s62, s5
	s_cselect_b32 s5, 0, 0xac
	v_lshl_or_b32 v0, s4, 6, v3
	s_ashr_i32 s63, s62, 31
	v_lshl_add_u64 v[108:109], s[62:63], 2, v[28:29]
	v_or_b32_e32 v31, 4, v0
	v_mad_i64_i32 v[52:53], s[62:63], v31, s78, v[108:109]
	v_or_b32_e32 v31, 8, v0
	v_mad_i64_i32 v[56:57], s[62:63], v31, s78, v[108:109]
	v_or_b32_e32 v31, 12, v0
	v_mad_i64_i32 v[60:61], s[62:63], v31, s78, v[108:109]
	v_or_b32_e32 v31, 16, v0
	v_mad_i64_i32 v[64:65], s[62:63], v31, s78, v[108:109]
	v_or_b32_e32 v31, 20, v0
	v_mad_i64_i32 v[68:69], s[62:63], v31, s78, v[108:109]
	v_or_b32_e32 v31, 24, v0
	v_mad_i64_i32 v[72:73], s[62:63], v31, s78, v[108:109]
	v_or_b32_e32 v31, 28, v0
	v_mad_i64_i32 v[76:77], s[62:63], v31, s78, v[108:109]
	v_or_b32_e32 v31, 32, v0
	v_mad_i64_i32 v[80:81], s[62:63], v31, s78, v[108:109]
	v_or_b32_e32 v31, 36, v0
	v_mad_i64_i32 v[84:85], s[62:63], v31, s78, v[108:109]
	v_or_b32_e32 v31, 40, v0
	v_mad_i64_i32 v[48:49], s[62:63], v0, s78, v[108:109]
	v_mad_i64_i32 v[88:89], s[62:63], v31, s78, v[108:109]
	global_load_dwordx4 v[48:51], v[48:49], off nt
	s_nop 0
	global_load_dwordx4 v[52:55], v[52:53], off nt
	s_nop 0
	global_load_dwordx4 v[56:59], v[56:57], off nt
	s_nop 0
	global_load_dwordx4 v[60:63], v[60:61], off nt
	s_nop 0
	global_load_dwordx4 v[64:67], v[64:65], off nt
	s_nop 0
	global_load_dwordx4 v[68:71], v[68:69], off nt
	s_nop 0
	global_load_dwordx4 v[72:75], v[72:73], off nt
	s_nop 0
	global_load_dwordx4 v[76:79], v[76:77], off nt
	s_nop 0
	global_load_dwordx4 v[80:83], v[80:81], off nt
	s_nop 0
	global_load_dwordx4 v[84:87], v[84:85], off nt
	v_or_b32_e32 v31, 44, v0
	global_load_dwordx4 v[88:91], v[88:89], off nt
	v_mad_i64_i32 v[92:93], s[62:63], v31, s78, v[108:109]
	global_load_dwordx4 v[92:95], v[92:93], off nt
	v_or_b32_e32 v31, 48, v0
	v_mad_i64_i32 v[96:97], s[62:63], v31, s78, v[108:109]
	global_load_dwordx4 v[96:99], v[96:97], off nt
	v_or_b32_e32 v31, 52, v0
	v_mad_i64_i32 v[100:101], s[62:63], v31, s78, v[108:109]
	global_load_dwordx4 v[100:103], v[100:101], off nt
	v_or_b32_e32 v31, 56, v0
	v_mad_i64_i32 v[104:105], s[62:63], v31, s78, v[108:109]
	global_load_dwordx4 v[104:107], v[104:105], off nt
	v_or_b32_e32 v0, 60, v0
	v_mad_i64_i32 v[108:109], s[62:63], v0, s78, v[108:109]
	global_load_dwordx4 v[108:111], v[108:109], off nt
	v_add_u32_e32 v0, 0xf0a0, v5
	s_and_b32 s33, s0, 64
	s_or_b32 s33, s33, s5
	s_ashr_i32 s62, s0, 7
	s_lshl_b32 s0, s33, 7
	s_ashr_i32 s5, s4, 31
	s_ashr_i32 s63, s62, 31
	s_and_b32 s0, s0, 0x6000
	s_add_u32 s0, s39, s0
	s_addc_u32 s33, s41, 0
	s_lshl_b64 s[62:63], s[62:63], 21
	s_lshl_b64 s[4:5], s[4:5], 15
	s_add_u32 s0, s0, s62
	v_add_u32_e32 v31, 0xc800, v9
	s_addc_u32 s33, s33, s63
	s_add_u32 s4, s0, s4
	v_add_u32_e32 v47, 0xcc00, v9
	s_addc_u32 s5, s33, s5
	s_waitcnt vmcnt(15)
	ds_write2_b32 v7, v48, v49 offset1:1
	ds_write2_b32 v11, v50, v51 offset1:1
	s_waitcnt vmcnt(14)
	ds_write2_b32 v13, v52, v53 offset1:1
	ds_write2_b32 v15, v54, v55 offset1:1
	s_waitcnt vmcnt(13)
	ds_write2_b32 v17, v56, v57 offset1:1
	ds_write2_b32 v19, v58, v59 offset1:1
	s_waitcnt vmcnt(12)
	ds_write2_b32 v32, v60, v61 offset1:1
	ds_write2_b32 v33, v62, v63 offset1:1
	s_waitcnt vmcnt(11)
	ds_write2_b32 v34, v64, v65 offset1:1
	ds_write2_b32 v36, v66, v67 offset1:1
	s_waitcnt vmcnt(10)
	ds_write2_b32 v37, v68, v69 offset1:1
	ds_write2_b32 v38, v70, v71 offset1:1
	s_waitcnt vmcnt(9)
	ds_write2_b32 v39, v72, v73 offset1:1
	ds_write2_b32 v40, v74, v75 offset1:1
	s_waitcnt vmcnt(8)
	ds_write2_b32 v41, v76, v77 offset1:1
	ds_write2_b32 v42, v78, v79 offset1:1
	s_waitcnt vmcnt(7)
	ds_write2_b32 v43, v80, v81 offset1:1
	ds_write2_b32 v44, v82, v83 offset1:1
	s_waitcnt vmcnt(6)
	ds_write2_b32 v45, v84, v85 offset1:1
	ds_write2_b32 v46, v86, v87 offset1:1
	s_waitcnt vmcnt(5)
	ds_write2_b32 v0, v88, v89 offset1:1
	v_add_u32_e32 v0, 0xf0a8, v5
	ds_write2_b32 v0, v90, v91 offset1:1
	v_add_u32_e32 v0, 0xf4b0, v5
	s_waitcnt vmcnt(4)
	ds_write2_b32 v0, v92, v93 offset1:1
	v_add_u32_e32 v0, 0xf4b8, v5
	ds_write2_b32 v0, v94, v95 offset1:1
	v_add_u32_e32 v0, 0xf8c0, v5
	s_waitcnt vmcnt(3)
	ds_write2_b32 v0, v96, v97 offset1:1
	v_add_u32_e32 v0, 0xf8c8, v5
	ds_write2_b32 v0, v98, v99 offset1:1
	v_add_u32_e32 v0, 0xfcd0, v5
	s_waitcnt vmcnt(2)
	ds_write2_b32 v0, v100, v101 offset1:1
	v_add_u32_e32 v0, 0xfcd8, v5
	ds_write2_b32 v0, v102, v103 offset1:1
	v_add_u32_e32 v0, 0x38e0, v7
	s_waitcnt vmcnt(1)
; #define LAS __attribute__((address_space(3)))
; __device__ __forceinline__ unsigned cvt_pk_bf16(float lo, float hi) { unsigned r; asm volatile("v_cvt_pk_bf16_f32 %0, %1, %2" : "=v"(r) : "v"(lo), "v"(hi)); return r; }
; #define LDS_WAIT() asm volatile("s_waitcnt lgkmcnt(0)" ::: "memory")
; __device__ __forceinline__ void transpose_item(const float* W, int N, bf16_t* WT, int nkt, int k0, int n0, int r0, int kbd, LAS float* scr, int lane) {
;     ...
;     for (int i = 0; i < 16; ++i) { LAS float* d = scr + (4 * i + lq) * 65 + 4 * l15; d[0] = v[i][0]; d[1] = v[i][1]; d[2] = v[i][2]; d[3] = v[i][3]; }
;     LDS_WAIT();
;     const int c = lane & 7;
; #pragma unroll
;     for (int j = 0; j < 8; ++j) { const int n = (lane >> 3) + 8 * j; const LAS float* s = scr + (8 * c) * 65 + n;
;         u32x4 o; o.x = cvt_pk_bf16(s[0], s[65]); o.y = cvt_pk_bf16(s[2 * 65], s[3 * 65]); o.z = cvt_pk_bf16(s[4 * 65], s[5 * 65]); o.w = cvt_pk_bf16(s[6 * 65], s[7 * 65]);
;         *(u32x4*)(WT + dst_off + (size_t)n * 64 + 8 * c) = o; }
;     LDS_WAIT();
	ds_write2_b32 v0, v104, v105 offset1:1
	v_add_u32_e32 v0, 0x38e8, v7
	ds_write2_b32 v0, v106, v107 offset1:1
	v_add_u32_e32 v0, 0x3cf0, v7
	s_waitcnt vmcnt(0)
	ds_write2_b32 v0, v108, v109 offset1:1
	v_add_u32_e32 v0, 0x3cf8, v7
	ds_write2_b32 v0, v110, v111 offset1:1
	s_waitcnt lgkmcnt(0)
	ds_read2_b32 v[48:49], v31 offset1:65
	s_waitcnt lgkmcnt(0)
	v_cvt_pk_bf16_f32 v48, v48, v49
	ds_read2_b32 v[50:51], v31 offset0:130 offset1:195
	v_lshlrev_b32_e32 v0, 1, v2
	s_waitcnt lgkmcnt(0)
	v_cvt_pk_bf16_f32 v49, v50, v51
	ds_read2_b32 v[50:51], v47 offset0:4 offset1:69
	v_lshl_add_u64 v[54:55], s[4:5], 0, v[0:1]
	v_lshlrev_b32_e32 v0, 1, v4
	s_waitcnt lgkmcnt(0)
	v_cvt_pk_bf16_f32 v50, v50, v51
	ds_read2_b32 v[52:53], v47 offset0:134 offset1:199
	s_waitcnt lgkmcnt(0)
	v_cvt_pk_bf16_f32 v51, v52, v53
	v_lshl_add_u64 v[56:57], v[54:55], 0, v[0:1]
	ds_read2_b32 v[52:53], v31 offset0:8 offset1:73
	global_store_dwordx4 v[56:57], v[48:51], off nt
	v_lshlrev_b32_e32 v0, 1, v6
	v_lshl_add_u64 v[56:57], v[54:55], 0, v[0:1]
	s_waitcnt lgkmcnt(0)
	v_cvt_pk_bf16_f32 v48, v52, v53
	ds_read2_b32 v[50:51], v31 offset0:138 offset1:203
	s_waitcnt lgkmcnt(0)
	v_cvt_pk_bf16_f32 v49, v50, v51
	ds_read2_b32 v[50:51], v47 offset0:12 offset1:77
	s_waitcnt lgkmcnt(0)
	v_cvt_pk_bf16_f32 v50, v50, v51
	ds_read2_b32 v[52:53], v47 offset0:142 offset1:207
	s_waitcnt lgkmcnt(0)
	v_cvt_pk_bf16_f32 v51, v52, v53
	ds_read2_b32 v[52:53], v31 offset0:16 offset1:81
	global_store_dwordx4 v[56:57], v[48:51], off nt
	v_lshlrev_b32_e32 v0, 1, v8
	v_lshl_add_u64 v[56:57], v[54:55], 0, v[0:1]
	s_waitcnt lgkmcnt(0)
	v_cvt_pk_bf16_f32 v48, v52, v53
	ds_read2_b32 v[50:51], v31 offset0:146 offset1:211
	s_waitcnt lgkmcnt(0)
	v_cvt_pk_bf16_f32 v49, v50, v51
	ds_read2_b32 v[50:51], v47 offset0:20 offset1:85
	s_waitcnt lgkmcnt(0)
	v_cvt_pk_bf16_f32 v50, v50, v51
	ds_read2_b32 v[52:53], v47 offset0:150 offset1:215
	s_waitcnt lgkmcnt(0)
	v_cvt_pk_bf16_f32 v51, v52, v53
	ds_read2_b32 v[52:53], v31 offset0:24 offset1:89
	global_store_dwordx4 v[56:57], v[48:51], off nt
	v_lshlrev_b32_e32 v0, 1, v10
	v_lshl_add_u64 v[56:57], v[54:55], 0, v[0:1]
	s_waitcnt lgkmcnt(0)
	v_cvt_pk_bf16_f32 v48, v52, v53
	ds_read2_b32 v[50:51], v31 offset0:154 offset1:219
	s_waitcnt lgkmcnt(0)
	v_cvt_pk_bf16_f32 v49, v50, v51
	ds_read2_b32 v[50:51], v47 offset0:28 offset1:93
	s_waitcnt lgkmcnt(0)
	v_cvt_pk_bf16_f32 v50, v50, v51
	ds_read2_b32 v[52:53], v47 offset0:158 offset1:223
	s_waitcnt lgkmcnt(0)
	v_cvt_pk_bf16_f32 v51, v52, v53
	ds_read2_b32 v[52:53], v31 offset0:32 offset1:97
	global_store_dwordx4 v[56:57], v[48:51], off nt
	v_lshlrev_b32_e32 v0, 1, v12
	v_lshl_add_u64 v[56:57], v[54:55], 0, v[0:1]
	s_waitcnt lgkmcnt(0)
	v_cvt_pk_bf16_f32 v48, v52, v53
	ds_read2_b32 v[50:51], v31 offset0:162 offset1:227
	s_waitcnt lgkmcnt(0)
	v_cvt_pk_bf16_f32 v49, v50, v51
	ds_read2_b32 v[50:51], v47 offset0:36 offset1:101
	s_waitcnt lgkmcnt(0)
	v_cvt_pk_bf16_f32 v50, v50, v51
	ds_read2_b32 v[52:53], v47 offset0:166 offset1:231
	s_waitcnt lgkmcnt(0)
	v_cvt_pk_bf16_f32 v51, v52, v53
	ds_read2_b32 v[52:53], v31 offset0:40 offset1:105
	global_store_dwordx4 v[56:57], v[48:51], off nt
	v_lshlrev_b32_e32 v0, 1, v14
	v_lshl_add_u64 v[56:57], v[54:55], 0, v[0:1]
	s_waitcnt lgkmcnt(0)
	v_cvt_pk_bf16_f32 v48, v52, v53
	ds_read2_b32 v[50:51], v31 offset0:170 offset1:235
	s_waitcnt lgkmcnt(0)
	v_cvt_pk_bf16_f32 v49, v50, v51
	ds_read2_b32 v[50:51], v47 offset0:44 offset1:109
	s_waitcnt lgkmcnt(0)
	v_cvt_pk_bf16_f32 v50, v50, v51
	ds_read2_b32 v[52:53], v47 offset0:174 offset1:239
	s_waitcnt lgkmcnt(0)
	v_cvt_pk_bf16_f32 v51, v52, v53
	ds_read2_b32 v[52:53], v31 offset0:48 offset1:113
	global_store_dwordx4 v[56:57], v[48:51], off nt
	v_lshlrev_b32_e32 v0, 1, v16
	v_lshl_add_u64 v[56:57], v[54:55], 0, v[0:1]
	s_waitcnt lgkmcnt(0)
	v_cvt_pk_bf16_f32 v48, v52, v53
	ds_read2_b32 v[50:51], v31 offset0:178 offset1:243
	s_waitcnt lgkmcnt(0)
	v_cvt_pk_bf16_f32 v49, v50, v51
	ds_read2_b32 v[50:51], v47 offset0:52 offset1:117
	s_waitcnt lgkmcnt(0)
	v_cvt_pk_bf16_f32 v50, v50, v51
	ds_read2_b32 v[52:53], v47 offset0:182 offset1:247
	s_waitcnt lgkmcnt(0)
	v_cvt_pk_bf16_f32 v51, v52, v53
	ds_read2_b32 v[52:53], v31 offset0:56 offset1:121
	global_store_dwordx4 v[56:57], v[48:51], off nt
	v_lshlrev_b32_e32 v0, 1, v18
	s_waitcnt lgkmcnt(0)
	v_cvt_pk_bf16_f32 v48, v52, v53
	ds_read2_b32 v[50:51], v31 offset0:186 offset1:251
	s_waitcnt lgkmcnt(0)
	v_cvt_pk_bf16_f32 v49, v50, v51
	ds_read2_b32 v[50:51], v47 offset0:60 offset1:125
	s_waitcnt lgkmcnt(0)
	v_cvt_pk_bf16_f32 v50, v50, v51
	ds_read2_b32 v[52:53], v47 offset0:190 offset1:255
	s_waitcnt lgkmcnt(0)
	v_cvt_pk_bf16_f32 v51, v52, v53
	v_lshl_add_u64 v[52:53], v[54:55], 0, v[0:1]
	global_store_dwordx4 v[52:53], v[48:51], off nt
	s_waitcnt lgkmcnt(0)
	s_branch .LBB0_313

; __device__ __forceinline__ float sigm(float x) { return __builtin_amdgcn_rcpf(1.f + __builtin_amdgcn_exp2f(-1.4426950409f * x)); }
; __device__ __forceinline__ u32x4 pack8(const f32x4 v0, const f32x4 v1) { u32x4 w; w.x = cvt_pk_bf16(v0[0], v0[1]); w.y = cvt_pk_bf16(v0[2], v0[3]); w.z = cvt_pk_bf16(v1[0], v1[1]); w.w = cvt_pk_bf16(v1[2], v1[3]); return w; }
; __device__ __forceinline__ void unpack8(const u32x4 w, f32x4& lo, f32x4& hi) { lo = (f32x4){bf_lo(w.x), bf_hi(w.x), bf_lo(w.y), bf_hi(w.y)}; hi = (f32x4){bf_lo(w.z), bf_hi(w.z), bf_lo(w.w), bf_hi(w.w)}; }
;     __device__ __forceinline__ void operator()(AccT& acc, const Unit& u, int wr, int wc, int fr, int fq) const {
;         const int row0 = u.pm * 256 + wr * 64 + fr, col0 = u.pn * 256 + wc * 32 + 8 * fq;
;         if (u.kind == 0) {
; #pragma unroll
;             for (int bj = 0; bj < 2; ++bj) { const f32x4 b0 = *(const f32x4*)(glu_b + col0 + bj * 128), b1 = *(const f32x4*)(glu_b + col0 + bj * 128 + 4);
; #pragma unroll
;                 for (int ai = 0; ai < 2; ++ai)
; #pragma unroll
;                     for (int m = 0; m < 4; ++m) { const size_t off = (size_t)(row0 + ai * 128 + m * 16) * DSS + col0 + bj * 128;
;                         f32x4 y0, y1; unpack8(*(const u32x4*)(YG + off), y0, y1);
;                         f32x4 v0 = acc[ai][bj][m][0] + b0, v1 = acc[ai][bj][m][1] + b1;
; #pragma unroll
;                         for (int j = 0; j < 4; ++j) { v0[j] = y0[j] * sigm(v0[j]); v1[j] = y1[j] * sigm(v1[j]); }
;                         *(u32x4*)(YS + off) = pack8(v0, v1); } }
;         } else {
; #pragma unroll
;             for (int bj = 0; bj < 2; ++bj) { const f32x4 b0 = *(const f32x4*)(pool_b + col0 + bj * 128), b1 = *(const f32x4*)(pool_b + col0 + bj * 128 + 4);
;                 const f32x4 s0 = *(const f32x4*)(pool_scale + col0 + bj * 128), s1 = *(const f32x4*)(pool_scale + col0 + bj * 128 + 4);
; #pragma unroll
;                 for (int ai = 0; ai < 2; ++ai)
; #pragma unroll
;                     for (int m = 0; m < 4; ++m) { const size_t off = (size_t)(row0 + ai * 128 + m * 16) * DSS + col0 + bj * 128;
;                         *(u32x4*)(ZP + off) = pack8((acc[ai][bj][m][0] + b0) * s0, (acc[ai][bj][m][1] + b1) * s1); } }
.LBB0_411:
	v_mov_b32_e32 v104, v254
	s_lshl_b32 s4, s8, 8
	s_add_i32 s4, s4, s84
	v_and_or_b32 v150, v104, 15, s4
	s_lshl_b32 s3, s3, 8
	v_lshrrev_b32_e32 v104, 1, v104
	v_and_or_b32 v104, v104, 24, s3
	v_or_b32_e32 v148, s85, v104
	v_or_b32_e32 v156, 16, v150
	v_or_b32_e32 v154, 32, v150
	v_or_b32_e32 v152, 48, v150
	s_cmp_eq_u32 s33, 0
	v_ashrrev_i32_e32 v149, 31, v148
	v_ashrrev_i32_e32 v151, 31, v150
	v_ashrrev_i32_e32 v157, 31, v156
	v_ashrrev_i32_e32 v155, 31, v154
	v_ashrrev_i32_e32 v153, 31, v152
	s_cbranch_scc1 .LBB0_417
	v_lshlrev_b64 v[136:137], 2, v[148:149]
	v_lshl_add_u64 v[158:159], s[48:49], 0, v[136:137]
	global_load_dwordx4 v[108:111], v[158:159], off
	global_load_dwordx4 v[104:107], v[158:159], off offset:16
	v_lshl_add_u64 v[160:161], s[50:51], 0, v[136:137]
	global_load_dwordx4 v[140:143], v[160:161], off
	global_load_dwordx4 v[136:139], v[160:161], off offset:16
	v_lshlrev_b64 v[164:165], 12, v[150:151]
	v_lshlrev_b64 v[166:167], 12, v[156:157]
	v_lshlrev_b64 v[168:169], 12, v[154:155]
	v_lshlrev_b64 v[170:171], 12, v[152:153]
	v_lshlrev_b64 v[162:163], 1, v[148:149]
	v_lshl_add_u64 v[164:165], s[46:47], 0, v[164:165]
	v_lshl_add_u64 v[166:167], s[46:47], 0, v[166:167]
	v_lshl_add_u64 v[172:173], s[46:47], 0, v[168:169]
	v_lshl_add_u64 v[170:171], s[46:47], 0, v[170:171]
	v_lshl_add_u64 v[168:169], v[164:165], 0, v[162:163]
	v_lshl_add_u64 v[166:167], v[166:167], 0, v[162:163]
	v_lshl_add_u64 v[164:165], v[172:173], 0, v[162:163]
	v_lshl_add_u64 v[162:163], v[170:171], 0, v[162:163]
	s_mov_b32 s3, 0x80000
	v_add_co_u32_e32 v174, vcc, s3, v168
	s_mov_b32 s3, 0x90000
	s_nop 0
	v_addc_co_u32_e32 v175, vcc, 0, v169, vcc
	s_mov_b64 s[4:5], 0x80000
	s_mov_b64 s[8:9], 0x90000
	s_mov_b64 s[16:17], 0xa0000
	s_mov_b64 s[18:19], 0xb0000
	s_waitcnt vmcnt(3)
	v_pk_add_f32 v[170:171], v[134:135], v[110:111]
	v_pk_add_f32 v[172:173], v[132:133], v[108:109]
	s_waitcnt vmcnt(2)
	v_pk_add_f32 v[188:189], v[128:129], v[104:105]
	v_pk_add_f32 v[186:187], v[130:131], v[106:107]
	s_waitcnt vmcnt(1)
	v_pk_mul_f32 v[222:223], v[170:171], v[142:143]
	v_pk_mul_f32 v[170:171], v[172:173], v[140:141]
	s_waitcnt vmcnt(0)
	v_pk_mul_f32 v[172:173], v[188:189], v[136:137]
	v_pk_add_f32 v[190:191], v[126:127], v[110:111]
	v_pk_add_f32 v[192:193], v[124:125], v[108:109]
	v_pk_add_f32 v[194:195], v[122:123], v[106:107]
	v_pk_add_f32 v[196:197], v[120:121], v[104:105]
	v_pk_mul_f32 v[186:187], v[186:187], v[138:139]
	v_cvt_pk_bf16_f32 v170, v170, v171
	v_cvt_pk_bf16_f32 v171, v222, v223
	v_cvt_pk_bf16_f32 v172, v172, v173
	v_pk_add_f32 v[198:199], v[118:119], v[110:111]
	v_cvt_pk_bf16_f32 v173, v186, v187
	v_pk_add_f32 v[200:201], v[116:117], v[108:109]
	v_pk_add_f32 v[202:203], v[114:115], v[106:107]
	v_pk_add_f32 v[204:205], v[112:113], v[104:105]
	v_pk_mul_f32 v[188:189], v[190:191], v[142:143]
	v_pk_mul_f32 v[190:191], v[192:193], v[140:141]
	v_pk_mul_f32 v[192:193], v[194:195], v[138:139]
	v_pk_mul_f32 v[194:195], v[196:197], v[136:137]
	global_store_dwordx4 v[168:169], v[170:173], off nt
	v_pk_add_f32 v[206:207], v[102:103], v[110:111]
	v_pk_add_f32 v[208:209], v[100:101], v[108:109]
	v_cvt_pk_bf16_f32 v170, v190, v191
	v_cvt_pk_bf16_f32 v171, v188, v189
	v_cvt_pk_bf16_f32 v172, v194, v195
	v_cvt_pk_bf16_f32 v173, v192, v193
	v_pk_add_f32 v[210:211], v[98:99], v[106:107]
	v_pk_add_f32 v[212:213], v[96:97], v[104:105]
	v_pk_mul_f32 v[196:197], v[198:199], v[142:143]
	v_pk_mul_f32 v[198:199], v[200:201], v[140:141]
	v_pk_mul_f32 v[200:201], v[202:203], v[138:139]
	v_pk_mul_f32 v[202:203], v[204:205], v[136:137]
	global_store_dwordx4 v[166:167], v[170:173], off nt
	v_pk_add_f32 v[214:215], v[94:95], v[110:111]
	v_pk_add_f32 v[216:217], v[92:93], v[108:109]
	v_cvt_pk_bf16_f32 v170, v198, v199
	v_cvt_pk_bf16_f32 v171, v196, v197
	v_cvt_pk_bf16_f32 v172, v202, v203
	v_cvt_pk_bf16_f32 v173, v200, v201
	v_pk_add_f32 v[218:219], v[90:91], v[106:107]
	v_pk_add_f32 v[220:221], v[88:89], v[104:105]
	v_pk_mul_f32 v[204:205], v[206:207], v[142:143]
	v_pk_mul_f32 v[206:207], v[208:209], v[140:141]
	v_pk_mul_f32 v[208:209], v[210:211], v[138:139]
	v_pk_mul_f32 v[210:211], v[212:213], v[136:137]
	global_store_dwordx4 v[164:165], v[170:173], off nt
	v_pk_mul_f32 v[212:213], v[214:215], v[142:143]
	v_pk_mul_f32 v[214:215], v[216:217], v[140:141]
	v_cvt_pk_bf16_f32 v170, v206, v207
	v_cvt_pk_bf16_f32 v171, v204, v205
	v_cvt_pk_bf16_f32 v172, v210, v211
	v_cvt_pk_bf16_f32 v173, v208, v209
	v_pk_mul_f32 v[216:217], v[218:219], v[138:139]
	v_pk_mul_f32 v[218:219], v[220:221], v[136:137]
	global_store_dwordx4 v[162:163], v[170:173], off nt
	v_pk_add_f32 v[186:187], v[80:81], v[104:105]
	s_nop 0
	v_cvt_pk_bf16_f32 v170, v214, v215
	v_cvt_pk_bf16_f32 v171, v212, v213
	v_cvt_pk_bf16_f32 v172, v218, v219
	v_cvt_pk_bf16_f32 v173, v216, v217
	global_store_dwordx4 v[174:175], v[170:173], off nt
	s_nop 1
	v_pk_add_f32 v[170:171], v[86:87], v[110:111]
	v_pk_add_f32 v[172:173], v[84:85], v[108:109]
	v_pk_mul_f32 v[174:175], v[170:171], v[142:143]
	v_pk_mul_f32 v[170:171], v[172:173], v[140:141]
	v_pk_add_f32 v[172:173], v[82:83], v[106:107]
	v_cvt_pk_bf16_f32 v170, v170, v171
	v_cvt_pk_bf16_f32 v171, v174, v175
	v_add_co_u32_e32 v174, vcc, s3, v168
	v_pk_mul_f32 v[188:189], v[172:173], v[138:139]
	v_pk_mul_f32 v[172:173], v[186:187], v[136:137]
	v_addc_co_u32_e32 v175, vcc, 0, v169, vcc
	v_cvt_pk_bf16_f32 v172, v172, v173
	v_cvt_pk_bf16_f32 v173, v188, v189
	global_store_dwordx4 v[174:175], v[170:173], off nt
	s_mov_b32 s3, 0xa0000
	v_pk_add_f32 v[186:187], v[72:73], v[104:105]
	v_pk_add_f32 v[170:171], v[78:79], v[110:111]
	v_pk_add_f32 v[172:173], v[76:77], v[108:109]
; __device__ __forceinline__ u32x4 pack8(const f32x4 v0, const f32x4 v1) { u32x4 w; w.x = cvt_pk_bf16(v0[0], v0[1]); w.y = cvt_pk_bf16(v0[2], v0[3]); w.z = cvt_pk_bf16(v1[0], v1[1]); w.w = cvt_pk_bf16(v1[2], v1[3]); return w; }
;     __device__ __forceinline__ void operator()(AccT& acc, const Unit& u, int wr, int wc, int fr, int fq) const {
;     ...
; #pragma unroll
;             for (int bj = 0; bj < 2; ++bj) { const f32x4 b0 = *(const f32x4*)(pool_b + col0 + bj * 128), b1 = *(const f32x4*)(pool_b + col0 + bj * 128 + 4);
;                 const f32x4 s0 = *(const f32x4*)(pool_scale + col0 + bj * 128), s1 = *(const f32x4*)(pool_scale + col0 + bj * 128 + 4);
; #pragma unroll
;                 for (int ai = 0; ai < 2; ++ai)
; #pragma unroll
;                     for (int m = 0; m < 4; ++m) { const size_t off = (size_t)(row0 + ai * 128 + m * 16) * DSS + col0 + bj * 128;
;                         *(u32x4*)(ZP + off) = pack8((acc[ai][bj][m][0] + b0) * s0, (acc[ai][bj][m][1] + b1) * s1); } }
	v_pk_mul_f32 v[174:175], v[170:171], v[142:143]
	v_pk_mul_f32 v[170:171], v[172:173], v[140:141]
	v_pk_add_f32 v[172:173], v[74:75], v[106:107]
	v_cvt_pk_bf16_f32 v170, v170, v171
	v_cvt_pk_bf16_f32 v171, v174, v175
	v_add_co_u32_e32 v174, vcc, s3, v168
	v_pk_add_f32 v[108:109], v[68:69], v[108:109]
	v_pk_mul_f32 v[188:189], v[172:173], v[138:139]
	v_pk_mul_f32 v[172:173], v[186:187], v[136:137]
	v_addc_co_u32_e32 v175, vcc, 0, v169, vcc
	v_pk_mul_f32 v[108:109], v[108:109], v[140:141]
	v_pk_add_f32 v[106:107], v[66:67], v[106:107]
	v_pk_add_f32 v[104:105], v[64:65], v[104:105]
	s_mov_b32 s3, 0xb0000
	v_cvt_pk_bf16_f32 v172, v172, v173
	v_cvt_pk_bf16_f32 v173, v188, v189
	global_store_dwordx4 v[174:175], v[170:173], off nt
	v_pk_mul_f32 v[138:139], v[106:107], v[138:139]
	v_pk_mul_f32 v[106:107], v[104:105], v[136:137]
	v_cvt_pk_bf16_f32 v104, v108, v109
	v_add_co_u32_e32 v108, vcc, s3, v168
	v_pk_add_f32 v[110:111], v[70:71], v[110:111]
	s_nop 0
	v_addc_co_u32_e32 v109, vcc, 0, v169, vcc
	v_pk_mul_f32 v[110:111], v[110:111], v[142:143]
	v_lshl_add_u64 v[174:175], v[168:169], 0, s[4:5]
	v_cvt_pk_bf16_f32 v105, v110, v111
	v_cvt_pk_bf16_f32 v106, v106, v107
	v_cvt_pk_bf16_f32 v107, v138, v139
	global_store_dwordx4 v[108:109], v[104:107], off nt
	global_load_dwordx4 v[108:111], v[158:159], off offset:512
	s_nop 0
	global_load_dwordx4 v[104:107], v[158:159], off offset:528
	global_load_dwordx4 v[140:143], v[160:161], off offset:512
	global_load_dwordx4 v[136:139], v[160:161], off offset:528
	v_lshl_add_u64 v[170:171], v[168:169], 0, s[8:9]
	v_lshl_add_u64 v[160:161], v[168:169], 0, s[16:17]
	v_lshl_add_u64 v[158:159], v[168:169], 0, s[18:19]
	s_waitcnt vmcnt(3)
	v_pk_add_f32 v[186:187], v[60:61], v[108:109]
	s_waitcnt vmcnt(2)
	v_pk_add_f32 v[188:189], v[58:59], v[106:107]
	v_pk_add_f32 v[190:191], v[56:57], v[104:105]
	v_pk_add_f32 v[172:173], v[62:63], v[110:111]
	s_waitcnt vmcnt(1)
	v_pk_mul_f32 v[186:187], v[186:187], v[140:141]
	s_waitcnt vmcnt(0)
	v_pk_mul_f32 v[196:197], v[188:189], v[138:139]
	v_pk_mul_f32 v[188:189], v[190:191], v[136:137]
	v_pk_mul_f32 v[172:173], v[172:173], v[142:143]
	v_cvt_pk_bf16_f32 v186, v186, v187
	v_pk_add_f32 v[192:193], v[54:55], v[110:111]
	v_cvt_pk_bf16_f32 v187, v172, v173
	v_cvt_pk_bf16_f32 v188, v188, v189
	v_cvt_pk_bf16_f32 v189, v196, v197
	global_store_dwordx4 v[168:169], v[186:189], off offset:256 nt
	v_pk_add_f32 v[168:169], v[50:51], v[106:107]
	v_pk_add_f32 v[194:195], v[52:53], v[108:109]
	v_pk_add_f32 v[172:173], v[48:49], v[104:105]
	v_pk_mul_f32 v[168:169], v[168:169], v[138:139]
	v_pk_mul_f32 v[190:191], v[192:193], v[142:143]
	v_pk_mul_f32 v[192:193], v[194:195], v[140:141]
	v_pk_mul_f32 v[172:173], v[172:173], v[136:137]
	v_cvt_pk_bf16_f32 v186, v192, v193
	v_cvt_pk_bf16_f32 v187, v190, v191
	s_nop 0
	v_cvt_pk_bf16_f32 v188, v172, v173
	v_cvt_pk_bf16_f32 v189, v168, v169
	global_store_dwordx4 v[166:167], v[186:189], off offset:256 nt
	v_pk_add_f32 v[166:167], v[46:47], v[110:111]
	v_pk_add_f32 v[168:169], v[44:45], v[108:109]
	v_pk_mul_f32 v[172:173], v[166:167], v[142:143]
	v_pk_mul_f32 v[166:167], v[168:169], v[140:141]
	v_pk_add_f32 v[168:169], v[42:43], v[106:107]
	v_pk_add_f32 v[186:187], v[40:41], v[104:105]
	v_pk_mul_f32 v[188:189], v[168:169], v[138:139]
	v_pk_mul_f32 v[168:169], v[186:187], v[136:137]
	v_cvt_pk_bf16_f32 v166, v166, v167
	v_cvt_pk_bf16_f32 v167, v172, v173
	v_pk_add_f32 v[172:173], v[32:33], v[104:105]
	v_cvt_pk_bf16_f32 v168, v168, v169
	v_cvt_pk_bf16_f32 v169, v188, v189
	global_store_dwordx4 v[164:165], v[166:169], off offset:256 nt
	v_pk_add_f32 v[164:165], v[38:39], v[110:111]
	s_nop 0
	v_pk_add_f32 v[166:167], v[36:37], v[108:109]
	v_pk_mul_f32 v[168:169], v[164:165], v[142:143]
	v_pk_mul_f32 v[164:165], v[166:167], v[140:141]
	v_pk_add_f32 v[166:167], v[34:35], v[106:107]
	v_cvt_pk_bf16_f32 v164, v164, v165
	v_cvt_pk_bf16_f32 v165, v168, v169
	v_pk_add_f32 v[168:169], v[24:25], v[104:105]
	v_pk_mul_f32 v[186:187], v[166:167], v[138:139]
	v_pk_mul_f32 v[166:167], v[172:173], v[136:137]
	s_nop 0
	v_cvt_pk_bf16_f32 v166, v166, v167
	v_cvt_pk_bf16_f32 v167, v186, v187
	global_store_dwordx4 v[162:163], v[164:167], off offset:256 nt
	v_pk_add_f32 v[162:163], v[30:31], v[110:111]
	s_nop 0
	v_pk_add_f32 v[164:165], v[28:29], v[108:109]
	v_pk_mul_f32 v[166:167], v[162:163], v[142:143]
	v_pk_mul_f32 v[162:163], v[164:165], v[140:141]
	v_pk_add_f32 v[164:165], v[26:27], v[106:107]
	v_cvt_pk_bf16_f32 v162, v162, v163
	v_cvt_pk_bf16_f32 v163, v166, v167
	s_nop 0
	v_pk_mul_f32 v[172:173], v[164:165], v[138:139]
	v_pk_mul_f32 v[164:165], v[168:169], v[136:137]
	v_pk_add_f32 v[168:169], v[16:17], v[104:105]
	v_cvt_pk_bf16_f32 v164, v164, v165
	v_cvt_pk_bf16_f32 v165, v172, v173
	global_store_dwordx4 v[174:175], v[162:165], off offset:256 nt
	s_nop 1
	v_pk_add_f32 v[162:163], v[22:23], v[110:111]
	v_pk_add_f32 v[164:165], v[20:21], v[108:109]
	v_pk_mul_f32 v[166:167], v[162:163], v[142:143]
	v_pk_mul_f32 v[162:163], v[164:165], v[140:141]
	v_pk_add_f32 v[164:165], v[18:19], v[106:107]
	v_cvt_pk_bf16_f32 v162, v162, v163
	v_cvt_pk_bf16_f32 v163, v166, v167
	s_nop 0
	v_pk_mul_f32 v[172:173], v[164:165], v[138:139]
	v_pk_mul_f32 v[164:165], v[168:169], v[136:137]
	v_pk_add_f32 v[168:169], v[8:9], v[104:105]
	v_cvt_pk_bf16_f32 v164, v164, v165
	v_cvt_pk_bf16_f32 v165, v172, v173
	global_store_dwordx4 v[170:171], v[162:165], off offset:256 nt
	v_pk_add_f32 v[104:105], v[0:1], v[104:105]
	s_nop 0
	v_pk_add_f32 v[162:163], v[14:15], v[110:111]
	v_pk_add_f32 v[164:165], v[12:13], v[108:109]
	v_pk_mul_f32 v[166:167], v[162:163], v[142:143]
	v_pk_mul_f32 v[162:163], v[164:165], v[140:141]
	v_pk_add_f32 v[164:165], v[10:11], v[106:107]
	v_pk_add_f32 v[106:107], v[2:3], v[106:107]
	v_pk_mul_f32 v[170:171], v[164:165], v[138:139]
	v_pk_mul_f32 v[164:165], v[168:169], v[136:137]
	v_pk_add_f32 v[110:111], v[6:7], v[110:111]
	v_pk_add_f32 v[108:109], v[4:5], v[108:109]
	v_pk_mul_f32 v[138:139], v[106:107], v[138:139]
	v_pk_mul_f32 v[106:107], v[104:105], v[136:137]
	v_cvt_pk_bf16_f32 v162, v162, v163
	v_cvt_pk_bf16_f32 v163, v166, v167
	v_cvt_pk_bf16_f32 v164, v164, v165
	v_cvt_pk_bf16_f32 v165, v170, v171
	global_store_dwordx4 v[160:161], v[162:165], off offset:256 nt
	v_pk_mul_f32 v[110:111], v[110:111], v[142:143]
	v_pk_mul_f32 v[108:109], v[108:109], v[140:141]
	s_nop 0
	v_cvt_pk_bf16_f32 v104, v108, v109
	v_cvt_pk_bf16_f32 v105, v110, v111
	v_cvt_pk_bf16_f32 v106, v106, v107
	v_cvt_pk_bf16_f32 v107, v138, v139
	global_store_dwordx4 v[158:159], v[104:107], off offset:256 nt
	s_cbranch_execnz .LBB0_414
; __device__ __forceinline__ float sigm(float x) { return __builtin_amdgcn_rcpf(1.f + __builtin_amdgcn_exp2f(-1.4426950409f * x)); }
; __device__ __forceinline__ u32x4 pack8(const f32x4 v0, const f32x4 v1) { u32x4 w; w.x = cvt_pk_bf16(v0[0], v0[1]); w.y = cvt_pk_bf16(v0[2], v0[3]); w.z = cvt_pk_bf16(v1[0], v1[1]); w.w = cvt_pk_bf16(v1[2], v1[3]); return w; }
; __device__ __forceinline__ void unpack8(const u32x4 w, f32x4& lo, f32x4& hi) { lo = (f32x4){bf_lo(w.x), bf_hi(w.x), bf_lo(w.y), bf_hi(w.y)}; hi = (f32x4){bf_lo(w.z), bf_hi(w.z), bf_lo(w.w), bf_hi(w.w)}; }
;     __device__ __forceinline__ void operator()(AccT& acc, const Unit& u, int wr, int wc, int fr, int fq) const {
;     ...
;         if (u.kind == 0) {
; #pragma unroll
;             for (int bj = 0; bj < 2; ++bj) { const f32x4 b0 = *(const f32x4*)(glu_b + col0 + bj * 128), b1 = *(const f32x4*)(glu_b + col0 + bj * 128 + 4);
; #pragma unroll
;                 for (int ai = 0; ai < 2; ++ai)
; #pragma unroll
;                     for (int m = 0; m < 4; ++m) { const size_t off = (size_t)(row0 + ai * 128 + m * 16) * DSS + col0 + bj * 128;
;                         f32x4 y0, y1; unpack8(*(const u32x4*)(YG + off), y0, y1);
;                         f32x4 v0 = acc[ai][bj][m][0] + b0, v1 = acc[ai][bj][m][1] + b1;
; #pragma unroll
;                         for (int j = 0; j < 4; ++j) { v0[j] = y0[j] * sigm(v0[j]); v1[j] = y1[j] * sigm(v1[j]); }
;                         *(u32x4*)(YS + off) = pack8(v0, v1); } }
.LBB0_413:
	v_lshl_add_u64 v[140:141], v[148:149], 2, s[44:45]
	global_load_dwordx4 v[108:111], v[140:141], off
	global_load_dwordx4 v[104:107], v[140:141], off offset:16
	v_lshlrev_b64 v[150:151], 11, v[150:151]
	v_lshl_add_u64 v[136:137], v[150:151], 0, v[148:149]
	v_lshlrev_b64 v[158:159], 1, v[136:137]
	v_lshl_add_u64 v[136:137], s[14:15], 0, v[158:159]
	global_load_dwordx4 v[136:139], v[136:137], off
	v_lshlrev_b64 v[142:143], 11, v[156:157]
	v_lshl_add_u64 v[156:157], v[142:143], 0, v[148:149]
	v_lshlrev_b64 v[156:157], 1, v[156:157]
	v_lshl_add_u64 v[158:159], s[26:27], 0, v[158:159]
	v_lshl_add_u64 v[160:161], s[14:15], 0, v[156:157]
	s_mov_b64 s[4:5], 0x40000
	s_waitcnt vmcnt(2)
	v_pk_add_f32 v[134:135], v[134:135], v[110:111]
	v_pk_add_f32 v[132:133], v[132:133], v[108:109]
	s_waitcnt vmcnt(1)
	v_pk_add_f32 v[130:131], v[130:131], v[106:107]
	v_pk_add_f32 v[128:129], v[128:129], v[104:105]
	v_mul_f32_e32 v132, 0xbfb8aa3b, v132
	v_mul_f32_e32 v128, 0xbfb8aa3b, v128
	v_mul_f32_e32 v133, 0xbfb8aa3b, v133
	v_mul_f32_e32 v129, 0xbfb8aa3b, v129
	v_mul_f32_e32 v134, 0xbfb8aa3b, v134
	v_mul_f32_e32 v130, 0xbfb8aa3b, v130
	v_mul_f32_e32 v135, 0xbfb8aa3b, v135
	v_mul_f32_e32 v131, 0xbfb8aa3b, v131
	v_exp_f32_e32 v132, v132
	v_exp_f32_e32 v128, v128
	v_exp_f32_e32 v133, v133
	v_exp_f32_e32 v129, v129
	v_exp_f32_e32 v134, v134
	v_exp_f32_e32 v130, v130
	v_exp_f32_e32 v135, v135
	v_exp_f32_e32 v131, v131
	v_add_f32_e32 v132, 1.0, v132
	v_add_f32_e32 v128, 1.0, v128
	v_add_f32_e32 v133, 1.0, v133
	v_add_f32_e32 v129, 1.0, v129
	v_add_f32_e32 v134, 1.0, v134
	v_add_f32_e32 v130, 1.0, v130
	v_add_f32_e32 v135, 1.0, v135
	v_add_f32_e32 v131, 1.0, v131
	v_rcp_f32_e32 v132, v132
	v_rcp_f32_e32 v128, v128
	v_rcp_f32_e32 v133, v133
	v_rcp_f32_e32 v129, v129
	v_rcp_f32_e32 v134, v134
	v_rcp_f32_e32 v130, v130
	v_rcp_f32_e32 v135, v135
	v_rcp_f32_e32 v131, v131
	s_waitcnt vmcnt(0)
	v_lshlrev_b32_e32 v162, 16, v136
	v_and_b32_e32 v136, 0xffff0000, v136
	v_lshlrev_b32_e32 v163, 16, v137
	v_and_b32_e32 v137, 0xffff0000, v137
	v_lshlrev_b32_e32 v164, 16, v138
	v_and_b32_e32 v138, 0xffff0000, v138
	v_lshlrev_b32_e32 v165, 16, v139
	v_and_b32_e32 v139, 0xffff0000, v139
	v_mul_f32_e32 v132, v132, v162
	v_mul_f32_e32 v162, v128, v164
	v_mul_f32_e32 v128, v133, v136
	v_mul_f32_e32 v133, v129, v138
	v_mul_f32_e32 v129, v134, v163
	v_mul_f32_e32 v134, v130, v165
	v_mul_f32_e32 v130, v135, v137
	v_mul_f32_e32 v131, v131, v139
	v_cvt_pk_bf16_f32 v128, v132, v128
	v_cvt_pk_bf16_f32 v129, v129, v130
	v_cvt_pk_bf16_f32 v130, v162, v133
	v_cvt_pk_bf16_f32 v131, v134, v131
	global_store_dwordx4 v[158:159], v[128:131], off nt
	global_load_dwordx4 v[128:131], v[160:161], off
	v_pk_add_f32 v[126:127], v[126:127], v[110:111]
	v_pk_add_f32 v[124:125], v[124:125], v[108:109]
	v_pk_add_f32 v[122:123], v[122:123], v[106:107]
	v_pk_add_f32 v[120:121], v[120:121], v[104:105]
	v_mul_f32_e32 v124, 0xbfb8aa3b, v124
	v_mul_f32_e32 v120, 0xbfb8aa3b, v120
	v_mul_f32_e32 v125, 0xbfb8aa3b, v125
	v_mul_f32_e32 v121, 0xbfb8aa3b, v121
	v_mul_f32_e32 v126, 0xbfb8aa3b, v126
	v_mul_f32_e32 v122, 0xbfb8aa3b, v122
	v_mul_f32_e32 v127, 0xbfb8aa3b, v127
	v_mul_f32_e32 v123, 0xbfb8aa3b, v123
	v_exp_f32_e32 v124, v124
	v_exp_f32_e32 v120, v120
	v_exp_f32_e32 v125, v125
	v_exp_f32_e32 v121, v121
	v_exp_f32_e32 v126, v126
	v_exp_f32_e32 v122, v122
	v_exp_f32_e32 v127, v127
	v_exp_f32_e32 v123, v123
	v_add_f32_e32 v124, 1.0, v124
	v_add_f32_e32 v120, 1.0, v120
	v_add_f32_e32 v125, 1.0, v125
	v_add_f32_e32 v121, 1.0, v121
	v_add_f32_e32 v126, 1.0, v126
	v_add_f32_e32 v122, 1.0, v122
	v_add_f32_e32 v127, 1.0, v127
	v_add_f32_e32 v123, 1.0, v123
	v_rcp_f32_e32 v124, v124
	v_rcp_f32_e32 v120, v120
	v_rcp_f32_e32 v125, v125
	v_rcp_f32_e32 v121, v121
	v_rcp_f32_e32 v126, v126
	v_rcp_f32_e32 v122, v122
	v_rcp_f32_e32 v127, v127
	v_rcp_f32_e32 v123, v123
	v_lshlrev_b64 v[132:133], 11, v[154:155]
	v_lshl_add_u64 v[134:135], v[132:133], 0, v[148:149]
	v_lshl_add_u64 v[136:137], s[26:27], 0, v[156:157]
	v_lshlrev_b64 v[134:135], 1, v[134:135]
	v_lshl_add_u64 v[138:139], s[14:15], 0, v[134:135]
	v_pk_add_f32 v[118:119], v[118:119], v[110:111]
	v_pk_add_f32 v[116:117], v[116:117], v[108:109]
	v_pk_add_f32 v[114:115], v[114:115], v[106:107]
	v_pk_add_f32 v[112:113], v[112:113], v[104:105]
	v_mul_f32_e32 v116, 0xbfb8aa3b, v116
	v_mul_f32_e32 v112, 0xbfb8aa3b, v112
	v_mul_f32_e32 v117, 0xbfb8aa3b, v117
	v_mul_f32_e32 v113, 0xbfb8aa3b, v113
	v_mul_f32_e32 v118, 0xbfb8aa3b, v118
	v_mul_f32_e32 v114, 0xbfb8aa3b, v114
	v_mul_f32_e32 v119, 0xbfb8aa3b, v119
	v_mul_f32_e32 v115, 0xbfb8aa3b, v115
	v_exp_f32_e32 v116, v116
	v_exp_f32_e32 v112, v112
	v_exp_f32_e32 v117, v117
	v_exp_f32_e32 v113, v113
	v_exp_f32_e32 v118, v118
	v_exp_f32_e32 v114, v114
	v_exp_f32_e32 v119, v119
	v_exp_f32_e32 v115, v115
	v_add_f32_e32 v116, 1.0, v116
	v_add_f32_e32 v112, 1.0, v112
	v_add_f32_e32 v117, 1.0, v117
	v_add_f32_e32 v113, 1.0, v113
	v_add_f32_e32 v118, 1.0, v118
	v_add_f32_e32 v114, 1.0, v114
	v_add_f32_e32 v119, 1.0, v119
	v_add_f32_e32 v115, 1.0, v115
	v_rcp_f32_e32 v116, v116
	v_rcp_f32_e32 v112, v112
	v_rcp_f32_e32 v117, v117
	v_rcp_f32_e32 v113, v113
	v_rcp_f32_e32 v118, v118
	v_rcp_f32_e32 v114, v114
	v_rcp_f32_e32 v119, v119
	v_rcp_f32_e32 v115, v115
	v_pk_add_f32 v[102:103], v[102:103], v[110:111]
	v_pk_add_f32 v[100:101], v[100:101], v[108:109]
	s_waitcnt vmcnt(0)
; __device__ __forceinline__ float sigm(float x) { return __builtin_amdgcn_rcpf(1.f + __builtin_amdgcn_exp2f(-1.4426950409f * x)); }
; __device__ __forceinline__ u32x4 pack8(const f32x4 v0, const f32x4 v1) { u32x4 w; w.x = cvt_pk_bf16(v0[0], v0[1]); w.y = cvt_pk_bf16(v0[2], v0[3]); w.z = cvt_pk_bf16(v1[0], v1[1]); w.w = cvt_pk_bf16(v1[2], v1[3]); return w; }
; __device__ __forceinline__ void unpack8(const u32x4 w, f32x4& lo, f32x4& hi) { lo = (f32x4){bf_lo(w.x), bf_hi(w.x), bf_lo(w.y), bf_hi(w.y)}; hi = (f32x4){bf_lo(w.z), bf_hi(w.z), bf_lo(w.w), bf_hi(w.w)}; }
;     __device__ __forceinline__ void operator()(AccT& acc, const Unit& u, int wr, int wc, int fr, int fq) const {
;     ...
;         if (u.kind == 0) {
; #pragma unroll
;             for (int bj = 0; bj < 2; ++bj) { const f32x4 b0 = *(const f32x4*)(glu_b + col0 + bj * 128), b1 = *(const f32x4*)(glu_b + col0 + bj * 128 + 4);
; #pragma unroll
;                 for (int ai = 0; ai < 2; ++ai)
; #pragma unroll
;                     for (int m = 0; m < 4; ++m) { const size_t off = (size_t)(row0 + ai * 128 + m * 16) * DSS + col0 + bj * 128;
;                         f32x4 y0, y1; unpack8(*(const u32x4*)(YG + off), y0, y1);
;                         f32x4 v0 = acc[ai][bj][m][0] + b0, v1 = acc[ai][bj][m][1] + b1;
; #pragma unroll
;                         for (int j = 0; j < 4; ++j) { v0[j] = y0[j] * sigm(v0[j]); v1[j] = y1[j] * sigm(v1[j]); }
;                         *(u32x4*)(YS + off) = pack8(v0, v1); } }
	v_lshlrev_b32_e32 v154, 16, v128
	v_and_b32_e32 v128, 0xffff0000, v128
	v_lshlrev_b32_e32 v155, 16, v129
	v_and_b32_e32 v129, 0xffff0000, v129
	v_lshlrev_b32_e32 v156, 16, v130
	v_and_b32_e32 v130, 0xffff0000, v130
	v_lshlrev_b32_e32 v157, 16, v131
	v_and_b32_e32 v131, 0xffff0000, v131
	v_mul_f32_e32 v124, v124, v154
	v_mul_f32_e32 v154, v120, v156
	v_mul_f32_e32 v120, v125, v128
	v_mul_f32_e32 v125, v121, v130
	v_mul_f32_e32 v121, v126, v155
	v_mul_f32_e32 v126, v122, v157
	v_mul_f32_e32 v122, v127, v129
	v_mul_f32_e32 v123, v123, v131
	v_cvt_pk_bf16_f32 v120, v124, v120
	v_cvt_pk_bf16_f32 v121, v121, v122
	v_cvt_pk_bf16_f32 v122, v154, v125
	v_cvt_pk_bf16_f32 v123, v126, v123
	global_store_dwordx4 v[136:137], v[120:123], off nt
	global_load_dwordx4 v[120:123], v[138:139], off
	v_lshlrev_b64 v[124:125], 11, v[152:153]
	v_lshl_add_u64 v[126:127], v[124:125], 0, v[148:149]
	v_lshl_add_u64 v[128:129], s[26:27], 0, v[134:135]
	v_lshlrev_b64 v[126:127], 1, v[126:127]
	v_lshl_add_u64 v[130:131], s[14:15], 0, v[126:127]
	v_pk_add_f32 v[98:99], v[98:99], v[106:107]
	v_pk_add_f32 v[96:97], v[96:97], v[104:105]
	v_mul_f32_e32 v100, 0xbfb8aa3b, v100
	v_mul_f32_e32 v96, 0xbfb8aa3b, v96
	v_mul_f32_e32 v101, 0xbfb8aa3b, v101
	v_mul_f32_e32 v97, 0xbfb8aa3b, v97
	v_mul_f32_e32 v102, 0xbfb8aa3b, v102
	v_mul_f32_e32 v98, 0xbfb8aa3b, v98
	v_mul_f32_e32 v103, 0xbfb8aa3b, v103
	v_mul_f32_e32 v99, 0xbfb8aa3b, v99
	v_exp_f32_e32 v100, v100
	v_exp_f32_e32 v96, v96
	v_exp_f32_e32 v101, v101
	v_exp_f32_e32 v97, v97
	v_exp_f32_e32 v102, v102
	v_exp_f32_e32 v98, v98
	v_exp_f32_e32 v103, v103
	v_exp_f32_e32 v99, v99
	v_add_f32_e32 v100, 1.0, v100
	v_add_f32_e32 v96, 1.0, v96
	v_add_f32_e32 v101, 1.0, v101
	v_add_f32_e32 v97, 1.0, v97
	v_add_f32_e32 v102, 1.0, v102
	v_add_f32_e32 v98, 1.0, v98
	v_add_f32_e32 v103, 1.0, v103
	v_add_f32_e32 v99, 1.0, v99
	v_rcp_f32_e32 v100, v100
	v_rcp_f32_e32 v96, v96
	v_rcp_f32_e32 v101, v101
	v_rcp_f32_e32 v97, v97
	v_rcp_f32_e32 v102, v102
	v_rcp_f32_e32 v98, v98
	v_rcp_f32_e32 v103, v103
	v_rcp_f32_e32 v99, v99
	v_pk_add_f32 v[94:95], v[94:95], v[110:111]
	v_pk_add_f32 v[92:93], v[92:93], v[108:109]
	v_pk_add_f32 v[90:91], v[90:91], v[106:107]
	v_pk_add_f32 v[88:89], v[88:89], v[104:105]
	v_mul_f32_e32 v92, 0xbfb8aa3b, v92
	v_mul_f32_e32 v88, 0xbfb8aa3b, v88
	v_mul_f32_e32 v93, 0xbfb8aa3b, v93
	v_mul_f32_e32 v89, 0xbfb8aa3b, v89
	v_mul_f32_e32 v94, 0xbfb8aa3b, v94
	v_mul_f32_e32 v90, 0xbfb8aa3b, v90
	v_mul_f32_e32 v95, 0xbfb8aa3b, v95
	v_mul_f32_e32 v91, 0xbfb8aa3b, v91
	v_exp_f32_e32 v92, v92
	v_exp_f32_e32 v88, v88
	v_exp_f32_e32 v93, v93
	v_exp_f32_e32 v89, v89
	v_exp_f32_e32 v94, v94
	v_exp_f32_e32 v90, v90
	v_exp_f32_e32 v95, v95
	v_exp_f32_e32 v91, v91
	v_add_f32_e32 v92, 1.0, v92
	v_add_f32_e32 v88, 1.0, v88
	v_add_f32_e32 v93, 1.0, v93
	v_add_f32_e32 v89, 1.0, v89
	v_add_f32_e32 v94, 1.0, v94
	v_add_f32_e32 v90, 1.0, v90
	v_add_f32_e32 v95, 1.0, v95
	v_add_f32_e32 v91, 1.0, v91
	v_rcp_f32_e32 v92, v92
	v_rcp_f32_e32 v88, v88
	v_rcp_f32_e32 v93, v93
	v_rcp_f32_e32 v89, v89
	v_rcp_f32_e32 v94, v94
	v_rcp_f32_e32 v90, v90
	v_rcp_f32_e32 v95, v95
	v_rcp_f32_e32 v91, v91
	v_pk_add_f32 v[86:87], v[86:87], v[110:111]
	v_pk_add_f32 v[84:85], v[84:85], v[108:109]
	v_pk_add_f32 v[82:83], v[82:83], v[106:107]
	v_pk_add_f32 v[80:81], v[80:81], v[104:105]
	s_waitcnt vmcnt(0)
	v_lshlrev_b32_e32 v134, 16, v120
	v_and_b32_e32 v120, 0xffff0000, v120
	v_lshlrev_b32_e32 v135, 16, v121
	v_and_b32_e32 v121, 0xffff0000, v121
	v_lshlrev_b32_e32 v136, 16, v122
	v_and_b32_e32 v122, 0xffff0000, v122
	v_lshlrev_b32_e32 v137, 16, v123
	v_and_b32_e32 v123, 0xffff0000, v123
	v_mul_f32_e32 v116, v116, v134
	v_mul_f32_e32 v134, v112, v136
	v_mul_f32_e32 v112, v117, v120
	v_mul_f32_e32 v117, v113, v122
	v_mul_f32_e32 v113, v118, v135
	v_mul_f32_e32 v118, v114, v137
	v_mul_f32_e32 v114, v119, v121
	v_mul_f32_e32 v115, v115, v123
	v_cvt_pk_bf16_f32 v112, v116, v112
	v_cvt_pk_bf16_f32 v113, v113, v114
	v_cvt_pk_bf16_f32 v114, v134, v117
	v_cvt_pk_bf16_f32 v115, v118, v115
	global_store_dwordx4 v[128:129], v[112:115], off nt
	global_load_dwordx4 v[112:115], v[130:131], off
	v_lshl_add_u64 v[116:117], v[150:151], 0, s[4:5]
	v_lshl_add_u64 v[118:119], v[116:117], 0, v[148:149]
	v_lshl_add_u64 v[120:121], s[26:27], 0, v[126:127]
	v_lshlrev_b64 v[118:119], 1, v[118:119]
	v_lshl_add_u64 v[122:123], s[14:15], 0, v[118:119]
	s_mov_b64 s[4:5], 0x48000
	v_mul_f32_e32 v84, 0xbfb8aa3b, v84
	v_mul_f32_e32 v80, 0xbfb8aa3b, v80
	v_mul_f32_e32 v85, 0xbfb8aa3b, v85
	v_mul_f32_e32 v81, 0xbfb8aa3b, v81
	v_mul_f32_e32 v86, 0xbfb8aa3b, v86
	v_mul_f32_e32 v82, 0xbfb8aa3b, v82
	v_mul_f32_e32 v87, 0xbfb8aa3b, v87
	v_mul_f32_e32 v83, 0xbfb8aa3b, v83
	v_exp_f32_e32 v84, v84
	v_exp_f32_e32 v80, v80
	v_exp_f32_e32 v85, v85
	v_exp_f32_e32 v81, v81
	v_exp_f32_e32 v86, v86
	v_exp_f32_e32 v82, v82
	v_exp_f32_e32 v87, v87
	v_exp_f32_e32 v83, v83
	v_add_f32_e32 v84, 1.0, v84
	v_add_f32_e32 v80, 1.0, v80
	v_add_f32_e32 v85, 1.0, v85
	v_add_f32_e32 v81, 1.0, v81
	v_add_f32_e32 v86, 1.0, v86
	v_add_f32_e32 v82, 1.0, v82
	v_add_f32_e32 v87, 1.0, v87
	v_add_f32_e32 v83, 1.0, v83
	v_rcp_f32_e32 v84, v84
	v_rcp_f32_e32 v80, v80
	v_rcp_f32_e32 v85, v85
	v_rcp_f32_e32 v81, v81
	v_rcp_f32_e32 v86, v86
	v_rcp_f32_e32 v82, v82
	v_rcp_f32_e32 v87, v87
	v_rcp_f32_e32 v83, v83
	v_pk_add_f32 v[78:79], v[78:79], v[110:111]
	v_pk_add_f32 v[76:77], v[76:77], v[108:109]
	v_pk_add_f32 v[74:75], v[74:75], v[106:107]
	v_pk_add_f32 v[72:73], v[72:73], v[104:105]
	v_mul_f32_e32 v76, 0xbfb8aa3b, v76
	v_mul_f32_e32 v72, 0xbfb8aa3b, v72
	v_mul_f32_e32 v77, 0xbfb8aa3b, v77
	v_mul_f32_e32 v73, 0xbfb8aa3b, v73
	v_mul_f32_e32 v78, 0xbfb8aa3b, v78
	v_mul_f32_e32 v74, 0xbfb8aa3b, v74
	v_mul_f32_e32 v79, 0xbfb8aa3b, v79
	v_mul_f32_e32 v75, 0xbfb8aa3b, v75
	v_exp_f32_e32 v76, v76
	v_exp_f32_e32 v72, v72
	v_exp_f32_e32 v77, v77
	v_exp_f32_e32 v73, v73
	v_exp_f32_e32 v78, v78
	v_exp_f32_e32 v74, v74
	v_exp_f32_e32 v79, v79
	v_exp_f32_e32 v75, v75
	v_add_f32_e32 v76, 1.0, v76
	v_add_f32_e32 v72, 1.0, v72
	v_add_f32_e32 v77, 1.0, v77
	v_add_f32_e32 v73, 1.0, v73
	v_add_f32_e32 v78, 1.0, v78
	v_add_f32_e32 v74, 1.0, v74
	v_add_f32_e32 v79, 1.0, v79
	v_add_f32_e32 v75, 1.0, v75
	v_rcp_f32_e32 v76, v76
	v_rcp_f32_e32 v72, v72
	v_rcp_f32_e32 v77, v77
	v_rcp_f32_e32 v73, v73
	v_rcp_f32_e32 v78, v78
	v_rcp_f32_e32 v74, v74
	v_rcp_f32_e32 v79, v79
	v_rcp_f32_e32 v75, v75
	v_pk_add_f32 v[70:71], v[70:71], v[110:111]
	v_pk_add_f32 v[68:69], v[68:69], v[108:109]
	v_pk_add_f32 v[66:67], v[66:67], v[106:107]
	v_pk_add_f32 v[64:65], v[64:65], v[104:105]
	v_mul_f32_e32 v68, 0xbfb8aa3b, v68
	s_waitcnt vmcnt(0)
; __device__ __forceinline__ float sigm(float x) { return __builtin_amdgcn_rcpf(1.f + __builtin_amdgcn_exp2f(-1.4426950409f * x)); }
; __device__ __forceinline__ u32x4 pack8(const f32x4 v0, const f32x4 v1) { u32x4 w; w.x = cvt_pk_bf16(v0[0], v0[1]); w.y = cvt_pk_bf16(v0[2], v0[3]); w.z = cvt_pk_bf16(v1[0], v1[1]); w.w = cvt_pk_bf16(v1[2], v1[3]); return w; }
; __device__ __forceinline__ void unpack8(const u32x4 w, f32x4& lo, f32x4& hi) { lo = (f32x4){bf_lo(w.x), bf_hi(w.x), bf_lo(w.y), bf_hi(w.y)}; hi = (f32x4){bf_lo(w.z), bf_hi(w.z), bf_lo(w.w), bf_hi(w.w)}; }
;     __device__ __forceinline__ void operator()(AccT& acc, const Unit& u, int wr, int wc, int fr, int fq) const {
;     ...
;         if (u.kind == 0) {
; #pragma unroll
;             for (int bj = 0; bj < 2; ++bj) { const f32x4 b0 = *(const f32x4*)(glu_b + col0 + bj * 128), b1 = *(const f32x4*)(glu_b + col0 + bj * 128 + 4);
; #pragma unroll
;                 for (int ai = 0; ai < 2; ++ai)
; #pragma unroll
;                     for (int m = 0; m < 4; ++m) { const size_t off = (size_t)(row0 + ai * 128 + m * 16) * DSS + col0 + bj * 128;
;                         f32x4 y0, y1; unpack8(*(const u32x4*)(YG + off), y0, y1);
;                         f32x4 v0 = acc[ai][bj][m][0] + b0, v1 = acc[ai][bj][m][1] + b1;
; #pragma unroll
;                         for (int j = 0; j < 4; ++j) { v0[j] = y0[j] * sigm(v0[j]); v1[j] = y1[j] * sigm(v1[j]); }
;                         *(u32x4*)(YS + off) = pack8(v0, v1); } }
	v_lshlrev_b32_e32 v126, 16, v112
	v_and_b32_e32 v112, 0xffff0000, v112
	v_lshlrev_b32_e32 v127, 16, v113
	v_and_b32_e32 v113, 0xffff0000, v113
	v_lshlrev_b32_e32 v128, 16, v114
	v_and_b32_e32 v114, 0xffff0000, v114
	v_lshlrev_b32_e32 v129, 16, v115
	v_and_b32_e32 v115, 0xffff0000, v115
	v_mul_f32_e32 v100, v100, v126
	v_mul_f32_e32 v126, v96, v128
	v_mul_f32_e32 v96, v101, v112
	v_mul_f32_e32 v101, v97, v114
	v_mul_f32_e32 v97, v102, v127
	v_mul_f32_e32 v102, v98, v129
	v_mul_f32_e32 v98, v103, v113
	v_mul_f32_e32 v99, v99, v115
	v_cvt_pk_bf16_f32 v96, v100, v96
	v_cvt_pk_bf16_f32 v97, v97, v98
	v_cvt_pk_bf16_f32 v98, v126, v101
	v_cvt_pk_bf16_f32 v99, v102, v99
	global_store_dwordx4 v[120:121], v[96:99], off nt
	global_load_dwordx4 v[96:99], v[122:123], off
	v_lshl_add_u64 v[100:101], v[150:151], 0, s[4:5]
	v_lshl_add_u64 v[102:103], v[100:101], 0, v[148:149]
	v_lshl_add_u64 v[112:113], s[26:27], 0, v[118:119]
	v_lshlrev_b64 v[102:103], 1, v[102:103]
	v_lshl_add_u64 v[114:115], s[14:15], 0, v[102:103]
	s_mov_b64 s[4:5], 0x50000
	v_mul_f32_e32 v64, 0xbfb8aa3b, v64
	v_mul_f32_e32 v69, 0xbfb8aa3b, v69
	v_mul_f32_e32 v65, 0xbfb8aa3b, v65
	v_mul_f32_e32 v70, 0xbfb8aa3b, v70
	v_mul_f32_e32 v66, 0xbfb8aa3b, v66
	v_mul_f32_e32 v71, 0xbfb8aa3b, v71
	v_mul_f32_e32 v67, 0xbfb8aa3b, v67
	v_exp_f32_e32 v68, v68
	v_exp_f32_e32 v64, v64
	v_exp_f32_e32 v69, v69
	v_exp_f32_e32 v65, v65
	v_exp_f32_e32 v70, v70
	v_exp_f32_e32 v66, v66
	v_exp_f32_e32 v71, v71
	v_exp_f32_e32 v67, v67
	v_add_f32_e32 v68, 1.0, v68
	v_add_f32_e32 v64, 1.0, v64
	v_add_f32_e32 v69, 1.0, v69
	v_add_f32_e32 v65, 1.0, v65
	v_add_f32_e32 v70, 1.0, v70
	v_add_f32_e32 v66, 1.0, v66
	v_add_f32_e32 v71, 1.0, v71
	v_add_f32_e32 v67, 1.0, v67
	v_rcp_f32_e32 v68, v68
	v_rcp_f32_e32 v64, v64
	v_rcp_f32_e32 v69, v69
	v_rcp_f32_e32 v65, v65
	v_rcp_f32_e32 v70, v70
	v_rcp_f32_e32 v66, v66
	v_rcp_f32_e32 v71, v71
	v_rcp_f32_e32 v67, v67
	s_waitcnt vmcnt(0)
	v_lshlrev_b32_e32 v118, 16, v96
	v_and_b32_e32 v96, 0xffff0000, v96
	v_lshlrev_b32_e32 v119, 16, v97
	v_and_b32_e32 v97, 0xffff0000, v97
	v_lshlrev_b32_e32 v120, 16, v98
	v_and_b32_e32 v98, 0xffff0000, v98
	v_lshlrev_b32_e32 v121, 16, v99
	v_and_b32_e32 v99, 0xffff0000, v99
	v_mul_f32_e32 v92, v92, v118
	v_mul_f32_e32 v118, v88, v120
	v_mul_f32_e32 v88, v93, v96
	v_mul_f32_e32 v93, v89, v98
	v_mul_f32_e32 v89, v94, v119
	v_mul_f32_e32 v94, v90, v121
	v_mul_f32_e32 v90, v95, v97
	v_mul_f32_e32 v91, v91, v99
	v_cvt_pk_bf16_f32 v88, v92, v88
	v_cvt_pk_bf16_f32 v89, v89, v90
	v_cvt_pk_bf16_f32 v90, v118, v93
	v_cvt_pk_bf16_f32 v91, v94, v91
	global_store_dwordx4 v[112:113], v[88:91], off nt
	global_load_dwordx4 v[88:91], v[114:115], off
	v_lshl_add_u64 v[92:93], v[150:151], 0, s[4:5]
	v_lshl_add_u64 v[94:95], v[92:93], 0, v[148:149]
	v_lshl_add_u64 v[96:97], s[26:27], 0, v[102:103]
	v_lshlrev_b64 v[94:95], 1, v[94:95]
	v_lshl_add_u64 v[98:99], s[14:15], 0, v[94:95]
	s_mov_b64 s[4:5], 0x58000
	s_waitcnt vmcnt(0)
	v_lshlrev_b32_e32 v102, 16, v88
	v_and_b32_e32 v88, 0xffff0000, v88
	v_lshlrev_b32_e32 v103, 16, v89
	v_and_b32_e32 v89, 0xffff0000, v89
	v_lshlrev_b32_e32 v112, 16, v90
	v_and_b32_e32 v90, 0xffff0000, v90
	v_lshlrev_b32_e32 v113, 16, v91
	v_and_b32_e32 v91, 0xffff0000, v91
	v_mul_f32_e32 v84, v84, v102
	v_mul_f32_e32 v102, v80, v112
	v_mul_f32_e32 v80, v85, v88
	v_mul_f32_e32 v85, v81, v90
	v_mul_f32_e32 v81, v86, v103
	v_mul_f32_e32 v86, v82, v113
	v_mul_f32_e32 v82, v87, v89
	v_mul_f32_e32 v83, v83, v91
	v_cvt_pk_bf16_f32 v80, v84, v80
	v_cvt_pk_bf16_f32 v81, v81, v82
	v_cvt_pk_bf16_f32 v82, v102, v85
	v_cvt_pk_bf16_f32 v83, v86, v83
	global_store_dwordx4 v[96:97], v[80:83], off nt
	global_load_dwordx4 v[80:83], v[98:99], off
	v_lshl_add_u64 v[84:85], v[150:151], 0, s[4:5]
	v_lshl_add_u64 v[86:87], v[84:85], 0, v[148:149]
	v_lshl_add_u64 v[88:89], s[26:27], 0, v[94:95]
	v_lshlrev_b64 v[86:87], 1, v[86:87]
	v_lshl_add_u64 v[90:91], s[14:15], 0, v[86:87]
	v_or_b32_e32 v148, 0x80, v148
	s_waitcnt vmcnt(0)
	v_lshlrev_b32_e32 v94, 16, v80
	v_and_b32_e32 v80, 0xffff0000, v80
	v_lshlrev_b32_e32 v95, 16, v81
	v_and_b32_e32 v81, 0xffff0000, v81
	v_lshlrev_b32_e32 v96, 16, v82
	v_and_b32_e32 v82, 0xffff0000, v82
	v_lshlrev_b32_e32 v97, 16, v83
	v_and_b32_e32 v83, 0xffff0000, v83
	v_mul_f32_e32 v76, v76, v94
	v_mul_f32_e32 v94, v72, v96
	v_mul_f32_e32 v72, v77, v80
	v_mul_f32_e32 v77, v73, v82
	v_mul_f32_e32 v73, v78, v95
	v_mul_f32_e32 v78, v74, v97
	v_mul_f32_e32 v74, v79, v81
	v_mul_f32_e32 v75, v75, v83
	v_cvt_pk_bf16_f32 v72, v76, v72
	v_cvt_pk_bf16_f32 v73, v73, v74
	v_cvt_pk_bf16_f32 v74, v94, v77
	v_cvt_pk_bf16_f32 v75, v78, v75
	global_store_dwordx4 v[88:89], v[72:75], off nt
	global_load_dwordx4 v[72:75], v[90:91], off
	v_lshl_add_u64 v[76:77], v[148:149], 0, v[150:151]
	v_lshl_add_u64 v[78:79], s[26:27], 0, v[86:87]
	v_lshlrev_b64 v[76:77], 1, v[76:77]
	v_lshl_add_u64 v[80:81], s[14:15], 0, v[76:77]
	v_lshl_add_u64 v[76:77], s[26:27], 0, v[76:77]
	s_waitcnt vmcnt(0)
	v_lshlrev_b32_e32 v82, 16, v72
	v_and_b32_e32 v72, 0xffff0000, v72
	v_lshlrev_b32_e32 v83, 16, v73
	v_and_b32_e32 v73, 0xffff0000, v73
	v_lshlrev_b32_e32 v86, 16, v74
	v_and_b32_e32 v74, 0xffff0000, v74
	v_lshlrev_b32_e32 v87, 16, v75
	v_and_b32_e32 v75, 0xffff0000, v75
	v_mul_f32_e32 v68, v68, v82
	v_mul_f32_e32 v82, v64, v86
	v_mul_f32_e32 v64, v69, v72
	v_mul_f32_e32 v69, v65, v74
	v_mul_f32_e32 v65, v70, v83
	v_mul_f32_e32 v70, v66, v87
	v_mul_f32_e32 v66, v71, v73
	v_mul_f32_e32 v67, v67, v75
	v_cvt_pk_bf16_f32 v64, v68, v64
	v_cvt_pk_bf16_f32 v65, v65, v66
	v_cvt_pk_bf16_f32 v66, v82, v69
	v_cvt_pk_bf16_f32 v67, v70, v67
	global_store_dwordx4 v[78:79], v[64:67], off nt
	global_load_dwordx4 v[72:75], v[80:81], off
	global_load_dwordx4 v[68:71], v[140:141], off offset:512
	s_nop 0
	global_load_dwordx4 v[64:67], v[140:141], off offset:528
	v_lshl_add_u64 v[78:79], v[148:149], 0, v[142:143]
	v_lshlrev_b64 v[78:79], 1, v[78:79]
	v_lshl_add_u64 v[80:81], s[14:15], 0, v[78:79]
	s_waitcnt vmcnt(2)
; __device__ __forceinline__ float sigm(float x) { return __builtin_amdgcn_rcpf(1.f + __builtin_amdgcn_exp2f(-1.4426950409f * x)); }
; __device__ __forceinline__ u32x4 pack8(const f32x4 v0, const f32x4 v1) { u32x4 w; w.x = cvt_pk_bf16(v0[0], v0[1]); w.y = cvt_pk_bf16(v0[2], v0[3]); w.z = cvt_pk_bf16(v1[0], v1[1]); w.w = cvt_pk_bf16(v1[2], v1[3]); return w; }
; __device__ __forceinline__ void unpack8(const u32x4 w, f32x4& lo, f32x4& hi) { lo = (f32x4){bf_lo(w.x), bf_hi(w.x), bf_lo(w.y), bf_hi(w.y)}; hi = (f32x4){bf_lo(w.z), bf_hi(w.z), bf_lo(w.w), bf_hi(w.w)}; }
;     __device__ __forceinline__ void operator()(AccT& acc, const Unit& u, int wr, int wc, int fr, int fq) const {
;     ...
;         if (u.kind == 0) {
; #pragma unroll
;             for (int bj = 0; bj < 2; ++bj) { const f32x4 b0 = *(const f32x4*)(glu_b + col0 + bj * 128), b1 = *(const f32x4*)(glu_b + col0 + bj * 128 + 4);
; #pragma unroll
;                 for (int ai = 0; ai < 2; ++ai)
; #pragma unroll
;                     for (int m = 0; m < 4; ++m) { const size_t off = (size_t)(row0 + ai * 128 + m * 16) * DSS + col0 + bj * 128;
;                         f32x4 y0, y1; unpack8(*(const u32x4*)(YG + off), y0, y1);
;                         f32x4 v0 = acc[ai][bj][m][0] + b0, v1 = acc[ai][bj][m][1] + b1;
; #pragma unroll
;                         for (int j = 0; j < 4; ++j) { v0[j] = y0[j] * sigm(v0[j]); v1[j] = y1[j] * sigm(v1[j]); }
;                         *(u32x4*)(YS + off) = pack8(v0, v1); } }
	v_lshlrev_b32_e32 v82, 16, v72
	s_waitcnt vmcnt(1)
	v_pk_add_f32 v[62:63], v[62:63], v[70:71]
	v_pk_add_f32 v[60:61], v[60:61], v[68:69]
	s_waitcnt vmcnt(0)
	v_pk_add_f32 v[58:59], v[58:59], v[66:67]
	v_pk_add_f32 v[56:57], v[56:57], v[64:65]
	v_mul_f32_e32 v60, 0xbfb8aa3b, v60
	v_mul_f32_e32 v56, 0xbfb8aa3b, v56
	v_mul_f32_e32 v61, 0xbfb8aa3b, v61
	v_mul_f32_e32 v57, 0xbfb8aa3b, v57
	v_mul_f32_e32 v62, 0xbfb8aa3b, v62
	v_mul_f32_e32 v58, 0xbfb8aa3b, v58
	v_mul_f32_e32 v63, 0xbfb8aa3b, v63
	v_mul_f32_e32 v59, 0xbfb8aa3b, v59
	v_exp_f32_e32 v60, v60
	v_exp_f32_e32 v56, v56
	v_exp_f32_e32 v61, v61
	v_exp_f32_e32 v57, v57
	v_exp_f32_e32 v62, v62
	v_exp_f32_e32 v58, v58
	v_exp_f32_e32 v63, v63
	v_exp_f32_e32 v59, v59
	v_add_f32_e32 v60, 1.0, v60
	v_add_f32_e32 v56, 1.0, v56
	v_add_f32_e32 v61, 1.0, v61
	v_add_f32_e32 v57, 1.0, v57
	v_add_f32_e32 v62, 1.0, v62
	v_add_f32_e32 v58, 1.0, v58
	v_add_f32_e32 v63, 1.0, v63
	v_add_f32_e32 v59, 1.0, v59
	v_rcp_f32_e32 v60, v60
	v_rcp_f32_e32 v56, v56
	v_rcp_f32_e32 v61, v61
	v_rcp_f32_e32 v57, v57
	v_rcp_f32_e32 v62, v62
	v_rcp_f32_e32 v58, v58
	v_rcp_f32_e32 v63, v63
	v_rcp_f32_e32 v59, v59
	v_and_b32_e32 v72, 0xffff0000, v72
	v_lshlrev_b32_e32 v83, 16, v73
	v_and_b32_e32 v73, 0xffff0000, v73
	v_lshlrev_b32_e32 v86, 16, v74
	v_and_b32_e32 v74, 0xffff0000, v74
	v_lshlrev_b32_e32 v87, 16, v75
	v_and_b32_e32 v75, 0xffff0000, v75
	v_mul_f32_e32 v60, v60, v82
	v_mul_f32_e32 v82, v56, v86
	v_mul_f32_e32 v56, v61, v72
	v_mul_f32_e32 v61, v57, v74
	v_mul_f32_e32 v57, v62, v83
	v_mul_f32_e32 v62, v58, v87
	v_mul_f32_e32 v58, v63, v73
	v_mul_f32_e32 v59, v59, v75
	v_cvt_pk_bf16_f32 v56, v60, v56
	v_cvt_pk_bf16_f32 v57, v57, v58
	v_cvt_pk_bf16_f32 v58, v82, v61
	v_cvt_pk_bf16_f32 v59, v62, v59
	global_store_dwordx4 v[76:77], v[56:59], off nt
	global_load_dwordx4 v[56:59], v[80:81], off
	v_pk_add_f32 v[54:55], v[54:55], v[70:71]
	v_pk_add_f32 v[52:53], v[52:53], v[68:69]
	v_pk_add_f32 v[50:51], v[50:51], v[66:67]
	v_pk_add_f32 v[48:49], v[48:49], v[64:65]
	v_mul_f32_e32 v52, 0xbfb8aa3b, v52
	v_mul_f32_e32 v48, 0xbfb8aa3b, v48
	v_mul_f32_e32 v53, 0xbfb8aa3b, v53
	v_mul_f32_e32 v49, 0xbfb8aa3b, v49
	v_mul_f32_e32 v54, 0xbfb8aa3b, v54
	v_mul_f32_e32 v50, 0xbfb8aa3b, v50
	v_mul_f32_e32 v55, 0xbfb8aa3b, v55
	v_mul_f32_e32 v51, 0xbfb8aa3b, v51
	v_exp_f32_e32 v52, v52
	v_exp_f32_e32 v48, v48
	v_exp_f32_e32 v53, v53
	v_exp_f32_e32 v49, v49
	v_exp_f32_e32 v54, v54
	v_exp_f32_e32 v50, v50
	v_exp_f32_e32 v55, v55
	v_exp_f32_e32 v51, v51
	v_add_f32_e32 v52, 1.0, v52
	v_add_f32_e32 v48, 1.0, v48
	v_add_f32_e32 v53, 1.0, v53
	v_add_f32_e32 v49, 1.0, v49
	v_add_f32_e32 v54, 1.0, v54
	v_add_f32_e32 v50, 1.0, v50
	v_add_f32_e32 v55, 1.0, v55
	v_add_f32_e32 v51, 1.0, v51
	v_rcp_f32_e32 v52, v52
	v_rcp_f32_e32 v48, v48
	v_rcp_f32_e32 v53, v53
	v_rcp_f32_e32 v49, v49
	v_rcp_f32_e32 v54, v54
	v_rcp_f32_e32 v50, v50
	v_rcp_f32_e32 v55, v55
	v_rcp_f32_e32 v51, v51
	v_lshl_add_u64 v[60:61], v[148:149], 0, v[132:133]
	v_lshlrev_b64 v[60:61], 1, v[60:61]
	v_lshl_add_u64 v[62:63], s[26:27], 0, v[78:79]
	v_lshl_add_u64 v[72:73], s[14:15], 0, v[60:61]
	v_pk_add_f32 v[46:47], v[46:47], v[70:71]
	v_pk_add_f32 v[44:45], v[44:45], v[68:69]
	v_pk_add_f32 v[42:43], v[42:43], v[66:67]
	v_pk_add_f32 v[40:41], v[40:41], v[64:65]
	v_mul_f32_e32 v44, 0xbfb8aa3b, v44
	v_mul_f32_e32 v40, 0xbfb8aa3b, v40
	v_mul_f32_e32 v45, 0xbfb8aa3b, v45
	v_mul_f32_e32 v41, 0xbfb8aa3b, v41
	v_mul_f32_e32 v46, 0xbfb8aa3b, v46
	v_mul_f32_e32 v42, 0xbfb8aa3b, v42
	v_mul_f32_e32 v47, 0xbfb8aa3b, v47
	v_mul_f32_e32 v43, 0xbfb8aa3b, v43
	v_exp_f32_e32 v44, v44
	v_exp_f32_e32 v40, v40
	v_exp_f32_e32 v45, v45
	v_exp_f32_e32 v41, v41
	v_exp_f32_e32 v46, v46
	v_exp_f32_e32 v42, v42
	v_exp_f32_e32 v47, v47
	v_exp_f32_e32 v43, v43
	v_add_f32_e32 v44, 1.0, v44
	v_add_f32_e32 v40, 1.0, v40
	v_add_f32_e32 v45, 1.0, v45
	v_add_f32_e32 v41, 1.0, v41
	v_add_f32_e32 v46, 1.0, v46
	v_add_f32_e32 v42, 1.0, v42
	v_add_f32_e32 v47, 1.0, v47
	v_add_f32_e32 v43, 1.0, v43
	v_rcp_f32_e32 v44, v44
	v_rcp_f32_e32 v40, v40
	v_rcp_f32_e32 v45, v45
	v_rcp_f32_e32 v41, v41
	v_rcp_f32_e32 v46, v46
	v_rcp_f32_e32 v42, v42
	v_rcp_f32_e32 v47, v47
	v_rcp_f32_e32 v43, v43
	v_pk_add_f32 v[38:39], v[38:39], v[70:71]
	v_pk_add_f32 v[36:37], v[36:37], v[68:69]
	v_pk_add_f32 v[34:35], v[34:35], v[66:67]
	s_waitcnt vmcnt(0)
; __device__ __forceinline__ float sigm(float x) { return __builtin_amdgcn_rcpf(1.f + __builtin_amdgcn_exp2f(-1.4426950409f * x)); }
; __device__ __forceinline__ u32x4 pack8(const f32x4 v0, const f32x4 v1) { u32x4 w; w.x = cvt_pk_bf16(v0[0], v0[1]); w.y = cvt_pk_bf16(v0[2], v0[3]); w.z = cvt_pk_bf16(v1[0], v1[1]); w.w = cvt_pk_bf16(v1[2], v1[3]); return w; }
; __device__ __forceinline__ void unpack8(const u32x4 w, f32x4& lo, f32x4& hi) { lo = (f32x4){bf_lo(w.x), bf_hi(w.x), bf_lo(w.y), bf_hi(w.y)}; hi = (f32x4){bf_lo(w.z), bf_hi(w.z), bf_lo(w.w), bf_hi(w.w)}; }
;     __device__ __forceinline__ void operator()(AccT& acc, const Unit& u, int wr, int wc, int fr, int fq) const {
;     ...
;         if (u.kind == 0) {
; #pragma unroll
;             for (int bj = 0; bj < 2; ++bj) { const f32x4 b0 = *(const f32x4*)(glu_b + col0 + bj * 128), b1 = *(const f32x4*)(glu_b + col0 + bj * 128 + 4);
; #pragma unroll
;                 for (int ai = 0; ai < 2; ++ai)
; #pragma unroll
;                     for (int m = 0; m < 4; ++m) { const size_t off = (size_t)(row0 + ai * 128 + m * 16) * DSS + col0 + bj * 128;
;                         f32x4 y0, y1; unpack8(*(const u32x4*)(YG + off), y0, y1);
;                         f32x4 v0 = acc[ai][bj][m][0] + b0, v1 = acc[ai][bj][m][1] + b1;
; #pragma unroll
;                         for (int j = 0; j < 4; ++j) { v0[j] = y0[j] * sigm(v0[j]); v1[j] = y1[j] * sigm(v1[j]); }
;                         *(u32x4*)(YS + off) = pack8(v0, v1); } }
	v_lshlrev_b32_e32 v74, 16, v56
	v_and_b32_e32 v56, 0xffff0000, v56
	v_lshlrev_b32_e32 v75, 16, v57
	v_and_b32_e32 v57, 0xffff0000, v57
	v_lshlrev_b32_e32 v76, 16, v58
	v_and_b32_e32 v58, 0xffff0000, v58
	v_lshlrev_b32_e32 v77, 16, v59
	v_and_b32_e32 v59, 0xffff0000, v59
	v_mul_f32_e32 v52, v52, v74
	v_mul_f32_e32 v74, v48, v76
	v_mul_f32_e32 v48, v53, v56
	v_mul_f32_e32 v53, v49, v58
	v_mul_f32_e32 v49, v54, v75
	v_mul_f32_e32 v54, v50, v77
	v_mul_f32_e32 v50, v55, v57
	v_mul_f32_e32 v51, v51, v59
	v_cvt_pk_bf16_f32 v48, v52, v48
	v_cvt_pk_bf16_f32 v49, v49, v50
	v_cvt_pk_bf16_f32 v50, v74, v53
	v_cvt_pk_bf16_f32 v51, v54, v51
	global_store_dwordx4 v[62:63], v[48:51], off nt
	global_load_dwordx4 v[48:51], v[72:73], off
	v_lshl_add_u64 v[52:53], v[148:149], 0, v[124:125]
	v_lshl_add_u64 v[54:55], s[26:27], 0, v[60:61]
	v_lshlrev_b64 v[52:53], 1, v[52:53]
	v_lshl_add_u64 v[56:57], s[14:15], 0, v[52:53]
	v_pk_add_f32 v[32:33], v[32:33], v[64:65]
	v_mul_f32_e32 v36, 0xbfb8aa3b, v36
	v_mul_f32_e32 v32, 0xbfb8aa3b, v32
	v_mul_f32_e32 v37, 0xbfb8aa3b, v37
	v_mul_f32_e32 v33, 0xbfb8aa3b, v33
	v_mul_f32_e32 v38, 0xbfb8aa3b, v38
	v_mul_f32_e32 v34, 0xbfb8aa3b, v34
	v_mul_f32_e32 v39, 0xbfb8aa3b, v39
	v_mul_f32_e32 v35, 0xbfb8aa3b, v35
	v_exp_f32_e32 v36, v36
	v_exp_f32_e32 v32, v32
	v_exp_f32_e32 v37, v37
	v_exp_f32_e32 v33, v33
	v_exp_f32_e32 v38, v38
	v_exp_f32_e32 v34, v34
	v_exp_f32_e32 v39, v39
	v_exp_f32_e32 v35, v35
	v_add_f32_e32 v36, 1.0, v36
	v_add_f32_e32 v32, 1.0, v32
	v_add_f32_e32 v37, 1.0, v37
	v_add_f32_e32 v33, 1.0, v33
	v_add_f32_e32 v38, 1.0, v38
	v_add_f32_e32 v34, 1.0, v34
	v_add_f32_e32 v39, 1.0, v39
	v_add_f32_e32 v35, 1.0, v35
	v_rcp_f32_e32 v36, v36
	v_rcp_f32_e32 v32, v32
	v_rcp_f32_e32 v37, v37
	v_rcp_f32_e32 v33, v33
	v_rcp_f32_e32 v38, v38
	v_rcp_f32_e32 v34, v34
	v_rcp_f32_e32 v39, v39
	v_rcp_f32_e32 v35, v35
	v_pk_add_f32 v[30:31], v[30:31], v[70:71]
	v_pk_add_f32 v[28:29], v[28:29], v[68:69]
	v_pk_add_f32 v[26:27], v[26:27], v[66:67]
	v_pk_add_f32 v[24:25], v[24:25], v[64:65]
	v_mul_f32_e32 v28, 0xbfb8aa3b, v28
	v_mul_f32_e32 v24, 0xbfb8aa3b, v24
	v_mul_f32_e32 v29, 0xbfb8aa3b, v29
	v_mul_f32_e32 v25, 0xbfb8aa3b, v25
	v_mul_f32_e32 v30, 0xbfb8aa3b, v30
	v_mul_f32_e32 v26, 0xbfb8aa3b, v26
	v_mul_f32_e32 v31, 0xbfb8aa3b, v31
	v_mul_f32_e32 v27, 0xbfb8aa3b, v27
	v_exp_f32_e32 v28, v28
	v_exp_f32_e32 v24, v24
	v_exp_f32_e32 v29, v29
	v_exp_f32_e32 v25, v25
	v_exp_f32_e32 v30, v30
	v_exp_f32_e32 v26, v26
	v_exp_f32_e32 v31, v31
	v_exp_f32_e32 v27, v27
	v_add_f32_e32 v28, 1.0, v28
	v_add_f32_e32 v24, 1.0, v24
	v_add_f32_e32 v29, 1.0, v29
	v_add_f32_e32 v25, 1.0, v25
	v_add_f32_e32 v30, 1.0, v30
	v_add_f32_e32 v26, 1.0, v26
	v_add_f32_e32 v31, 1.0, v31
	v_add_f32_e32 v27, 1.0, v27
	v_rcp_f32_e32 v28, v28
	v_rcp_f32_e32 v24, v24
	v_rcp_f32_e32 v29, v29
	v_rcp_f32_e32 v25, v25
	v_rcp_f32_e32 v30, v30
	v_rcp_f32_e32 v26, v26
	v_rcp_f32_e32 v31, v31
	v_rcp_f32_e32 v27, v27
	v_pk_add_f32 v[22:23], v[22:23], v[70:71]
	v_pk_add_f32 v[20:21], v[20:21], v[68:69]
	v_pk_add_f32 v[18:19], v[18:19], v[66:67]
	v_pk_add_f32 v[16:17], v[16:17], v[64:65]
	v_mul_f32_e32 v20, 0xbfb8aa3b, v20
	v_mul_f32_e32 v16, 0xbfb8aa3b, v16
	s_waitcnt vmcnt(0)
	v_lshlrev_b32_e32 v58, 16, v48
	v_and_b32_e32 v48, 0xffff0000, v48
	v_lshlrev_b32_e32 v59, 16, v49
	v_and_b32_e32 v49, 0xffff0000, v49
	v_lshlrev_b32_e32 v60, 16, v50
	v_and_b32_e32 v50, 0xffff0000, v50
	v_lshlrev_b32_e32 v61, 16, v51
	v_and_b32_e32 v51, 0xffff0000, v51
	v_mul_f32_e32 v44, v44, v58
	v_mul_f32_e32 v58, v40, v60
	v_mul_f32_e32 v40, v45, v48
	v_mul_f32_e32 v45, v41, v50
	v_mul_f32_e32 v41, v46, v59
	v_mul_f32_e32 v46, v42, v61
	v_mul_f32_e32 v42, v47, v49
	v_mul_f32_e32 v43, v43, v51
	v_cvt_pk_bf16_f32 v40, v44, v40
	v_cvt_pk_bf16_f32 v41, v41, v42
	v_cvt_pk_bf16_f32 v42, v58, v45
	v_cvt_pk_bf16_f32 v43, v46, v43
	global_store_dwordx4 v[54:55], v[40:43], off nt
	global_load_dwordx4 v[40:43], v[56:57], off
	v_lshl_add_u64 v[44:45], v[148:149], 0, v[116:117]
	v_lshl_add_u64 v[46:47], s[26:27], 0, v[52:53]
	v_lshlrev_b64 v[44:45], 1, v[44:45]
	v_lshl_add_u64 v[48:49], s[14:15], 0, v[44:45]
	v_mul_f32_e32 v21, 0xbfb8aa3b, v21
	v_mul_f32_e32 v17, 0xbfb8aa3b, v17
	v_mul_f32_e32 v22, 0xbfb8aa3b, v22
	v_mul_f32_e32 v18, 0xbfb8aa3b, v18
	v_mul_f32_e32 v23, 0xbfb8aa3b, v23
	v_mul_f32_e32 v19, 0xbfb8aa3b, v19
	v_exp_f32_e32 v20, v20
	v_exp_f32_e32 v16, v16
	v_exp_f32_e32 v21, v21
	v_exp_f32_e32 v17, v17
	v_exp_f32_e32 v22, v22
	v_exp_f32_e32 v18, v18
	v_exp_f32_e32 v23, v23
	v_exp_f32_e32 v19, v19
	v_add_f32_e32 v20, 1.0, v20
	v_add_f32_e32 v16, 1.0, v16
	v_add_f32_e32 v21, 1.0, v21
	v_add_f32_e32 v17, 1.0, v17
	v_add_f32_e32 v22, 1.0, v22
	v_add_f32_e32 v18, 1.0, v18
	v_add_f32_e32 v23, 1.0, v23
	v_add_f32_e32 v19, 1.0, v19
	v_rcp_f32_e32 v20, v20
	v_rcp_f32_e32 v16, v16
	v_rcp_f32_e32 v21, v21
	v_rcp_f32_e32 v17, v17
	v_rcp_f32_e32 v22, v22
	v_rcp_f32_e32 v18, v18
	v_rcp_f32_e32 v23, v23
	v_rcp_f32_e32 v19, v19
	v_pk_add_f32 v[14:15], v[14:15], v[70:71]
	v_pk_add_f32 v[12:13], v[12:13], v[68:69]
	v_pk_add_f32 v[10:11], v[10:11], v[66:67]
	v_pk_add_f32 v[8:9], v[8:9], v[64:65]
	v_mul_f32_e32 v12, 0xbfb8aa3b, v12
	v_mul_f32_e32 v8, 0xbfb8aa3b, v8
	v_mul_f32_e32 v13, 0xbfb8aa3b, v13
	v_mul_f32_e32 v9, 0xbfb8aa3b, v9
	v_mul_f32_e32 v14, 0xbfb8aa3b, v14
	v_mul_f32_e32 v10, 0xbfb8aa3b, v10
	v_mul_f32_e32 v15, 0xbfb8aa3b, v15
	v_mul_f32_e32 v11, 0xbfb8aa3b, v11
	v_exp_f32_e32 v12, v12
	v_exp_f32_e32 v8, v8
	v_exp_f32_e32 v13, v13
	v_exp_f32_e32 v9, v9
	v_exp_f32_e32 v14, v14
	v_exp_f32_e32 v10, v10
	v_exp_f32_e32 v15, v15
	v_exp_f32_e32 v11, v11
	v_add_f32_e32 v12, 1.0, v12
	v_add_f32_e32 v8, 1.0, v8
	v_add_f32_e32 v13, 1.0, v13
	v_add_f32_e32 v9, 1.0, v9
	v_add_f32_e32 v14, 1.0, v14
	v_add_f32_e32 v10, 1.0, v10
	v_add_f32_e32 v15, 1.0, v15
	v_add_f32_e32 v11, 1.0, v11
	v_rcp_f32_e32 v12, v12
	v_rcp_f32_e32 v8, v8
	v_rcp_f32_e32 v13, v13
	v_rcp_f32_e32 v9, v9
	v_rcp_f32_e32 v14, v14
	v_rcp_f32_e32 v10, v10
	v_rcp_f32_e32 v15, v15
	v_rcp_f32_e32 v11, v11
	v_pk_add_f32 v[6:7], v[6:7], v[70:71]
	v_pk_add_f32 v[4:5], v[4:5], v[68:69]
	v_pk_add_f32 v[2:3], v[2:3], v[66:67]
	v_pk_add_f32 v[0:1], v[0:1], v[64:65]
	v_mul_f32_e32 v4, 0xbfb8aa3b, v4
	v_mul_f32_e32 v0, 0xbfb8aa3b, v0
	v_mul_f32_e32 v5, 0xbfb8aa3b, v5
	v_mul_f32_e32 v1, 0xbfb8aa3b, v1
	v_mul_f32_e32 v6, 0xbfb8aa3b, v6
	s_waitcnt vmcnt(0)
; __device__ __forceinline__ float sigm(float x) { return __builtin_amdgcn_rcpf(1.f + __builtin_amdgcn_exp2f(-1.4426950409f * x)); }
; __device__ __forceinline__ u32x4 pack8(const f32x4 v0, const f32x4 v1) { u32x4 w; w.x = cvt_pk_bf16(v0[0], v0[1]); w.y = cvt_pk_bf16(v0[2], v0[3]); w.z = cvt_pk_bf16(v1[0], v1[1]); w.w = cvt_pk_bf16(v1[2], v1[3]); return w; }
; __device__ __forceinline__ void unpack8(const u32x4 w, f32x4& lo, f32x4& hi) { lo = (f32x4){bf_lo(w.x), bf_hi(w.x), bf_lo(w.y), bf_hi(w.y)}; hi = (f32x4){bf_lo(w.z), bf_hi(w.z), bf_lo(w.w), bf_hi(w.w)}; }
;     __device__ __forceinline__ void operator()(AccT& acc, const Unit& u, int wr, int wc, int fr, int fq) const {
;     ...
;         if (u.kind == 0) {
; #pragma unroll
;             for (int bj = 0; bj < 2; ++bj) { const f32x4 b0 = *(const f32x4*)(glu_b + col0 + bj * 128), b1 = *(const f32x4*)(glu_b + col0 + bj * 128 + 4);
; #pragma unroll
;                 for (int ai = 0; ai < 2; ++ai)
; #pragma unroll
;                     for (int m = 0; m < 4; ++m) { const size_t off = (size_t)(row0 + ai * 128 + m * 16) * DSS + col0 + bj * 128;
;                         f32x4 y0, y1; unpack8(*(const u32x4*)(YG + off), y0, y1);
;                         f32x4 v0 = acc[ai][bj][m][0] + b0, v1 = acc[ai][bj][m][1] + b1;
; #pragma unroll
;                         for (int j = 0; j < 4; ++j) { v0[j] = y0[j] * sigm(v0[j]); v1[j] = y1[j] * sigm(v1[j]); }
;                         *(u32x4*)(YS + off) = pack8(v0, v1); } }
	v_lshlrev_b32_e32 v50, 16, v40
	v_and_b32_e32 v40, 0xffff0000, v40
	v_lshlrev_b32_e32 v51, 16, v41
	v_and_b32_e32 v41, 0xffff0000, v41
	v_lshlrev_b32_e32 v52, 16, v42
	v_and_b32_e32 v42, 0xffff0000, v42
	v_lshlrev_b32_e32 v53, 16, v43
	v_and_b32_e32 v43, 0xffff0000, v43
	v_mul_f32_e32 v36, v36, v50
	v_mul_f32_e32 v50, v32, v52
	v_mul_f32_e32 v32, v37, v40
	v_mul_f32_e32 v37, v33, v42
	v_mul_f32_e32 v33, v38, v51
	v_mul_f32_e32 v38, v34, v53
	v_mul_f32_e32 v34, v39, v41
	v_mul_f32_e32 v35, v35, v43
	v_cvt_pk_bf16_f32 v32, v36, v32
	v_cvt_pk_bf16_f32 v33, v33, v34
	v_cvt_pk_bf16_f32 v34, v50, v37
	v_cvt_pk_bf16_f32 v35, v38, v35
	global_store_dwordx4 v[46:47], v[32:35], off nt
	global_load_dwordx4 v[32:35], v[48:49], off
	v_lshl_add_u64 v[36:37], v[148:149], 0, v[100:101]
	v_lshl_add_u64 v[38:39], s[26:27], 0, v[44:45]
	v_lshlrev_b64 v[36:37], 1, v[36:37]
	v_lshl_add_u64 v[40:41], s[14:15], 0, v[36:37]
	v_mul_f32_e32 v2, 0xbfb8aa3b, v2
	v_mul_f32_e32 v7, 0xbfb8aa3b, v7
	v_mul_f32_e32 v3, 0xbfb8aa3b, v3
	v_exp_f32_e32 v4, v4
	v_exp_f32_e32 v0, v0
	v_exp_f32_e32 v5, v5
	v_exp_f32_e32 v1, v1
	v_exp_f32_e32 v6, v6
	v_exp_f32_e32 v2, v2
	v_exp_f32_e32 v7, v7
	v_exp_f32_e32 v3, v3
	v_add_f32_e32 v4, 1.0, v4
	v_add_f32_e32 v0, 1.0, v0
	v_add_f32_e32 v5, 1.0, v5
	v_add_f32_e32 v1, 1.0, v1
	v_add_f32_e32 v6, 1.0, v6
	v_add_f32_e32 v2, 1.0, v2
	v_add_f32_e32 v7, 1.0, v7
	v_add_f32_e32 v3, 1.0, v3
	v_rcp_f32_e32 v4, v4
	v_rcp_f32_e32 v0, v0
	v_rcp_f32_e32 v5, v5
	v_rcp_f32_e32 v1, v1
	v_rcp_f32_e32 v6, v6
	v_rcp_f32_e32 v2, v2
	v_rcp_f32_e32 v7, v7
	v_rcp_f32_e32 v3, v3
	s_waitcnt vmcnt(0)
	v_lshlrev_b32_e32 v42, 16, v32
	v_and_b32_e32 v32, 0xffff0000, v32
	v_lshlrev_b32_e32 v43, 16, v33
	v_and_b32_e32 v33, 0xffff0000, v33
	v_lshlrev_b32_e32 v44, 16, v34
	v_and_b32_e32 v34, 0xffff0000, v34
	v_lshlrev_b32_e32 v45, 16, v35
	v_and_b32_e32 v35, 0xffff0000, v35
	v_mul_f32_e32 v28, v28, v42
	v_mul_f32_e32 v42, v24, v44
	v_mul_f32_e32 v24, v29, v32
	v_mul_f32_e32 v29, v25, v34
	v_mul_f32_e32 v25, v30, v43
	v_mul_f32_e32 v30, v26, v45
	v_mul_f32_e32 v26, v31, v33
	v_mul_f32_e32 v27, v27, v35
	v_cvt_pk_bf16_f32 v24, v28, v24
	v_cvt_pk_bf16_f32 v25, v25, v26
	v_cvt_pk_bf16_f32 v26, v42, v29
	v_cvt_pk_bf16_f32 v27, v30, v27
	global_store_dwordx4 v[38:39], v[24:27], off nt
	global_load_dwordx4 v[24:27], v[40:41], off
	v_lshl_add_u64 v[28:29], v[148:149], 0, v[92:93]
	v_lshl_add_u64 v[30:31], s[26:27], 0, v[36:37]
	v_lshlrev_b64 v[28:29], 1, v[28:29]
	v_lshl_add_u64 v[32:33], s[14:15], 0, v[28:29]
	s_waitcnt vmcnt(0)
	v_lshlrev_b32_e32 v34, 16, v24
	v_and_b32_e32 v24, 0xffff0000, v24
	v_lshlrev_b32_e32 v35, 16, v25
	v_and_b32_e32 v25, 0xffff0000, v25
	v_lshlrev_b32_e32 v36, 16, v26
	v_and_b32_e32 v26, 0xffff0000, v26
	v_lshlrev_b32_e32 v37, 16, v27
	v_and_b32_e32 v27, 0xffff0000, v27
	v_mul_f32_e32 v20, v20, v34
	v_mul_f32_e32 v34, v16, v36
	v_mul_f32_e32 v16, v21, v24
	v_mul_f32_e32 v21, v17, v26
	v_mul_f32_e32 v17, v22, v35
	v_mul_f32_e32 v22, v18, v37
	v_mul_f32_e32 v18, v23, v25
	v_mul_f32_e32 v19, v19, v27
	v_cvt_pk_bf16_f32 v16, v20, v16
	v_cvt_pk_bf16_f32 v17, v17, v18
	v_cvt_pk_bf16_f32 v18, v34, v21
	v_cvt_pk_bf16_f32 v19, v22, v19
	global_store_dwordx4 v[30:31], v[16:19], off nt
	global_load_dwordx4 v[16:19], v[32:33], off
	v_lshl_add_u64 v[20:21], v[148:149], 0, v[84:85]
	v_lshl_add_u64 v[22:23], s[26:27], 0, v[28:29]
	v_lshlrev_b64 v[20:21], 1, v[20:21]
	v_lshl_add_u64 v[24:25], s[14:15], 0, v[20:21]
	s_waitcnt vmcnt(0)
	v_lshlrev_b32_e32 v26, 16, v16
	v_and_b32_e32 v16, 0xffff0000, v16
	v_lshlrev_b32_e32 v27, 16, v17
	v_and_b32_e32 v17, 0xffff0000, v17
	v_lshlrev_b32_e32 v28, 16, v18
	v_and_b32_e32 v18, 0xffff0000, v18
	v_lshlrev_b32_e32 v29, 16, v19
	v_and_b32_e32 v19, 0xffff0000, v19
	v_mul_f32_e32 v12, v12, v26
	v_mul_f32_e32 v26, v8, v28
	v_mul_f32_e32 v8, v13, v16
	v_mul_f32_e32 v13, v9, v18
	v_mul_f32_e32 v9, v14, v27
	v_mul_f32_e32 v14, v10, v29
	v_mul_f32_e32 v10, v15, v17
	v_mul_f32_e32 v11, v11, v19
	v_cvt_pk_bf16_f32 v8, v12, v8
	v_cvt_pk_bf16_f32 v9, v9, v10
	v_cvt_pk_bf16_f32 v10, v26, v13
	v_cvt_pk_bf16_f32 v11, v14, v11
	global_store_dwordx4 v[22:23], v[8:11], off nt
	global_load_dwordx4 v[8:11], v[24:25], off
	s_waitcnt vmcnt(0)
	v_lshlrev_b32_e32 v12, 16, v8
	v_and_b32_e32 v8, 0xffff0000, v8
	v_lshlrev_b32_e32 v13, 16, v9
	v_and_b32_e32 v9, 0xffff0000, v9
	v_lshlrev_b32_e32 v14, 16, v10
	v_and_b32_e32 v10, 0xffff0000, v10
	v_lshlrev_b32_e32 v15, 16, v11
	v_and_b32_e32 v11, 0xffff0000, v11
	v_mul_f32_e32 v4, v4, v12
	v_mul_f32_e32 v12, v0, v14
	v_mul_f32_e32 v0, v5, v8
	v_mul_f32_e32 v5, v1, v10
	v_mul_f32_e32 v1, v6, v13
	v_mul_f32_e32 v6, v2, v15
	v_mul_f32_e32 v2, v7, v9
	v_mul_f32_e32 v3, v3, v11
	v_cvt_pk_bf16_f32 v0, v4, v0
	v_cvt_pk_bf16_f32 v1, v1, v2
	v_cvt_pk_bf16_f32 v2, v12, v5
	v_lshl_add_u64 v[4:5], s[26:27], 0, v[20:21]
	v_cvt_pk_bf16_f32 v3, v6, v3
	global_store_dwordx4 v[4:5], v[0:3], off nt

; __device__ __forceinline__ u32x4 pack8(const f32x4 v0, const f32x4 v1) { u32x4 w; w.x = cvt_pk_bf16(v0[0], v0[1]); w.y = cvt_pk_bf16(v0[2], v0[3]); w.z = cvt_pk_bf16(v1[0], v1[1]); w.w = cvt_pk_bf16(v1[2], v1[3]); return w; }
; __device__ __forceinline__ void unpack8(const u32x4 w, f32x4& lo, f32x4& hi) { lo = (f32x4){bf_lo(w.x), bf_hi(w.x), bf_lo(w.y), bf_hi(w.y)}; hi = (f32x4){bf_lo(w.z), bf_hi(w.z), bf_lo(w.w), bf_hi(w.w)}; }
;     __device__ __forceinline__ void operator()(AccT& acc, const Unit& u, int wr, int wc, int fr, int fq) const {
;         const int row0 = u.pm * 256 + wr * 64 + fr, col0 = u.pn * 256 + wc * 32 + 8 * fq;
;         constexpr float TINY = 1e-30f;
; #pragma unroll
;         for (int ai = 0; ai < 2; ++ai)
; #pragma unroll
;             for (int m = 0; m < 4; ++m) { const size_t row = (size_t)(row0 + ai * 128 + m * 16);
; #pragma unroll
;                 for (int bj = 0; bj < 2; ++bj) { f32x4 p0, p1; unpack8(*(const u32x4*)(PROJ + row * DIN + 8192 + col0 + bj * 128), p0, p1);
; #pragma unroll
;                     for (int j = 0; j < 4; ++j) { p0[j] = fmaxf(p0[j], TINY); p1[j] = fmaxf(p1[j], TINY); }
;                     if (u.kind == 0) { f32x4 s0, s1; unpack8(*(const u32x4*)(PROJ + row * DIN + 4096 + col0 + bj * 128), s0, s1);
; #pragma unroll
;                         for (int j = 0; j < 4; ++j) { acc[ai][bj][m][0][j] *= s0[j] * __builtin_amdgcn_rcpf(p0[j]); acc[ai][bj][m][1][j] *= s1[j] * __builtin_amdgcn_rcpf(p1[j]); } }
;                     else *(u32x4*)(MG + row * DM + col0 + bj * 128) = pack8(acc[ai][bj][m][0] * p0, acc[ai][bj][m][1] * p1); } }
.LBB0_488:
	v_mov_b32_e32 v133, v254
	s_lshl_b32 s4, s66, 8
	v_lshrrev_b32_e32 v132, 1, v133
	v_and_or_b32 v132, v132, 24, s4
	v_and_or_b32 v133, v133, 15, s83
	v_or_b32_e32 v132, s84, v132
	v_lshl_add_u32 v134, s3, 8, v133
	v_mov_b64_e32 v[136:137], s[20:21]
	v_ashrrev_i32_e32 v133, 31, v132
	v_mad_i64_i32 v[136:137], s[4:5], v134, s78, v[136:137]
	v_lshl_add_u64 v[136:137], v[132:133], 1, v[136:137]
	v_add_co_u32_e32 v138, vcc, s77, v136
	v_ashrrev_i32_e32 v135, 31, v134
	s_nop 0
	v_addc_co_u32_e32 v139, vcc, 0, v137, vcc
	global_load_dwordx4 v[140:143], v[138:139], off
	s_cmp_lg_u32 s8, 0
	v_lshlrev_b64 v[138:139], 13, v[134:135]
	s_cselect_b64 s[16:17], -1, 0
	v_lshl_add_u64 v[138:139], s[26:27], 0, v[138:139]
	s_and_b64 vcc, exec, s[16:17]
	v_lshl_add_u64 v[138:139], v[132:133], 1, v[138:139]
	s_waitcnt vmcnt(0)
	v_lshlrev_b32_e32 v135, 16, v140
	v_and_b32_e32 v140, 0xffff0000, v140
	v_lshlrev_b32_e32 v144, 16, v141
	v_and_b32_e32 v141, 0xffff0000, v141
	v_lshlrev_b32_e32 v145, 16, v142
	v_and_b32_e32 v142, 0xffff0000, v142
	v_lshlrev_b32_e32 v146, 16, v143
	v_and_b32_e32 v143, 0xffff0000, v143
	v_max_f32_e32 v135, v135, v135
	v_max_f32_e32 v145, v145, v145
	v_max_f32_e32 v140, v140, v140
	v_max_f32_e32 v142, v142, v142
	v_max_f32_e32 v154, v144, v144
	v_max_f32_e32 v155, v146, v146
	v_max_f32_e32 v141, v141, v141
	v_max_f32_e32 v156, v143, v143
	v_max_f32_e32 v146, 0xda24260, v135
	v_max_f32_e32 v144, 0xda24260, v145
	v_max_f32_e32 v147, 0xda24260, v140
	v_max_f32_e32 v145, 0xda24260, v142
	v_max_f32_e32 v142, 0xda24260, v154
	v_max_f32_e32 v140, 0xda24260, v155
	v_max_f32_e32 v143, 0xda24260, v141
	v_max_f32_e32 v141, 0xda24260, v156
	s_cbranch_vccz .LBB0_541
	v_pk_mul_f32 v[156:157], v[126:127], v[142:143]
	v_pk_mul_f32 v[154:155], v[124:125], v[146:147]
	v_pk_mul_f32 v[158:159], v[122:123], v[140:141]
	v_pk_mul_f32 v[160:161], v[120:121], v[144:145]
	v_cvt_pk_bf16_f32 v154, v154, v155
	v_cvt_pk_bf16_f32 v155, v156, v157
	s_nop 0
	v_cvt_pk_bf16_f32 v156, v160, v161
	v_cvt_pk_bf16_f32 v157, v158, v159
	global_store_dwordx4 v[138:139], v[154:157], off nt
	s_cbranch_execnz .LBB0_491

; __device__ __forceinline__ u32x4 pack8(const f32x4 v0, const f32x4 v1) { u32x4 w; w.x = cvt_pk_bf16(v0[0], v0[1]); w.y = cvt_pk_bf16(v0[2], v0[3]); w.z = cvt_pk_bf16(v1[0], v1[1]); w.w = cvt_pk_bf16(v1[2], v1[3]); return w; }
; __device__ __forceinline__ void unpack8(const u32x4 w, f32x4& lo, f32x4& hi) { lo = (f32x4){bf_lo(w.x), bf_hi(w.x), bf_lo(w.y), bf_hi(w.y)}; hi = (f32x4){bf_lo(w.z), bf_hi(w.z), bf_lo(w.w), bf_hi(w.w)}; }
;     __device__ __forceinline__ void operator()(AccT& acc, const Unit& u, int wr, int wc, int fr, int fq) const {
;     ...
;             for (int m = 0; m < 4; ++m) { const size_t row = (size_t)(row0 + ai * 128 + m * 16);
; #pragma unroll
;                 for (int bj = 0; bj < 2; ++bj) { f32x4 p0, p1; unpack8(*(const u32x4*)(PROJ + row * DIN + 8192 + col0 + bj * 128), p0, p1);
; #pragma unroll
;                     for (int j = 0; j < 4; ++j) { p0[j] = fmaxf(p0[j], TINY); p1[j] = fmaxf(p1[j], TINY); }
;                     if (u.kind == 0) { f32x4 s0, s1; unpack8(*(const u32x4*)(PROJ + row * DIN + 4096 + col0 + bj * 128), s0, s1);
; #pragma unroll
;                         for (int j = 0; j < 4; ++j) { acc[ai][bj][m][0][j] *= s0[j] * __builtin_amdgcn_rcpf(p0[j]); acc[ai][bj][m][1][j] *= s1[j] * __builtin_amdgcn_rcpf(p1[j]); } }
;                     else *(u32x4*)(MG + row * DM + col0 + bj * 128) = pack8(acc[ai][bj][m][0] * p0, acc[ai][bj][m][1] * p1); } }
.LBB0_491:
	v_add_co_u32_e32 v140, vcc, 0x4000, v136
	v_cndmask_b32_e64 v135, 0, 1, s[16:17]
	s_nop 0
	v_addc_co_u32_e32 v141, vcc, 0, v137, vcc
	global_load_dwordx4 v[140:143], v[140:141], off offset:256
	v_cmp_ne_u32_e64 s[4:5], 1, v135
	s_andn2_b64 vcc, exec, s[16:17]
	s_waitcnt vmcnt(0)
	v_lshlrev_b32_e32 v135, 16, v140
	v_and_b32_e32 v140, 0xffff0000, v140
	v_lshlrev_b32_e32 v144, 16, v141
	v_and_b32_e32 v141, 0xffff0000, v141
	v_lshlrev_b32_e32 v145, 16, v142
	v_and_b32_e32 v142, 0xffff0000, v142
	v_lshlrev_b32_e32 v146, 16, v143
	v_and_b32_e32 v143, 0xffff0000, v143
	v_max_f32_e32 v135, v135, v135
	v_max_f32_e32 v145, v145, v145
	v_max_f32_e32 v140, v140, v140
	v_max_f32_e32 v142, v142, v142
	v_max_f32_e32 v154, v144, v144
	v_max_f32_e32 v155, v146, v146
	v_max_f32_e32 v141, v141, v141
	v_max_f32_e32 v156, v143, v143
	v_max_f32_e32 v146, 0xda24260, v135
	v_max_f32_e32 v144, 0xda24260, v145
	v_max_f32_e32 v147, 0xda24260, v140
	v_max_f32_e32 v145, 0xda24260, v142
	v_max_f32_e32 v142, 0xda24260, v154
	v_max_f32_e32 v140, 0xda24260, v155
	v_max_f32_e32 v143, 0xda24260, v141
	v_max_f32_e32 v141, 0xda24260, v156
	s_cbranch_vccnz .LBB0_542
	v_pk_mul_f32 v[156:157], v[94:95], v[142:143]
	v_pk_mul_f32 v[154:155], v[92:93], v[146:147]
	v_pk_mul_f32 v[158:159], v[90:91], v[140:141]
	v_pk_mul_f32 v[160:161], v[88:89], v[144:145]
	v_cvt_pk_bf16_f32 v154, v154, v155
	v_cvt_pk_bf16_f32 v155, v156, v157
	s_nop 0
	v_cvt_pk_bf16_f32 v156, v160, v161
	v_cvt_pk_bf16_f32 v157, v158, v159
	global_store_dwordx4 v[138:139], v[154:157], off offset:256 nt
	s_cbranch_execnz .LBB0_494

; __device__ __forceinline__ u32x4 pack8(const f32x4 v0, const f32x4 v1) { u32x4 w; w.x = cvt_pk_bf16(v0[0], v0[1]); w.y = cvt_pk_bf16(v0[2], v0[3]); w.z = cvt_pk_bf16(v1[0], v1[1]); w.w = cvt_pk_bf16(v1[2], v1[3]); return w; }
; __device__ __forceinline__ void unpack8(const u32x4 w, f32x4& lo, f32x4& hi) { lo = (f32x4){bf_lo(w.x), bf_hi(w.x), bf_lo(w.y), bf_hi(w.y)}; hi = (f32x4){bf_lo(w.z), bf_hi(w.z), bf_lo(w.w), bf_hi(w.w)}; }
;     __device__ __forceinline__ void operator()(AccT& acc, const Unit& u, int wr, int wc, int fr, int fq) const {
;     ...
;             for (int m = 0; m < 4; ++m) { const size_t row = (size_t)(row0 + ai * 128 + m * 16);
; #pragma unroll
;                 for (int bj = 0; bj < 2; ++bj) { f32x4 p0, p1; unpack8(*(const u32x4*)(PROJ + row * DIN + 8192 + col0 + bj * 128), p0, p1);
; #pragma unroll
;                     for (int j = 0; j < 4; ++j) { p0[j] = fmaxf(p0[j], TINY); p1[j] = fmaxf(p1[j], TINY); }
;                     if (u.kind == 0) { f32x4 s0, s1; unpack8(*(const u32x4*)(PROJ + row * DIN + 4096 + col0 + bj * 128), s0, s1);
; #pragma unroll
;                         for (int j = 0; j < 4; ++j) { acc[ai][bj][m][0][j] *= s0[j] * __builtin_amdgcn_rcpf(p0[j]); acc[ai][bj][m][1][j] *= s1[j] * __builtin_amdgcn_rcpf(p1[j]); } }
;                     else *(u32x4*)(MG + row * DM + col0 + bj * 128) = pack8(acc[ai][bj][m][0] * p0, acc[ai][bj][m][1] * p1); } }
.LBB0_494:
	v_or_b32_e32 v142, 16, v134
	v_mov_b64_e32 v[136:137], s[20:21]
	v_mad_i64_i32 v[136:137], s[8:9], v142, s78, v[136:137]
	v_lshl_add_u64 v[136:137], v[132:133], 1, v[136:137]
	v_add_co_u32_e32 v138, vcc, 0x4000, v136
	v_ashrrev_i32_e32 v143, 31, v142
	s_nop 0
	v_addc_co_u32_e32 v139, vcc, 0, v137, vcc
	global_load_dwordx4 v[138:141], v[138:139], off
	v_lshlrev_b64 v[142:143], 13, v[142:143]
	v_lshl_add_u64 v[154:155], s[26:27], 0, v[142:143]
	s_and_b64 vcc, exec, s[4:5]
	s_waitcnt vmcnt(0)
	v_lshlrev_b32_e32 v135, 16, v138
	v_and_b32_e32 v138, 0xffff0000, v138
	v_lshlrev_b32_e32 v142, 16, v139
	v_and_b32_e32 v139, 0xffff0000, v139
	v_lshlrev_b32_e32 v143, 16, v140
	v_and_b32_e32 v140, 0xffff0000, v140
	v_lshlrev_b32_e32 v144, 16, v141
	v_and_b32_e32 v141, 0xffff0000, v141
	v_max_f32_e32 v135, v135, v135
	v_max_f32_e32 v143, v143, v143
	v_max_f32_e32 v138, v138, v138
	v_max_f32_e32 v140, v140, v140
	v_max_f32_e32 v142, v142, v142
	v_max_f32_e32 v156, v144, v144
	v_max_f32_e32 v139, v139, v139
	v_max_f32_e32 v141, v141, v141
	v_max_f32_e32 v146, 0xda24260, v135
	v_max_f32_e32 v144, 0xda24260, v143
	v_max_f32_e32 v147, 0xda24260, v138
	v_max_f32_e32 v145, 0xda24260, v140
	v_max_f32_e32 v142, 0xda24260, v142
	v_max_f32_e32 v140, 0xda24260, v156
	v_max_f32_e32 v143, 0xda24260, v139
	v_max_f32_e32 v141, 0xda24260, v141
	v_lshl_add_u64 v[138:139], v[132:133], 1, v[154:155]
	s_cbranch_vccnz .LBB0_543
	v_pk_mul_f32 v[156:157], v[118:119], v[142:143]
	v_pk_mul_f32 v[154:155], v[116:117], v[146:147]
	v_pk_mul_f32 v[158:159], v[114:115], v[140:141]
	v_pk_mul_f32 v[160:161], v[112:113], v[144:145]
	v_cvt_pk_bf16_f32 v154, v154, v155
	v_cvt_pk_bf16_f32 v155, v156, v157
	s_nop 0
	v_cvt_pk_bf16_f32 v156, v160, v161
	v_cvt_pk_bf16_f32 v157, v158, v159
	global_store_dwordx4 v[138:139], v[154:157], off nt
	s_cbranch_execnz .LBB0_497

; __device__ __forceinline__ u32x4 pack8(const f32x4 v0, const f32x4 v1) { u32x4 w; w.x = cvt_pk_bf16(v0[0], v0[1]); w.y = cvt_pk_bf16(v0[2], v0[3]); w.z = cvt_pk_bf16(v1[0], v1[1]); w.w = cvt_pk_bf16(v1[2], v1[3]); return w; }
; __device__ __forceinline__ void unpack8(const u32x4 w, f32x4& lo, f32x4& hi) { lo = (f32x4){bf_lo(w.x), bf_hi(w.x), bf_lo(w.y), bf_hi(w.y)}; hi = (f32x4){bf_lo(w.z), bf_hi(w.z), bf_lo(w.w), bf_hi(w.w)}; }
;     __device__ __forceinline__ void operator()(AccT& acc, const Unit& u, int wr, int wc, int fr, int fq) const {
;     ...
;             for (int m = 0; m < 4; ++m) { const size_t row = (size_t)(row0 + ai * 128 + m * 16);
; #pragma unroll
;                 for (int bj = 0; bj < 2; ++bj) { f32x4 p0, p1; unpack8(*(const u32x4*)(PROJ + row * DIN + 8192 + col0 + bj * 128), p0, p1);
; #pragma unroll
;                     for (int j = 0; j < 4; ++j) { p0[j] = fmaxf(p0[j], TINY); p1[j] = fmaxf(p1[j], TINY); }
;                     if (u.kind == 0) { f32x4 s0, s1; unpack8(*(const u32x4*)(PROJ + row * DIN + 4096 + col0 + bj * 128), s0, s1);
; #pragma unroll
;                         for (int j = 0; j < 4; ++j) { acc[ai][bj][m][0][j] *= s0[j] * __builtin_amdgcn_rcpf(p0[j]); acc[ai][bj][m][1][j] *= s1[j] * __builtin_amdgcn_rcpf(p1[j]); } }
;                     else *(u32x4*)(MG + row * DM + col0 + bj * 128) = pack8(acc[ai][bj][m][0] * p0, acc[ai][bj][m][1] * p1); } }
.LBB0_497:
	v_add_co_u32_e32 v140, vcc, 0x4000, v136
	s_nop 1
	v_addc_co_u32_e32 v141, vcc, 0, v137, vcc
	global_load_dwordx4 v[140:143], v[140:141], off offset:256
	s_and_b64 vcc, exec, s[4:5]
	s_waitcnt vmcnt(0)
	v_lshlrev_b32_e32 v135, 16, v140
	v_and_b32_e32 v140, 0xffff0000, v140
	v_lshlrev_b32_e32 v144, 16, v141
	v_and_b32_e32 v141, 0xffff0000, v141
	v_lshlrev_b32_e32 v145, 16, v142
	v_and_b32_e32 v142, 0xffff0000, v142
	v_lshlrev_b32_e32 v146, 16, v143
	v_and_b32_e32 v143, 0xffff0000, v143
	v_max_f32_e32 v135, v135, v135
	v_max_f32_e32 v145, v145, v145
	v_max_f32_e32 v140, v140, v140
	v_max_f32_e32 v142, v142, v142
	v_max_f32_e32 v154, v144, v144
	v_max_f32_e32 v155, v146, v146
	v_max_f32_e32 v141, v141, v141
	v_max_f32_e32 v156, v143, v143
	v_max_f32_e32 v146, 0xda24260, v135
	v_max_f32_e32 v144, 0xda24260, v145
	v_max_f32_e32 v147, 0xda24260, v140
	v_max_f32_e32 v145, 0xda24260, v142
	v_max_f32_e32 v142, 0xda24260, v154
	v_max_f32_e32 v140, 0xda24260, v155
	v_max_f32_e32 v143, 0xda24260, v141
	v_max_f32_e32 v141, 0xda24260, v156
	s_cbranch_vccnz .LBB0_544
	v_pk_mul_f32 v[156:157], v[86:87], v[142:143]
	v_pk_mul_f32 v[154:155], v[84:85], v[146:147]
	v_pk_mul_f32 v[158:159], v[82:83], v[140:141]
	v_pk_mul_f32 v[160:161], v[80:81], v[144:145]
	v_cvt_pk_bf16_f32 v154, v154, v155
	v_cvt_pk_bf16_f32 v155, v156, v157
	s_nop 0
	v_cvt_pk_bf16_f32 v156, v160, v161
	v_cvt_pk_bf16_f32 v157, v158, v159
	global_store_dwordx4 v[138:139], v[154:157], off offset:256 nt
	s_cbranch_execnz .LBB0_500

; __device__ __forceinline__ u32x4 pack8(const f32x4 v0, const f32x4 v1) { u32x4 w; w.x = cvt_pk_bf16(v0[0], v0[1]); w.y = cvt_pk_bf16(v0[2], v0[3]); w.z = cvt_pk_bf16(v1[0], v1[1]); w.w = cvt_pk_bf16(v1[2], v1[3]); return w; }
; __device__ __forceinline__ void unpack8(const u32x4 w, f32x4& lo, f32x4& hi) { lo = (f32x4){bf_lo(w.x), bf_hi(w.x), bf_lo(w.y), bf_hi(w.y)}; hi = (f32x4){bf_lo(w.z), bf_hi(w.z), bf_lo(w.w), bf_hi(w.w)}; }
;     __device__ __forceinline__ void operator()(AccT& acc, const Unit& u, int wr, int wc, int fr, int fq) const {
;     ...
;             for (int m = 0; m < 4; ++m) { const size_t row = (size_t)(row0 + ai * 128 + m * 16);
; #pragma unroll
;                 for (int bj = 0; bj < 2; ++bj) { f32x4 p0, p1; unpack8(*(const u32x4*)(PROJ + row * DIN + 8192 + col0 + bj * 128), p0, p1);
; #pragma unroll
;                     for (int j = 0; j < 4; ++j) { p0[j] = fmaxf(p0[j], TINY); p1[j] = fmaxf(p1[j], TINY); }
;                     if (u.kind == 0) { f32x4 s0, s1; unpack8(*(const u32x4*)(PROJ + row * DIN + 4096 + col0 + bj * 128), s0, s1);
; #pragma unroll
;                         for (int j = 0; j < 4; ++j) { acc[ai][bj][m][0][j] *= s0[j] * __builtin_amdgcn_rcpf(p0[j]); acc[ai][bj][m][1][j] *= s1[j] * __builtin_amdgcn_rcpf(p1[j]); } }
;                     else *(u32x4*)(MG + row * DM + col0 + bj * 128) = pack8(acc[ai][bj][m][0] * p0, acc[ai][bj][m][1] * p1); } }
.LBB0_500:
	v_or_b32_e32 v142, 32, v134
	v_mov_b64_e32 v[136:137], s[20:21]
	v_mad_i64_i32 v[136:137], s[8:9], v142, s78, v[136:137]
	v_lshl_add_u64 v[136:137], v[132:133], 1, v[136:137]
	v_add_co_u32_e32 v138, vcc, 0x4000, v136
	v_ashrrev_i32_e32 v143, 31, v142
	s_nop 0
	v_addc_co_u32_e32 v139, vcc, 0, v137, vcc
	global_load_dwordx4 v[138:141], v[138:139], off
	v_lshlrev_b64 v[142:143], 13, v[142:143]
	v_lshl_add_u64 v[154:155], s[26:27], 0, v[142:143]
	s_and_b64 vcc, exec, s[4:5]
	s_waitcnt vmcnt(0)
	v_lshlrev_b32_e32 v135, 16, v138
	v_and_b32_e32 v138, 0xffff0000, v138
	v_lshlrev_b32_e32 v142, 16, v139
	v_and_b32_e32 v139, 0xffff0000, v139
	v_lshlrev_b32_e32 v143, 16, v140
	v_and_b32_e32 v140, 0xffff0000, v140
	v_lshlrev_b32_e32 v144, 16, v141
	v_and_b32_e32 v141, 0xffff0000, v141
	v_max_f32_e32 v135, v135, v135
	v_max_f32_e32 v143, v143, v143
	v_max_f32_e32 v138, v138, v138
	v_max_f32_e32 v140, v140, v140
	v_max_f32_e32 v142, v142, v142
	v_max_f32_e32 v156, v144, v144
	v_max_f32_e32 v139, v139, v139
	v_max_f32_e32 v141, v141, v141
	v_max_f32_e32 v146, 0xda24260, v135
	v_max_f32_e32 v144, 0xda24260, v143
	v_max_f32_e32 v147, 0xda24260, v138
	v_max_f32_e32 v145, 0xda24260, v140
	v_max_f32_e32 v142, 0xda24260, v142
	v_max_f32_e32 v140, 0xda24260, v156
	v_max_f32_e32 v143, 0xda24260, v139
	v_max_f32_e32 v141, 0xda24260, v141
	v_lshl_add_u64 v[138:139], v[132:133], 1, v[154:155]
	s_cbranch_vccnz .LBB0_545
	v_pk_mul_f32 v[156:157], v[110:111], v[142:143]
	v_pk_mul_f32 v[154:155], v[108:109], v[146:147]
	v_pk_mul_f32 v[158:159], v[106:107], v[140:141]
	v_pk_mul_f32 v[160:161], v[104:105], v[144:145]
	v_cvt_pk_bf16_f32 v154, v154, v155
	v_cvt_pk_bf16_f32 v155, v156, v157
	s_nop 0
	v_cvt_pk_bf16_f32 v156, v160, v161
	v_cvt_pk_bf16_f32 v157, v158, v159
	global_store_dwordx4 v[138:139], v[154:157], off nt
	s_cbranch_execnz .LBB0_503

; __device__ __forceinline__ u32x4 pack8(const f32x4 v0, const f32x4 v1) { u32x4 w; w.x = cvt_pk_bf16(v0[0], v0[1]); w.y = cvt_pk_bf16(v0[2], v0[3]); w.z = cvt_pk_bf16(v1[0], v1[1]); w.w = cvt_pk_bf16(v1[2], v1[3]); return w; }
; __device__ __forceinline__ void unpack8(const u32x4 w, f32x4& lo, f32x4& hi) { lo = (f32x4){bf_lo(w.x), bf_hi(w.x), bf_lo(w.y), bf_hi(w.y)}; hi = (f32x4){bf_lo(w.z), bf_hi(w.z), bf_lo(w.w), bf_hi(w.w)}; }
;     __device__ __forceinline__ void operator()(AccT& acc, const Unit& u, int wr, int wc, int fr, int fq) const {
;     ...
;             for (int m = 0; m < 4; ++m) { const size_t row = (size_t)(row0 + ai * 128 + m * 16);
; #pragma unroll
;                 for (int bj = 0; bj < 2; ++bj) { f32x4 p0, p1; unpack8(*(const u32x4*)(PROJ + row * DIN + 8192 + col0 + bj * 128), p0, p1);
; #pragma unroll
;                     for (int j = 0; j < 4; ++j) { p0[j] = fmaxf(p0[j], TINY); p1[j] = fmaxf(p1[j], TINY); }
;                     if (u.kind == 0) { f32x4 s0, s1; unpack8(*(const u32x4*)(PROJ + row * DIN + 4096 + col0 + bj * 128), s0, s1);
; #pragma unroll
;                         for (int j = 0; j < 4; ++j) { acc[ai][bj][m][0][j] *= s0[j] * __builtin_amdgcn_rcpf(p0[j]); acc[ai][bj][m][1][j] *= s1[j] * __builtin_amdgcn_rcpf(p1[j]); } }
;                     else *(u32x4*)(MG + row * DM + col0 + bj * 128) = pack8(acc[ai][bj][m][0] * p0, acc[ai][bj][m][1] * p1); } }
.LBB0_503:
	v_add_co_u32_e32 v140, vcc, 0x4000, v136
	s_nop 1
	v_addc_co_u32_e32 v141, vcc, 0, v137, vcc
	global_load_dwordx4 v[140:143], v[140:141], off offset:256
	s_and_b64 vcc, exec, s[4:5]
	s_waitcnt vmcnt(0)
	v_lshlrev_b32_e32 v135, 16, v140
	v_and_b32_e32 v140, 0xffff0000, v140
	v_lshlrev_b32_e32 v144, 16, v141
	v_and_b32_e32 v141, 0xffff0000, v141
	v_lshlrev_b32_e32 v145, 16, v142
	v_and_b32_e32 v142, 0xffff0000, v142
	v_lshlrev_b32_e32 v146, 16, v143
	v_and_b32_e32 v143, 0xffff0000, v143
	v_max_f32_e32 v135, v135, v135
	v_max_f32_e32 v145, v145, v145
	v_max_f32_e32 v140, v140, v140
	v_max_f32_e32 v142, v142, v142
	v_max_f32_e32 v154, v144, v144
	v_max_f32_e32 v155, v146, v146
	v_max_f32_e32 v141, v141, v141
	v_max_f32_e32 v156, v143, v143
	v_max_f32_e32 v146, 0xda24260, v135
	v_max_f32_e32 v144, 0xda24260, v145
	v_max_f32_e32 v147, 0xda24260, v140
	v_max_f32_e32 v145, 0xda24260, v142
	v_max_f32_e32 v142, 0xda24260, v154
	v_max_f32_e32 v140, 0xda24260, v155
	v_max_f32_e32 v143, 0xda24260, v141
	v_max_f32_e32 v141, 0xda24260, v156
	s_cbranch_vccnz .LBB0_546
	v_pk_mul_f32 v[156:157], v[78:79], v[142:143]
	v_pk_mul_f32 v[154:155], v[76:77], v[146:147]
	v_pk_mul_f32 v[158:159], v[74:75], v[140:141]
	v_pk_mul_f32 v[160:161], v[72:73], v[144:145]
	v_cvt_pk_bf16_f32 v154, v154, v155
	v_cvt_pk_bf16_f32 v155, v156, v157
	s_nop 0
	v_cvt_pk_bf16_f32 v156, v160, v161
	v_cvt_pk_bf16_f32 v157, v158, v159
	global_store_dwordx4 v[138:139], v[154:157], off offset:256 nt
	s_cbranch_execnz .LBB0_506

; __device__ __forceinline__ u32x4 pack8(const f32x4 v0, const f32x4 v1) { u32x4 w; w.x = cvt_pk_bf16(v0[0], v0[1]); w.y = cvt_pk_bf16(v0[2], v0[3]); w.z = cvt_pk_bf16(v1[0], v1[1]); w.w = cvt_pk_bf16(v1[2], v1[3]); return w; }
; __device__ __forceinline__ void unpack8(const u32x4 w, f32x4& lo, f32x4& hi) { lo = (f32x4){bf_lo(w.x), bf_hi(w.x), bf_lo(w.y), bf_hi(w.y)}; hi = (f32x4){bf_lo(w.z), bf_hi(w.z), bf_lo(w.w), bf_hi(w.w)}; }
;     __device__ __forceinline__ void operator()(AccT& acc, const Unit& u, int wr, int wc, int fr, int fq) const {
;     ...
;             for (int m = 0; m < 4; ++m) { const size_t row = (size_t)(row0 + ai * 128 + m * 16);
; #pragma unroll
;                 for (int bj = 0; bj < 2; ++bj) { f32x4 p0, p1; unpack8(*(const u32x4*)(PROJ + row * DIN + 8192 + col0 + bj * 128), p0, p1);
; #pragma unroll
;                     for (int j = 0; j < 4; ++j) { p0[j] = fmaxf(p0[j], TINY); p1[j] = fmaxf(p1[j], TINY); }
;                     if (u.kind == 0) { f32x4 s0, s1; unpack8(*(const u32x4*)(PROJ + row * DIN + 4096 + col0 + bj * 128), s0, s1);
; #pragma unroll
;                         for (int j = 0; j < 4; ++j) { acc[ai][bj][m][0][j] *= s0[j] * __builtin_amdgcn_rcpf(p0[j]); acc[ai][bj][m][1][j] *= s1[j] * __builtin_amdgcn_rcpf(p1[j]); } }
;                     else *(u32x4*)(MG + row * DM + col0 + bj * 128) = pack8(acc[ai][bj][m][0] * p0, acc[ai][bj][m][1] * p1); } }
.LBB0_506:
	v_or_b32_e32 v142, 48, v134
	v_mov_b64_e32 v[136:137], s[20:21]
	v_mad_i64_i32 v[136:137], s[8:9], v142, s78, v[136:137]
	v_lshl_add_u64 v[136:137], v[132:133], 1, v[136:137]
	v_add_co_u32_e32 v138, vcc, 0x4000, v136
	v_ashrrev_i32_e32 v143, 31, v142
	s_nop 0
	v_addc_co_u32_e32 v139, vcc, 0, v137, vcc
	global_load_dwordx4 v[138:141], v[138:139], off
	v_lshlrev_b64 v[142:143], 13, v[142:143]
	v_lshl_add_u64 v[154:155], s[26:27], 0, v[142:143]
	s_and_b64 vcc, exec, s[4:5]
	s_waitcnt vmcnt(0)
	v_lshlrev_b32_e32 v135, 16, v138
	v_and_b32_e32 v138, 0xffff0000, v138
	v_lshlrev_b32_e32 v142, 16, v139
	v_and_b32_e32 v139, 0xffff0000, v139
	v_lshlrev_b32_e32 v143, 16, v140
	v_and_b32_e32 v140, 0xffff0000, v140
	v_lshlrev_b32_e32 v144, 16, v141
	v_and_b32_e32 v141, 0xffff0000, v141
	v_max_f32_e32 v135, v135, v135
	v_max_f32_e32 v143, v143, v143
	v_max_f32_e32 v138, v138, v138
	v_max_f32_e32 v140, v140, v140
	v_max_f32_e32 v142, v142, v142
	v_max_f32_e32 v156, v144, v144
	v_max_f32_e32 v139, v139, v139
	v_max_f32_e32 v141, v141, v141
	v_max_f32_e32 v146, 0xda24260, v135
	v_max_f32_e32 v144, 0xda24260, v143
	v_max_f32_e32 v147, 0xda24260, v138
	v_max_f32_e32 v145, 0xda24260, v140
	v_max_f32_e32 v142, 0xda24260, v142
	v_max_f32_e32 v140, 0xda24260, v156
	v_max_f32_e32 v143, 0xda24260, v139
	v_max_f32_e32 v141, 0xda24260, v141
	v_lshl_add_u64 v[138:139], v[132:133], 1, v[154:155]
	s_cbranch_vccnz .LBB0_547
	v_pk_mul_f32 v[156:157], v[102:103], v[142:143]
	v_pk_mul_f32 v[154:155], v[100:101], v[146:147]
	v_pk_mul_f32 v[158:159], v[98:99], v[140:141]
	v_pk_mul_f32 v[160:161], v[96:97], v[144:145]
	v_cvt_pk_bf16_f32 v154, v154, v155
	v_cvt_pk_bf16_f32 v155, v156, v157
	s_nop 0
	v_cvt_pk_bf16_f32 v156, v160, v161
	v_cvt_pk_bf16_f32 v157, v158, v159
	global_store_dwordx4 v[138:139], v[154:157], off nt
	s_cbranch_execnz .LBB0_509

; __device__ __forceinline__ u32x4 pack8(const f32x4 v0, const f32x4 v1) { u32x4 w; w.x = cvt_pk_bf16(v0[0], v0[1]); w.y = cvt_pk_bf16(v0[2], v0[3]); w.z = cvt_pk_bf16(v1[0], v1[1]); w.w = cvt_pk_bf16(v1[2], v1[3]); return w; }
; __device__ __forceinline__ void unpack8(const u32x4 w, f32x4& lo, f32x4& hi) { lo = (f32x4){bf_lo(w.x), bf_hi(w.x), bf_lo(w.y), bf_hi(w.y)}; hi = (f32x4){bf_lo(w.z), bf_hi(w.z), bf_lo(w.w), bf_hi(w.w)}; }
;     __device__ __forceinline__ void operator()(AccT& acc, const Unit& u, int wr, int wc, int fr, int fq) const {
;     ...
;             for (int m = 0; m < 4; ++m) { const size_t row = (size_t)(row0 + ai * 128 + m * 16);
; #pragma unroll
;                 for (int bj = 0; bj < 2; ++bj) { f32x4 p0, p1; unpack8(*(const u32x4*)(PROJ + row * DIN + 8192 + col0 + bj * 128), p0, p1);
; #pragma unroll
;                     for (int j = 0; j < 4; ++j) { p0[j] = fmaxf(p0[j], TINY); p1[j] = fmaxf(p1[j], TINY); }
;                     if (u.kind == 0) { f32x4 s0, s1; unpack8(*(const u32x4*)(PROJ + row * DIN + 4096 + col0 + bj * 128), s0, s1);
; #pragma unroll
;                         for (int j = 0; j < 4; ++j) { acc[ai][bj][m][0][j] *= s0[j] * __builtin_amdgcn_rcpf(p0[j]); acc[ai][bj][m][1][j] *= s1[j] * __builtin_amdgcn_rcpf(p1[j]); } }
;                     else *(u32x4*)(MG + row * DM + col0 + bj * 128) = pack8(acc[ai][bj][m][0] * p0, acc[ai][bj][m][1] * p1); } }
.LBB0_509:
	v_add_co_u32_e32 v140, vcc, 0x4000, v136
	s_nop 1
	v_addc_co_u32_e32 v141, vcc, 0, v137, vcc
	global_load_dwordx4 v[140:143], v[140:141], off offset:256
	s_and_b64 vcc, exec, s[4:5]
	s_waitcnt vmcnt(0)
	v_lshlrev_b32_e32 v135, 16, v140
	v_and_b32_e32 v140, 0xffff0000, v140
	v_lshlrev_b32_e32 v144, 16, v141
	v_and_b32_e32 v141, 0xffff0000, v141
	v_lshlrev_b32_e32 v145, 16, v142
	v_and_b32_e32 v142, 0xffff0000, v142
	v_lshlrev_b32_e32 v146, 16, v143
	v_and_b32_e32 v143, 0xffff0000, v143
	v_max_f32_e32 v135, v135, v135
	v_max_f32_e32 v145, v145, v145
	v_max_f32_e32 v140, v140, v140
	v_max_f32_e32 v142, v142, v142
	v_max_f32_e32 v154, v144, v144
	v_max_f32_e32 v155, v146, v146
	v_max_f32_e32 v141, v141, v141
	v_max_f32_e32 v156, v143, v143
	v_max_f32_e32 v146, 0xda24260, v135
	v_max_f32_e32 v144, 0xda24260, v145
	v_max_f32_e32 v147, 0xda24260, v140
	v_max_f32_e32 v145, 0xda24260, v142
	v_max_f32_e32 v142, 0xda24260, v154
	v_max_f32_e32 v140, 0xda24260, v155
	v_max_f32_e32 v143, 0xda24260, v141
	v_max_f32_e32 v141, 0xda24260, v156
	s_cbranch_vccnz .LBB0_548
	v_pk_mul_f32 v[156:157], v[70:71], v[142:143]
	v_pk_mul_f32 v[154:155], v[68:69], v[146:147]
	v_pk_mul_f32 v[158:159], v[66:67], v[140:141]
	v_pk_mul_f32 v[160:161], v[64:65], v[144:145]
	v_cvt_pk_bf16_f32 v154, v154, v155
	v_cvt_pk_bf16_f32 v155, v156, v157
	s_nop 0
	v_cvt_pk_bf16_f32 v156, v160, v161
	v_cvt_pk_bf16_f32 v157, v158, v159
	global_store_dwordx4 v[138:139], v[154:157], off offset:256 nt
	s_cbranch_execnz .LBB0_512

; __device__ __forceinline__ u32x4 pack8(const f32x4 v0, const f32x4 v1) { u32x4 w; w.x = cvt_pk_bf16(v0[0], v0[1]); w.y = cvt_pk_bf16(v0[2], v0[3]); w.z = cvt_pk_bf16(v1[0], v1[1]); w.w = cvt_pk_bf16(v1[2], v1[3]); return w; }
; __device__ __forceinline__ void unpack8(const u32x4 w, f32x4& lo, f32x4& hi) { lo = (f32x4){bf_lo(w.x), bf_hi(w.x), bf_lo(w.y), bf_hi(w.y)}; hi = (f32x4){bf_lo(w.z), bf_hi(w.z), bf_lo(w.w), bf_hi(w.w)}; }
;     __device__ __forceinline__ void operator()(AccT& acc, const Unit& u, int wr, int wc, int fr, int fq) const {
;     ...
;             for (int m = 0; m < 4; ++m) { const size_t row = (size_t)(row0 + ai * 128 + m * 16);
; #pragma unroll
;                 for (int bj = 0; bj < 2; ++bj) { f32x4 p0, p1; unpack8(*(const u32x4*)(PROJ + row * DIN + 8192 + col0 + bj * 128), p0, p1);
; #pragma unroll
;                     for (int j = 0; j < 4; ++j) { p0[j] = fmaxf(p0[j], TINY); p1[j] = fmaxf(p1[j], TINY); }
;                     if (u.kind == 0) { f32x4 s0, s1; unpack8(*(const u32x4*)(PROJ + row * DIN + 4096 + col0 + bj * 128), s0, s1);
; #pragma unroll
;                         for (int j = 0; j < 4; ++j) { acc[ai][bj][m][0][j] *= s0[j] * __builtin_amdgcn_rcpf(p0[j]); acc[ai][bj][m][1][j] *= s1[j] * __builtin_amdgcn_rcpf(p1[j]); } }
;                     else *(u32x4*)(MG + row * DM + col0 + bj * 128) = pack8(acc[ai][bj][m][0] * p0, acc[ai][bj][m][1] * p1); } }
.LBB0_512:
	v_add_u32_e32 v142, 0x80, v134
	v_mov_b64_e32 v[136:137], s[20:21]
	v_mad_i64_i32 v[136:137], s[8:9], v142, s78, v[136:137]
	v_lshl_add_u64 v[136:137], v[132:133], 1, v[136:137]
	v_add_co_u32_e32 v138, vcc, 0x4000, v136
	v_ashrrev_i32_e32 v143, 31, v142
	s_nop 0
	v_addc_co_u32_e32 v139, vcc, 0, v137, vcc
	global_load_dwordx4 v[138:141], v[138:139], off
	v_lshlrev_b64 v[142:143], 13, v[142:143]
	v_lshl_add_u64 v[154:155], s[26:27], 0, v[142:143]
	s_and_b64 vcc, exec, s[4:5]
	s_waitcnt vmcnt(0)
	v_lshlrev_b32_e32 v135, 16, v138
	v_and_b32_e32 v138, 0xffff0000, v138
	v_lshlrev_b32_e32 v142, 16, v139
	v_and_b32_e32 v139, 0xffff0000, v139
	v_lshlrev_b32_e32 v143, 16, v140
	v_and_b32_e32 v140, 0xffff0000, v140
	v_lshlrev_b32_e32 v144, 16, v141
	v_and_b32_e32 v141, 0xffff0000, v141
	v_max_f32_e32 v135, v135, v135
	v_max_f32_e32 v143, v143, v143
	v_max_f32_e32 v138, v138, v138
	v_max_f32_e32 v140, v140, v140
	v_max_f32_e32 v142, v142, v142
	v_max_f32_e32 v156, v144, v144
	v_max_f32_e32 v139, v139, v139
	v_max_f32_e32 v141, v141, v141
	v_max_f32_e32 v146, 0xda24260, v135
	v_max_f32_e32 v144, 0xda24260, v143
	v_max_f32_e32 v147, 0xda24260, v138
	v_max_f32_e32 v145, 0xda24260, v140
	v_max_f32_e32 v142, 0xda24260, v142
	v_max_f32_e32 v140, 0xda24260, v156
	v_max_f32_e32 v143, 0xda24260, v139
	v_max_f32_e32 v141, 0xda24260, v141
	v_lshl_add_u64 v[138:139], v[132:133], 1, v[154:155]
	s_cbranch_vccnz .LBB0_549
	v_pk_mul_f32 v[156:157], v[62:63], v[142:143]
	v_pk_mul_f32 v[154:155], v[60:61], v[146:147]
	v_pk_mul_f32 v[158:159], v[58:59], v[140:141]
	v_pk_mul_f32 v[160:161], v[56:57], v[144:145]
	v_cvt_pk_bf16_f32 v154, v154, v155
	v_cvt_pk_bf16_f32 v155, v156, v157
	s_nop 0
	v_cvt_pk_bf16_f32 v156, v160, v161
	v_cvt_pk_bf16_f32 v157, v158, v159
	global_store_dwordx4 v[138:139], v[154:157], off nt
	s_cbranch_execnz .LBB0_515

; __device__ __forceinline__ u32x4 pack8(const f32x4 v0, const f32x4 v1) { u32x4 w; w.x = cvt_pk_bf16(v0[0], v0[1]); w.y = cvt_pk_bf16(v0[2], v0[3]); w.z = cvt_pk_bf16(v1[0], v1[1]); w.w = cvt_pk_bf16(v1[2], v1[3]); return w; }
; __device__ __forceinline__ void unpack8(const u32x4 w, f32x4& lo, f32x4& hi) { lo = (f32x4){bf_lo(w.x), bf_hi(w.x), bf_lo(w.y), bf_hi(w.y)}; hi = (f32x4){bf_lo(w.z), bf_hi(w.z), bf_lo(w.w), bf_hi(w.w)}; }
;     __device__ __forceinline__ void operator()(AccT& acc, const Unit& u, int wr, int wc, int fr, int fq) const {
;     ...
;             for (int m = 0; m < 4; ++m) { const size_t row = (size_t)(row0 + ai * 128 + m * 16);
; #pragma unroll
;                 for (int bj = 0; bj < 2; ++bj) { f32x4 p0, p1; unpack8(*(const u32x4*)(PROJ + row * DIN + 8192 + col0 + bj * 128), p0, p1);
; #pragma unroll
;                     for (int j = 0; j < 4; ++j) { p0[j] = fmaxf(p0[j], TINY); p1[j] = fmaxf(p1[j], TINY); }
;                     if (u.kind == 0) { f32x4 s0, s1; unpack8(*(const u32x4*)(PROJ + row * DIN + 4096 + col0 + bj * 128), s0, s1);
; #pragma unroll
;                         for (int j = 0; j < 4; ++j) { acc[ai][bj][m][0][j] *= s0[j] * __builtin_amdgcn_rcpf(p0[j]); acc[ai][bj][m][1][j] *= s1[j] * __builtin_amdgcn_rcpf(p1[j]); } }
;                     else *(u32x4*)(MG + row * DM + col0 + bj * 128) = pack8(acc[ai][bj][m][0] * p0, acc[ai][bj][m][1] * p1); } }
.LBB0_515:
	v_add_co_u32_e32 v140, vcc, 0x4000, v136
	s_nop 1
	v_addc_co_u32_e32 v141, vcc, 0, v137, vcc
	global_load_dwordx4 v[140:143], v[140:141], off offset:256
	s_and_b64 vcc, exec, s[4:5]
	s_waitcnt vmcnt(0)
	v_lshlrev_b32_e32 v135, 16, v140
	v_and_b32_e32 v140, 0xffff0000, v140
	v_lshlrev_b32_e32 v144, 16, v141
	v_and_b32_e32 v141, 0xffff0000, v141
	v_lshlrev_b32_e32 v145, 16, v142
	v_and_b32_e32 v142, 0xffff0000, v142
	v_lshlrev_b32_e32 v146, 16, v143
	v_and_b32_e32 v143, 0xffff0000, v143
	v_max_f32_e32 v135, v135, v135
	v_max_f32_e32 v145, v145, v145
	v_max_f32_e32 v140, v140, v140
	v_max_f32_e32 v142, v142, v142
	v_max_f32_e32 v154, v144, v144
	v_max_f32_e32 v155, v146, v146
	v_max_f32_e32 v141, v141, v141
	v_max_f32_e32 v156, v143, v143
	v_max_f32_e32 v146, 0xda24260, v135
	v_max_f32_e32 v144, 0xda24260, v145
	v_max_f32_e32 v147, 0xda24260, v140
	v_max_f32_e32 v145, 0xda24260, v142
	v_max_f32_e32 v142, 0xda24260, v154
	v_max_f32_e32 v140, 0xda24260, v155
	v_max_f32_e32 v143, 0xda24260, v141
	v_max_f32_e32 v141, 0xda24260, v156
	s_cbranch_vccnz .LBB0_550
	v_pk_mul_f32 v[156:157], v[30:31], v[142:143]
	v_pk_mul_f32 v[154:155], v[28:29], v[146:147]
	v_pk_mul_f32 v[158:159], v[26:27], v[140:141]
	v_pk_mul_f32 v[160:161], v[24:25], v[144:145]
	v_cvt_pk_bf16_f32 v154, v154, v155
	v_cvt_pk_bf16_f32 v155, v156, v157
	s_nop 0
	v_cvt_pk_bf16_f32 v156, v160, v161
	v_cvt_pk_bf16_f32 v157, v158, v159
	global_store_dwordx4 v[138:139], v[154:157], off offset:256 nt
	s_cbranch_execnz .LBB0_518

; __device__ __forceinline__ u32x4 pack8(const f32x4 v0, const f32x4 v1) { u32x4 w; w.x = cvt_pk_bf16(v0[0], v0[1]); w.y = cvt_pk_bf16(v0[2], v0[3]); w.z = cvt_pk_bf16(v1[0], v1[1]); w.w = cvt_pk_bf16(v1[2], v1[3]); return w; }
; __device__ __forceinline__ void unpack8(const u32x4 w, f32x4& lo, f32x4& hi) { lo = (f32x4){bf_lo(w.x), bf_hi(w.x), bf_lo(w.y), bf_hi(w.y)}; hi = (f32x4){bf_lo(w.z), bf_hi(w.z), bf_lo(w.w), bf_hi(w.w)}; }
;     __device__ __forceinline__ void operator()(AccT& acc, const Unit& u, int wr, int wc, int fr, int fq) const {
;     ...
;             for (int m = 0; m < 4; ++m) { const size_t row = (size_t)(row0 + ai * 128 + m * 16);
; #pragma unroll
;                 for (int bj = 0; bj < 2; ++bj) { f32x4 p0, p1; unpack8(*(const u32x4*)(PROJ + row * DIN + 8192 + col0 + bj * 128), p0, p1);
; #pragma unroll
;                     for (int j = 0; j < 4; ++j) { p0[j] = fmaxf(p0[j], TINY); p1[j] = fmaxf(p1[j], TINY); }
;                     if (u.kind == 0) { f32x4 s0, s1; unpack8(*(const u32x4*)(PROJ + row * DIN + 4096 + col0 + bj * 128), s0, s1);
; #pragma unroll
;                         for (int j = 0; j < 4; ++j) { acc[ai][bj][m][0][j] *= s0[j] * __builtin_amdgcn_rcpf(p0[j]); acc[ai][bj][m][1][j] *= s1[j] * __builtin_amdgcn_rcpf(p1[j]); } }
;                     else *(u32x4*)(MG + row * DM + col0 + bj * 128) = pack8(acc[ai][bj][m][0] * p0, acc[ai][bj][m][1] * p1); } }
.LBB0_518:
	v_add_u32_e32 v142, 0x90, v134
	v_mov_b64_e32 v[136:137], s[20:21]
	v_mad_i64_i32 v[136:137], s[8:9], v142, s78, v[136:137]
	v_lshl_add_u64 v[136:137], v[132:133], 1, v[136:137]
	v_add_co_u32_e32 v138, vcc, 0x4000, v136
	v_ashrrev_i32_e32 v143, 31, v142
	s_nop 0
	v_addc_co_u32_e32 v139, vcc, 0, v137, vcc
	global_load_dwordx4 v[138:141], v[138:139], off
	v_lshlrev_b64 v[142:143], 13, v[142:143]
	v_lshl_add_u64 v[154:155], s[26:27], 0, v[142:143]
	s_and_b64 vcc, exec, s[4:5]
	s_waitcnt vmcnt(0)
	v_lshlrev_b32_e32 v135, 16, v138
	v_and_b32_e32 v138, 0xffff0000, v138
	v_lshlrev_b32_e32 v142, 16, v139
	v_and_b32_e32 v139, 0xffff0000, v139
	v_lshlrev_b32_e32 v143, 16, v140
	v_and_b32_e32 v140, 0xffff0000, v140
	v_lshlrev_b32_e32 v144, 16, v141
	v_and_b32_e32 v141, 0xffff0000, v141
	v_max_f32_e32 v135, v135, v135
	v_max_f32_e32 v143, v143, v143
	v_max_f32_e32 v138, v138, v138
	v_max_f32_e32 v140, v140, v140
	v_max_f32_e32 v142, v142, v142
	v_max_f32_e32 v156, v144, v144
	v_max_f32_e32 v139, v139, v139
	v_max_f32_e32 v141, v141, v141
	v_max_f32_e32 v146, 0xda24260, v135
	v_max_f32_e32 v144, 0xda24260, v143
	v_max_f32_e32 v147, 0xda24260, v138
	v_max_f32_e32 v145, 0xda24260, v140
	v_max_f32_e32 v142, 0xda24260, v142
	v_max_f32_e32 v140, 0xda24260, v156
	v_max_f32_e32 v143, 0xda24260, v139
	v_max_f32_e32 v141, 0xda24260, v141
	v_lshl_add_u64 v[138:139], v[132:133], 1, v[154:155]
	s_cbranch_vccnz .LBB0_551
	v_pk_mul_f32 v[156:157], v[54:55], v[142:143]
	v_pk_mul_f32 v[154:155], v[52:53], v[146:147]
	v_pk_mul_f32 v[158:159], v[50:51], v[140:141]
	v_pk_mul_f32 v[160:161], v[48:49], v[144:145]
	v_cvt_pk_bf16_f32 v154, v154, v155
	v_cvt_pk_bf16_f32 v155, v156, v157
	s_nop 0
	v_cvt_pk_bf16_f32 v156, v160, v161
	v_cvt_pk_bf16_f32 v157, v158, v159
	global_store_dwordx4 v[138:139], v[154:157], off nt
	s_cbranch_execnz .LBB0_521

; __device__ __forceinline__ u32x4 pack8(const f32x4 v0, const f32x4 v1) { u32x4 w; w.x = cvt_pk_bf16(v0[0], v0[1]); w.y = cvt_pk_bf16(v0[2], v0[3]); w.z = cvt_pk_bf16(v1[0], v1[1]); w.w = cvt_pk_bf16(v1[2], v1[3]); return w; }
; __device__ __forceinline__ void unpack8(const u32x4 w, f32x4& lo, f32x4& hi) { lo = (f32x4){bf_lo(w.x), bf_hi(w.x), bf_lo(w.y), bf_hi(w.y)}; hi = (f32x4){bf_lo(w.z), bf_hi(w.z), bf_lo(w.w), bf_hi(w.w)}; }
;     __device__ __forceinline__ void operator()(AccT& acc, const Unit& u, int wr, int wc, int fr, int fq) const {
;     ...
;             for (int m = 0; m < 4; ++m) { const size_t row = (size_t)(row0 + ai * 128 + m * 16);
; #pragma unroll
;                 for (int bj = 0; bj < 2; ++bj) { f32x4 p0, p1; unpack8(*(const u32x4*)(PROJ + row * DIN + 8192 + col0 + bj * 128), p0, p1);
; #pragma unroll
;                     for (int j = 0; j < 4; ++j) { p0[j] = fmaxf(p0[j], TINY); p1[j] = fmaxf(p1[j], TINY); }
;                     if (u.kind == 0) { f32x4 s0, s1; unpack8(*(const u32x4*)(PROJ + row * DIN + 4096 + col0 + bj * 128), s0, s1);
; #pragma unroll
;                         for (int j = 0; j < 4; ++j) { acc[ai][bj][m][0][j] *= s0[j] * __builtin_amdgcn_rcpf(p0[j]); acc[ai][bj][m][1][j] *= s1[j] * __builtin_amdgcn_rcpf(p1[j]); } }
;                     else *(u32x4*)(MG + row * DM + col0 + bj * 128) = pack8(acc[ai][bj][m][0] * p0, acc[ai][bj][m][1] * p1); } }
.LBB0_521:
	v_add_co_u32_e32 v140, vcc, 0x4000, v136
	s_nop 1
	v_addc_co_u32_e32 v141, vcc, 0, v137, vcc
	global_load_dwordx4 v[140:143], v[140:141], off offset:256
	s_and_b64 vcc, exec, s[4:5]
	s_waitcnt vmcnt(0)
	v_lshlrev_b32_e32 v135, 16, v140
	v_and_b32_e32 v140, 0xffff0000, v140
	v_lshlrev_b32_e32 v144, 16, v141
	v_and_b32_e32 v141, 0xffff0000, v141
	v_lshlrev_b32_e32 v145, 16, v142
	v_and_b32_e32 v142, 0xffff0000, v142
	v_lshlrev_b32_e32 v146, 16, v143
	v_and_b32_e32 v143, 0xffff0000, v143
	v_max_f32_e32 v135, v135, v135
	v_max_f32_e32 v145, v145, v145
	v_max_f32_e32 v140, v140, v140
	v_max_f32_e32 v142, v142, v142
	v_max_f32_e32 v154, v144, v144
	v_max_f32_e32 v155, v146, v146
	v_max_f32_e32 v141, v141, v141
	v_max_f32_e32 v156, v143, v143
	v_max_f32_e32 v146, 0xda24260, v135
	v_max_f32_e32 v144, 0xda24260, v145
	v_max_f32_e32 v147, 0xda24260, v140
	v_max_f32_e32 v145, 0xda24260, v142
	v_max_f32_e32 v142, 0xda24260, v154
	v_max_f32_e32 v140, 0xda24260, v155
	v_max_f32_e32 v143, 0xda24260, v141
	v_max_f32_e32 v141, 0xda24260, v156
	s_cbranch_vccnz .LBB0_552
	v_pk_mul_f32 v[156:157], v[22:23], v[142:143]
	v_pk_mul_f32 v[154:155], v[20:21], v[146:147]
	v_pk_mul_f32 v[158:159], v[18:19], v[140:141]
	v_pk_mul_f32 v[160:161], v[16:17], v[144:145]
	v_cvt_pk_bf16_f32 v154, v154, v155
	v_cvt_pk_bf16_f32 v155, v156, v157
	s_nop 0
	v_cvt_pk_bf16_f32 v156, v160, v161
	v_cvt_pk_bf16_f32 v157, v158, v159
	global_store_dwordx4 v[138:139], v[154:157], off offset:256 nt
	s_cbranch_execnz .LBB0_524

; __device__ __forceinline__ u32x4 pack8(const f32x4 v0, const f32x4 v1) { u32x4 w; w.x = cvt_pk_bf16(v0[0], v0[1]); w.y = cvt_pk_bf16(v0[2], v0[3]); w.z = cvt_pk_bf16(v1[0], v1[1]); w.w = cvt_pk_bf16(v1[2], v1[3]); return w; }
; __device__ __forceinline__ void unpack8(const u32x4 w, f32x4& lo, f32x4& hi) { lo = (f32x4){bf_lo(w.x), bf_hi(w.x), bf_lo(w.y), bf_hi(w.y)}; hi = (f32x4){bf_lo(w.z), bf_hi(w.z), bf_lo(w.w), bf_hi(w.w)}; }
;     __device__ __forceinline__ void operator()(AccT& acc, const Unit& u, int wr, int wc, int fr, int fq) const {
;     ...
;             for (int m = 0; m < 4; ++m) { const size_t row = (size_t)(row0 + ai * 128 + m * 16);
; #pragma unroll
;                 for (int bj = 0; bj < 2; ++bj) { f32x4 p0, p1; unpack8(*(const u32x4*)(PROJ + row * DIN + 8192 + col0 + bj * 128), p0, p1);
; #pragma unroll
;                     for (int j = 0; j < 4; ++j) { p0[j] = fmaxf(p0[j], TINY); p1[j] = fmaxf(p1[j], TINY); }
;                     if (u.kind == 0) { f32x4 s0, s1; unpack8(*(const u32x4*)(PROJ + row * DIN + 4096 + col0 + bj * 128), s0, s1);
; #pragma unroll
;                         for (int j = 0; j < 4; ++j) { acc[ai][bj][m][0][j] *= s0[j] * __builtin_amdgcn_rcpf(p0[j]); acc[ai][bj][m][1][j] *= s1[j] * __builtin_amdgcn_rcpf(p1[j]); } }
;                     else *(u32x4*)(MG + row * DM + col0 + bj * 128) = pack8(acc[ai][bj][m][0] * p0, acc[ai][bj][m][1] * p1); } }
.LBB0_524:
	v_add_u32_e32 v142, 0xa0, v134
	v_mov_b64_e32 v[136:137], s[20:21]
	v_mad_i64_i32 v[136:137], s[8:9], v142, s78, v[136:137]
	v_lshl_add_u64 v[136:137], v[132:133], 1, v[136:137]
	v_add_co_u32_e32 v138, vcc, 0x4000, v136
	v_ashrrev_i32_e32 v143, 31, v142
	s_nop 0
	v_addc_co_u32_e32 v139, vcc, 0, v137, vcc
	global_load_dwordx4 v[138:141], v[138:139], off
	v_lshlrev_b64 v[142:143], 13, v[142:143]
	v_lshl_add_u64 v[154:155], s[26:27], 0, v[142:143]
	s_and_b64 vcc, exec, s[4:5]
	s_waitcnt vmcnt(0)
	v_lshlrev_b32_e32 v135, 16, v138
	v_and_b32_e32 v138, 0xffff0000, v138
	v_lshlrev_b32_e32 v142, 16, v139
	v_and_b32_e32 v139, 0xffff0000, v139
	v_lshlrev_b32_e32 v143, 16, v140
	v_and_b32_e32 v140, 0xffff0000, v140
	v_lshlrev_b32_e32 v144, 16, v141
	v_and_b32_e32 v141, 0xffff0000, v141
	v_max_f32_e32 v135, v135, v135
	v_max_f32_e32 v143, v143, v143
	v_max_f32_e32 v138, v138, v138
	v_max_f32_e32 v140, v140, v140
	v_max_f32_e32 v142, v142, v142
	v_max_f32_e32 v156, v144, v144
	v_max_f32_e32 v139, v139, v139
	v_max_f32_e32 v141, v141, v141
	v_max_f32_e32 v146, 0xda24260, v135
	v_max_f32_e32 v144, 0xda24260, v143
	v_max_f32_e32 v147, 0xda24260, v138
	v_max_f32_e32 v145, 0xda24260, v140
	v_max_f32_e32 v142, 0xda24260, v142
	v_max_f32_e32 v140, 0xda24260, v156
	v_max_f32_e32 v143, 0xda24260, v139
	v_max_f32_e32 v141, 0xda24260, v141
	v_lshl_add_u64 v[138:139], v[132:133], 1, v[154:155]
	s_cbranch_vccnz .LBB0_553
	v_pk_mul_f32 v[156:157], v[46:47], v[142:143]
	v_pk_mul_f32 v[154:155], v[44:45], v[146:147]
	v_pk_mul_f32 v[158:159], v[42:43], v[140:141]
	v_pk_mul_f32 v[160:161], v[40:41], v[144:145]
	v_cvt_pk_bf16_f32 v154, v154, v155
	v_cvt_pk_bf16_f32 v155, v156, v157
	s_nop 0
	v_cvt_pk_bf16_f32 v156, v160, v161
	v_cvt_pk_bf16_f32 v157, v158, v159
	global_store_dwordx4 v[138:139], v[154:157], off nt
	s_cbranch_execnz .LBB0_527

; __device__ __forceinline__ u32x4 pack8(const f32x4 v0, const f32x4 v1) { u32x4 w; w.x = cvt_pk_bf16(v0[0], v0[1]); w.y = cvt_pk_bf16(v0[2], v0[3]); w.z = cvt_pk_bf16(v1[0], v1[1]); w.w = cvt_pk_bf16(v1[2], v1[3]); return w; }
; __device__ __forceinline__ void unpack8(const u32x4 w, f32x4& lo, f32x4& hi) { lo = (f32x4){bf_lo(w.x), bf_hi(w.x), bf_lo(w.y), bf_hi(w.y)}; hi = (f32x4){bf_lo(w.z), bf_hi(w.z), bf_lo(w.w), bf_hi(w.w)}; }
;     __device__ __forceinline__ void operator()(AccT& acc, const Unit& u, int wr, int wc, int fr, int fq) const {
;     ...
;             for (int m = 0; m < 4; ++m) { const size_t row = (size_t)(row0 + ai * 128 + m * 16);
; #pragma unroll
;                 for (int bj = 0; bj < 2; ++bj) { f32x4 p0, p1; unpack8(*(const u32x4*)(PROJ + row * DIN + 8192 + col0 + bj * 128), p0, p1);
; #pragma unroll
;                     for (int j = 0; j < 4; ++j) { p0[j] = fmaxf(p0[j], TINY); p1[j] = fmaxf(p1[j], TINY); }
;                     if (u.kind == 0) { f32x4 s0, s1; unpack8(*(const u32x4*)(PROJ + row * DIN + 4096 + col0 + bj * 128), s0, s1);
; #pragma unroll
;                         for (int j = 0; j < 4; ++j) { acc[ai][bj][m][0][j] *= s0[j] * __builtin_amdgcn_rcpf(p0[j]); acc[ai][bj][m][1][j] *= s1[j] * __builtin_amdgcn_rcpf(p1[j]); } }
;                     else *(u32x4*)(MG + row * DM + col0 + bj * 128) = pack8(acc[ai][bj][m][0] * p0, acc[ai][bj][m][1] * p1); } }
.LBB0_527:
	v_add_co_u32_e32 v140, vcc, 0x4000, v136
	s_nop 1
	v_addc_co_u32_e32 v141, vcc, 0, v137, vcc
	global_load_dwordx4 v[140:143], v[140:141], off offset:256
	s_and_b64 vcc, exec, s[4:5]
	s_waitcnt vmcnt(0)
	v_lshlrev_b32_e32 v135, 16, v140
	v_and_b32_e32 v140, 0xffff0000, v140
	v_lshlrev_b32_e32 v144, 16, v141
	v_and_b32_e32 v141, 0xffff0000, v141
	v_lshlrev_b32_e32 v145, 16, v142
	v_and_b32_e32 v142, 0xffff0000, v142
	v_lshlrev_b32_e32 v146, 16, v143
	v_and_b32_e32 v143, 0xffff0000, v143
	v_max_f32_e32 v135, v135, v135
	v_max_f32_e32 v145, v145, v145
	v_max_f32_e32 v140, v140, v140
	v_max_f32_e32 v142, v142, v142
	v_max_f32_e32 v154, v144, v144
	v_max_f32_e32 v155, v146, v146
	v_max_f32_e32 v141, v141, v141
	v_max_f32_e32 v156, v143, v143
	v_max_f32_e32 v146, 0xda24260, v135
	v_max_f32_e32 v144, 0xda24260, v145
	v_max_f32_e32 v147, 0xda24260, v140
	v_max_f32_e32 v145, 0xda24260, v142
	v_max_f32_e32 v142, 0xda24260, v154
	v_max_f32_e32 v140, 0xda24260, v155
	v_max_f32_e32 v143, 0xda24260, v141
	v_max_f32_e32 v141, 0xda24260, v156
	s_cbranch_vccnz .LBB0_554
	v_pk_mul_f32 v[156:157], v[14:15], v[142:143]
	v_pk_mul_f32 v[154:155], v[12:13], v[146:147]
	v_pk_mul_f32 v[158:159], v[10:11], v[140:141]
	v_pk_mul_f32 v[160:161], v[8:9], v[144:145]
	v_cvt_pk_bf16_f32 v154, v154, v155
	v_cvt_pk_bf16_f32 v155, v156, v157
	s_nop 0
	v_cvt_pk_bf16_f32 v156, v160, v161
	v_cvt_pk_bf16_f32 v157, v158, v159
	global_store_dwordx4 v[138:139], v[154:157], off offset:256 nt
	s_cbranch_execnz .LBB0_530

; __device__ __forceinline__ u32x4 pack8(const f32x4 v0, const f32x4 v1) { u32x4 w; w.x = cvt_pk_bf16(v0[0], v0[1]); w.y = cvt_pk_bf16(v0[2], v0[3]); w.z = cvt_pk_bf16(v1[0], v1[1]); w.w = cvt_pk_bf16(v1[2], v1[3]); return w; }
; __device__ __forceinline__ void unpack8(const u32x4 w, f32x4& lo, f32x4& hi) { lo = (f32x4){bf_lo(w.x), bf_hi(w.x), bf_lo(w.y), bf_hi(w.y)}; hi = (f32x4){bf_lo(w.z), bf_hi(w.z), bf_lo(w.w), bf_hi(w.w)}; }
;     __device__ __forceinline__ void operator()(AccT& acc, const Unit& u, int wr, int wc, int fr, int fq) const {
;     ...
;             for (int m = 0; m < 4; ++m) { const size_t row = (size_t)(row0 + ai * 128 + m * 16);
; #pragma unroll
;                 for (int bj = 0; bj < 2; ++bj) { f32x4 p0, p1; unpack8(*(const u32x4*)(PROJ + row * DIN + 8192 + col0 + bj * 128), p0, p1);
; #pragma unroll
;                     for (int j = 0; j < 4; ++j) { p0[j] = fmaxf(p0[j], TINY); p1[j] = fmaxf(p1[j], TINY); }
;                     if (u.kind == 0) { f32x4 s0, s1; unpack8(*(const u32x4*)(PROJ + row * DIN + 4096 + col0 + bj * 128), s0, s1);
; #pragma unroll
;                         for (int j = 0; j < 4; ++j) { acc[ai][bj][m][0][j] *= s0[j] * __builtin_amdgcn_rcpf(p0[j]); acc[ai][bj][m][1][j] *= s1[j] * __builtin_amdgcn_rcpf(p1[j]); } }
;                     else *(u32x4*)(MG + row * DM + col0 + bj * 128) = pack8(acc[ai][bj][m][0] * p0, acc[ai][bj][m][1] * p1); } }
.LBB0_530:
	v_add_u32_e32 v140, 0xb0, v134
	v_mov_b64_e32 v[134:135], s[20:21]
	v_mad_i64_i32 v[134:135], s[8:9], v140, s78, v[134:135]
	v_lshl_add_u64 v[134:135], v[132:133], 1, v[134:135]
	v_add_co_u32_e32 v136, vcc, 0x4000, v134
	v_ashrrev_i32_e32 v141, 31, v140
	s_nop 0
	v_addc_co_u32_e32 v137, vcc, 0, v135, vcc
	global_load_dwordx4 v[136:139], v[136:137], off
	v_lshlrev_b64 v[140:141], 13, v[140:141]
	v_lshl_add_u64 v[144:145], s[26:27], 0, v[140:141]
	s_and_b64 vcc, exec, s[4:5]
	v_lshl_add_u64 v[132:133], v[132:133], 1, v[144:145]
	s_waitcnt vmcnt(0)
	v_lshlrev_b32_e32 v140, 16, v136
	v_and_b32_e32 v136, 0xffff0000, v136
	v_lshlrev_b32_e32 v141, 16, v137
	v_and_b32_e32 v137, 0xffff0000, v137
	v_lshlrev_b32_e32 v142, 16, v138
	v_and_b32_e32 v138, 0xffff0000, v138
	v_lshlrev_b32_e32 v143, 16, v139
	v_and_b32_e32 v139, 0xffff0000, v139
	v_max_f32_e32 v140, v140, v140
	v_max_f32_e32 v146, v142, v142
	v_max_f32_e32 v136, v136, v136
	v_max_f32_e32 v138, v138, v138
	v_max_f32_e32 v147, v141, v141
	v_max_f32_e32 v154, v143, v143
	v_max_f32_e32 v137, v137, v137
	v_max_f32_e32 v155, v139, v139
	v_max_f32_e32 v142, 0xda24260, v140
	v_max_f32_e32 v140, 0xda24260, v146
	v_max_f32_e32 v143, 0xda24260, v136
	v_max_f32_e32 v141, 0xda24260, v138
	v_max_f32_e32 v138, 0xda24260, v147
	v_max_f32_e32 v136, 0xda24260, v154
	v_max_f32_e32 v139, 0xda24260, v137
	v_max_f32_e32 v137, 0xda24260, v155
	s_cbranch_vccnz .LBB0_555
	v_pk_mul_f32 v[146:147], v[38:39], v[138:139]
	v_pk_mul_f32 v[144:145], v[36:37], v[142:143]
	v_pk_mul_f32 v[154:155], v[34:35], v[136:137]
	v_pk_mul_f32 v[156:157], v[32:33], v[140:141]
	v_cvt_pk_bf16_f32 v144, v144, v145
	v_cvt_pk_bf16_f32 v145, v146, v147
	s_nop 0
	v_cvt_pk_bf16_f32 v146, v156, v157
	v_cvt_pk_bf16_f32 v147, v154, v155
	global_store_dwordx4 v[132:133], v[144:147], off nt
	s_cbranch_execnz .LBB0_533

; __device__ __forceinline__ u32x4 pack8(const f32x4 v0, const f32x4 v1) { u32x4 w; w.x = cvt_pk_bf16(v0[0], v0[1]); w.y = cvt_pk_bf16(v0[2], v0[3]); w.z = cvt_pk_bf16(v1[0], v1[1]); w.w = cvt_pk_bf16(v1[2], v1[3]); return w; }
; __device__ __forceinline__ void unpack8(const u32x4 w, f32x4& lo, f32x4& hi) { lo = (f32x4){bf_lo(w.x), bf_hi(w.x), bf_lo(w.y), bf_hi(w.y)}; hi = (f32x4){bf_lo(w.z), bf_hi(w.z), bf_lo(w.w), bf_hi(w.w)}; }
;     __device__ __forceinline__ void operator()(AccT& acc, const Unit& u, int wr, int wc, int fr, int fq) const {
;     ...
;             for (int m = 0; m < 4; ++m) { const size_t row = (size_t)(row0 + ai * 128 + m * 16);
; #pragma unroll
;                 for (int bj = 0; bj < 2; ++bj) { f32x4 p0, p1; unpack8(*(const u32x4*)(PROJ + row * DIN + 8192 + col0 + bj * 128), p0, p1);
; #pragma unroll
;                     for (int j = 0; j < 4; ++j) { p0[j] = fmaxf(p0[j], TINY); p1[j] = fmaxf(p1[j], TINY); }
;                     if (u.kind == 0) { f32x4 s0, s1; unpack8(*(const u32x4*)(PROJ + row * DIN + 4096 + col0 + bj * 128), s0, s1);
; #pragma unroll
;                         for (int j = 0; j < 4; ++j) { acc[ai][bj][m][0][j] *= s0[j] * __builtin_amdgcn_rcpf(p0[j]); acc[ai][bj][m][1][j] *= s1[j] * __builtin_amdgcn_rcpf(p1[j]); } }
;                     else *(u32x4*)(MG + row * DM + col0 + bj * 128) = pack8(acc[ai][bj][m][0] * p0, acc[ai][bj][m][1] * p1); } }
.LBB0_533:
	v_add_co_u32_e32 v136, vcc, 0x4000, v134
	s_nop 1
	v_addc_co_u32_e32 v137, vcc, 0, v135, vcc
	global_load_dwordx4 v[136:139], v[136:137], off offset:256
	s_and_b64 vcc, exec, s[4:5]
	s_waitcnt vmcnt(0)
	v_lshlrev_b32_e32 v140, 16, v136
	v_and_b32_e32 v136, 0xffff0000, v136
	v_lshlrev_b32_e32 v141, 16, v137
	v_and_b32_e32 v137, 0xffff0000, v137
	v_lshlrev_b32_e32 v142, 16, v138
	v_and_b32_e32 v138, 0xffff0000, v138
	v_lshlrev_b32_e32 v143, 16, v139
	v_and_b32_e32 v139, 0xffff0000, v139
	v_max_f32_e32 v140, v140, v140
	v_max_f32_e32 v144, v142, v142
	v_max_f32_e32 v136, v136, v136
	v_max_f32_e32 v138, v138, v138
	v_max_f32_e32 v145, v141, v141
	v_max_f32_e32 v146, v143, v143
	v_max_f32_e32 v137, v137, v137
	v_max_f32_e32 v147, v139, v139
	v_max_f32_e32 v142, 0xda24260, v140
	v_max_f32_e32 v140, 0xda24260, v144
	v_max_f32_e32 v143, 0xda24260, v136
	v_max_f32_e32 v141, 0xda24260, v138
	v_max_f32_e32 v138, 0xda24260, v145
	v_max_f32_e32 v136, 0xda24260, v146
	v_max_f32_e32 v139, 0xda24260, v137
	v_max_f32_e32 v137, 0xda24260, v147
	s_cbranch_vccnz .LBB0_556
	v_pk_mul_f32 v[146:147], v[6:7], v[138:139]
	v_pk_mul_f32 v[144:145], v[4:5], v[142:143]
	v_pk_mul_f32 v[154:155], v[2:3], v[136:137]
	v_pk_mul_f32 v[156:157], v[0:1], v[140:141]
	v_cvt_pk_bf16_f32 v144, v144, v145
	v_cvt_pk_bf16_f32 v145, v146, v147
	s_nop 0
	v_cvt_pk_bf16_f32 v146, v156, v157
	v_cvt_pk_bf16_f32 v147, v154, v155
	global_store_dwordx4 v[132:133], v[144:147], off offset:256 nt
	s_cbranch_execnz .LBB0_536

; __device__ __forceinline__ u32x4 pack8(const f32x4 v0, const f32x4 v1) { u32x4 w; w.x = cvt_pk_bf16(v0[0], v0[1]); w.y = cvt_pk_bf16(v0[2], v0[3]); w.z = cvt_pk_bf16(v1[0], v1[1]); w.w = cvt_pk_bf16(v1[2], v1[3]); return w; }
;     __device__ __forceinline__ void operator()(AccT& acc, const Unit& u, int wr, int wc, int fr, int fq) const {
;     ...
; #pragma unroll
;         for (int ai = 0; ai < 2; ++ai)
; #pragma unroll
;             for (int m = 0; m < 4; ++m) { const int row = row0 + ai * 128 + m * 16; bf16_t* rowp = O + (size_t)row * DM + col0; float ss = 0.f;
; #pragma unroll
;                 for (int bj = 0; bj < 2; ++bj) { const f32x4 v0 = acc[ai][bj][m][0], v1 = acc[ai][bj][m][1];
;                     ss += (v0[0] * v0[0] + v0[1] * v0[1]) + (v0[2] * v0[2] + v0[3] * v0[3]) + (v1[0] * v1[0] + v1[1] * v1[1]) + (v1[2] * v1[2] + v1[3] * v1[3]);
;                     *(u32x4*)(rowp + bj * 128) = pack8(v0, v1); }
;                 ss += __shfl_xor(ss, 16); ss += __shfl_xor(ss, 32);
;                 if (fq == 0) SSQ[(size_t)(u.pn * 4 + wc) * MT + row] = ss; }
.LBB0_635:
	v_mul_f32_e32 v148, v125, v125
	v_mul_f32_e32 v149, v127, v127
	v_fmac_f32_e32 v148, v124, v124
	v_fmac_f32_e32 v149, v126, v126
	v_add_f32_e32 v148, v148, v149
	v_mul_f32_e32 v149, v121, v121
	v_fmac_f32_e32 v149, v120, v120
	v_add_f32_e32 v148, v149, v148
	v_mul_f32_e32 v149, v123, v123
	v_mov_b32_e32 v132, v254
	v_fmac_f32_e32 v149, v122, v122
	v_add_f32_e32 v150, v149, v148
	v_cvt_pk_bf16_f32 v148, v124, v125
	v_mul_f32_e32 v124, v117, v117
	v_mul_f32_e32 v125, v119, v119
	s_lshl_b32 s4, s72, 8
	v_fmac_f32_e32 v124, v116, v116
	v_fmac_f32_e32 v125, v118, v118
	s_add_i32 s4, s4, s84
	v_add_f32_e32 v124, v124, v125
	v_mul_f32_e32 v125, v113, v113
	v_bfe_u32 v133, v132, 4, 2
	v_and_or_b32 v132, v132, 15, s4
	s_lshl_b32 s4, s63, 8
	v_fmac_f32_e32 v125, v112, v112
	s_or_b32 s4, s4, s85
	v_add_f32_e32 v124, v125, v124
	v_mul_f32_e32 v125, v115, v115
	v_lshl_or_b32 v136, v133, 3, s4
	s_lshl_b32 s4, s63, 2
	v_fmac_f32_e32 v125, v114, v114
	s_or_b32 s4, s4, s83
	v_cvt_pk_bf16_f32 v149, v126, v127
	v_add_f32_e32 v124, v125, v124
	v_and_b32_e32 v126, 64, v147
	s_ashr_i32 s5, s4, 31
	v_add_f32_e32 v125, v124, v150
	v_xor_b32_e32 v124, 16, v147
	v_add_u32_e32 v126, 64, v126
	s_lshl_b64 s[16:17], s[4:5], 15
	v_cmp_lt_i32_e64 s[4:5], v124, v126
	v_cmp_eq_u32_e32 vcc, 0, v133
	v_ashrrev_i32_e32 v133, 31, v132
	v_cndmask_b32_e64 v124, v147, v124, s[4:5]
	v_lshlrev_b64 v[134:135], 13, v[132:133]
	v_lshlrev_b32_e32 v124, 2, v124
	v_ashrrev_i32_e32 v137, 31, v136
	v_lshl_add_u64 v[134:135], s[20:21], 0, v[134:135]
	ds_bpermute_b32 v127, v124, v125
	v_lshl_add_u64 v[134:135], v[136:137], 1, v[134:135]
	v_cvt_pk_bf16_f32 v150, v120, v121
	v_cvt_pk_bf16_f32 v151, v122, v123
	global_store_dwordx4 v[134:135], v[148:151], off nt
	s_nop 1
	v_cvt_pk_bf16_f32 v148, v116, v117
	v_xor_b32_e32 v116, 32, v147
	v_cmp_lt_i32_e64 s[4:5], v116, v126
	s_waitcnt lgkmcnt(0)
	v_add_f32_e32 v117, v125, v127
	v_cvt_pk_bf16_f32 v149, v118, v119
	v_cvt_pk_bf16_f32 v150, v112, v113
	v_cvt_pk_bf16_f32 v151, v114, v115
	global_store_dwordx4 v[134:135], v[148:151], off offset:256 nt
	v_cndmask_b32_e64 v116, v147, v116, s[4:5]
	v_lshlrev_b32_e32 v116, 2, v116
	ds_bpermute_b32 v120, v116, v117
	s_and_saveexec_b64 s[4:5], vcc
	s_cbranch_execz .LBB0_637
	s_add_u32 s18, s81, s16
	s_addc_u32 s19, s82, s17
	s_waitcnt lgkmcnt(0)
	v_add_f32_e32 v114, v117, v120
	v_lshl_add_u64 v[112:113], v[132:133], 2, s[18:19]
	global_store_dword v[112:113], v114, off
.LBB0_637:
	s_or_b64 exec, exec, s[4:5]
	v_mul_f32_e32 v114, v109, v109
	v_mul_f32_e32 v115, v111, v111
	v_fmac_f32_e32 v114, v108, v108
	v_fmac_f32_e32 v115, v110, v110
	v_cvt_pk_bf16_f32 v108, v108, v109
	v_cvt_pk_bf16_f32 v109, v110, v111
	v_mul_f32_e32 v110, v101, v101
	v_mul_f32_e32 v111, v103, v103
	v_fmac_f32_e32 v110, v100, v100
	v_fmac_f32_e32 v111, v102, v102
	v_add_f32_e32 v114, v114, v115
	v_mul_f32_e32 v115, v105, v105
	v_add_f32_e32 v110, v110, v111
	v_mul_f32_e32 v111, v97, v97
	v_fmac_f32_e32 v115, v104, v104
	v_fmac_f32_e32 v111, v96, v96
	v_add_f32_e32 v114, v115, v114
	v_mul_f32_e32 v115, v107, v107
	v_add_f32_e32 v110, v111, v110
	v_mul_f32_e32 v111, v99, v99
	v_fmac_f32_e32 v115, v106, v106
	v_fmac_f32_e32 v111, v98, v98
	v_add_f32_e32 v114, v115, v114
	v_add_f32_e32 v110, v111, v110
	v_add_f32_e32 v114, v110, v114
	v_or_b32_e32 v112, 16, v132
	ds_bpermute_b32 v115, v124, v114
	v_ashrrev_i32_e32 v113, 31, v112
	v_lshlrev_b64 v[112:113], 13, v[112:113]
	v_lshl_add_u64 v[112:113], s[20:21], 0, v[112:113]
	v_lshl_add_u64 v[112:113], v[136:137], 1, v[112:113]
	v_cvt_pk_bf16_f32 v110, v104, v105
	v_cvt_pk_bf16_f32 v111, v106, v107
	global_store_dwordx4 v[112:113], v[108:111], off nt
	v_cvt_pk_bf16_f32 v104, v100, v101
	s_waitcnt lgkmcnt(0)
	v_add_f32_e32 v100, v114, v115
	ds_bpermute_b32 v101, v116, v100
	v_cvt_pk_bf16_f32 v105, v102, v103
	v_cvt_pk_bf16_f32 v106, v96, v97
	v_cvt_pk_bf16_f32 v107, v98, v99
	global_store_dwordx4 v[112:113], v[104:107], off offset:256 nt
	s_and_saveexec_b64 s[4:5], vcc
	s_cbranch_execz .LBB0_639
	s_add_u32 s18, s81, s16
	s_addc_u32 s19, s82, s17
	s_waitcnt lgkmcnt(0)
	v_add_f32_e32 v98, v100, v101
	v_lshl_add_u64 v[96:97], v[132:133], 2, s[18:19]
	global_store_dword v[96:97], v98, off offset:64
.LBB0_639:
	s_or_b64 exec, exec, s[4:5]
	v_mul_f32_e32 v98, v93, v93
	v_mul_f32_e32 v99, v95, v95
	v_fmac_f32_e32 v98, v92, v92
	v_fmac_f32_e32 v99, v94, v94
	v_cvt_pk_bf16_f32 v92, v92, v93
	v_cvt_pk_bf16_f32 v93, v94, v95
	v_mul_f32_e32 v94, v85, v85
	v_mul_f32_e32 v95, v87, v87
	v_fmac_f32_e32 v94, v84, v84
	v_fmac_f32_e32 v95, v86, v86
	v_add_f32_e32 v98, v98, v99
	v_mul_f32_e32 v99, v89, v89
	v_add_f32_e32 v94, v94, v95
	v_mul_f32_e32 v95, v81, v81
	v_fmac_f32_e32 v99, v88, v88
	v_fmac_f32_e32 v95, v80, v80
	v_add_f32_e32 v98, v99, v98
	v_mul_f32_e32 v99, v91, v91
	v_add_f32_e32 v94, v95, v94
	v_mul_f32_e32 v95, v83, v83
	v_fmac_f32_e32 v99, v90, v90
	v_fmac_f32_e32 v95, v82, v82
	v_add_f32_e32 v98, v99, v98
	v_add_f32_e32 v94, v95, v94
	v_add_f32_e32 v98, v94, v98
	v_or_b32_e32 v96, 32, v132
	ds_bpermute_b32 v99, v124, v98
	v_ashrrev_i32_e32 v97, 31, v96
	v_lshlrev_b64 v[96:97], 13, v[96:97]
	v_lshl_add_u64 v[96:97], s[20:21], 0, v[96:97]
	v_lshl_add_u64 v[96:97], v[136:137], 1, v[96:97]
	v_cvt_pk_bf16_f32 v94, v88, v89
	v_cvt_pk_bf16_f32 v95, v90, v91
	global_store_dwordx4 v[96:97], v[92:95], off nt
	v_cvt_pk_bf16_f32 v88, v84, v85
	s_waitcnt lgkmcnt(0)
	v_add_f32_e32 v84, v98, v99
	ds_bpermute_b32 v85, v116, v84
	v_cvt_pk_bf16_f32 v89, v86, v87
	v_cvt_pk_bf16_f32 v90, v80, v81
	v_cvt_pk_bf16_f32 v91, v82, v83
	global_store_dwordx4 v[96:97], v[88:91], off offset:256 nt
	s_and_saveexec_b64 s[4:5], vcc
	s_cbranch_execz .LBB0_641
	s_add_u32 s18, s81, s16
	s_addc_u32 s19, s82, s17
	s_waitcnt lgkmcnt(0)
	v_add_f32_e32 v82, v84, v85
	v_lshl_add_u64 v[80:81], v[132:133], 2, s[18:19]
	global_store_dword v[80:81], v82, off offset:128
; __device__ __forceinline__ u32x4 pack8(const f32x4 v0, const f32x4 v1) { u32x4 w; w.x = cvt_pk_bf16(v0[0], v0[1]); w.y = cvt_pk_bf16(v0[2], v0[3]); w.z = cvt_pk_bf16(v1[0], v1[1]); w.w = cvt_pk_bf16(v1[2], v1[3]); return w; }
;     __device__ __forceinline__ void operator()(AccT& acc, const Unit& u, int wr, int wc, int fr, int fq) const {
;     ...
; #pragma unroll
;         for (int ai = 0; ai < 2; ++ai)
; #pragma unroll
;             for (int m = 0; m < 4; ++m) { const int row = row0 + ai * 128 + m * 16; bf16_t* rowp = O + (size_t)row * DM + col0; float ss = 0.f;
; #pragma unroll
;                 for (int bj = 0; bj < 2; ++bj) { const f32x4 v0 = acc[ai][bj][m][0], v1 = acc[ai][bj][m][1];
;                     ss += (v0[0] * v0[0] + v0[1] * v0[1]) + (v0[2] * v0[2] + v0[3] * v0[3]) + (v1[0] * v1[0] + v1[1] * v1[1]) + (v1[2] * v1[2] + v1[3] * v1[3]);
;                     *(u32x4*)(rowp + bj * 128) = pack8(v0, v1); }
;                 ss += __shfl_xor(ss, 16); ss += __shfl_xor(ss, 32);
;                 if (fq == 0) SSQ[(size_t)(u.pn * 4 + wc) * MT + row] = ss; }
.LBB0_641:
	s_or_b64 exec, exec, s[4:5]
	v_mul_f32_e32 v82, v77, v77
	v_mul_f32_e32 v83, v79, v79
	v_fmac_f32_e32 v82, v76, v76
	v_fmac_f32_e32 v83, v78, v78
	v_cvt_pk_bf16_f32 v76, v76, v77
	v_cvt_pk_bf16_f32 v77, v78, v79
	v_mul_f32_e32 v78, v69, v69
	v_mul_f32_e32 v79, v71, v71
	v_fmac_f32_e32 v78, v68, v68
	v_fmac_f32_e32 v79, v70, v70
	v_add_f32_e32 v82, v82, v83
	v_mul_f32_e32 v83, v73, v73
	v_add_f32_e32 v78, v78, v79
	v_mul_f32_e32 v79, v65, v65
	v_fmac_f32_e32 v83, v72, v72
	v_fmac_f32_e32 v79, v64, v64
	v_add_f32_e32 v82, v83, v82
	v_mul_f32_e32 v83, v75, v75
	v_add_f32_e32 v78, v79, v78
	v_mul_f32_e32 v79, v67, v67
	v_fmac_f32_e32 v83, v74, v74
	v_fmac_f32_e32 v79, v66, v66
	v_add_f32_e32 v82, v83, v82
	v_add_f32_e32 v78, v79, v78
	v_add_f32_e32 v82, v78, v82
	v_or_b32_e32 v80, 48, v132
	ds_bpermute_b32 v83, v124, v82
	v_ashrrev_i32_e32 v81, 31, v80
	v_lshlrev_b64 v[80:81], 13, v[80:81]
	v_lshl_add_u64 v[80:81], s[20:21], 0, v[80:81]
	v_lshl_add_u64 v[80:81], v[136:137], 1, v[80:81]
	v_cvt_pk_bf16_f32 v78, v72, v73
	v_cvt_pk_bf16_f32 v79, v74, v75
	global_store_dwordx4 v[80:81], v[76:79], off nt
	v_cvt_pk_bf16_f32 v72, v68, v69
	s_waitcnt lgkmcnt(0)
	v_add_f32_e32 v68, v82, v83
	ds_bpermute_b32 v69, v116, v68
	v_cvt_pk_bf16_f32 v73, v70, v71
	v_cvt_pk_bf16_f32 v74, v64, v65
	v_cvt_pk_bf16_f32 v75, v66, v67
	global_store_dwordx4 v[80:81], v[72:75], off offset:256 nt
	s_and_saveexec_b64 s[4:5], vcc
	s_cbranch_execz .LBB0_643
	s_add_u32 s18, s81, s16
	s_addc_u32 s19, s82, s17
	s_waitcnt lgkmcnt(0)
	v_add_f32_e32 v66, v68, v69
	v_lshl_add_u64 v[64:65], v[132:133], 2, s[18:19]
	global_store_dword v[64:65], v66, off offset:192
.LBB0_643:
	s_or_b64 exec, exec, s[4:5]
	v_mul_f32_e32 v66, v61, v61
	v_mul_f32_e32 v67, v63, v63
	v_fmac_f32_e32 v66, v60, v60
	v_fmac_f32_e32 v67, v62, v62
	v_add_f32_e32 v66, v66, v67
	v_mul_f32_e32 v67, v57, v57
	v_fmac_f32_e32 v67, v56, v56
	v_cvt_pk_bf16_f32 v60, v60, v61
	v_cvt_pk_bf16_f32 v61, v62, v63
	v_cvt_pk_bf16_f32 v62, v56, v57
	v_mul_f32_e32 v56, v53, v53
	v_mul_f32_e32 v57, v55, v55
	v_fmac_f32_e32 v56, v52, v52
	v_fmac_f32_e32 v57, v54, v54
	v_add_f32_e32 v56, v56, v57
	v_mul_f32_e32 v57, v49, v49
	v_fmac_f32_e32 v57, v48, v48
	v_add_f32_e32 v66, v67, v66
	v_mul_f32_e32 v67, v59, v59
	v_add_f32_e32 v56, v57, v56
	v_mul_f32_e32 v57, v51, v51
	v_fmac_f32_e32 v67, v58, v58
	v_fmac_f32_e32 v57, v50, v50
	v_add_f32_e32 v66, v67, v66
	v_add_f32_e32 v56, v57, v56
	v_cvt_pk_bf16_f32 v63, v58, v59
	v_add_f32_e32 v58, v56, v66
	ds_bpermute_b32 v59, v124, v58
	s_mov_b64 s[4:5], 0x100000
	v_lshl_add_u64 v[64:65], v[134:135], 0, s[4:5]
	s_mov_b32 s4, 0x100000
	v_add_co_u32_e64 v56, s[4:5], s4, v134
	s_nop 1
	v_addc_co_u32_e64 v57, s[4:5], 0, v135, s[4:5]
	global_store_dwordx4 v[56:57], v[60:63], off nt
	v_cvt_pk_bf16_f32 v56, v52, v53
	s_waitcnt lgkmcnt(0)
	v_add_f32_e32 v52, v58, v59
	ds_bpermute_b32 v53, v116, v52
	v_cvt_pk_bf16_f32 v57, v54, v55
	v_cvt_pk_bf16_f32 v58, v48, v49
	v_cvt_pk_bf16_f32 v59, v50, v51
	global_store_dwordx4 v[64:65], v[56:59], off offset:256 nt
	s_and_saveexec_b64 s[4:5], vcc
	s_cbranch_execz .LBB0_645
	s_add_u32 s18, s81, s16
	s_addc_u32 s19, s82, s17
	s_waitcnt lgkmcnt(0)
	v_add_f32_e32 v50, v52, v53
	v_lshl_add_u64 v[48:49], v[132:133], 2, s[18:19]
	global_store_dword v[48:49], v50, off offset:512
; __device__ __forceinline__ u32x4 pack8(const f32x4 v0, const f32x4 v1) { u32x4 w; w.x = cvt_pk_bf16(v0[0], v0[1]); w.y = cvt_pk_bf16(v0[2], v0[3]); w.z = cvt_pk_bf16(v1[0], v1[1]); w.w = cvt_pk_bf16(v1[2], v1[3]); return w; }
;     __device__ __forceinline__ void operator()(AccT& acc, const Unit& u, int wr, int wc, int fr, int fq) const {
;     ...
; #pragma unroll
;         for (int ai = 0; ai < 2; ++ai)
; #pragma unroll
;             for (int m = 0; m < 4; ++m) { const int row = row0 + ai * 128 + m * 16; bf16_t* rowp = O + (size_t)row * DM + col0; float ss = 0.f;
; #pragma unroll
;                 for (int bj = 0; bj < 2; ++bj) { const f32x4 v0 = acc[ai][bj][m][0], v1 = acc[ai][bj][m][1];
;                     ss += (v0[0] * v0[0] + v0[1] * v0[1]) + (v0[2] * v0[2] + v0[3] * v0[3]) + (v1[0] * v1[0] + v1[1] * v1[1]) + (v1[2] * v1[2] + v1[3] * v1[3]);
;                     *(u32x4*)(rowp + bj * 128) = pack8(v0, v1); }
;                 ss += __shfl_xor(ss, 16); ss += __shfl_xor(ss, 32);
;                 if (fq == 0) SSQ[(size_t)(u.pn * 4 + wc) * MT + row] = ss; }
.LBB0_645:
	s_or_b64 exec, exec, s[4:5]
	v_mul_f32_e32 v50, v45, v45
	v_mul_f32_e32 v51, v47, v47
	v_fmac_f32_e32 v50, v44, v44
	v_fmac_f32_e32 v51, v46, v46
	v_add_f32_e32 v50, v50, v51
	v_mul_f32_e32 v51, v41, v41
	v_fmac_f32_e32 v51, v40, v40
	v_cvt_pk_bf16_f32 v44, v44, v45
	v_cvt_pk_bf16_f32 v45, v46, v47
	v_cvt_pk_bf16_f32 v46, v40, v41
	v_mul_f32_e32 v40, v37, v37
	v_mul_f32_e32 v41, v39, v39
	v_fmac_f32_e32 v40, v36, v36
	v_fmac_f32_e32 v41, v38, v38
	v_add_f32_e32 v40, v40, v41
	v_mul_f32_e32 v41, v33, v33
	v_fmac_f32_e32 v41, v32, v32
	v_add_f32_e32 v50, v51, v50
	v_mul_f32_e32 v51, v43, v43
	v_add_f32_e32 v40, v41, v40
	v_mul_f32_e32 v41, v35, v35
	v_fmac_f32_e32 v51, v42, v42
	v_fmac_f32_e32 v41, v34, v34
	v_add_f32_e32 v50, v51, v50
	v_add_f32_e32 v40, v41, v40
	v_cvt_pk_bf16_f32 v47, v42, v43
	v_add_f32_e32 v42, v40, v50
	ds_bpermute_b32 v43, v124, v42
	v_add_co_u32_e64 v40, s[4:5], s97, v134
	v_lshl_add_u64 v[48:49], v[134:135], 0, s[44:45]
	s_nop 0
	v_addc_co_u32_e64 v41, s[4:5], 0, v135, s[4:5]
	global_store_dwordx4 v[40:41], v[44:47], off nt
	v_cvt_pk_bf16_f32 v40, v36, v37
	s_waitcnt lgkmcnt(0)
	v_add_f32_e32 v36, v42, v43
	ds_bpermute_b32 v37, v116, v36
	v_cvt_pk_bf16_f32 v41, v38, v39
	v_cvt_pk_bf16_f32 v42, v32, v33
	v_cvt_pk_bf16_f32 v43, v34, v35
	global_store_dwordx4 v[48:49], v[40:43], off offset:256 nt
	s_and_saveexec_b64 s[4:5], vcc
	s_cbranch_execz .LBB0_647
	s_add_u32 s18, s81, s16
	s_addc_u32 s19, s82, s17
	s_waitcnt lgkmcnt(0)
	v_add_f32_e32 v34, v36, v37
	v_lshl_add_u64 v[32:33], v[132:133], 2, s[18:19]
	global_store_dword v[32:33], v34, off offset:576
.LBB0_647:
	s_or_b64 exec, exec, s[4:5]
	v_mul_f32_e32 v34, v29, v29
	v_mul_f32_e32 v35, v31, v31
	v_fmac_f32_e32 v34, v28, v28
	v_fmac_f32_e32 v35, v30, v30
	v_add_f32_e32 v34, v34, v35
	v_mul_f32_e32 v35, v25, v25
	v_fmac_f32_e32 v35, v24, v24
	v_cvt_pk_bf16_f32 v28, v28, v29
	v_cvt_pk_bf16_f32 v29, v30, v31
	v_cvt_pk_bf16_f32 v30, v24, v25
	v_mul_f32_e32 v24, v21, v21
	v_mul_f32_e32 v25, v23, v23
	v_fmac_f32_e32 v24, v20, v20
	v_fmac_f32_e32 v25, v22, v22
	v_add_f32_e32 v24, v24, v25
	v_mul_f32_e32 v25, v17, v17
	v_fmac_f32_e32 v25, v16, v16
	v_add_f32_e32 v34, v35, v34
	v_mul_f32_e32 v35, v27, v27
	v_add_f32_e32 v24, v25, v24
	v_mul_f32_e32 v25, v19, v19
	v_fmac_f32_e32 v35, v26, v26
	v_fmac_f32_e32 v25, v18, v18
	v_add_f32_e32 v34, v35, v34
	v_add_f32_e32 v24, v25, v24
	v_cvt_pk_bf16_f32 v31, v26, v27
	v_add_f32_e32 v26, v24, v34
	ds_bpermute_b32 v27, v124, v26
	v_add_co_u32_e64 v24, s[4:5], s33, v134
	v_lshl_add_u64 v[32:33], v[134:135], 0, s[46:47]
	s_nop 0
	v_addc_co_u32_e64 v25, s[4:5], 0, v135, s[4:5]
	global_store_dwordx4 v[24:25], v[28:31], off nt
	v_cvt_pk_bf16_f32 v24, v20, v21
	s_waitcnt lgkmcnt(0)
	v_add_f32_e32 v20, v26, v27
	ds_bpermute_b32 v21, v116, v20
	v_cvt_pk_bf16_f32 v25, v22, v23
	v_cvt_pk_bf16_f32 v26, v16, v17
	v_cvt_pk_bf16_f32 v27, v18, v19
	global_store_dwordx4 v[32:33], v[24:27], off offset:256 nt
	s_and_saveexec_b64 s[4:5], vcc
	s_cbranch_execz .LBB0_649
	s_add_u32 s18, s81, s16
	s_addc_u32 s19, s82, s17
	s_waitcnt lgkmcnt(0)
	v_add_f32_e32 v18, v20, v21
	v_lshl_add_u64 v[16:17], v[132:133], 2, s[18:19]
	global_store_dword v[16:17], v18, off offset:640
.LBB0_649:
	s_or_b64 exec, exec, s[4:5]
	v_mul_f32_e32 v18, v13, v13
	v_mul_f32_e32 v19, v15, v15
	v_fmac_f32_e32 v18, v12, v12
	v_fmac_f32_e32 v19, v14, v14
	v_add_f32_e32 v18, v18, v19
	v_mul_f32_e32 v19, v9, v9
	v_fmac_f32_e32 v19, v8, v8
	v_cvt_pk_bf16_f32 v12, v12, v13
	v_cvt_pk_bf16_f32 v13, v14, v15
	v_cvt_pk_bf16_f32 v14, v8, v9
	v_mul_f32_e32 v8, v5, v5
	v_mul_f32_e32 v9, v7, v7
	v_fmac_f32_e32 v8, v4, v4
	v_fmac_f32_e32 v9, v6, v6
	v_add_f32_e32 v8, v8, v9
	v_mul_f32_e32 v9, v1, v1
	v_fmac_f32_e32 v9, v0, v0
	v_add_f32_e32 v18, v19, v18
	v_mul_f32_e32 v19, v11, v11
	v_add_f32_e32 v8, v9, v8
	v_mul_f32_e32 v9, v3, v3
	v_fmac_f32_e32 v19, v10, v10
	v_fmac_f32_e32 v9, v2, v2
	v_add_f32_e32 v18, v19, v18
	v_add_f32_e32 v8, v9, v8
	v_cvt_pk_bf16_f32 v15, v10, v11
	v_add_f32_e32 v10, v8, v18
	ds_bpermute_b32 v11, v124, v10
	v_add_co_u32_e64 v8, s[4:5], s62, v134
	v_lshl_add_u64 v[16:17], v[134:135], 0, s[48:49]
	s_nop 0
	v_addc_co_u32_e64 v9, s[4:5], 0, v135, s[4:5]
	global_store_dwordx4 v[8:9], v[12:15], off nt
	v_cvt_pk_bf16_f32 v8, v4, v5
	s_waitcnt lgkmcnt(0)
	v_add_f32_e32 v4, v10, v11
	ds_bpermute_b32 v5, v116, v4
	v_cvt_pk_bf16_f32 v9, v6, v7
	v_cvt_pk_bf16_f32 v10, v0, v1
	v_cvt_pk_bf16_f32 v11, v2, v3
	global_store_dwordx4 v[16:17], v[8:11], off offset:256 nt
	s_and_saveexec_b64 s[4:5], vcc
	s_cbranch_execz .LBB0_651
	s_add_u32 s16, s81, s16
	s_addc_u32 s17, s82, s17
	s_waitcnt lgkmcnt(0)
	v_add_f32_e32 v2, v4, v5
	v_lshl_add_u64 v[0:1], v[132:133], 2, s[16:17]
	global_store_dword v[0:1], v2, off offset:704

; #define LAS __attribute__((address_space(3)))
;     __device__ __forceinline__ int xidx(int ai, int w_r, int wc, int rsel, int fq, int bj, int n) const { return (((((ai * 2 + w_r) * 4 + wc) * 2 + rsel) * 4 + fq) * 4 + bj * 2 + n) * 16; }
;     __device__ __forceinline__ void operator()(AccT& acc, const Unit& u, int wr, int wc, int fr, int fq) const {
;     ...
;         if (fr >= 14) {
; #pragma unroll
;             for (int ai = 0; ai < 2; ++ai)
; #pragma unroll
;                 for (int bj = 0; bj < 2; ++bj)
; #pragma unroll
;                     for (int n = 0; n < 2; ++n) *(LAS f32x4*)(xl + xidx(ai, wr, wc, fr - 14, fq, bj, n)) = acc[ai][bj][3][n];
;             if (wr == 1) {
; #pragma unroll
;                 for (int bj = 0; bj < 2; ++bj)
; #pragma unroll
;                     for (int n = 0; n < 2; ++n) *(f32x4*)(HB + (size_t)(u.pm * 4 + fr - 14) * FF2 + u.pn * 256 + bj * 128 + lcol + 4 * n) = acc[1][bj][3][n]; }
;         }
;         if (wr == 0 && fr < 2) {
; #pragma unroll
;             for (int bj = 0; bj < 2; ++bj)
; #pragma unroll
;                 for (int n = 0; n < 2; ++n) *(f32x4*)(HB + (size_t)(u.pm * 4 + 2 + fr) * FF2 + u.pn * 256 + bj * 128 + lcol + 4 * n) = acc[0][bj][0][n]; }
.LBB0_781:
	v_mov_b32_e32 v108, v254
	v_cndmask_b32_e64 v118, 0, 1, s[26:27]
	v_and_b32_e32 v199, 15, v108
	v_bfe_u32 v108, v108, 4, 2
	v_lshl_or_b32 v109, v108, 3, s77
	v_cmp_lt_u32_e64 s[6:7], 13, v199
	v_lshl_or_b32 v108, v199, 2, v108
	v_cmp_ne_u32_e64 s[4:5], 1, v118
	s_and_saveexec_b64 s[12:13], s[6:7]
	s_cbranch_execz .LBB0_784
	v_add_u32_e32 v118, s85, v108
	v_lshl_add_u32 v118, v118, 6, 0
	v_add_u32_e32 v118, 0x1f200, v118
	s_and_b64 vcc, exec, s[4:5]
	ds_write_b128 v118, v[110:113]
	ds_write_b128 v118, v[36:39] offset:16
	ds_write_b128 v118, v[96:99] offset:32
	ds_write_b128 v118, v[32:35] offset:48
	ds_write_b128 v118, v[72:75] offset:4096
	ds_write_b128 v118, v[4:7] offset:4112
	ds_write_b128 v118, v[64:67] offset:4128
	ds_write_b128 v118, v[0:3] offset:4144
	s_cbranch_vccnz .LBB0_784
	s_lshl_b32 s8, s50, 2
	v_add3_u32 v120, s8, -14, v199
	s_lshl_b32 s8, s3, 8
	v_mov_b64_e32 v[118:119], s[38:39]
	s_ashr_i32 s9, s8, 31
	v_mad_i64_i32 v[118:119], s[16:17], v120, s93, v[118:119]
	v_lshl_add_u64 v[118:119], s[8:9], 2, v[118:119]
	v_lshlrev_b32_e32 v184, 2, v109
	v_lshl_add_u64 v[118:119], v[118:119], 0, v[184:185]
	global_store_dwordx4 v[118:119], v[72:75], off nt
	global_store_dwordx4 v[118:119], v[4:7], off offset:16 nt
	global_store_dwordx4 v[118:119], v[64:67], off offset:512 nt
	global_store_dwordx4 v[118:119], v[0:3], off offset:528 nt
.LBB0_784:
	s_or_b64 exec, exec, s[12:13]
	v_cmp_gt_u32_e32 vcc, 2, v199
	s_and_b64 s[8:9], s[40:41], vcc
	s_and_saveexec_b64 s[12:13], s[8:9]
	s_cbranch_execz .LBB0_786
	s_lshl_b32 s8, s50, 2
	v_or3_b32 v120, v199, s8, 2
	s_lshl_b32 s8, s3, 8
	v_mov_b64_e32 v[118:119], s[38:39]
	s_ashr_i32 s9, s8, 31
	v_mad_i64_i32 v[118:119], s[16:17], v120, s93, v[118:119]
	v_lshl_add_u64 v[118:119], s[8:9], 2, v[118:119]
	v_lshlrev_b32_e32 v184, 2, v109
	v_lshl_add_u64 v[118:119], v[118:119], 0, v[184:185]
	global_store_dwordx4 v[118:119], v[158:161], off nt
	global_store_dwordx4 v[118:119], v[60:63], off offset:16 nt
	global_store_dwordx4 v[118:119], v[104:107], off offset:512 nt
	global_store_dwordx4 v[118:119], v[56:59], off offset:528 nt

; #define LAS __attribute__((address_space(3)))
; __device__ __forceinline__ unsigned cvt_pk_bf16(float lo, float hi) { unsigned r; asm volatile("v_cvt_pk_bf16_f32 %0, %1, %2" : "=v"(r) : "v"(lo), "v"(hi)); return r; }
; __device__ __forceinline__ float gelu_t(float x) { const float u = 1.5957691216f * (x + 0.044715f * x * x * x); return x * sigm(u); }
; __device__ __forceinline__ float dpp_shr1(float old, float src) { return __int_as_float(__builtin_amdgcn_update_dpp(__float_as_int(old), __float_as_int(src), 0x111, 0xf, 0xf, false)); }
; __device__ __forceinline__ float dpp_shr2(float old, float src) { return __int_as_float(__builtin_amdgcn_update_dpp(__float_as_int(old), __float_as_int(src), 0x112, 0xf, 0xf, false)); }
;     __device__ __forceinline__ void operator()(AccT& acc, const Unit& u, int wr, int wc, int fr, int fq) const {
;     ...
;             for (int ai = 0; ai < 2; ++ai) {
;                 f32x4 hv[2]; hv[0] = (f32x4){0.f, 0.f, 0.f, 0.f}; hv[1] = hv[0];
;                 const bool has_pred = (wr == 1) || (ai == 1);
;                 const int pa = (wr == 1) ? ai : 0, pw = (wr == 1) ? 0 : 1;
;                 if (has_pred && fr >= 14) { hv[0] = *(const LAS f32x4*)(xl + xidx(pa, pw, wc, fr - 14, fq, 0, n)); hv[1] = *(const LAS f32x4*)(xl + xidx(pa, pw, wc, fr - 14, fq, 1, n)); }
; #pragma unroll
;                 for (int m = 0; m < 4; ++m) {
;                     f32x4 c2[2];
; #pragma unroll
;                     for (int bj = 0; bj < 2; ++bj) { const f32x4 cur = acc[ai][bj][m][n]; const f32x4 pv = (m == 0) ? hv[bj] : acc[ai][bj][m == 0 ? 0 : m - 1][n];
; #pragma unroll
;                         for (int j = 0; j < 4; ++j) { const float p1 = dpp_shr1(dpp_ror1(pv[j]), cur[j]), p2 = dpp_shr2(dpp_ror2(pv[j]), cur[j]);
;                             c2[bj][j] = bia[bj][j] + wgt[bj][0][j] * p2 + wgt[bj][1][j] * p1 + wgt[bj][2][j] * cur[j]; } }
;                     u32x2 w; w.x = cvt_pk_bf16(gelu_t(c2[0][0]) * c2[1][0], gelu_t(c2[0][1]) * c2[1][1]); w.y = cvt_pk_bf16(gelu_t(c2[0][2]) * c2[1][2], gelu_t(c2[0][3]) * c2[1][3]);
;                     if (n == 0) pend[ai][m] = w;
;                     else { u32x4 w4; w4.x = pend[ai][m].x; w4.y = pend[ai][m].y; w4.z = w.x; w4.w = w.y;
;                         *(u32x4*)(F + (size_t)(t0 + ai * 128 + wr * 64 + m * 16 + fr) * FF + cg - 4) = w4; }
;                 }
.LBB0_792:
	s_or_b64 exec, exec, s[16:17]
	v_mov_b32_e32 v126, 0
	v_mov_b32_e32 v127, 0
	v_mov_b32_e32 v82, 0
	s_waitcnt lgkmcnt(1)
	v_mov_b32_dpp v126, v122 row_ror:2 row_mask:0xf bank_mask:0xf
	v_mov_b32_e32 v128, 0
	v_mov_b32_e32 v130, 0
	v_mov_b32_e32 v83, 0
	s_waitcnt lgkmcnt(0)
	v_mov_b32_dpp v127, v118 row_ror:2 row_mask:0xf bank_mask:0xf
	v_mov_b32_dpp v82, v122 row_ror:1 row_mask:0xf bank_mask:0xf
	v_mov_b32_dpp v126, v60 row_shr:2 row_mask:0xf bank_mask:0xf
	v_mov_b32_dpp v128, v123 row_ror:1 row_mask:0xf bank_mask:0xf
	v_mov_b32_dpp v130, v123 row_ror:2 row_mask:0xf bank_mask:0xf
	v_mov_b32_e32 v134, 0
	v_mov_b32_e32 v136, 0
	v_mov_b32_e32 v138, 0
	v_mov_b32_e32 v140, 0
	v_mov_b32_dpp v83, v118 row_ror:1 row_mask:0xf bank_mask:0xf
	v_mov_b32_dpp v127, v56 row_shr:2 row_mask:0xf bank_mask:0xf
	s_waitcnt vmcnt(6)
	v_mov_b32_e32 v78, v114
	s_waitcnt vmcnt(2)
	v_mov_b32_e32 v79, v74
	v_mov_b32_e32 v122, v100
	v_mov_b32_e32 v123, v70
	v_mov_b32_dpp v82, v60 row_shr:1 row_mask:0xf bank_mask:0xf
	v_mov_b32_dpp v134, v124 row_ror:1 row_mask:0xf bank_mask:0xf
	v_mov_b32_dpp v136, v124 row_ror:2 row_mask:0xf bank_mask:0xf
	v_mov_b32_dpp v138, v125 row_ror:1 row_mask:0xf bank_mask:0xf
	v_mov_b32_dpp v140, v125 row_ror:2 row_mask:0xf bank_mask:0xf
	v_mov_b32_dpp v83, v56 row_shr:1 row_mask:0xf bank_mask:0xf
	v_pk_fma_f32 v[126:127], v[78:79], v[126:127], v[122:123]
	v_mov_b32_e32 v124, v110
	s_waitcnt vmcnt(1)
	v_mov_b32_e32 v125, v84
	v_mov_b32_e32 v131, 0
	v_pk_fma_f32 v[82:83], v[124:125], v[82:83], v[126:127]
	v_mov_b32_e32 v142, v60
	v_mov_b32_e32 v143, v56
	v_mov_b32_e32 v126, v92
	s_waitcnt vmcnt(0)
	v_mov_b32_e32 v127, v66
	v_mov_b32_dpp v131, v119 row_ror:2 row_mask:0xf bank_mask:0xf
	v_mov_b32_dpp v130, v61 row_shr:2 row_mask:0xf bank_mask:0xf
	v_pk_fma_f32 v[82:83], v[142:143], v[126:127], v[82:83]
	v_mov_b32_dpp v131, v57 row_shr:2 row_mask:0xf bank_mask:0xf
	v_mov_b32_e32 v74, v115
	v_mov_b32_e32 v70, v101
	v_mov_b32_e32 v129, 0
	v_pk_fma_f32 v[100:101], v[74:75], v[130:131], v[70:71]
	v_mov_b32_e32 v131, v68
	v_mul_f32_e32 v68, 0x3d372713, v82
	v_mov_b32_dpp v129, v119 row_ror:1 row_mask:0xf bank_mask:0xf
	v_mul_f32_e32 v68, v82, v68
	v_mov_b32_dpp v128, v61 row_shr:1 row_mask:0xf bank_mask:0xf
	v_mov_b32_dpp v129, v57 row_shr:1 row_mask:0xf bank_mask:0xf
	v_mov_b32_e32 v84, v111
	v_fma_f32 v68, v82, v68, v82
	v_pk_fma_f32 v[100:101], v[84:85], v[128:129], v[100:101]
	v_mov_b32_e32 v110, v61
	v_mov_b32_e32 v111, v57
	v_mov_b32_e32 v66, v93
	v_mul_f32_e32 v68, 0x3fcc422a, v68
	v_pk_fma_f32 v[92:93], v[110:111], v[66:67], v[100:101]
	v_mul_f32_e32 v68, 0xbfb8aa3b, v68
	v_exp_f32_e32 v91, v68
	v_mul_f32_e32 v68, 0x3d372713, v92
	v_mul_f32_e32 v68, v92, v68
	v_fma_f32 v68, v92, v68, v92
	v_mul_f32_e32 v68, 0x3fcc422a, v68
	v_mul_f32_e32 v68, 0xbfb8aa3b, v68
	v_mov_b32_e32 v130, v94
	v_exp_f32_e32 v94, v68
	v_mov_b32_e32 v137, 0
	v_mov_b32_e32 v135, 0
	v_mov_b32_e32 v141, 0
	v_mov_b32_dpp v137, v120 row_ror:2 row_mask:0xf bank_mask:0xf
	v_add_f32_e32 v91, 1.0, v91
	v_mov_b32_dpp v136, v62 row_shr:2 row_mask:0xf bank_mask:0xf
	v_mov_b32_dpp v135, v120 row_ror:1 row_mask:0xf bank_mask:0xf
	v_mov_b32_dpp v137, v58 row_shr:2 row_mask:0xf bank_mask:0xf
	v_mov_b32_e32 v114, v116
	v_mov_b32_e32 v115, v76
	v_mov_b32_e32 v118, v102
	v_mov_b32_e32 v119, v72
	v_mov_b32_e32 v139, 0
	v_mov_b32_dpp v141, v121 row_ror:2 row_mask:0xf bank_mask:0xf
	v_rcp_f32_e32 v91, v91
	v_add_f32_e32 v94, 1.0, v94
	v_mov_b32_dpp v134, v62 row_shr:1 row_mask:0xf bank_mask:0xf
	v_mov_b32_dpp v140, v63 row_shr:2 row_mask:0xf bank_mask:0xf
	v_mov_b32_dpp v135, v58 row_shr:1 row_mask:0xf bank_mask:0xf
	v_pk_fma_f32 v[100:101], v[114:115], v[136:137], v[118:119]
	v_mov_b32_e32 v128, v112
	v_mov_b32_e32 v129, v86
	v_mov_b32_dpp v139, v121 row_ror:1 row_mask:0xf bank_mask:0xf
	v_mov_b32_dpp v141, v59 row_shr:2 row_mask:0xf bank_mask:0xf
	v_mov_b32_e32 v76, v117
	v_mov_b32_e32 v72, v103
	v_rcp_f32_e32 v112, v94
	v_mov_b32_dpp v138, v63 row_shr:1 row_mask:0xf bank_mask:0xf
	v_pk_fma_f32 v[100:101], v[128:129], v[134:135], v[100:101]
	v_mov_b32_e32 v110, v62
	v_mov_b32_e32 v111, v58
	v_mov_b32_dpp v139, v59 row_shr:1 row_mask:0xf bank_mask:0xf
	v_pk_fma_f32 v[102:103], v[76:77], v[140:141], v[72:73]
	v_mov_b32_e32 v86, v113
	v_pk_fma_f32 v[100:101], v[110:111], v[130:131], v[100:101]
	v_pk_fma_f32 v[102:103], v[86:87], v[138:139], v[102:103]
	v_mov_b32_e32 v110, v63
	v_mov_b32_e32 v111, v59
	v_mov_b32_e32 v68, v95
	v_pk_fma_f32 v[94:95], v[110:111], v[68:69], v[102:103]
	v_mul_f32_e32 v82, v82, v91
	v_mul_f32_e32 v82, v82, v83
	v_mul_f32_e32 v83, v92, v112
	v_mul_f32_e32 v91, 0x3d372713, v100
	v_mul_f32_e32 v92, 0x3d372713, v94
	v_mul_f32_e32 v91, v100, v91
	v_mul_f32_e32 v92, v94, v92
	v_fma_f32 v91, v100, v91, v100
	v_fma_f32 v92, v94, v92, v94
	v_mul_f32_e32 v91, 0x3fcc422a, v91
	v_mul_f32_e32 v92, 0x3fcc422a, v92
	v_mul_f32_e32 v91, 0xbfb8aa3b, v91
	v_mul_f32_e32 v92, 0xbfb8aa3b, v92
	v_exp_f32_e32 v91, v91
	v_exp_f32_e32 v92, v92
	v_mul_f32_e32 v83, v83, v93
	s_lshl_b32 s3, s50, 8
	v_add_f32_e32 v91, 1.0, v91
	v_add_f32_e32 v92, 1.0, v92
	v_rcp_f32_e32 v91, v91
	v_rcp_f32_e32 v92, v92
	v_cvt_pk_bf16_f32 v110, v82, v83
	s_add_i32 s3, s3, s76
	v_mul_f32_e32 v82, v100, v91
	v_mul_f32_e32 v83, v94, v92
	v_mul_f32_e32 v82, v82, v101
	v_mul_f32_e32 v83, v83, v95
	v_or_b32_e32 v132, s3, v199
	v_cvt_pk_bf16_f32 v111, v82, v83
	v_mov_b64_e32 v[82:83], s[36:37]
	v_mad_i64_i32 v[92:93], s[8:9], v132, s94, v[82:83]
	v_lshlrev_b64 v[94:95], 1, v[186:187]
	v_lshl_add_u64 v[92:93], v[92:93], 0, v[94:95]
	v_mov_b32_e32 v100, 0
	v_mov_b32_e32 v101, 0
	global_store_dwordx4 v[92:93], v[108:111], off nt
; #define LAS __attribute__((address_space(3)))
; __device__ __forceinline__ unsigned cvt_pk_bf16(float lo, float hi) { unsigned r; asm volatile("v_cvt_pk_bf16_f32 %0, %1, %2" : "=v"(r) : "v"(lo), "v"(hi)); return r; }
; __device__ __forceinline__ float gelu_t(float x) { const float u = 1.5957691216f * (x + 0.044715f * x * x * x); return x * sigm(u); }
; __device__ __forceinline__ float dpp_shr1(float old, float src) { return __int_as_float(__builtin_amdgcn_update_dpp(__float_as_int(old), __float_as_int(src), 0x111, 0xf, 0xf, false)); }
; __device__ __forceinline__ float dpp_shr2(float old, float src) { return __int_as_float(__builtin_amdgcn_update_dpp(__float_as_int(old), __float_as_int(src), 0x112, 0xf, 0xf, false)); }
;     __device__ __forceinline__ void operator()(AccT& acc, const Unit& u, int wr, int wc, int fr, int fq) const {
;     ...
;             for (int ai = 0; ai < 2; ++ai) {
;                 f32x4 hv[2]; hv[0] = (f32x4){0.f, 0.f, 0.f, 0.f}; hv[1] = hv[0];
;                 const bool has_pred = (wr == 1) || (ai == 1);
;                 const int pa = (wr == 1) ? ai : 0, pw = (wr == 1) ? 0 : 1;
;                 if (has_pred && fr >= 14) { hv[0] = *(const LAS f32x4*)(xl + xidx(pa, pw, wc, fr - 14, fq, 0, n)); hv[1] = *(const LAS f32x4*)(xl + xidx(pa, pw, wc, fr - 14, fq, 1, n)); }
; #pragma unroll
;                 for (int m = 0; m < 4; ++m) {
;                     f32x4 c2[2];
; #pragma unroll
;                     for (int bj = 0; bj < 2; ++bj) { const f32x4 cur = acc[ai][bj][m][n]; const f32x4 pv = (m == 0) ? hv[bj] : acc[ai][bj][m == 0 ? 0 : m - 1][n];
; #pragma unroll
;                         for (int j = 0; j < 4; ++j) { const float p1 = dpp_shr1(dpp_ror1(pv[j]), cur[j]), p2 = dpp_shr2(dpp_ror2(pv[j]), cur[j]);
;                             c2[bj][j] = bia[bj][j] + wgt[bj][0][j] * p2 + wgt[bj][1][j] * p1 + wgt[bj][2][j] * cur[j]; } }
;                     u32x2 w; w.x = cvt_pk_bf16(gelu_t(c2[0][0]) * c2[1][0], gelu_t(c2[0][1]) * c2[1][1]); w.y = cvt_pk_bf16(gelu_t(c2[0][2]) * c2[1][2], gelu_t(c2[0][3]) * c2[1][3]);
;                     if (n == 0) pend[ai][m] = w;
;                     else { u32x4 w4; w4.x = pend[ai][m].x; w4.y = pend[ai][m].y; w4.z = w.x; w4.w = w.y;
;                         *(u32x4*)(F + (size_t)(t0 + ai * 128 + wr * 64 + m * 16 + fr) * FF + cg - 4) = w4; }
;                 }
	v_mov_b32_e32 v92, 0
	v_mov_b32_dpp v100, v60 row_ror:2 row_mask:0xf bank_mask:0xf
	v_mov_b32_e32 v108, 0
	v_mov_b32_e32 v110, 0
	v_mov_b32_e32 v93, 0
	v_mov_b32_dpp v101, v56 row_ror:2 row_mask:0xf bank_mask:0xf
	v_mov_b32_dpp v92, v60 row_ror:1 row_mask:0xf bank_mask:0xf
	v_mov_b32_dpp v100, v52 row_shr:2 row_mask:0xf bank_mask:0xf
	v_mov_b32_dpp v108, v62 row_ror:1 row_mask:0xf bank_mask:0xf
	v_mov_b32_dpp v110, v62 row_ror:2 row_mask:0xf bank_mask:0xf
	v_mov_b32_e32 v62, 0
	v_mov_b32_e32 v112, 0
	v_mov_b32_dpp v93, v56 row_ror:1 row_mask:0xf bank_mask:0xf
	v_mov_b32_dpp v101, v48 row_shr:2 row_mask:0xf bank_mask:0xf
	v_mov_b32_e32 v113, 0
	v_mov_b32_dpp v92, v52 row_shr:1 row_mask:0xf bank_mask:0xf
	v_mov_b32_dpp v62, v63 row_ror:1 row_mask:0xf bank_mask:0xf
	v_mov_b32_dpp v112, v63 row_ror:2 row_mask:0xf bank_mask:0xf
	v_mov_b32_dpp v93, v48 row_shr:1 row_mask:0xf bank_mask:0xf
	v_pk_fma_f32 v[100:101], v[78:79], v[100:101], v[122:123]
	v_mov_b32_e32 v63, 0
	v_mov_b32_dpp v113, v59 row_ror:2 row_mask:0xf bank_mask:0xf
	v_mov_b32_dpp v112, v55 row_shr:2 row_mask:0xf bank_mask:0xf
	v_pk_fma_f32 v[92:93], v[124:125], v[92:93], v[100:101]
	v_mov_b32_e32 v100, v52
	v_mov_b32_e32 v101, v48
	v_mov_b32_e32 v109, 0
	v_mov_b32_e32 v111, 0
	v_mov_b32_dpp v63, v59 row_ror:1 row_mask:0xf bank_mask:0xf
	v_mov_b32_dpp v113, v51 row_shr:2 row_mask:0xf bank_mask:0xf
	v_mov_b32_dpp v62, v55 row_shr:1 row_mask:0xf bank_mask:0xf
	v_pk_fma_f32 v[92:93], v[100:101], v[126:127], v[92:93]
	v_mov_b32_dpp v109, v58 row_ror:1 row_mask:0xf bank_mask:0xf
	v_mov_b32_dpp v111, v58 row_ror:2 row_mask:0xf bank_mask:0xf
	v_mov_b32_dpp v63, v51 row_shr:1 row_mask:0xf bank_mask:0xf
	v_pk_fma_f32 v[58:59], v[76:77], v[112:113], v[72:73]
	v_mov_b32_e32 v60, 0
	v_pk_fma_f32 v[58:59], v[86:87], v[62:63], v[58:59]
	v_mul_f32_e32 v63, 0x3d372713, v92
	v_mov_b32_e32 v102, 0
	v_mov_b32_e32 v103, 0
	v_mul_f32_e32 v63, v92, v63
	v_mov_b32_dpp v60, v61 row_ror:1 row_mask:0xf bank_mask:0xf
	v_mov_b32_dpp v102, v61 row_ror:2 row_mask:0xf bank_mask:0xf
	v_mov_b32_e32 v61, 0
	v_mov_b32_dpp v103, v57 row_ror:2 row_mask:0xf bank_mask:0xf
	v_fma_f32 v63, v92, v63, v92
	v_mov_b32_dpp v102, v53 row_shr:2 row_mask:0xf bank_mask:0xf
	v_mov_b32_dpp v61, v57 row_ror:1 row_mask:0xf bank_mask:0xf
	v_mov_b32_dpp v103, v49 row_shr:2 row_mask:0xf bank_mask:0xf
	v_mul_f32_e32 v63, 0x3fcc422a, v63
	v_mov_b32_dpp v60, v53 row_shr:1 row_mask:0xf bank_mask:0xf
	v_mov_b32_dpp v61, v49 row_shr:1 row_mask:0xf bank_mask:0xf
	v_pk_fma_f32 v[56:57], v[74:75], v[102:103], v[70:71]
	v_mul_f32_e32 v63, 0xbfb8aa3b, v63
	v_pk_fma_f32 v[56:57], v[84:85], v[60:61], v[56:57]
	v_mov_b32_e32 v60, v53
	v_mov_b32_e32 v61, v49
	v_exp_f32_e32 v91, v63
	v_pk_fma_f32 v[56:57], v[60:61], v[66:67], v[56:57]
	v_mov_b32_dpp v110, v54 row_shr:2 row_mask:0xf bank_mask:0xf
	v_mul_f32_e32 v63, 0x3d372713, v56
	v_mul_f32_e32 v63, v56, v63
	v_mov_b32_dpp v111, v50 row_shr:2 row_mask:0xf bank_mask:0xf
	v_fma_f32 v63, v56, v63, v56
	v_add_f32_e32 v91, 1.0, v91
	v_mov_b32_dpp v108, v54 row_shr:1 row_mask:0xf bank_mask:0xf
	v_mov_b32_dpp v109, v50 row_shr:1 row_mask:0xf bank_mask:0xf
	v_pk_fma_f32 v[60:61], v[114:115], v[110:111], v[118:119]
	v_mul_f32_e32 v63, 0x3fcc422a, v63
	v_rcp_f32_e32 v91, v91
	v_pk_fma_f32 v[60:61], v[128:129], v[108:109], v[60:61]
	v_mov_b32_e32 v100, v54
	v_mov_b32_e32 v101, v50
	v_mul_f32_e32 v63, 0xbfb8aa3b, v63
	v_pk_fma_f32 v[60:61], v[100:101], v[130:131], v[60:61]
	v_mov_b32_e32 v62, v55
	v_exp_f32_e32 v100, v63
	v_mov_b32_e32 v63, v51
	v_pk_fma_f32 v[58:59], v[62:63], v[68:69], v[58:59]
	v_mul_f32_e32 v63, 0x3d372713, v60
	v_mul_f32_e32 v62, v92, v91
	v_mul_f32_e32 v63, v60, v63
	v_mul_f32_e32 v91, 0x3d372713, v58
	v_fma_f32 v63, v60, v63, v60
	v_mul_f32_e32 v91, v58, v91
	v_add_f32_e32 v100, 1.0, v100
	v_mul_f32_e32 v63, 0x3fcc422a, v63
	v_fma_f32 v91, v58, v91, v58
	v_rcp_f32_e32 v100, v100
	v_mul_f32_e32 v63, 0xbfb8aa3b, v63
	v_mul_f32_e32 v91, 0x3fcc422a, v91
	v_exp_f32_e32 v63, v63
	v_mul_f32_e32 v91, 0xbfb8aa3b, v91
	v_exp_f32_e32 v91, v91
	v_mul_f32_e32 v56, v56, v100
	v_mul_f32_e32 v56, v56, v57
	v_add_f32_e32 v57, 1.0, v63
	v_rcp_f32_e32 v57, v57
	v_add_f32_e32 v63, 1.0, v91
	v_rcp_f32_e32 v63, v63
	v_mul_f32_e32 v62, v62, v93
	v_cvt_pk_bf16_f32 v108, v62, v56
	v_mul_f32_e32 v56, v60, v57
	v_mul_f32_e32 v56, v56, v61
	v_mul_f32_e32 v57, v58, v63
	v_mul_f32_e32 v57, v57, v59
	v_cvt_pk_bf16_f32 v109, v56, v57
	v_or_b32_e32 v56, 16, v132
	v_mad_i64_i32 v[56:57], s[8:9], v56, s94, v[82:83]
	v_lshl_add_u64 v[56:57], v[56:57], 0, v[94:95]
	v_mov_b32_e32 v58, 0
	v_mov_b32_e32 v59, 0
	global_store_dwordx4 v[56:57], v[106:109], off nt
	v_mov_b32_e32 v56, 0
	v_mov_b32_dpp v58, v52 row_ror:2 row_mask:0xf bank_mask:0xf
	v_mov_b32_e32 v62, 0
	v_mov_b32_e32 v92, 0
	v_mov_b32_e32 v57, 0
	v_mov_b32_dpp v59, v48 row_ror:2 row_mask:0xf bank_mask:0xf
	v_mov_b32_dpp v56, v52 row_ror:1 row_mask:0xf bank_mask:0xf
	v_mov_b32_dpp v58, v44 row_shr:2 row_mask:0xf bank_mask:0xf
	v_mov_b32_dpp v62, v54 row_ror:1 row_mask:0xf bank_mask:0xf
	v_mov_b32_dpp v92, v54 row_ror:2 row_mask:0xf bank_mask:0xf
	v_mov_b32_e32 v54, 0
	v_mov_b32_e32 v100, 0
	v_mov_b32_dpp v57, v48 row_ror:1 row_mask:0xf bank_mask:0xf
	v_mov_b32_dpp v59, v40 row_shr:2 row_mask:0xf bank_mask:0xf
	v_mov_b32_e32 v101, 0
	v_mov_b32_dpp v56, v44 row_shr:1 row_mask:0xf bank_mask:0xf
	v_mov_b32_dpp v54, v55 row_ror:1 row_mask:0xf bank_mask:0xf
	v_mov_b32_dpp v100, v55 row_ror:2 row_mask:0xf bank_mask:0xf
	v_mov_b32_dpp v57, v40 row_shr:1 row_mask:0xf bank_mask:0xf
	v_pk_fma_f32 v[58:59], v[78:79], v[58:59], v[122:123]
	v_mov_b32_e32 v55, 0
; #define LAS __attribute__((address_space(3)))
; __device__ __forceinline__ unsigned cvt_pk_bf16(float lo, float hi) { unsigned r; asm volatile("v_cvt_pk_bf16_f32 %0, %1, %2" : "=v"(r) : "v"(lo), "v"(hi)); return r; }
; __device__ __forceinline__ float gelu_t(float x) { const float u = 1.5957691216f * (x + 0.044715f * x * x * x); return x * sigm(u); }
; __device__ __forceinline__ float dpp_shr1(float old, float src) { return __int_as_float(__builtin_amdgcn_update_dpp(__float_as_int(old), __float_as_int(src), 0x111, 0xf, 0xf, false)); }
; __device__ __forceinline__ float dpp_shr2(float old, float src) { return __int_as_float(__builtin_amdgcn_update_dpp(__float_as_int(old), __float_as_int(src), 0x112, 0xf, 0xf, false)); }
;     __device__ __forceinline__ void operator()(AccT& acc, const Unit& u, int wr, int wc, int fr, int fq) const {
;     ...
;             for (int ai = 0; ai < 2; ++ai) {
;                 f32x4 hv[2]; hv[0] = (f32x4){0.f, 0.f, 0.f, 0.f}; hv[1] = hv[0];
;                 const bool has_pred = (wr == 1) || (ai == 1);
;                 const int pa = (wr == 1) ? ai : 0, pw = (wr == 1) ? 0 : 1;
;                 if (has_pred && fr >= 14) { hv[0] = *(const LAS f32x4*)(xl + xidx(pa, pw, wc, fr - 14, fq, 0, n)); hv[1] = *(const LAS f32x4*)(xl + xidx(pa, pw, wc, fr - 14, fq, 1, n)); }
; #pragma unroll
;                 for (int m = 0; m < 4; ++m) {
;                     f32x4 c2[2];
; #pragma unroll
;                     for (int bj = 0; bj < 2; ++bj) { const f32x4 cur = acc[ai][bj][m][n]; const f32x4 pv = (m == 0) ? hv[bj] : acc[ai][bj][m == 0 ? 0 : m - 1][n];
; #pragma unroll
;                         for (int j = 0; j < 4; ++j) { const float p1 = dpp_shr1(dpp_ror1(pv[j]), cur[j]), p2 = dpp_shr2(dpp_ror2(pv[j]), cur[j]);
;                             c2[bj][j] = bia[bj][j] + wgt[bj][0][j] * p2 + wgt[bj][1][j] * p1 + wgt[bj][2][j] * cur[j]; } }
;                     u32x2 w; w.x = cvt_pk_bf16(gelu_t(c2[0][0]) * c2[1][0], gelu_t(c2[0][1]) * c2[1][1]); w.y = cvt_pk_bf16(gelu_t(c2[0][2]) * c2[1][2], gelu_t(c2[0][3]) * c2[1][3]);
;                     if (n == 0) pend[ai][m] = w;
;                     else { u32x4 w4; w4.x = pend[ai][m].x; w4.y = pend[ai][m].y; w4.z = w.x; w4.w = w.y;
;                         *(u32x4*)(F + (size_t)(t0 + ai * 128 + wr * 64 + m * 16 + fr) * FF + cg - 4) = w4; }
;                 }
	v_mov_b32_dpp v101, v51 row_ror:2 row_mask:0xf bank_mask:0xf
	v_mov_b32_e32 v52, 0
	v_mov_b32_e32 v60, 0
	v_mov_b32_dpp v100, v47 row_shr:2 row_mask:0xf bank_mask:0xf
	v_pk_fma_f32 v[56:57], v[124:125], v[56:57], v[58:59]
	v_mov_b32_e32 v58, v44
	v_mov_b32_e32 v59, v40
	v_mov_b32_e32 v61, 0
	v_mov_b32_e32 v63, 0
	v_mov_b32_e32 v93, 0
	v_mov_b32_dpp v55, v51 row_ror:1 row_mask:0xf bank_mask:0xf
	v_mov_b32_dpp v101, v43 row_shr:2 row_mask:0xf bank_mask:0xf
	v_mov_b32_dpp v52, v53 row_ror:1 row_mask:0xf bank_mask:0xf
	v_mov_b32_dpp v60, v53 row_ror:2 row_mask:0xf bank_mask:0xf
	v_mov_b32_dpp v54, v47 row_shr:1 row_mask:0xf bank_mask:0xf
	v_pk_fma_f32 v[56:57], v[58:59], v[126:127], v[56:57]
	v_mov_b32_e32 v53, 0
	v_mov_b32_dpp v61, v49 row_ror:2 row_mask:0xf bank_mask:0xf
	v_mov_b32_dpp v63, v50 row_ror:1 row_mask:0xf bank_mask:0xf
	v_mov_b32_dpp v93, v50 row_ror:2 row_mask:0xf bank_mask:0xf
	v_mov_b32_dpp v55, v43 row_shr:1 row_mask:0xf bank_mask:0xf
	v_pk_fma_f32 v[50:51], v[76:77], v[100:101], v[72:73]
	v_mov_b32_dpp v60, v45 row_shr:2 row_mask:0xf bank_mask:0xf
	v_mov_b32_dpp v53, v49 row_ror:1 row_mask:0xf bank_mask:0xf
	v_mov_b32_dpp v61, v41 row_shr:2 row_mask:0xf bank_mask:0xf
	v_pk_fma_f32 v[50:51], v[86:87], v[54:55], v[50:51]
	v_mul_f32_e32 v55, 0x3d372713, v56
	v_mov_b32_dpp v52, v45 row_shr:1 row_mask:0xf bank_mask:0xf
	v_mov_b32_dpp v53, v41 row_shr:1 row_mask:0xf bank_mask:0xf
	v_pk_fma_f32 v[48:49], v[74:75], v[60:61], v[70:71]
	v_mul_f32_e32 v55, v56, v55
	v_mov_b32_dpp v92, v46 row_shr:2 row_mask:0xf bank_mask:0xf
	v_pk_fma_f32 v[48:49], v[84:85], v[52:53], v[48:49]
	v_mov_b32_e32 v52, v45
	v_mov_b32_e32 v53, v41
	v_mov_b32_dpp v93, v42 row_shr:2 row_mask:0xf bank_mask:0xf
	v_fma_f32 v55, v56, v55, v56
	v_mov_b32_dpp v62, v46 row_shr:1 row_mask:0xf bank_mask:0xf
	v_pk_fma_f32 v[48:49], v[52:53], v[66:67], v[48:49]
	v_mov_b32_dpp v63, v42 row_shr:1 row_mask:0xf bank_mask:0xf
	v_pk_fma_f32 v[52:53], v[114:115], v[92:93], v[118:119]
	v_mul_f32_e32 v55, 0x3fcc422a, v55
	v_pk_fma_f32 v[52:53], v[128:129], v[62:63], v[52:53]
	v_mov_b32_e32 v58, v46
	v_mov_b32_e32 v59, v42
	v_mul_f32_e32 v55, 0xbfb8aa3b, v55
	v_pk_fma_f32 v[52:53], v[58:59], v[130:131], v[52:53]
	v_exp_f32_e32 v58, v55
	v_mul_f32_e32 v55, 0x3d372713, v48
	v_mul_f32_e32 v55, v48, v55
	v_fma_f32 v55, v48, v55, v48
	v_add_f32_e32 v58, 1.0, v58
	v_mul_f32_e32 v55, 0x3fcc422a, v55
	v_rcp_f32_e32 v58, v58
	v_mul_f32_e32 v55, 0xbfb8aa3b, v55
	v_mov_b32_e32 v54, v47
	v_exp_f32_e32 v59, v55
	v_mov_b32_e32 v55, v43
	v_pk_fma_f32 v[50:51], v[54:55], v[68:69], v[50:51]
	v_mul_f32_e32 v55, 0x3d372713, v52
	v_mul_f32_e32 v54, v56, v58
	v_mul_f32_e32 v55, v52, v55
	v_mul_f32_e32 v56, 0x3d372713, v50
	v_fma_f32 v55, v52, v55, v52
	v_mul_f32_e32 v56, v50, v56
	v_add_f32_e32 v59, 1.0, v59
	v_mul_f32_e32 v55, 0x3fcc422a, v55
	v_fma_f32 v56, v50, v56, v50
	v_rcp_f32_e32 v59, v59
	v_mul_f32_e32 v55, 0xbfb8aa3b, v55
	v_mul_f32_e32 v56, 0x3fcc422a, v56
	v_exp_f32_e32 v55, v55
	v_mul_f32_e32 v56, 0xbfb8aa3b, v56
	v_exp_f32_e32 v56, v56
	v_mul_f32_e32 v48, v48, v59
	v_mul_f32_e32 v48, v48, v49
	v_add_f32_e32 v49, 1.0, v55
	v_rcp_f32_e32 v49, v49
	v_add_f32_e32 v55, 1.0, v56
	v_rcp_f32_e32 v55, v55
	v_mul_f32_e32 v54, v54, v57
	v_cvt_pk_bf16_f32 v106, v54, v48
	v_mul_f32_e32 v48, v52, v49
	v_mul_f32_e32 v48, v48, v53
	v_mul_f32_e32 v49, v50, v55
	v_mul_f32_e32 v49, v49, v51
	v_cvt_pk_bf16_f32 v107, v48, v49
	v_or_b32_e32 v48, 32, v132
	v_mad_i64_i32 v[48:49], s[8:9], v48, s94, v[82:83]
	v_lshl_add_u64 v[48:49], v[48:49], 0, v[94:95]
	global_store_dwordx4 v[48:49], v[104:107], off nt
	v_mov_b32_e32 v48, 0
	v_mov_b32_e32 v50, 0
	v_mov_b32_e32 v51, 0
	v_mov_b32_dpp v48, v44 row_ror:1 row_mask:0xf bank_mask:0xf
	v_mov_b32_dpp v50, v44 row_ror:2 row_mask:0xf bank_mask:0xf
	v_mov_b32_e32 v44, 0
	v_mov_b32_e32 v52, 0
	v_mov_b32_e32 v49, 0
	v_mov_b32_dpp v51, v40 row_ror:2 row_mask:0xf bank_mask:0xf
	v_mov_b32_e32 v53, 0
	v_mov_b32_dpp v50, v36 row_shr:2 row_mask:0xf bank_mask:0xf
	v_mov_b32_dpp v44, v45 row_ror:1 row_mask:0xf bank_mask:0xf
	v_mov_b32_dpp v52, v45 row_ror:2 row_mask:0xf bank_mask:0xf
	v_mov_b32_dpp v49, v40 row_ror:1 row_mask:0xf bank_mask:0xf
	v_mov_b32_dpp v51, v32 row_shr:2 row_mask:0xf bank_mask:0xf
	v_mov_b32_e32 v45, 0
	v_mov_b32_dpp v53, v41 row_ror:2 row_mask:0xf bank_mask:0xf
	v_mov_b32_dpp v48, v36 row_shr:1 row_mask:0xf bank_mask:0xf
	v_mov_b32_dpp v52, v37 row_shr:2 row_mask:0xf bank_mask:0xf
	v_mov_b32_dpp v49, v32 row_shr:1 row_mask:0xf bank_mask:0xf
	v_pk_fma_f32 v[50:51], v[78:79], v[50:51], v[122:123]
	v_mov_b32_dpp v45, v41 row_ror:1 row_mask:0xf bank_mask:0xf
	v_mov_b32_dpp v53, v33 row_shr:2 row_mask:0xf bank_mask:0xf
	v_mov_b32_dpp v44, v37 row_shr:1 row_mask:0xf bank_mask:0xf
	v_pk_fma_f32 v[48:49], v[124:125], v[48:49], v[50:51]
	v_mov_b32_e32 v50, v36
	v_mov_b32_e32 v51, v32
	v_mov_b32_dpp v45, v33 row_shr:1 row_mask:0xf bank_mask:0xf
	v_pk_fma_f32 v[40:41], v[74:75], v[52:53], v[70:71]
	v_mov_b32_e32 v55, 0
	v_mov_b32_e32 v57, 0
	v_pk_fma_f32 v[48:49], v[50:51], v[126:127], v[48:49]
	v_pk_fma_f32 v[40:41], v[84:85], v[44:45], v[40:41]
	v_mov_b32_e32 v32, v37
	v_mov_b32_dpp v55, v42 row_ror:1 row_mask:0xf bank_mask:0xf
	v_mov_b32_dpp v57, v42 row_ror:2 row_mask:0xf bank_mask:0xf
	v_pk_fma_f32 v[32:33], v[32:33], v[66:67], v[40:41]
	v_mov_b32_dpp v55, v34 row_shr:1 row_mask:0xf bank_mask:0xf
	v_mov_b32_dpp v57, v34 row_shr:2 row_mask:0xf bank_mask:0xf
	v_mov_b32_e32 v41, v34
	v_mul_f32_e32 v34, 0x3d372713, v48
	v_mul_f32_e32 v34, v48, v34
	v_fma_f32 v34, v48, v34, v48
	v_mov_b32_e32 v54, 0
	v_mov_b32_e32 v56, 0
	v_mul_f32_e32 v34, 0x3fcc422a, v34
; #define LAS __attribute__((address_space(3)))
; __device__ __forceinline__ unsigned cvt_pk_bf16(float lo, float hi) { unsigned r; asm volatile("v_cvt_pk_bf16_f32 %0, %1, %2" : "=v"(r) : "v"(lo), "v"(hi)); return r; }
; __device__ __forceinline__ float gelu_t(float x) { const float u = 1.5957691216f * (x + 0.044715f * x * x * x); return x * sigm(u); }
; __device__ __forceinline__ float dpp_shr1(float old, float src) { return __int_as_float(__builtin_amdgcn_update_dpp(__float_as_int(old), __float_as_int(src), 0x111, 0xf, 0xf, false)); }
; __device__ __forceinline__ float dpp_shr2(float old, float src) { return __int_as_float(__builtin_amdgcn_update_dpp(__float_as_int(old), __float_as_int(src), 0x112, 0xf, 0xf, false)); }
;     __device__ __forceinline__ void operator()(AccT& acc, const Unit& u, int wr, int wc, int fr, int fq) const {
;     ...
;             for (int ai = 0; ai < 2; ++ai) {
;                 f32x4 hv[2]; hv[0] = (f32x4){0.f, 0.f, 0.f, 0.f}; hv[1] = hv[0];
;                 const bool has_pred = (wr == 1) || (ai == 1);
;                 const int pa = (wr == 1) ? ai : 0, pw = (wr == 1) ? 0 : 1;
;                 if (has_pred && fr >= 14) { hv[0] = *(const LAS f32x4*)(xl + xidx(pa, pw, wc, fr - 14, fq, 0, n)); hv[1] = *(const LAS f32x4*)(xl + xidx(pa, pw, wc, fr - 14, fq, 1, n)); }
; #pragma unroll
;                 for (int m = 0; m < 4; ++m) {
;                     f32x4 c2[2];
; #pragma unroll
;                     for (int bj = 0; bj < 2; ++bj) { const f32x4 cur = acc[ai][bj][m][n]; const f32x4 pv = (m == 0) ? hv[bj] : acc[ai][bj][m == 0 ? 0 : m - 1][n];
; #pragma unroll
;                         for (int j = 0; j < 4; ++j) { const float p1 = dpp_shr1(dpp_ror1(pv[j]), cur[j]), p2 = dpp_shr2(dpp_ror2(pv[j]), cur[j]);
;                             c2[bj][j] = bia[bj][j] + wgt[bj][0][j] * p2 + wgt[bj][1][j] * p1 + wgt[bj][2][j] * cur[j]; } }
;                     u32x2 w; w.x = cvt_pk_bf16(gelu_t(c2[0][0]) * c2[1][0], gelu_t(c2[0][1]) * c2[1][1]); w.y = cvt_pk_bf16(gelu_t(c2[0][2]) * c2[1][2], gelu_t(c2[0][3]) * c2[1][3]);
;                     if (n == 0) pend[ai][m] = w;
;                     else { u32x4 w4; w4.x = pend[ai][m].x; w4.y = pend[ai][m].y; w4.z = w.x; w4.w = w.y;
;                         *(u32x4*)(F + (size_t)(t0 + ai * 128 + wr * 64 + m * 16 + fr) * FF + cg - 4) = w4; }
;                 }
	v_mov_b32_dpp v54, v46 row_ror:1 row_mask:0xf bank_mask:0xf
	v_mov_b32_dpp v56, v46 row_ror:2 row_mask:0xf bank_mask:0xf
	v_mul_f32_e32 v34, 0xbfb8aa3b, v34
	v_mov_b32_dpp v54, v38 row_shr:1 row_mask:0xf bank_mask:0xf
	v_mov_b32_dpp v56, v38 row_shr:2 row_mask:0xf bank_mask:0xf
	v_mov_b32_e32 v40, v38
	v_exp_f32_e32 v38, v34
	v_mul_f32_e32 v34, 0x3d372713, v32
	v_mul_f32_e32 v34, v32, v34
	v_fma_f32 v34, v32, v34, v32
	v_mul_f32_e32 v34, 0x3fcc422a, v34
	v_mul_f32_e32 v34, 0xbfb8aa3b, v34
	v_exp_f32_e32 v42, v34
	v_mov_b32_e32 v46, 0
	v_mov_b32_e32 v58, 0
	v_mov_b32_e32 v59, 0
	v_mov_b32_dpp v46, v47 row_ror:1 row_mask:0xf bank_mask:0xf
	v_mov_b32_dpp v58, v47 row_ror:2 row_mask:0xf bank_mask:0xf
	v_mov_b32_e32 v34, v39
	v_mov_b32_dpp v46, v39 row_shr:1 row_mask:0xf bank_mask:0xf
	v_mov_b32_dpp v58, v39 row_shr:2 row_mask:0xf bank_mask:0xf
	v_add_f32_e32 v39, 1.0, v42
	v_pk_fma_f32 v[36:37], v[114:115], v[56:57], v[118:119]
	v_mov_b32_e32 v47, 0
	v_mov_b32_dpp v59, v43 row_ror:2 row_mask:0xf bank_mask:0xf
	v_rcp_f32_e32 v39, v39
	v_pk_fma_f32 v[36:37], v[128:129], v[54:55], v[36:37]
	v_mov_b32_dpp v47, v43 row_ror:1 row_mask:0xf bank_mask:0xf
	v_mov_b32_dpp v59, v35 row_shr:2 row_mask:0xf bank_mask:0xf
	v_pk_fma_f32 v[36:37], v[40:41], v[130:131], v[36:37]
	v_mov_b32_dpp v47, v35 row_shr:1 row_mask:0xf bank_mask:0xf
	v_pk_fma_f32 v[40:41], v[76:77], v[58:59], v[72:73]
	v_mul_f32_e32 v32, v32, v39
	v_pk_fma_f32 v[40:41], v[86:87], v[46:47], v[40:41]
	v_mul_f32_e32 v39, 0x3d372713, v36
	v_pk_fma_f32 v[34:35], v[34:35], v[68:69], v[40:41]
	v_mul_f32_e32 v39, v36, v39
	v_mul_f32_e32 v40, 0x3d372713, v34
	v_fma_f32 v39, v36, v39, v36
	v_mul_f32_e32 v40, v34, v40
	v_mul_f32_e32 v39, 0x3fcc422a, v39
	v_fma_f32 v40, v34, v40, v34
	v_mul_f32_e32 v39, 0xbfb8aa3b, v39
	v_mul_f32_e32 v40, 0x3fcc422a, v40
	v_exp_f32_e32 v39, v39
	v_mul_f32_e32 v40, 0xbfb8aa3b, v40
	v_exp_f32_e32 v40, v40
	v_add_f32_e32 v38, 1.0, v38
	v_rcp_f32_e32 v38, v38
	v_mul_f32_e32 v32, v32, v33
	v_add_f32_e32 v33, 1.0, v39
	v_rcp_f32_e32 v33, v33
	v_add_f32_e32 v39, 1.0, v40
	v_rcp_f32_e32 v39, v39
	v_mul_f32_e32 v38, v48, v38
	v_mul_f32_e32 v38, v38, v49
	v_cvt_pk_bf16_f32 v100, v38, v32
	v_mul_f32_e32 v32, v36, v33
	v_mul_f32_e32 v32, v32, v37
	v_mul_f32_e32 v33, v34, v39
	v_mul_f32_e32 v33, v33, v35
	v_cvt_pk_bf16_f32 v101, v32, v33
	v_or_b32_e32 v32, 48, v132
	v_mad_i64_i32 v[32:33], s[8:9], v32, s94, v[82:83]
	v_lshl_add_u64 v[32:33], v[32:33], 0, v[94:95]
	global_store_dwordx4 v[32:33], v[98:101], off nt
	v_mov_b32_e32 v91, 0
	v_mov_b32_e32 v92, 0
	v_mov_b32_e32 v93, 0
	v_mov_b32_e32 v32, 0
	v_mov_b32_e32 v33, 0
	v_mov_b32_e32 v34, 0
	v_mov_b32_e32 v35, 0
	s_and_saveexec_b64 s[12:13], s[6:7]
	s_cbranch_execz .LBB0_794
	ds_read_b128 v[32:35], v154 offset:16
	ds_read_b128 v[90:93], v154 offset:48
.LBB0_794:
	s_or_b64 exec, exec, s[12:13]
	v_mov_b32_e32 v38, 0
	v_mov_b32_e32 v39, 0
	v_mov_b32_e32 v36, 0
	s_waitcnt lgkmcnt(1)
	v_mov_b32_dpp v38, v32 row_ror:2 row_mask:0xf bank_mask:0xf
	v_mov_b32_e32 v37, 0
	s_waitcnt lgkmcnt(0)
	v_mov_b32_dpp v39, v90 row_ror:2 row_mask:0xf bank_mask:0xf
	v_mov_b32_dpp v36, v32 row_ror:1 row_mask:0xf bank_mask:0xf
	v_mov_b32_dpp v38, v28 row_shr:2 row_mask:0xf bank_mask:0xf
	v_mov_b32_e32 v32, 0
	v_mov_b32_e32 v40, 0
	v_mov_b32_dpp v37, v90 row_ror:1 row_mask:0xf bank_mask:0xf
	v_mov_b32_dpp v39, v24 row_shr:2 row_mask:0xf bank_mask:0xf
	v_mov_b32_e32 v41, 0
	v_mov_b32_dpp v36, v28 row_shr:1 row_mask:0xf bank_mask:0xf
	v_mov_b32_dpp v32, v33 row_ror:1 row_mask:0xf bank_mask:0xf
	v_mov_b32_dpp v40, v33 row_ror:2 row_mask:0xf bank_mask:0xf
	v_mov_b32_dpp v37, v24 row_shr:1 row_mask:0xf bank_mask:0xf
	v_pk_fma_f32 v[38:39], v[78:79], v[38:39], v[122:123]
	v_mov_b32_e32 v33, 0
	v_mov_b32_dpp v41, v91 row_ror:2 row_mask:0xf bank_mask:0xf
	v_mov_b32_dpp v40, v29 row_shr:2 row_mask:0xf bank_mask:0xf
	v_mov_b32_e32 v44, 0
	v_pk_fma_f32 v[36:37], v[124:125], v[36:37], v[38:39]
	v_mov_b32_e32 v38, v28
	v_mov_b32_e32 v39, v24
	v_mov_b32_dpp v33, v91 row_ror:1 row_mask:0xf bank_mask:0xf
	v_mov_b32_dpp v41, v25 row_shr:2 row_mask:0xf bank_mask:0xf
	v_mov_b32_e32 v45, 0
	v_mov_b32_dpp v32, v29 row_shr:1 row_mask:0xf bank_mask:0xf
	v_mov_b32_e32 v42, 0
	v_mov_b32_dpp v44, v34 row_ror:2 row_mask:0xf bank_mask:0xf
	v_pk_fma_f32 v[36:37], v[38:39], v[126:127], v[36:37]
	v_mov_b32_dpp v33, v25 row_shr:1 row_mask:0xf bank_mask:0xf
	v_pk_fma_f32 v[38:39], v[74:75], v[40:41], v[70:71]
	v_mov_b32_e32 v43, 0
	v_mov_b32_dpp v45, v92 row_ror:2 row_mask:0xf bank_mask:0xf
	v_mov_b32_dpp v42, v34 row_ror:1 row_mask:0xf bank_mask:0xf
	v_mov_b32_dpp v44, v30 row_shr:2 row_mask:0xf bank_mask:0xf
	v_mov_b32_e32 v34, 0
	v_mov_b32_e32 v46, 0
	v_pk_fma_f32 v[32:33], v[84:85], v[32:33], v[38:39]
	v_mov_b32_e32 v38, v29
	v_mov_b32_e32 v39, v25
	v_mov_b32_dpp v43, v92 row_ror:1 row_mask:0xf bank_mask:0xf
	v_mov_b32_dpp v45, v26 row_shr:2 row_mask:0xf bank_mask:0xf
	v_mov_b32_e32 v47, 0
	v_mov_b32_dpp v42, v30 row_shr:1 row_mask:0xf bank_mask:0xf
	v_mov_b32_dpp v34, v35 row_ror:1 row_mask:0xf bank_mask:0xf
	v_mov_b32_dpp v46, v35 row_ror:2 row_mask:0xf bank_mask:0xf
	v_pk_fma_f32 v[32:33], v[38:39], v[66:67], v[32:33]
	v_mov_b32_dpp v43, v26 row_shr:1 row_mask:0xf bank_mask:0xf
	v_pk_fma_f32 v[38:39], v[114:115], v[44:45], v[118:119]
	v_mov_b32_e32 v35, 0
	v_mov_b32_dpp v47, v93 row_ror:2 row_mask:0xf bank_mask:0xf
	v_mov_b32_dpp v46, v31 row_shr:2 row_mask:0xf bank_mask:0xf
	v_pk_fma_f32 v[38:39], v[128:129], v[42:43], v[38:39]
	v_mov_b32_e32 v40, v30
	v_mov_b32_e32 v41, v26
	v_mov_b32_dpp v35, v93 row_ror:1 row_mask:0xf bank_mask:0xf
	v_mov_b32_dpp v47, v27 row_shr:2 row_mask:0xf bank_mask:0xf
; #define LAS __attribute__((address_space(3)))
; __device__ __forceinline__ unsigned cvt_pk_bf16(float lo, float hi) { unsigned r; asm volatile("v_cvt_pk_bf16_f32 %0, %1, %2" : "=v"(r) : "v"(lo), "v"(hi)); return r; }
; __device__ __forceinline__ float gelu_t(float x) { const float u = 1.5957691216f * (x + 0.044715f * x * x * x); return x * sigm(u); }
; __device__ __forceinline__ float dpp_shr1(float old, float src) { return __int_as_float(__builtin_amdgcn_update_dpp(__float_as_int(old), __float_as_int(src), 0x111, 0xf, 0xf, false)); }
; __device__ __forceinline__ float dpp_shr2(float old, float src) { return __int_as_float(__builtin_amdgcn_update_dpp(__float_as_int(old), __float_as_int(src), 0x112, 0xf, 0xf, false)); }
;     __device__ __forceinline__ void operator()(AccT& acc, const Unit& u, int wr, int wc, int fr, int fq) const {
;     ...
;             for (int ai = 0; ai < 2; ++ai) {
;                 f32x4 hv[2]; hv[0] = (f32x4){0.f, 0.f, 0.f, 0.f}; hv[1] = hv[0];
;                 const bool has_pred = (wr == 1) || (ai == 1);
;                 const int pa = (wr == 1) ? ai : 0, pw = (wr == 1) ? 0 : 1;
;                 if (has_pred && fr >= 14) { hv[0] = *(const LAS f32x4*)(xl + xidx(pa, pw, wc, fr - 14, fq, 0, n)); hv[1] = *(const LAS f32x4*)(xl + xidx(pa, pw, wc, fr - 14, fq, 1, n)); }
; #pragma unroll
;                 for (int m = 0; m < 4; ++m) {
;                     f32x4 c2[2];
; #pragma unroll
;                     for (int bj = 0; bj < 2; ++bj) { const f32x4 cur = acc[ai][bj][m][n]; const f32x4 pv = (m == 0) ? hv[bj] : acc[ai][bj][m == 0 ? 0 : m - 1][n];
; #pragma unroll
;                         for (int j = 0; j < 4; ++j) { const float p1 = dpp_shr1(dpp_ror1(pv[j]), cur[j]), p2 = dpp_shr2(dpp_ror2(pv[j]), cur[j]);
;                             c2[bj][j] = bia[bj][j] + wgt[bj][0][j] * p2 + wgt[bj][1][j] * p1 + wgt[bj][2][j] * cur[j]; } }
;                     u32x2 w; w.x = cvt_pk_bf16(gelu_t(c2[0][0]) * c2[1][0], gelu_t(c2[0][1]) * c2[1][1]); w.y = cvt_pk_bf16(gelu_t(c2[0][2]) * c2[1][2], gelu_t(c2[0][3]) * c2[1][3]);
;                     if (n == 0) pend[ai][m] = w;
;                     else { u32x4 w4; w4.x = pend[ai][m].x; w4.y = pend[ai][m].y; w4.z = w.x; w4.w = w.y;
;                         *(u32x4*)(F + (size_t)(t0 + ai * 128 + wr * 64 + m * 16 + fr) * FF + cg - 4) = w4; }
;                 }
	v_mov_b32_dpp v34, v31 row_shr:1 row_mask:0xf bank_mask:0xf
	v_pk_fma_f32 v[38:39], v[40:41], v[130:131], v[38:39]
	v_mov_b32_dpp v35, v27 row_shr:1 row_mask:0xf bank_mask:0xf
	v_pk_fma_f32 v[40:41], v[76:77], v[46:47], v[72:73]
	v_add_u32_e32 v48, 0x80, v132
	v_pk_fma_f32 v[34:35], v[86:87], v[34:35], v[40:41]
	v_mul_f32_e32 v41, 0x3d372713, v36
	v_mul_f32_e32 v41, v36, v41
	v_fma_f32 v41, v36, v41, v36
	v_mul_f32_e32 v41, 0x3fcc422a, v41
	v_mul_f32_e32 v41, 0xbfb8aa3b, v41
	v_exp_f32_e32 v42, v41
	v_mul_f32_e32 v41, 0x3d372713, v32
	v_mul_f32_e32 v41, v32, v41
	v_fma_f32 v41, v32, v41, v32
	v_add_f32_e32 v42, 1.0, v42
	v_rcp_f32_e32 v42, v42
	v_mul_f32_e32 v41, 0x3fcc422a, v41
	v_mul_f32_e32 v41, 0xbfb8aa3b, v41
	v_mov_b32_e32 v40, v31
	v_exp_f32_e32 v43, v41
	v_mov_b32_e32 v41, v27
	v_pk_fma_f32 v[34:35], v[40:41], v[68:69], v[34:35]
	v_mul_f32_e32 v36, v36, v42
	v_mul_f32_e32 v36, v36, v37
	v_mul_f32_e32 v37, 0x3d372713, v38
	v_mul_f32_e32 v40, 0x3d372713, v34
	v_mul_f32_e32 v37, v38, v37
	v_mul_f32_e32 v40, v34, v40
	v_fma_f32 v37, v38, v37, v38
	v_fma_f32 v40, v34, v40, v34
	v_add_f32_e32 v43, 1.0, v43
	v_mul_f32_e32 v37, 0x3fcc422a, v37
	v_mul_f32_e32 v40, 0x3fcc422a, v40
	v_rcp_f32_e32 v43, v43
	v_mul_f32_e32 v37, 0xbfb8aa3b, v37
	v_mul_f32_e32 v40, 0xbfb8aa3b, v40
	v_exp_f32_e32 v37, v37
	v_exp_f32_e32 v40, v40
	v_mul_f32_e32 v32, v32, v43
	v_mul_f32_e32 v32, v32, v33
	v_add_f32_e32 v33, 1.0, v37
	v_add_f32_e32 v37, 1.0, v40
	v_rcp_f32_e32 v33, v33
	v_rcp_f32_e32 v37, v37
	v_cvt_pk_bf16_f32 v98, v36, v32
	v_mov_b32_e32 v36, 0
	v_mul_f32_e32 v32, v38, v33
	v_mul_f32_e32 v33, v34, v37
	v_mul_f32_e32 v32, v32, v39
	v_mul_f32_e32 v33, v33, v35
	v_cvt_pk_bf16_f32 v99, v32, v33
	v_mov_b64_e32 v[32:33], s[36:37]
	v_mad_i64_i32 v[34:35], s[6:7], v48, s94, v[32:33]
	v_lshl_add_u64 v[34:35], v[34:35], 0, v[94:95]
	v_mov_b32_e32 v37, 0
	global_store_dwordx4 v[34:35], v[96:99], off nt
	v_mov_b32_e32 v34, 0
	v_mov_b32_dpp v36, v28 row_ror:2 row_mask:0xf bank_mask:0xf
	v_mov_b32_e32 v40, 0
	v_mov_b32_e32 v42, 0
	v_mov_b32_e32 v35, 0
	v_mov_b32_dpp v37, v24 row_ror:2 row_mask:0xf bank_mask:0xf
	v_mov_b32_dpp v34, v28 row_ror:1 row_mask:0xf bank_mask:0xf
	v_mov_b32_dpp v36, v20 row_shr:2 row_mask:0xf bank_mask:0xf
	v_mov_b32_dpp v40, v30 row_ror:1 row_mask:0xf bank_mask:0xf
	v_mov_b32_dpp v42, v30 row_ror:2 row_mask:0xf bank_mask:0xf
	v_mov_b32_e32 v30, 0
	v_mov_b32_e32 v44, 0
	v_mov_b32_dpp v35, v24 row_ror:1 row_mask:0xf bank_mask:0xf
	v_mov_b32_dpp v37, v16 row_shr:2 row_mask:0xf bank_mask:0xf
	v_mov_b32_e32 v45, 0
	v_mov_b32_dpp v34, v20 row_shr:1 row_mask:0xf bank_mask:0xf
	v_mov_b32_dpp v30, v31 row_ror:1 row_mask:0xf bank_mask:0xf
	v_mov_b32_dpp v44, v31 row_ror:2 row_mask:0xf bank_mask:0xf
	v_mov_b32_dpp v35, v16 row_shr:1 row_mask:0xf bank_mask:0xf
	v_pk_fma_f32 v[36:37], v[78:79], v[36:37], v[122:123]
	v_mov_b32_e32 v31, 0
	v_mov_b32_dpp v45, v27 row_ror:2 row_mask:0xf bank_mask:0xf
	v_mov_b32_e32 v28, 0
	v_mov_b32_e32 v38, 0
	v_mov_b32_dpp v44, v23 row_shr:2 row_mask:0xf bank_mask:0xf
	v_pk_fma_f32 v[34:35], v[124:125], v[34:35], v[36:37]
	v_mov_b32_e32 v36, v20
	v_mov_b32_e32 v37, v16
	v_mov_b32_e32 v39, 0
	v_mov_b32_e32 v41, 0
	v_mov_b32_e32 v43, 0
	v_mov_b32_dpp v31, v27 row_ror:1 row_mask:0xf bank_mask:0xf
	v_mov_b32_dpp v45, v19 row_shr:2 row_mask:0xf bank_mask:0xf
	v_mov_b32_dpp v28, v29 row_ror:1 row_mask:0xf bank_mask:0xf
	v_mov_b32_dpp v38, v29 row_ror:2 row_mask:0xf bank_mask:0xf
	v_mov_b32_dpp v30, v23 row_shr:1 row_mask:0xf bank_mask:0xf
	v_pk_fma_f32 v[34:35], v[36:37], v[126:127], v[34:35]
	v_mov_b32_e32 v29, 0
	v_mov_b32_dpp v39, v25 row_ror:2 row_mask:0xf bank_mask:0xf
	v_mov_b32_dpp v41, v26 row_ror:1 row_mask:0xf bank_mask:0xf
	v_mov_b32_dpp v43, v26 row_ror:2 row_mask:0xf bank_mask:0xf
	v_mov_b32_dpp v31, v19 row_shr:1 row_mask:0xf bank_mask:0xf
	v_pk_fma_f32 v[26:27], v[76:77], v[44:45], v[72:73]
	v_mov_b32_dpp v38, v21 row_shr:2 row_mask:0xf bank_mask:0xf
	v_mov_b32_dpp v29, v25 row_ror:1 row_mask:0xf bank_mask:0xf
	v_mov_b32_dpp v39, v17 row_shr:2 row_mask:0xf bank_mask:0xf
	v_pk_fma_f32 v[26:27], v[86:87], v[30:31], v[26:27]
	v_mul_f32_e32 v31, 0x3d372713, v34
	v_mov_b32_dpp v28, v21 row_shr:1 row_mask:0xf bank_mask:0xf
	v_mov_b32_dpp v29, v17 row_shr:1 row_mask:0xf bank_mask:0xf
	v_pk_fma_f32 v[24:25], v[74:75], v[38:39], v[70:71]
	v_mul_f32_e32 v31, v34, v31
	v_mov_b32_dpp v42, v22 row_shr:2 row_mask:0xf bank_mask:0xf
	v_pk_fma_f32 v[24:25], v[84:85], v[28:29], v[24:25]
	v_mov_b32_e32 v28, v21
	v_mov_b32_e32 v29, v17
	v_mov_b32_dpp v43, v18 row_shr:2 row_mask:0xf bank_mask:0xf
	v_fma_f32 v31, v34, v31, v34
	v_mov_b32_dpp v40, v22 row_shr:1 row_mask:0xf bank_mask:0xf
	v_pk_fma_f32 v[24:25], v[28:29], v[66:67], v[24:25]
	v_mov_b32_dpp v41, v18 row_shr:1 row_mask:0xf bank_mask:0xf
	v_pk_fma_f32 v[28:29], v[114:115], v[42:43], v[118:119]
	v_mul_f32_e32 v31, 0x3fcc422a, v31
	v_pk_fma_f32 v[28:29], v[128:129], v[40:41], v[28:29]
	v_mov_b32_e32 v36, v22
	v_mov_b32_e32 v37, v18
	v_mul_f32_e32 v31, 0xbfb8aa3b, v31
	v_pk_fma_f32 v[28:29], v[36:37], v[130:131], v[28:29]
	v_exp_f32_e32 v36, v31
	v_mul_f32_e32 v31, 0x3d372713, v24
	v_mul_f32_e32 v31, v24, v31
	v_fma_f32 v31, v24, v31, v24
	v_add_f32_e32 v36, 1.0, v36
	v_mul_f32_e32 v31, 0x3fcc422a, v31
	v_rcp_f32_e32 v36, v36
	v_mul_f32_e32 v31, 0xbfb8aa3b, v31
	v_mov_b32_e32 v30, v23
	v_exp_f32_e32 v37, v31
	v_mov_b32_e32 v31, v19
	v_pk_fma_f32 v[26:27], v[30:31], v[68:69], v[26:27]
	v_mul_f32_e32 v31, 0x3d372713, v28
	v_mul_f32_e32 v30, v34, v36
	v_mul_f32_e32 v31, v28, v31
	v_mul_f32_e32 v34, 0x3d372713, v26
	v_fma_f32 v31, v28, v31, v28
	v_mul_f32_e32 v34, v26, v34
; #define LAS __attribute__((address_space(3)))
; __device__ __forceinline__ unsigned cvt_pk_bf16(float lo, float hi) { unsigned r; asm volatile("v_cvt_pk_bf16_f32 %0, %1, %2" : "=v"(r) : "v"(lo), "v"(hi)); return r; }
; __device__ __forceinline__ float gelu_t(float x) { const float u = 1.5957691216f * (x + 0.044715f * x * x * x); return x * sigm(u); }
; __device__ __forceinline__ float dpp_shr1(float old, float src) { return __int_as_float(__builtin_amdgcn_update_dpp(__float_as_int(old), __float_as_int(src), 0x111, 0xf, 0xf, false)); }
; __device__ __forceinline__ float dpp_shr2(float old, float src) { return __int_as_float(__builtin_amdgcn_update_dpp(__float_as_int(old), __float_as_int(src), 0x112, 0xf, 0xf, false)); }
;     __device__ __forceinline__ void operator()(AccT& acc, const Unit& u, int wr, int wc, int fr, int fq) const {
;     ...
;             for (int ai = 0; ai < 2; ++ai) {
;                 f32x4 hv[2]; hv[0] = (f32x4){0.f, 0.f, 0.f, 0.f}; hv[1] = hv[0];
;                 const bool has_pred = (wr == 1) || (ai == 1);
;                 const int pa = (wr == 1) ? ai : 0, pw = (wr == 1) ? 0 : 1;
;                 if (has_pred && fr >= 14) { hv[0] = *(const LAS f32x4*)(xl + xidx(pa, pw, wc, fr - 14, fq, 0, n)); hv[1] = *(const LAS f32x4*)(xl + xidx(pa, pw, wc, fr - 14, fq, 1, n)); }
; #pragma unroll
;                 for (int m = 0; m < 4; ++m) {
;                     f32x4 c2[2];
; #pragma unroll
;                     for (int bj = 0; bj < 2; ++bj) { const f32x4 cur = acc[ai][bj][m][n]; const f32x4 pv = (m == 0) ? hv[bj] : acc[ai][bj][m == 0 ? 0 : m - 1][n];
; #pragma unroll
;                         for (int j = 0; j < 4; ++j) { const float p1 = dpp_shr1(dpp_ror1(pv[j]), cur[j]), p2 = dpp_shr2(dpp_ror2(pv[j]), cur[j]);
;                             c2[bj][j] = bia[bj][j] + wgt[bj][0][j] * p2 + wgt[bj][1][j] * p1 + wgt[bj][2][j] * cur[j]; } }
;                     u32x2 w; w.x = cvt_pk_bf16(gelu_t(c2[0][0]) * c2[1][0], gelu_t(c2[0][1]) * c2[1][1]); w.y = cvt_pk_bf16(gelu_t(c2[0][2]) * c2[1][2], gelu_t(c2[0][3]) * c2[1][3]);
;                     if (n == 0) pend[ai][m] = w;
;                     else { u32x4 w4; w4.x = pend[ai][m].x; w4.y = pend[ai][m].y; w4.z = w.x; w4.w = w.y;
;                         *(u32x4*)(F + (size_t)(t0 + ai * 128 + wr * 64 + m * 16 + fr) * FF + cg - 4) = w4; }
;                 }
	v_add_f32_e32 v37, 1.0, v37
	v_mul_f32_e32 v31, 0x3fcc422a, v31
	v_fma_f32 v34, v26, v34, v26
	v_rcp_f32_e32 v37, v37
	v_mul_f32_e32 v31, 0xbfb8aa3b, v31
	v_mul_f32_e32 v34, 0x3fcc422a, v34
	v_exp_f32_e32 v31, v31
	v_mul_f32_e32 v34, 0xbfb8aa3b, v34
	v_exp_f32_e32 v34, v34
	v_mul_f32_e32 v24, v24, v37
	v_mul_f32_e32 v24, v24, v25
	v_add_f32_e32 v25, 1.0, v31
	v_rcp_f32_e32 v25, v25
	v_add_f32_e32 v31, 1.0, v34
	v_rcp_f32_e32 v31, v31
	v_mul_f32_e32 v30, v30, v35
	v_cvt_pk_bf16_f32 v90, v30, v24
	v_mul_f32_e32 v24, v28, v25
	v_mul_f32_e32 v24, v24, v29
	v_mul_f32_e32 v25, v26, v31
	v_mul_f32_e32 v25, v25, v27
	v_cvt_pk_bf16_f32 v91, v24, v25
	v_add_u32_e32 v24, 0x90, v132
	v_mad_i64_i32 v[24:25], s[6:7], v24, s94, v[32:33]
	v_lshl_add_u64 v[24:25], v[24:25], 0, v[94:95]
	v_mov_b32_e32 v26, 0
	v_mov_b32_e32 v27, 0
	global_store_dwordx4 v[24:25], v[88:91], off nt
	v_mov_b32_e32 v24, 0
	v_mov_b32_dpp v26, v20 row_ror:2 row_mask:0xf bank_mask:0xf
	v_mov_b32_e32 v30, 0
	v_mov_b32_e32 v34, 0
	v_mov_b32_e32 v25, 0
	v_mov_b32_dpp v27, v16 row_ror:2 row_mask:0xf bank_mask:0xf
	v_mov_b32_dpp v24, v20 row_ror:1 row_mask:0xf bank_mask:0xf
	v_mov_b32_dpp v26, v12 row_shr:2 row_mask:0xf bank_mask:0xf
	v_mov_b32_dpp v30, v22 row_ror:1 row_mask:0xf bank_mask:0xf
	v_mov_b32_dpp v34, v22 row_ror:2 row_mask:0xf bank_mask:0xf
	v_mov_b32_e32 v22, 0
	v_mov_b32_e32 v36, 0
	v_mov_b32_dpp v25, v16 row_ror:1 row_mask:0xf bank_mask:0xf
	v_mov_b32_dpp v27, v8 row_shr:2 row_mask:0xf bank_mask:0xf
	v_mov_b32_e32 v37, 0
	v_mov_b32_dpp v24, v12 row_shr:1 row_mask:0xf bank_mask:0xf
	v_mov_b32_dpp v22, v23 row_ror:1 row_mask:0xf bank_mask:0xf
	v_mov_b32_dpp v36, v23 row_ror:2 row_mask:0xf bank_mask:0xf
	v_mov_b32_dpp v25, v8 row_shr:1 row_mask:0xf bank_mask:0xf
	v_pk_fma_f32 v[26:27], v[78:79], v[26:27], v[122:123]
	v_mov_b32_e32 v23, 0
	v_mov_b32_dpp v37, v19 row_ror:2 row_mask:0xf bank_mask:0xf
	v_mov_b32_e32 v20, 0
	v_mov_b32_e32 v28, 0
	v_mov_b32_dpp v36, v15 row_shr:2 row_mask:0xf bank_mask:0xf
	v_pk_fma_f32 v[24:25], v[124:125], v[24:25], v[26:27]
	v_mov_b32_e32 v26, v12
	v_mov_b32_e32 v27, v8
	v_mov_b32_e32 v29, 0
	v_mov_b32_e32 v31, 0
	v_mov_b32_e32 v35, 0
	v_mov_b32_dpp v23, v19 row_ror:1 row_mask:0xf bank_mask:0xf
	v_mov_b32_dpp v37, v11 row_shr:2 row_mask:0xf bank_mask:0xf
	v_mov_b32_dpp v20, v21 row_ror:1 row_mask:0xf bank_mask:0xf
	v_mov_b32_dpp v28, v21 row_ror:2 row_mask:0xf bank_mask:0xf
	v_mov_b32_dpp v22, v15 row_shr:1 row_mask:0xf bank_mask:0xf
	v_pk_fma_f32 v[24:25], v[26:27], v[126:127], v[24:25]
	v_mov_b32_e32 v21, 0
	v_mov_b32_dpp v29, v17 row_ror:2 row_mask:0xf bank_mask:0xf
	v_mov_b32_dpp v31, v18 row_ror:1 row_mask:0xf bank_mask:0xf
	v_mov_b32_dpp v35, v18 row_ror:2 row_mask:0xf bank_mask:0xf
	v_mov_b32_dpp v23, v11 row_shr:1 row_mask:0xf bank_mask:0xf
	v_pk_fma_f32 v[18:19], v[76:77], v[36:37], v[72:73]
	v_mov_b32_dpp v28, v13 row_shr:2 row_mask:0xf bank_mask:0xf
	v_mov_b32_dpp v21, v17 row_ror:1 row_mask:0xf bank_mask:0xf
	v_mov_b32_dpp v29, v9 row_shr:2 row_mask:0xf bank_mask:0xf
	v_pk_fma_f32 v[18:19], v[86:87], v[22:23], v[18:19]
	v_mul_f32_e32 v23, 0x3d372713, v24
	v_mov_b32_dpp v20, v13 row_shr:1 row_mask:0xf bank_mask:0xf
	v_mov_b32_dpp v21, v9 row_shr:1 row_mask:0xf bank_mask:0xf
	v_pk_fma_f32 v[16:17], v[74:75], v[28:29], v[70:71]
	v_mul_f32_e32 v23, v24, v23
	v_mov_b32_dpp v34, v14 row_shr:2 row_mask:0xf bank_mask:0xf
	v_pk_fma_f32 v[16:17], v[84:85], v[20:21], v[16:17]
	v_mov_b32_e32 v20, v13
	v_mov_b32_e32 v21, v9
	v_mov_b32_dpp v35, v10 row_shr:2 row_mask:0xf bank_mask:0xf
	v_fma_f32 v23, v24, v23, v24
	v_mov_b32_dpp v30, v14 row_shr:1 row_mask:0xf bank_mask:0xf
	v_pk_fma_f32 v[16:17], v[20:21], v[66:67], v[16:17]
	v_mov_b32_dpp v31, v10 row_shr:1 row_mask:0xf bank_mask:0xf
	v_pk_fma_f32 v[20:21], v[114:115], v[34:35], v[118:119]
	v_mul_f32_e32 v23, 0x3fcc422a, v23
	v_pk_fma_f32 v[20:21], v[128:129], v[30:31], v[20:21]
	v_mov_b32_e32 v26, v14
	v_mov_b32_e32 v27, v10
	v_mul_f32_e32 v23, 0xbfb8aa3b, v23
	v_pk_fma_f32 v[20:21], v[26:27], v[130:131], v[20:21]
	v_exp_f32_e32 v26, v23
	v_mul_f32_e32 v23, 0x3d372713, v16
	v_mul_f32_e32 v23, v16, v23
	v_fma_f32 v23, v16, v23, v16
	v_add_f32_e32 v26, 1.0, v26
	v_mul_f32_e32 v23, 0x3fcc422a, v23
	v_rcp_f32_e32 v26, v26
	v_mul_f32_e32 v23, 0xbfb8aa3b, v23
	v_mov_b32_e32 v22, v15
	v_exp_f32_e32 v27, v23
	v_mov_b32_e32 v23, v11
	v_pk_fma_f32 v[18:19], v[22:23], v[68:69], v[18:19]
	v_mul_f32_e32 v23, 0x3d372713, v20
	v_mul_f32_e32 v22, v24, v26
	v_mul_f32_e32 v23, v20, v23
	v_mul_f32_e32 v24, 0x3d372713, v18
	v_fma_f32 v23, v20, v23, v20
	v_mul_f32_e32 v24, v18, v24
	v_add_f32_e32 v27, 1.0, v27
	v_mul_f32_e32 v23, 0x3fcc422a, v23
	v_fma_f32 v24, v18, v24, v18
	v_rcp_f32_e32 v27, v27
	v_mul_f32_e32 v23, 0xbfb8aa3b, v23
	v_mul_f32_e32 v24, 0x3fcc422a, v24
	v_exp_f32_e32 v23, v23
	v_mul_f32_e32 v24, 0xbfb8aa3b, v24
	v_exp_f32_e32 v24, v24
	v_mul_f32_e32 v16, v16, v27
	v_mul_f32_e32 v16, v16, v17
	v_add_f32_e32 v17, 1.0, v23
	v_rcp_f32_e32 v17, v17
; #define LAS __attribute__((address_space(3)))
; __device__ __forceinline__ unsigned cvt_pk_bf16(float lo, float hi) { unsigned r; asm volatile("v_cvt_pk_bf16_f32 %0, %1, %2" : "=v"(r) : "v"(lo), "v"(hi)); return r; }
; __device__ __forceinline__ float gelu_t(float x) { const float u = 1.5957691216f * (x + 0.044715f * x * x * x); return x * sigm(u); }
; #define PG8_BAR __builtin_amdgcn_s_barrier()
; template <class Epi, class Sched, bool F8 = false>
; __device__ __forceinline__ void gemm_phase(LAS unsigned char* lds, const int lda, const int ldb, const Sched& S, const Epi& E) {
;     ...
;         cur = nxt; cA = nA; cB = nB; ++ui;
;         if (wr == 1) PG8_BAR;
;     __device__ __forceinline__ void operator()(AccT& acc, const Unit& u, int wr, int wc, int fr, int fq) const {
;     ...
;             for (int ai = 0; ai < 2; ++ai) {
;                 f32x4 hv[2]; hv[0] = (f32x4){0.f, 0.f, 0.f, 0.f}; hv[1] = hv[0];
;                 const bool has_pred = (wr == 1) || (ai == 1);
;                 const int pa = (wr == 1) ? ai : 0, pw = (wr == 1) ? 0 : 1;
;                 if (has_pred && fr >= 14) { hv[0] = *(const LAS f32x4*)(xl + xidx(pa, pw, wc, fr - 14, fq, 0, n)); hv[1] = *(const LAS f32x4*)(xl + xidx(pa, pw, wc, fr - 14, fq, 1, n)); }
; #pragma unroll
;                 for (int m = 0; m < 4; ++m) {
;                     f32x4 c2[2];
; #pragma unroll
;                     for (int bj = 0; bj < 2; ++bj) { const f32x4 cur = acc[ai][bj][m][n]; const f32x4 pv = (m == 0) ? hv[bj] : acc[ai][bj][m == 0 ? 0 : m - 1][n];
; #pragma unroll
;                         for (int j = 0; j < 4; ++j) { const float p1 = dpp_shr1(dpp_ror1(pv[j]), cur[j]), p2 = dpp_shr2(dpp_ror2(pv[j]), cur[j]);
;                             c2[bj][j] = bia[bj][j] + wgt[bj][0][j] * p2 + wgt[bj][1][j] * p1 + wgt[bj][2][j] * cur[j]; } }
;                     u32x2 w; w.x = cvt_pk_bf16(gelu_t(c2[0][0]) * c2[1][0], gelu_t(c2[0][1]) * c2[1][1]); w.y = cvt_pk_bf16(gelu_t(c2[0][2]) * c2[1][2], gelu_t(c2[0][3]) * c2[1][3]);
;                     if (n == 0) pend[ai][m] = w;
;                     else { u32x4 w4; w4.x = pend[ai][m].x; w4.y = pend[ai][m].y; w4.z = w.x; w4.w = w.y;
;                         *(u32x4*)(F + (size_t)(t0 + ai * 128 + wr * 64 + m * 16 + fr) * FF + cg - 4) = w4; }
;                 }
	v_add_f32_e32 v23, 1.0, v24
	v_rcp_f32_e32 v23, v23
	v_mul_f32_e32 v22, v22, v25
	v_cvt_pk_bf16_f32 v82, v22, v16
	v_mul_f32_e32 v16, v20, v17
	v_mul_f32_e32 v16, v16, v21
	v_mul_f32_e32 v17, v18, v23
	v_mul_f32_e32 v17, v17, v19
	v_cvt_pk_bf16_f32 v83, v16, v17
	v_add_u32_e32 v16, 0xa0, v132
	v_mad_i64_i32 v[16:17], s[6:7], v16, s94, v[32:33]
	v_lshl_add_u64 v[16:17], v[16:17], 0, v[94:95]
	global_store_dwordx4 v[16:17], v[80:83], off nt
	v_mov_b32_e32 v16, 0
	v_mov_b32_e32 v18, 0
	v_mov_b32_e32 v19, 0
	v_mov_b32_dpp v16, v12 row_ror:1 row_mask:0xf bank_mask:0xf
	v_mov_b32_dpp v18, v12 row_ror:2 row_mask:0xf bank_mask:0xf
	v_mov_b32_e32 v12, 0
	v_mov_b32_e32 v20, 0
	v_mov_b32_e32 v17, 0
	v_mov_b32_dpp v19, v8 row_ror:2 row_mask:0xf bank_mask:0xf
	v_mov_b32_e32 v21, 0
	v_mov_b32_dpp v18, v4 row_shr:2 row_mask:0xf bank_mask:0xf
	v_mov_b32_dpp v12, v13 row_ror:1 row_mask:0xf bank_mask:0xf
	v_mov_b32_dpp v20, v13 row_ror:2 row_mask:0xf bank_mask:0xf
	v_mov_b32_dpp v17, v8 row_ror:1 row_mask:0xf bank_mask:0xf
	v_mov_b32_dpp v19, v0 row_shr:2 row_mask:0xf bank_mask:0xf
	v_mov_b32_e32 v13, 0
	v_mov_b32_dpp v21, v9 row_ror:2 row_mask:0xf bank_mask:0xf
	v_mov_b32_dpp v16, v4 row_shr:1 row_mask:0xf bank_mask:0xf
	v_mov_b32_dpp v20, v5 row_shr:2 row_mask:0xf bank_mask:0xf
	v_mov_b32_dpp v17, v0 row_shr:1 row_mask:0xf bank_mask:0xf
	v_pk_fma_f32 v[18:19], v[78:79], v[18:19], v[122:123]
	v_mov_b32_dpp v13, v9 row_ror:1 row_mask:0xf bank_mask:0xf
	v_mov_b32_dpp v21, v1 row_shr:2 row_mask:0xf bank_mask:0xf
	v_mov_b32_dpp v12, v5 row_shr:1 row_mask:0xf bank_mask:0xf
	v_pk_fma_f32 v[16:17], v[124:125], v[16:17], v[18:19]
	v_mov_b32_e32 v18, v4
	v_mov_b32_e32 v19, v0
	v_mov_b32_dpp v13, v1 row_shr:1 row_mask:0xf bank_mask:0xf
	v_pk_fma_f32 v[8:9], v[74:75], v[20:21], v[70:71]
	v_mov_b32_e32 v23, 0
	v_mov_b32_e32 v25, 0
	v_pk_fma_f32 v[16:17], v[18:19], v[126:127], v[16:17]
	v_pk_fma_f32 v[8:9], v[84:85], v[12:13], v[8:9]
	v_mov_b32_e32 v0, v5
	v_mov_b32_dpp v23, v10 row_ror:1 row_mask:0xf bank_mask:0xf
	v_mov_b32_dpp v25, v10 row_ror:2 row_mask:0xf bank_mask:0xf
	v_pk_fma_f32 v[0:1], v[0:1], v[66:67], v[8:9]
	v_mov_b32_dpp v23, v2 row_shr:1 row_mask:0xf bank_mask:0xf
	v_mov_b32_dpp v25, v2 row_shr:2 row_mask:0xf bank_mask:0xf
	v_mov_b32_e32 v9, v2
	v_mul_f32_e32 v2, 0x3d372713, v16
	v_mul_f32_e32 v2, v16, v2
	v_fma_f32 v2, v16, v2, v16
	v_mov_b32_e32 v22, 0
	v_mov_b32_e32 v24, 0
	v_mul_f32_e32 v2, 0x3fcc422a, v2
	v_mov_b32_dpp v22, v14 row_ror:1 row_mask:0xf bank_mask:0xf
	v_mov_b32_dpp v24, v14 row_ror:2 row_mask:0xf bank_mask:0xf
	v_mul_f32_e32 v2, 0xbfb8aa3b, v2
	v_mov_b32_dpp v22, v6 row_shr:1 row_mask:0xf bank_mask:0xf
	v_mov_b32_dpp v24, v6 row_shr:2 row_mask:0xf bank_mask:0xf
	v_mov_b32_e32 v8, v6
	v_exp_f32_e32 v6, v2
	v_mul_f32_e32 v2, 0x3d372713, v0
	v_mul_f32_e32 v2, v0, v2
	v_fma_f32 v2, v0, v2, v0
	v_mul_f32_e32 v2, 0x3fcc422a, v2
	v_mul_f32_e32 v2, 0xbfb8aa3b, v2
	v_exp_f32_e32 v10, v2
	v_mov_b32_e32 v14, 0
	v_mov_b32_e32 v26, 0
	v_mov_b32_e32 v27, 0
	v_mov_b32_dpp v14, v15 row_ror:1 row_mask:0xf bank_mask:0xf
	v_mov_b32_dpp v26, v15 row_ror:2 row_mask:0xf bank_mask:0xf
	v_mov_b32_e32 v2, v7
	v_mov_b32_dpp v14, v7 row_shr:1 row_mask:0xf bank_mask:0xf
	v_mov_b32_dpp v26, v7 row_shr:2 row_mask:0xf bank_mask:0xf
	v_add_f32_e32 v7, 1.0, v10
	v_pk_fma_f32 v[4:5], v[114:115], v[24:25], v[118:119]
	v_mov_b32_e32 v15, 0
	v_mov_b32_dpp v27, v11 row_ror:2 row_mask:0xf bank_mask:0xf
	v_rcp_f32_e32 v7, v7
	v_pk_fma_f32 v[4:5], v[128:129], v[22:23], v[4:5]
	v_mov_b32_dpp v15, v11 row_ror:1 row_mask:0xf bank_mask:0xf
	v_mov_b32_dpp v27, v3 row_shr:2 row_mask:0xf bank_mask:0xf
	v_pk_fma_f32 v[4:5], v[8:9], v[130:131], v[4:5]
	v_mov_b32_dpp v15, v3 row_shr:1 row_mask:0xf bank_mask:0xf
	v_pk_fma_f32 v[8:9], v[76:77], v[26:27], v[72:73]
	v_mul_f32_e32 v0, v0, v7
	v_pk_fma_f32 v[8:9], v[86:87], v[14:15], v[8:9]
	v_mul_f32_e32 v7, 0x3d372713, v4
	v_pk_fma_f32 v[2:3], v[2:3], v[68:69], v[8:9]
	v_mul_f32_e32 v7, v4, v7
	v_mul_f32_e32 v8, 0x3d372713, v2
	v_fma_f32 v7, v4, v7, v4
	v_mul_f32_e32 v8, v2, v8
	v_mul_f32_e32 v7, 0x3fcc422a, v7
	v_fma_f32 v8, v2, v8, v2
	v_mul_f32_e32 v7, 0xbfb8aa3b, v7
	v_mul_f32_e32 v8, 0x3fcc422a, v8
	v_exp_f32_e32 v7, v7
	v_mul_f32_e32 v8, 0xbfb8aa3b, v8
	v_exp_f32_e32 v8, v8
	v_add_f32_e32 v6, 1.0, v6
	v_rcp_f32_e32 v6, v6
	v_mul_f32_e32 v0, v0, v1
	v_add_f32_e32 v1, 1.0, v7
	v_rcp_f32_e32 v1, v1
	v_add_f32_e32 v7, 1.0, v8
	v_rcp_f32_e32 v7, v7
	v_mul_f32_e32 v6, v16, v6
	v_mul_f32_e32 v6, v6, v17
	v_cvt_pk_bf16_f32 v66, v6, v0
	v_mul_f32_e32 v0, v4, v1
	v_mul_f32_e32 v0, v0, v5
	v_mul_f32_e32 v1, v2, v7
	v_mul_f32_e32 v1, v1, v3
	v_cvt_pk_bf16_f32 v67, v0, v1
	v_add_u32_e32 v0, 0xb0, v132
	v_mad_i64_i32 v[0:1], s[6:7], v0, s94, v[32:33]
	v_lshl_add_u64 v[0:1], v[0:1], 0, v[94:95]
	s_andn2_b64 vcc, exec, s[0:1]
	s_mov_b64 s[0:1], -1
	global_store_dwordx4 v[0:1], v[64:67], off nt
	s_cbranch_vccnz .LBB0_774
	s_and_b64 vcc, exec, s[4:5]
	s_cbranch_vccnz .LBB0_773
	s_barrier
	s_branch .LBB0_773

; #define LAS __attribute__((address_space(3)))
; #define LDS_WAIT() asm volatile("s_waitcnt lgkmcnt(0)" ::: "memory")
; __device__ __forceinline__ void transpose_item(const float* W, int N, bf16_t* WT, int nkt, int k0, int n0, int r0, int kbd, LAS float* scr, int lane) {
;     const size_t dst_off = ((size_t)(r0 >> 8) * nkt + kbd) * 16384 + (size_t)(r0 & 255) * 64;
;     const int l15 = lane & 15, lq = lane >> 4;
;     f32x4 v[16];
; #pragma unroll
;     for (int i = 0; i < 16; ++i) v[i] = *(const f32x4*)(W + (size_t)(k0 + 4 * i + lq) * N + n0 + 4 * l15);
; #pragma unroll
;     for (int i = 0; i < 16; ++i) { LAS float* d = scr + (4 * i + lq) * 65 + 4 * l15; d[0] = v[i][0]; d[1] = v[i][1]; d[2] = v[i][2]; d[3] = v[i][3]; }
;     LDS_WAIT();
; __device__ __forceinline__ void phase_convert_wdown(const Params& p, LAS float* scr, int cw, int NCW, int lane) {
;     unsigned char* ws = p.ws;
;     for (int it = cw; it < 172 * 64; it += NCW) { const int nb = it % 64, kb = it / 64; transpose_item(p.in[24], 4096, (bf16_t*)(ws + WS_W_DOWN), 172, kb * 64, nb * 64, nb * 64, kb, scr, lane); }
.LBB0_801:
	s_ashr_i32 s9, s0, 31
	s_lshr_b32 s9, s9, 26
	s_add_i32 s9, s0, s9
	s_and_b32 s12, s7, 0x3000
	s_ashr_i32 s15, s9, 6
	s_andn2_b32 s9, s9, 63
	s_lshl_b32 s14, s12, 1
	s_lshl_b32 s12, s15, 12
	v_or_b32_e32 v20, s9, v22
	s_sub_i32 s12, s5, s12
	v_or_b32_e32 v56, 4, v20
	v_or_b32_e32 v58, 8, v20
	v_or_b32_e32 v60, 12, v20
	v_or_b32_e32 v62, 16, v20
	v_or_b32_e32 v64, 20, v20
	v_or_b32_e32 v66, 24, v20
	v_or_b32_e32 v68, 28, v20
	v_or_b32_e32 v70, 32, v20
	v_or_b32_e32 v72, 36, v20
	v_or_b32_e32 v74, 40, v20
	v_or_b32_e32 v76, 44, v20
	v_or_b32_e32 v78, 48, v20
	v_or_b32_e32 v80, 52, v20
	v_or_b32_e32 v82, 56, v20
	v_ashrrev_i32_e32 v21, 31, v20
	v_or_b32_e32 v84, 60, v20
	s_ashr_i32 s13, s12, 31
	v_ashrrev_i32_e32 v57, 31, v56
	v_ashrrev_i32_e32 v59, 31, v58
	v_ashrrev_i32_e32 v61, 31, v60
	v_ashrrev_i32_e32 v63, 31, v62
	v_ashrrev_i32_e32 v65, 31, v64
	v_ashrrev_i32_e32 v67, 31, v66
	v_ashrrev_i32_e32 v69, 31, v68
	v_ashrrev_i32_e32 v71, 31, v70
	v_ashrrev_i32_e32 v73, 31, v72
	v_ashrrev_i32_e32 v75, 31, v74
	v_ashrrev_i32_e32 v77, 31, v76
	v_ashrrev_i32_e32 v79, 31, v78
	v_ashrrev_i32_e32 v81, 31, v80
	v_ashrrev_i32_e32 v83, 31, v82
	v_lshlrev_b64 v[20:21], 14, v[20:21]
	v_ashrrev_i32_e32 v85, 31, v84
	v_lshl_add_u64 v[86:87], s[12:13], 2, v[2:3]
	v_lshlrev_b64 v[56:57], 14, v[56:57]
	v_lshlrev_b64 v[58:59], 14, v[58:59]
	v_lshlrev_b64 v[60:61], 14, v[60:61]
	v_lshlrev_b64 v[62:63], 14, v[62:63]
	v_lshlrev_b64 v[64:65], 14, v[64:65]
	v_lshlrev_b64 v[66:67], 14, v[66:67]
	v_lshlrev_b64 v[68:69], 14, v[68:69]
	v_lshlrev_b64 v[70:71], 14, v[70:71]
	v_lshlrev_b64 v[72:73], 14, v[72:73]
	v_lshlrev_b64 v[74:75], 14, v[74:75]
	v_lshlrev_b64 v[76:77], 14, v[76:77]
	v_lshlrev_b64 v[78:79], 14, v[78:79]
	v_lshlrev_b64 v[80:81], 14, v[80:81]
	v_lshlrev_b64 v[82:83], 14, v[82:83]
	v_lshlrev_b64 v[84:85], 14, v[84:85]
	v_lshl_add_u64 v[20:21], v[86:87], 0, v[20:21]
	v_lshl_add_u64 v[92:93], v[86:87], 0, v[56:57]
	v_lshl_add_u64 v[94:95], v[86:87], 0, v[58:59]
	v_lshl_add_u64 v[96:97], v[86:87], 0, v[60:61]
	v_lshl_add_u64 v[98:99], v[86:87], 0, v[62:63]
	v_lshl_add_u64 v[100:101], v[86:87], 0, v[64:65]
	v_lshl_add_u64 v[102:103], v[86:87], 0, v[66:67]
	v_lshl_add_u64 v[104:105], v[86:87], 0, v[68:69]
	v_lshl_add_u64 v[106:107], v[86:87], 0, v[70:71]
	v_lshl_add_u64 v[108:109], v[86:87], 0, v[72:73]
	v_lshl_add_u64 v[110:111], v[86:87], 0, v[74:75]
	v_lshl_add_u64 v[112:113], v[86:87], 0, v[76:77]
	v_lshl_add_u64 v[114:115], v[86:87], 0, v[78:79]
	v_lshl_add_u64 v[116:117], v[86:87], 0, v[80:81]
	v_lshl_add_u64 v[118:119], v[86:87], 0, v[82:83]
	v_lshl_add_u64 v[120:121], v[86:87], 0, v[84:85]
	global_load_dwordx4 v[56:59], v[20:21], off nt
	global_load_dwordx4 v[60:63], v[92:93], off nt
	global_load_dwordx4 v[64:67], v[94:95], off nt
	global_load_dwordx4 v[68:71], v[96:97], off nt
	global_load_dwordx4 v[72:75], v[98:99], off nt
	global_load_dwordx4 v[76:79], v[100:101], off nt
	global_load_dwordx4 v[80:83], v[102:103], off nt
	global_load_dwordx4 v[84:87], v[104:105], off nt
	global_load_dwordx4 v[88:91], v[106:107], off nt
	global_load_dwordx4 v[92:95], v[108:109], off nt
	global_load_dwordx4 v[96:99], v[110:111], off nt
	s_nop 0
	global_load_dwordx4 v[100:103], v[112:113], off nt
	global_load_dwordx4 v[104:107], v[114:115], off nt
	global_load_dwordx4 v[108:111], v[116:117], off nt
	s_nop 0
	global_load_dwordx4 v[112:115], v[118:119], off nt
	s_nop 0
	global_load_dwordx4 v[116:119], v[120:121], off nt
	s_sub_i32 s16, s0, s9
	s_lshr_b32 s9, s16, 2
	s_mulk_i32 s9, 0xac
	s_add_i32 s12, s9, s15
	s_ashr_i32 s13, s12, 31
	s_add_u32 s9, s3, s14
	s_addc_u32 s14, s4, 0
	s_lshl_b64 s[12:13], s[12:13], 15
	s_add_u32 s12, s9, s12
	s_addc_u32 s13, s14, s13
	v_lshl_add_u64 v[20:21], s[12:13], 0, v[0:1]
	v_lshl_add_u64 v[120:121], v[20:21], 0, v[4:5]
	v_lshl_add_u64 v[122:123], v[20:21], 0, v[6:7]
	s_waitcnt vmcnt(15)
	ds_write2_b32 v24, v56, v57 offset1:1
	ds_write2_b32 v24, v58, v59 offset0:2 offset1:3
	s_waitcnt vmcnt(14)
	ds_write2_b32 v25, v60, v61 offset1:1
	ds_write2_b32 v26, v62, v63 offset1:1
	s_waitcnt vmcnt(13)
	ds_write2_b32 v27, v64, v65 offset1:1
	ds_write2_b32 v28, v66, v67 offset1:1
	s_waitcnt vmcnt(12)
	ds_write2_b32 v29, v68, v69 offset1:1
	ds_write2_b32 v30, v70, v71 offset1:1
	s_waitcnt vmcnt(11)
	ds_write2_b32 v31, v72, v73 offset1:1
	ds_write2_b32 v32, v74, v75 offset1:1
	s_waitcnt vmcnt(10)
	ds_write2_b32 v33, v76, v77 offset1:1
	ds_write2_b32 v34, v78, v79 offset1:1
	s_waitcnt vmcnt(9)
	ds_write2_b32 v35, v80, v81 offset1:1
	ds_write2_b32 v36, v82, v83 offset1:1
	s_waitcnt vmcnt(8)
	ds_write2_b32 v37, v84, v85 offset1:1
	ds_write2_b32 v38, v86, v87 offset1:1
	s_waitcnt vmcnt(7)
	ds_write2_b32 v39, v88, v89 offset1:1
	ds_write2_b32 v40, v90, v91 offset1:1
	s_waitcnt vmcnt(6)
	ds_write2_b32 v41, v92, v93 offset1:1
	ds_write2_b32 v42, v94, v95 offset1:1
	s_waitcnt vmcnt(5)
; #define LAS __attribute__((address_space(3)))
; __device__ __forceinline__ unsigned cvt_pk_bf16(float lo, float hi) { unsigned r; asm volatile("v_cvt_pk_bf16_f32 %0, %1, %2" : "=v"(r) : "v"(lo), "v"(hi)); return r; }
; #define LDS_WAIT() asm volatile("s_waitcnt lgkmcnt(0)" ::: "memory")
; __device__ __forceinline__ void transpose_item(const float* W, int N, bf16_t* WT, int nkt, int k0, int n0, int r0, int kbd, LAS float* scr, int lane) {
;     ...
;     for (int i = 0; i < 16; ++i) { LAS float* d = scr + (4 * i + lq) * 65 + 4 * l15; d[0] = v[i][0]; d[1] = v[i][1]; d[2] = v[i][2]; d[3] = v[i][3]; }
;     LDS_WAIT();
;     const int c = lane & 7;
; #pragma unroll
;     for (int j = 0; j < 8; ++j) { const int n = (lane >> 3) + 8 * j; const LAS float* s = scr + (8 * c) * 65 + n;
;         u32x4 o; o.x = cvt_pk_bf16(s[0], s[65]); o.y = cvt_pk_bf16(s[2 * 65], s[3 * 65]); o.z = cvt_pk_bf16(s[4 * 65], s[5 * 65]); o.w = cvt_pk_bf16(s[6 * 65], s[7 * 65]);
;         *(u32x4*)(WT + dst_off + (size_t)n * 64 + 8 * c) = o; }
;     LDS_WAIT();
; __device__ __forceinline__ void phase_convert_wdown(const Params& p, LAS float* scr, int cw, int NCW, int lane) {
;     ...
;     for (int it = cw; it < 172 * 64; it += NCW) { const int nb = it % 64, kb = it / 64; transpose_item(p.in[24], 4096, (bf16_t*)(ws + WS_W_DOWN), 172, kb * 64, nb * 64, nb * 64, kb, scr, lane); }
	ds_write2_b32 v43, v96, v97 offset1:1
	ds_write2_b32 v44, v98, v99 offset1:1
	s_waitcnt vmcnt(4)
	ds_write2_b32 v45, v100, v101 offset1:1
	ds_write2_b32 v46, v102, v103 offset1:1
	s_waitcnt vmcnt(3)
	ds_write2_b32 v47, v104, v105 offset1:1
	ds_write2_b32 v48, v106, v107 offset1:1
	s_waitcnt vmcnt(2)
	ds_write2_b32 v49, v108, v109 offset1:1
	ds_write2_b32 v50, v110, v111 offset1:1
	s_waitcnt vmcnt(1)
	ds_write2_b32 v51, v112, v113 offset1:1
	ds_write2_b32 v52, v114, v115 offset1:1
	s_waitcnt vmcnt(0)
	ds_write2_b32 v53, v116, v117 offset1:1
	ds_write2_b32 v54, v118, v119 offset1:1
	s_waitcnt lgkmcnt(0)
	ds_read2_b32 v[56:57], v23 offset1:65
	s_waitcnt lgkmcnt(0)
	v_cvt_pk_bf16_f32 v56, v56, v57
	ds_read2_b32 v[58:59], v23 offset0:130 offset1:195
	s_waitcnt lgkmcnt(0)
	v_cvt_pk_bf16_f32 v57, v58, v59
	ds_read2_b32 v[58:59], v55 offset0:4 offset1:69
	s_waitcnt lgkmcnt(0)
	v_cvt_pk_bf16_f32 v58, v58, v59
	ds_read2_b32 v[60:61], v55 offset0:134 offset1:199
	s_waitcnt lgkmcnt(0)
	v_cvt_pk_bf16_f32 v59, v60, v61
	ds_read2_b32 v[60:61], v23 offset0:8 offset1:73
	global_store_dwordx4 v[120:121], v[56:59], off nt
	v_lshl_add_u64 v[124:125], v[20:21], 0, v[8:9]
	v_lshl_add_u64 v[126:127], v[20:21], 0, v[10:11]
	s_waitcnt lgkmcnt(0)
	v_cvt_pk_bf16_f32 v56, v60, v61
	ds_read2_b32 v[58:59], v23 offset0:138 offset1:203
	s_waitcnt lgkmcnt(0)
	v_cvt_pk_bf16_f32 v57, v58, v59
	ds_read2_b32 v[58:59], v55 offset0:12 offset1:77
	s_waitcnt lgkmcnt(0)
	v_cvt_pk_bf16_f32 v58, v58, v59
	ds_read2_b32 v[60:61], v55 offset0:142 offset1:207
	s_waitcnt lgkmcnt(0)
	v_cvt_pk_bf16_f32 v59, v60, v61
	ds_read2_b32 v[60:61], v23 offset0:16 offset1:81
	global_store_dwordx4 v[122:123], v[56:59], off nt
	v_lshl_add_u64 v[128:129], v[20:21], 0, v[12:13]
	v_lshl_add_u64 v[130:131], v[20:21], 0, v[14:15]
	s_waitcnt lgkmcnt(0)
	v_cvt_pk_bf16_f32 v56, v60, v61
	ds_read2_b32 v[58:59], v23 offset0:146 offset1:211
	s_waitcnt lgkmcnt(0)
	v_cvt_pk_bf16_f32 v57, v58, v59
	ds_read2_b32 v[58:59], v55 offset0:20 offset1:85
	s_waitcnt lgkmcnt(0)
	v_cvt_pk_bf16_f32 v58, v58, v59
	ds_read2_b32 v[60:61], v55 offset0:150 offset1:215
	s_waitcnt lgkmcnt(0)
	v_cvt_pk_bf16_f32 v59, v60, v61
	ds_read2_b32 v[60:61], v23 offset0:24 offset1:89
	global_store_dwordx4 v[124:125], v[56:59], off nt
	v_lshl_add_u64 v[132:133], v[20:21], 0, v[16:17]
	v_lshl_add_u64 v[20:21], v[20:21], 0, v[18:19]
	s_waitcnt lgkmcnt(0)
	v_cvt_pk_bf16_f32 v56, v60, v61
	ds_read2_b32 v[58:59], v23 offset0:154 offset1:219
	s_waitcnt lgkmcnt(0)
	v_cvt_pk_bf16_f32 v57, v58, v59
	ds_read2_b32 v[58:59], v55 offset0:28 offset1:93
	s_waitcnt lgkmcnt(0)
	v_cvt_pk_bf16_f32 v58, v58, v59
	ds_read2_b32 v[60:61], v55 offset0:158 offset1:223
	s_waitcnt lgkmcnt(0)
	v_cvt_pk_bf16_f32 v59, v60, v61
	ds_read2_b32 v[60:61], v23 offset0:32 offset1:97
	global_store_dwordx4 v[126:127], v[56:59], off nt
	s_add_i32 s0, s0, s1
	s_add_i32 s5, s5, s6
	s_waitcnt lgkmcnt(0)
	v_cvt_pk_bf16_f32 v56, v60, v61
	ds_read2_b32 v[58:59], v23 offset0:162 offset1:227
	s_waitcnt lgkmcnt(0)
	v_cvt_pk_bf16_f32 v57, v58, v59
	ds_read2_b32 v[58:59], v55 offset0:36 offset1:101
	s_waitcnt lgkmcnt(0)
	v_cvt_pk_bf16_f32 v58, v58, v59
	ds_read2_b32 v[60:61], v55 offset0:166 offset1:231
	s_waitcnt lgkmcnt(0)
	v_cvt_pk_bf16_f32 v59, v60, v61
	ds_read2_b32 v[60:61], v23 offset0:40 offset1:105
	global_store_dwordx4 v[128:129], v[56:59], off nt
	s_add_i32 s7, s7, s8
	s_cmpk_lt_i32 s0, 0x2b00
	s_waitcnt lgkmcnt(0)
	v_cvt_pk_bf16_f32 v56, v60, v61
	ds_read2_b32 v[58:59], v23 offset0:170 offset1:235
	s_waitcnt lgkmcnt(0)
	v_cvt_pk_bf16_f32 v57, v58, v59
	ds_read2_b32 v[58:59], v55 offset0:44 offset1:109
	s_waitcnt lgkmcnt(0)
	v_cvt_pk_bf16_f32 v58, v58, v59
	ds_read2_b32 v[60:61], v55 offset0:174 offset1:239
	s_waitcnt lgkmcnt(0)
	v_cvt_pk_bf16_f32 v59, v60, v61
	ds_read2_b32 v[60:61], v23 offset0:48 offset1:113
	global_store_dwordx4 v[130:131], v[56:59], off nt
	s_waitcnt lgkmcnt(0)
	s_nop 0
	v_cvt_pk_bf16_f32 v56, v60, v61
	ds_read2_b32 v[58:59], v23 offset0:178 offset1:243
	s_waitcnt lgkmcnt(0)
	v_cvt_pk_bf16_f32 v57, v58, v59
	ds_read2_b32 v[58:59], v55 offset0:52 offset1:117
	s_waitcnt lgkmcnt(0)
	v_cvt_pk_bf16_f32 v58, v58, v59
	ds_read2_b32 v[60:61], v55 offset0:182 offset1:247
	s_waitcnt lgkmcnt(0)
	v_cvt_pk_bf16_f32 v59, v60, v61
	ds_read2_b32 v[60:61], v23 offset0:56 offset1:121
	global_store_dwordx4 v[132:133], v[56:59], off nt
	s_waitcnt lgkmcnt(0)
	s_nop 0
	v_cvt_pk_bf16_f32 v56, v60, v61
	ds_read2_b32 v[58:59], v23 offset0:186 offset1:251
	s_waitcnt lgkmcnt(0)
	v_cvt_pk_bf16_f32 v57, v58, v59
	ds_read2_b32 v[58:59], v55 offset0:60 offset1:125
	s_waitcnt lgkmcnt(0)
	v_cvt_pk_bf16_f32 v58, v58, v59
	ds_read2_b32 v[60:61], v55 offset0:190 offset1:255
	s_waitcnt lgkmcnt(0)
	v_cvt_pk_bf16_f32 v59, v60, v61
	global_store_dwordx4 v[20:21], v[56:59], off nt
	s_waitcnt lgkmcnt(0)
	s_cbranch_scc1 .LBB0_801

; __device__ __forceinline__ u32x4 pack8(const f32x4 v0, const f32x4 v1) { u32x4 w; w.x = cvt_pk_bf16(v0[0], v0[1]); w.y = cvt_pk_bf16(v0[2], v0[3]); w.z = cvt_pk_bf16(v1[0], v1[1]); w.w = cvt_pk_bf16(v1[2], v1[3]); return w; }
;     __device__ __forceinline__ void operator()(AccT& acc, const Unit& u, int wr, int wc, int fr, int fq) const {
;         const int row0 = u.pm * 256 + wr * 64 + fr, col0 = u.pn * 256 + wc * 32 + 8 * fq;
; #pragma unroll
;         for (int ai = 0; ai < 2; ++ai)
; #pragma unroll
;             for (int m = 0; m < 4; ++m) { const int row = row0 + ai * 128 + m * 16; bf16_t* rowp = O + (size_t)row * DM + col0; float ss = 0.f;
; #pragma unroll
;                 for (int bj = 0; bj < 2; ++bj) { const f32x4 v0 = acc[ai][bj][m][0], v1 = acc[ai][bj][m][1];
;                     ss += (v0[0] * v0[0] + v0[1] * v0[1]) + (v0[2] * v0[2] + v0[3] * v0[3]) + (v1[0] * v1[0] + v1[1] * v1[1]) + (v1[2] * v1[2] + v1[3] * v1[3]);
;                     *(u32x4*)(rowp + bj * 128) = pack8(v0, v1); }
;                 ss += __shfl_xor(ss, 16); ss += __shfl_xor(ss, 32);
;                 if (fq == 0) SSQ[(size_t)(u.pn * 4 + wc) * MT + row] = ss; }
.LBB0_938:
	v_mul_f32_e32 v148, v125, v125
	v_mul_f32_e32 v149, v127, v127
	v_fmac_f32_e32 v148, v124, v124
	v_fmac_f32_e32 v149, v126, v126
	v_add_f32_e32 v148, v148, v149
	v_mul_f32_e32 v149, v121, v121
	v_fmac_f32_e32 v149, v120, v120
	v_add_f32_e32 v148, v149, v148
	v_mul_f32_e32 v149, v123, v123
	v_mov_b32_e32 v136, v254
	v_fmac_f32_e32 v149, v122, v122
	v_add_f32_e32 v150, v149, v148
	v_cvt_pk_bf16_f32 v148, v124, v125
	v_mul_f32_e32 v124, v117, v117
	v_mul_f32_e32 v125, v119, v119
	s_lshl_b32 s4, s88, 8
	v_fmac_f32_e32 v124, v116, v116
	v_fmac_f32_e32 v125, v118, v118
	s_add_i32 s4, s4, s71
	v_add_f32_e32 v124, v124, v125
	v_mul_f32_e32 v125, v113, v113
	v_bfe_u32 v137, v136, 4, 2
	v_and_or_b32 v136, v136, 15, s4
	s_lshl_b32 s4, s87, 8
	v_fmac_f32_e32 v125, v112, v112
	s_or_b32 s4, s4, s72
	v_add_f32_e32 v124, v125, v124
	v_mul_f32_e32 v125, v115, v115
	v_lshl_or_b32 v140, v137, 3, s4
	s_lshl_b32 s4, s87, 2
	v_fmac_f32_e32 v125, v114, v114
	s_or_b32 s4, s4, s70
	v_cvt_pk_bf16_f32 v149, v126, v127
	v_add_f32_e32 v124, v125, v124
	v_and_b32_e32 v126, 64, v147
	s_ashr_i32 s5, s4, 31
	v_add_f32_e32 v125, v124, v150
	v_xor_b32_e32 v124, 16, v147
	v_add_u32_e32 v126, 64, v126
	s_lshl_b64 s[12:13], s[4:5], 15
	v_cmp_lt_i32_e64 s[4:5], v124, v126
	v_cmp_eq_u32_e32 vcc, 0, v137
	v_ashrrev_i32_e32 v137, 31, v136
	v_cndmask_b32_e64 v124, v147, v124, s[4:5]
	v_lshlrev_b64 v[138:139], 13, v[136:137]
	v_lshlrev_b32_e32 v124, 2, v124
	v_ashrrev_i32_e32 v141, 31, v140
	v_lshl_add_u64 v[138:139], s[28:29], 0, v[138:139]
	ds_bpermute_b32 v127, v124, v125
	v_lshl_add_u64 v[138:139], v[140:141], 1, v[138:139]
	v_cvt_pk_bf16_f32 v150, v120, v121
	v_cvt_pk_bf16_f32 v151, v122, v123
	global_store_dwordx4 v[138:139], v[148:151], off nt
	s_nop 1
	v_cvt_pk_bf16_f32 v148, v116, v117
	v_xor_b32_e32 v116, 32, v147
	v_cmp_lt_i32_e64 s[4:5], v116, v126
	s_waitcnt lgkmcnt(0)
	v_add_f32_e32 v117, v125, v127
	v_cvt_pk_bf16_f32 v149, v118, v119
	v_cvt_pk_bf16_f32 v150, v112, v113
	v_cvt_pk_bf16_f32 v151, v114, v115
	global_store_dwordx4 v[138:139], v[148:151], off offset:256 nt
	v_cndmask_b32_e64 v116, v147, v116, s[4:5]
	v_lshlrev_b32_e32 v116, 2, v116
	ds_bpermute_b32 v120, v116, v117
	s_and_saveexec_b64 s[4:5], vcc
	s_cbranch_execz .LBB0_940
	s_add_u32 s14, s68, s12
	s_addc_u32 s15, s69, s13
	s_waitcnt lgkmcnt(0)
	v_add_f32_e32 v114, v117, v120
	v_lshl_add_u64 v[112:113], v[136:137], 2, s[14:15]
	global_store_dword v[112:113], v114, off
.LBB0_940:
	s_or_b64 exec, exec, s[4:5]
	v_mul_f32_e32 v114, v109, v109
	v_mul_f32_e32 v115, v111, v111
	v_fmac_f32_e32 v114, v108, v108
	v_fmac_f32_e32 v115, v110, v110
	v_cvt_pk_bf16_f32 v108, v108, v109
	v_cvt_pk_bf16_f32 v109, v110, v111
	v_mul_f32_e32 v110, v101, v101
	v_mul_f32_e32 v111, v103, v103
	v_fmac_f32_e32 v110, v100, v100
	v_fmac_f32_e32 v111, v102, v102
	v_add_f32_e32 v114, v114, v115
	v_mul_f32_e32 v115, v105, v105
	v_add_f32_e32 v110, v110, v111
	v_mul_f32_e32 v111, v97, v97
	v_fmac_f32_e32 v115, v104, v104
	v_fmac_f32_e32 v111, v96, v96
	v_add_f32_e32 v114, v115, v114
	v_mul_f32_e32 v115, v107, v107
	v_add_f32_e32 v110, v111, v110
	v_mul_f32_e32 v111, v99, v99
	v_fmac_f32_e32 v115, v106, v106
	v_fmac_f32_e32 v111, v98, v98
	v_add_f32_e32 v114, v115, v114
	v_add_f32_e32 v110, v111, v110
	v_add_f32_e32 v114, v110, v114
	v_or_b32_e32 v112, 16, v136
	ds_bpermute_b32 v115, v124, v114
	v_ashrrev_i32_e32 v113, 31, v112
	v_lshlrev_b64 v[112:113], 13, v[112:113]
	v_lshl_add_u64 v[112:113], s[28:29], 0, v[112:113]
	v_lshl_add_u64 v[112:113], v[140:141], 1, v[112:113]
	v_cvt_pk_bf16_f32 v110, v104, v105
	v_cvt_pk_bf16_f32 v111, v106, v107
	global_store_dwordx4 v[112:113], v[108:111], off nt
	v_cvt_pk_bf16_f32 v104, v100, v101
	s_waitcnt lgkmcnt(0)
	v_add_f32_e32 v100, v114, v115
	ds_bpermute_b32 v101, v116, v100
	v_cvt_pk_bf16_f32 v105, v102, v103
	v_cvt_pk_bf16_f32 v106, v96, v97
	v_cvt_pk_bf16_f32 v107, v98, v99
	global_store_dwordx4 v[112:113], v[104:107], off offset:256 nt
	s_and_saveexec_b64 s[4:5], vcc
	s_cbranch_execz .LBB0_942
	s_add_u32 s14, s68, s12
	s_addc_u32 s15, s69, s13
	s_waitcnt lgkmcnt(0)
	v_add_f32_e32 v98, v100, v101
	v_lshl_add_u64 v[96:97], v[136:137], 2, s[14:15]
	global_store_dword v[96:97], v98, off offset:64
.LBB0_942:
	s_or_b64 exec, exec, s[4:5]
	v_mul_f32_e32 v98, v93, v93
	v_mul_f32_e32 v99, v95, v95
	v_fmac_f32_e32 v98, v92, v92
	v_fmac_f32_e32 v99, v94, v94
	v_cvt_pk_bf16_f32 v92, v92, v93
	v_cvt_pk_bf16_f32 v93, v94, v95
	v_mul_f32_e32 v94, v85, v85
	v_mul_f32_e32 v95, v87, v87
	v_fmac_f32_e32 v94, v84, v84
	v_fmac_f32_e32 v95, v86, v86
	v_add_f32_e32 v98, v98, v99
	v_mul_f32_e32 v99, v89, v89
	v_add_f32_e32 v94, v94, v95
	v_mul_f32_e32 v95, v81, v81
	v_fmac_f32_e32 v99, v88, v88
	v_fmac_f32_e32 v95, v80, v80
	v_add_f32_e32 v98, v99, v98
	v_mul_f32_e32 v99, v91, v91
	v_add_f32_e32 v94, v95, v94
	v_mul_f32_e32 v95, v83, v83
	v_fmac_f32_e32 v99, v90, v90
	v_fmac_f32_e32 v95, v82, v82
	v_add_f32_e32 v98, v99, v98
	v_add_f32_e32 v94, v95, v94
	v_add_f32_e32 v98, v94, v98
	v_or_b32_e32 v96, 32, v136
	ds_bpermute_b32 v99, v124, v98
	v_ashrrev_i32_e32 v97, 31, v96
	v_lshlrev_b64 v[96:97], 13, v[96:97]
	v_lshl_add_u64 v[96:97], s[28:29], 0, v[96:97]
	v_lshl_add_u64 v[96:97], v[140:141], 1, v[96:97]
	v_cvt_pk_bf16_f32 v94, v88, v89
	v_cvt_pk_bf16_f32 v95, v90, v91
	global_store_dwordx4 v[96:97], v[92:95], off nt
	v_cvt_pk_bf16_f32 v88, v84, v85
	s_waitcnt lgkmcnt(0)
	v_add_f32_e32 v84, v98, v99
	ds_bpermute_b32 v85, v116, v84
	v_cvt_pk_bf16_f32 v89, v86, v87
	v_cvt_pk_bf16_f32 v90, v80, v81
	v_cvt_pk_bf16_f32 v91, v82, v83
	global_store_dwordx4 v[96:97], v[88:91], off offset:256 nt
	s_and_saveexec_b64 s[4:5], vcc
	s_cbranch_execz .LBB0_944
	s_add_u32 s14, s68, s12
	s_addc_u32 s15, s69, s13
	s_waitcnt lgkmcnt(0)
	v_add_f32_e32 v82, v84, v85
	v_lshl_add_u64 v[80:81], v[136:137], 2, s[14:15]
	global_store_dword v[80:81], v82, off offset:128
; __device__ __forceinline__ u32x4 pack8(const f32x4 v0, const f32x4 v1) { u32x4 w; w.x = cvt_pk_bf16(v0[0], v0[1]); w.y = cvt_pk_bf16(v0[2], v0[3]); w.z = cvt_pk_bf16(v1[0], v1[1]); w.w = cvt_pk_bf16(v1[2], v1[3]); return w; }
;     __device__ __forceinline__ void operator()(AccT& acc, const Unit& u, int wr, int wc, int fr, int fq) const {
;         const int row0 = u.pm * 256 + wr * 64 + fr, col0 = u.pn * 256 + wc * 32 + 8 * fq;
; #pragma unroll
;         for (int ai = 0; ai < 2; ++ai)
; #pragma unroll
;             for (int m = 0; m < 4; ++m) { const int row = row0 + ai * 128 + m * 16; bf16_t* rowp = O + (size_t)row * DM + col0; float ss = 0.f;
; #pragma unroll
;                 for (int bj = 0; bj < 2; ++bj) { const f32x4 v0 = acc[ai][bj][m][0], v1 = acc[ai][bj][m][1];
;                     ss += (v0[0] * v0[0] + v0[1] * v0[1]) + (v0[2] * v0[2] + v0[3] * v0[3]) + (v1[0] * v1[0] + v1[1] * v1[1]) + (v1[2] * v1[2] + v1[3] * v1[3]);
;                     *(u32x4*)(rowp + bj * 128) = pack8(v0, v1); }
;                 ss += __shfl_xor(ss, 16); ss += __shfl_xor(ss, 32);
;                 if (fq == 0) SSQ[(size_t)(u.pn * 4 + wc) * MT + row] = ss; }
.LBB0_944:
	s_or_b64 exec, exec, s[4:5]
	v_mul_f32_e32 v82, v77, v77
	v_mul_f32_e32 v83, v79, v79
	v_fmac_f32_e32 v82, v76, v76
	v_fmac_f32_e32 v83, v78, v78
	v_cvt_pk_bf16_f32 v76, v76, v77
	v_cvt_pk_bf16_f32 v77, v78, v79
	v_mul_f32_e32 v78, v69, v69
	v_mul_f32_e32 v79, v71, v71
	v_fmac_f32_e32 v78, v68, v68
	v_fmac_f32_e32 v79, v70, v70
	v_add_f32_e32 v82, v82, v83
	v_mul_f32_e32 v83, v73, v73
	v_add_f32_e32 v78, v78, v79
	v_mul_f32_e32 v79, v65, v65
	v_fmac_f32_e32 v83, v72, v72
	v_fmac_f32_e32 v79, v64, v64
	v_add_f32_e32 v82, v83, v82
	v_mul_f32_e32 v83, v75, v75
	v_add_f32_e32 v78, v79, v78
	v_mul_f32_e32 v79, v67, v67
	v_fmac_f32_e32 v83, v74, v74
	v_fmac_f32_e32 v79, v66, v66
	v_add_f32_e32 v82, v83, v82
	v_add_f32_e32 v78, v79, v78
	v_add_f32_e32 v82, v78, v82
	v_or_b32_e32 v80, 48, v136
	ds_bpermute_b32 v83, v124, v82
	v_ashrrev_i32_e32 v81, 31, v80
	v_lshlrev_b64 v[80:81], 13, v[80:81]
	v_lshl_add_u64 v[80:81], s[28:29], 0, v[80:81]
	v_lshl_add_u64 v[80:81], v[140:141], 1, v[80:81]
	v_cvt_pk_bf16_f32 v78, v72, v73
	v_cvt_pk_bf16_f32 v79, v74, v75
	global_store_dwordx4 v[80:81], v[76:79], off nt
	v_cvt_pk_bf16_f32 v72, v68, v69
	s_waitcnt lgkmcnt(0)
	v_add_f32_e32 v68, v82, v83
	ds_bpermute_b32 v69, v116, v68
	v_cvt_pk_bf16_f32 v73, v70, v71
	v_cvt_pk_bf16_f32 v74, v64, v65
	v_cvt_pk_bf16_f32 v75, v66, v67
	global_store_dwordx4 v[80:81], v[72:75], off offset:256 nt
	s_and_saveexec_b64 s[4:5], vcc
	s_cbranch_execz .LBB0_946
	s_add_u32 s14, s68, s12
	s_addc_u32 s15, s69, s13
	s_waitcnt lgkmcnt(0)
	v_add_f32_e32 v66, v68, v69
	v_lshl_add_u64 v[64:65], v[136:137], 2, s[14:15]
	global_store_dword v[64:65], v66, off offset:192
.LBB0_946:
	s_or_b64 exec, exec, s[4:5]
	v_mul_f32_e32 v66, v61, v61
	v_mul_f32_e32 v67, v63, v63
	v_fmac_f32_e32 v66, v60, v60
	v_fmac_f32_e32 v67, v62, v62
	v_add_f32_e32 v66, v66, v67
	v_mul_f32_e32 v67, v57, v57
	v_fmac_f32_e32 v67, v56, v56
	v_cvt_pk_bf16_f32 v60, v60, v61
	v_cvt_pk_bf16_f32 v61, v62, v63
	v_cvt_pk_bf16_f32 v62, v56, v57
	v_mul_f32_e32 v56, v53, v53
	v_mul_f32_e32 v57, v55, v55
	v_fmac_f32_e32 v56, v52, v52
	v_fmac_f32_e32 v57, v54, v54
	v_add_f32_e32 v56, v56, v57
	v_mul_f32_e32 v57, v49, v49
	v_fmac_f32_e32 v57, v48, v48
	v_add_f32_e32 v66, v67, v66
	v_mul_f32_e32 v67, v59, v59
	v_add_f32_e32 v56, v57, v56
	v_mul_f32_e32 v57, v51, v51
	v_fmac_f32_e32 v67, v58, v58
	v_fmac_f32_e32 v57, v50, v50
	v_add_f32_e32 v66, v67, v66
	v_add_f32_e32 v56, v57, v56
	v_cvt_pk_bf16_f32 v63, v58, v59
	v_add_f32_e32 v58, v56, v66
	ds_bpermute_b32 v59, v124, v58
	v_add_co_u32_e64 v56, s[4:5], s33, v138
	v_lshl_add_u64 v[64:65], v[138:139], 0, s[36:37]
	s_nop 0
	v_addc_co_u32_e64 v57, s[4:5], 0, v139, s[4:5]
	global_store_dwordx4 v[56:57], v[60:63], off nt
	v_cvt_pk_bf16_f32 v56, v52, v53
	s_waitcnt lgkmcnt(0)
	v_add_f32_e32 v52, v58, v59
	ds_bpermute_b32 v53, v116, v52
	v_cvt_pk_bf16_f32 v57, v54, v55
	v_cvt_pk_bf16_f32 v58, v48, v49
	v_cvt_pk_bf16_f32 v59, v50, v51
	global_store_dwordx4 v[64:65], v[56:59], off offset:256 nt
	s_and_saveexec_b64 s[4:5], vcc
	s_cbranch_execz .LBB0_948
	s_add_u32 s14, s68, s12
	s_addc_u32 s15, s69, s13
	s_waitcnt lgkmcnt(0)
	v_add_f32_e32 v50, v52, v53
	v_lshl_add_u64 v[48:49], v[136:137], 2, s[14:15]
	global_store_dword v[48:49], v50, off offset:512
; __device__ __forceinline__ u32x4 pack8(const f32x4 v0, const f32x4 v1) { u32x4 w; w.x = cvt_pk_bf16(v0[0], v0[1]); w.y = cvt_pk_bf16(v0[2], v0[3]); w.z = cvt_pk_bf16(v1[0], v1[1]); w.w = cvt_pk_bf16(v1[2], v1[3]); return w; }
;     __device__ __forceinline__ void operator()(AccT& acc, const Unit& u, int wr, int wc, int fr, int fq) const {
;         const int row0 = u.pm * 256 + wr * 64 + fr, col0 = u.pn * 256 + wc * 32 + 8 * fq;
; #pragma unroll
;         for (int ai = 0; ai < 2; ++ai)
; #pragma unroll
;             for (int m = 0; m < 4; ++m) { const int row = row0 + ai * 128 + m * 16; bf16_t* rowp = O + (size_t)row * DM + col0; float ss = 0.f;
; #pragma unroll
;                 for (int bj = 0; bj < 2; ++bj) { const f32x4 v0 = acc[ai][bj][m][0], v1 = acc[ai][bj][m][1];
;                     ss += (v0[0] * v0[0] + v0[1] * v0[1]) + (v0[2] * v0[2] + v0[3] * v0[3]) + (v1[0] * v1[0] + v1[1] * v1[1]) + (v1[2] * v1[2] + v1[3] * v1[3]);
;                     *(u32x4*)(rowp + bj * 128) = pack8(v0, v1); }
;                 ss += __shfl_xor(ss, 16); ss += __shfl_xor(ss, 32);
;                 if (fq == 0) SSQ[(size_t)(u.pn * 4 + wc) * MT + row] = ss; }
.LBB0_948:
	s_or_b64 exec, exec, s[4:5]
	v_mul_f32_e32 v50, v45, v45
	v_mul_f32_e32 v51, v47, v47
	v_fmac_f32_e32 v50, v44, v44
	v_fmac_f32_e32 v51, v46, v46
	v_add_f32_e32 v50, v50, v51
	v_mul_f32_e32 v51, v41, v41
	v_fmac_f32_e32 v51, v40, v40
	v_cvt_pk_bf16_f32 v44, v44, v45
	v_cvt_pk_bf16_f32 v45, v46, v47
	v_cvt_pk_bf16_f32 v46, v40, v41
	v_mul_f32_e32 v40, v37, v37
	v_mul_f32_e32 v41, v39, v39
	v_fmac_f32_e32 v40, v36, v36
	v_fmac_f32_e32 v41, v38, v38
	v_add_f32_e32 v40, v40, v41
	v_mul_f32_e32 v41, v33, v33
	v_fmac_f32_e32 v41, v32, v32
	v_add_f32_e32 v50, v51, v50
	v_mul_f32_e32 v51, v43, v43
	v_add_f32_e32 v40, v41, v40
	v_mul_f32_e32 v41, v35, v35
	v_fmac_f32_e32 v51, v42, v42
	v_fmac_f32_e32 v41, v34, v34
	v_add_f32_e32 v50, v51, v50
	v_add_f32_e32 v40, v41, v40
	v_cvt_pk_bf16_f32 v47, v42, v43
	v_add_f32_e32 v42, v40, v50
	ds_bpermute_b32 v43, v124, v42
	v_add_co_u32_e64 v40, s[4:5], s62, v138
	v_lshl_add_u64 v[48:49], v[138:139], 0, s[38:39]
	s_nop 0
	v_addc_co_u32_e64 v41, s[4:5], 0, v139, s[4:5]
	global_store_dwordx4 v[40:41], v[44:47], off nt
	v_cvt_pk_bf16_f32 v40, v36, v37
	s_waitcnt lgkmcnt(0)
	v_add_f32_e32 v36, v42, v43
	ds_bpermute_b32 v37, v116, v36
	v_cvt_pk_bf16_f32 v41, v38, v39
	v_cvt_pk_bf16_f32 v42, v32, v33
	v_cvt_pk_bf16_f32 v43, v34, v35
	global_store_dwordx4 v[48:49], v[40:43], off offset:256 nt
	s_and_saveexec_b64 s[4:5], vcc
	s_cbranch_execz .LBB0_950
	s_add_u32 s14, s68, s12
	s_addc_u32 s15, s69, s13
	s_waitcnt lgkmcnt(0)
	v_add_f32_e32 v34, v36, v37
	v_lshl_add_u64 v[32:33], v[136:137], 2, s[14:15]
	global_store_dword v[32:33], v34, off offset:576
.LBB0_950:
	s_or_b64 exec, exec, s[4:5]
	v_mul_f32_e32 v34, v29, v29
	v_mul_f32_e32 v35, v31, v31
	v_fmac_f32_e32 v34, v28, v28
	v_fmac_f32_e32 v35, v30, v30
	v_add_f32_e32 v34, v34, v35
	v_mul_f32_e32 v35, v25, v25
	v_fmac_f32_e32 v35, v24, v24
	v_cvt_pk_bf16_f32 v28, v28, v29
	v_cvt_pk_bf16_f32 v29, v30, v31
	v_cvt_pk_bf16_f32 v30, v24, v25
	v_mul_f32_e32 v24, v21, v21
	v_mul_f32_e32 v25, v23, v23
	v_fmac_f32_e32 v24, v20, v20
	v_fmac_f32_e32 v25, v22, v22
	v_add_f32_e32 v24, v24, v25
	v_mul_f32_e32 v25, v17, v17
	v_fmac_f32_e32 v25, v16, v16
	v_add_f32_e32 v34, v35, v34
	v_mul_f32_e32 v35, v27, v27
	v_add_f32_e32 v24, v25, v24
	v_mul_f32_e32 v25, v19, v19
	v_fmac_f32_e32 v35, v26, v26
	v_fmac_f32_e32 v25, v18, v18
	v_add_f32_e32 v34, v35, v34
	v_add_f32_e32 v24, v25, v24
	v_cvt_pk_bf16_f32 v31, v26, v27
	v_add_f32_e32 v26, v24, v34
	ds_bpermute_b32 v27, v124, v26
	v_add_co_u32_e64 v24, s[4:5], s63, v138
	v_lshl_add_u64 v[32:33], v[138:139], 0, s[40:41]
	s_nop 0
	v_addc_co_u32_e64 v25, s[4:5], 0, v139, s[4:5]
	global_store_dwordx4 v[24:25], v[28:31], off nt
	v_cvt_pk_bf16_f32 v24, v20, v21
	s_waitcnt lgkmcnt(0)
	v_add_f32_e32 v20, v26, v27
	ds_bpermute_b32 v21, v116, v20
	v_cvt_pk_bf16_f32 v25, v22, v23
	v_cvt_pk_bf16_f32 v26, v16, v17
	v_cvt_pk_bf16_f32 v27, v18, v19
	global_store_dwordx4 v[32:33], v[24:27], off offset:256 nt
	s_and_saveexec_b64 s[4:5], vcc
	s_cbranch_execz .LBB0_952
	s_add_u32 s14, s68, s12
	s_addc_u32 s15, s69, s13
	s_waitcnt lgkmcnt(0)
	v_add_f32_e32 v18, v20, v21
	v_lshl_add_u64 v[16:17], v[136:137], 2, s[14:15]
	global_store_dword v[16:17], v18, off offset:640
.LBB0_952:
	s_or_b64 exec, exec, s[4:5]
	v_mul_f32_e32 v18, v13, v13
	v_mul_f32_e32 v19, v15, v15
	v_fmac_f32_e32 v18, v12, v12
	v_fmac_f32_e32 v19, v14, v14
	v_add_f32_e32 v18, v18, v19
	v_mul_f32_e32 v19, v9, v9
	v_fmac_f32_e32 v19, v8, v8
	v_cvt_pk_bf16_f32 v12, v12, v13
	v_cvt_pk_bf16_f32 v13, v14, v15
	v_cvt_pk_bf16_f32 v14, v8, v9
	v_mul_f32_e32 v8, v5, v5
	v_mul_f32_e32 v9, v7, v7
	v_fmac_f32_e32 v8, v4, v4
	v_fmac_f32_e32 v9, v6, v6
	v_add_f32_e32 v8, v8, v9
	v_mul_f32_e32 v9, v1, v1
	v_fmac_f32_e32 v9, v0, v0
	v_add_f32_e32 v18, v19, v18
	v_mul_f32_e32 v19, v11, v11
	v_add_f32_e32 v8, v9, v8
	v_mul_f32_e32 v9, v3, v3
	v_fmac_f32_e32 v19, v10, v10
	v_fmac_f32_e32 v9, v2, v2
	v_add_f32_e32 v18, v19, v18
	v_add_f32_e32 v8, v9, v8
	v_cvt_pk_bf16_f32 v15, v10, v11
	v_add_f32_e32 v10, v8, v18
	ds_bpermute_b32 v11, v124, v10
	v_add_co_u32_e64 v8, s[4:5], s84, v138
	v_lshl_add_u64 v[16:17], v[138:139], 0, s[42:43]
	s_nop 0
	v_addc_co_u32_e64 v9, s[4:5], 0, v139, s[4:5]
	global_store_dwordx4 v[8:9], v[12:15], off nt
	v_cvt_pk_bf16_f32 v8, v4, v5
	s_waitcnt lgkmcnt(0)
	v_add_f32_e32 v4, v10, v11
	ds_bpermute_b32 v5, v116, v4
	v_cvt_pk_bf16_f32 v9, v6, v7
	v_cvt_pk_bf16_f32 v10, v0, v1
	v_cvt_pk_bf16_f32 v11, v2, v3
	global_store_dwordx4 v[16:17], v[8:11], off offset:256 nt
	s_and_saveexec_b64 s[4:5], vcc
	s_cbranch_execz .LBB0_954
	s_add_u32 s12, s68, s12
	s_addc_u32 s13, s69, s13
	s_waitcnt lgkmcnt(0)
	v_add_f32_e32 v2, v4, v5
	v_lshl_add_u64 v[0:1], v[136:137], 2, s[12:13]
	global_store_dword v[0:1], v2, off offset:704

; __device__ __forceinline__ float bf_lo(unsigned w) { return __uint_as_float(w << 16); }
; __device__ __forceinline__ float bf_hi(unsigned w) { return __uint_as_float(w & 0xffff0000u); }
; __device__ __forceinline__ void phase_final(const Params& p, int gw, int NGW, int lane) {
;     ...
;     for (int row = gw; row < MT; row += NGW) {
;         const float r = rsqrtf(wave_sum(SSQ[(size_t)lane * MT + row]) * (1.f / DM) + EPSN);
;         const u32x2* dr = (const u32x2*)(DN + (size_t)row * DM) + lane; const u32x2* hr = (const u32x2*)(H1 + (size_t)row * DM) + lane; f32x4* o = (f32x4*)(p.out + (size_t)row * DM) + lane;
;         const f32x4* gp = g + lane;
;         asm volatile("" : "+v"(gp), "+v"(dr), "+v"(hr), "+v"(o));
; #pragma unroll 8
;         for (int j = 0; j < 16; ++j) { const u32x2 dw = dr[64 * j]; const f32x4 dn = {bf_lo(dw.x), bf_hi(dw.x), bf_lo(dw.y), bf_hi(dw.y)}; const u32x2 hw = hr[64 * j]; const f32x4 hh = {bf_lo(hw.x), bf_hi(hw.x), bf_lo(hw.y), bf_hi(hw.y)}; o[64 * j] = hh + dn * r * gp[64 * j]; }
.Lfin_row:
	s_ashr_i32 s35, s34, 31
	s_lshl_b64 s[2:3], s[34:35], 13
	s_lshl_b64 s[6:7], s[34:35], 14
	s_add_i32 s10, s34, s60
	s_min_i32 s10, s10, 0x1fff
	s_ashr_i32 s11, s10, 31
	v_lshl_add_u64 v[10:11], s[10:11], 2, v[0:1]
	v_lshl_add_u64 v[12:13], v[2:3], 0, s[2:3]
	v_lshl_add_u64 v[14:15], v[4:5], 0, s[2:3]
	v_lshl_add_u64 v[16:17], v[8:9], 0, s[6:7]
	global_load_dword v33, v[10:11], off
	v_lshl_add_u64 v[22:23], v[16:17], 0, s[8:9]
	global_load_dwordx2 v[64:65], v[12:13], off offset:-4096 nt
	global_load_dwordx2 v[96:97], v[14:15], off offset:-4096 nt
	global_load_dwordx4 v[128:131], v[36:37], off offset:-4096
	global_load_dwordx2 v[66:67], v[12:13], off offset:-3584 nt
	global_load_dwordx2 v[98:99], v[14:15], off offset:-3584 nt
	global_load_dwordx4 v[132:135], v[36:37], off offset:-3072
	global_load_dwordx2 v[68:69], v[12:13], off offset:-3072 nt
	global_load_dwordx2 v[100:101], v[14:15], off offset:-3072 nt
	global_load_dwordx4 v[136:139], v[36:37], off offset:-2048
	global_load_dwordx2 v[70:71], v[12:13], off offset:-2560 nt
	global_load_dwordx2 v[102:103], v[14:15], off offset:-2560 nt
	global_load_dwordx4 v[140:143], v[36:37], off offset:-1024
	global_load_dwordx2 v[72:73], v[12:13], off offset:-2048 nt
	global_load_dwordx2 v[104:105], v[14:15], off offset:-2048 nt
	global_load_dwordx4 v[144:147], v[36:37], off
	global_load_dwordx2 v[74:75], v[12:13], off offset:-1536 nt
	global_load_dwordx2 v[106:107], v[14:15], off offset:-1536 nt
	global_load_dwordx4 v[148:151], v[36:37], off offset:1024
	global_load_dwordx2 v[76:77], v[12:13], off offset:-1024 nt
	global_load_dwordx2 v[108:109], v[14:15], off offset:-1024 nt
	global_load_dwordx4 v[152:155], v[36:37], off offset:2048
	global_load_dwordx2 v[78:79], v[12:13], off offset:-512 nt
	global_load_dwordx2 v[110:111], v[14:15], off offset:-512 nt
	global_load_dwordx4 v[156:159], v[36:37], off offset:3072
	global_load_dwordx2 v[80:81], v[12:13], off nt
	global_load_dwordx2 v[112:113], v[14:15], off nt
	global_load_dwordx4 v[160:163], v[38:39], off offset:-4096
	global_load_dwordx2 v[82:83], v[12:13], off offset:512 nt
	global_load_dwordx2 v[114:115], v[14:15], off offset:512 nt
	global_load_dwordx4 v[164:167], v[38:39], off offset:-3072
	global_load_dwordx2 v[84:85], v[12:13], off offset:1024 nt
	global_load_dwordx2 v[116:117], v[14:15], off offset:1024 nt
	global_load_dwordx4 v[168:171], v[38:39], off offset:-2048
	global_load_dwordx2 v[86:87], v[12:13], off offset:1536 nt
	global_load_dwordx2 v[118:119], v[14:15], off offset:1536 nt
	global_load_dwordx4 v[172:175], v[38:39], off offset:-1024
	global_load_dwordx2 v[88:89], v[12:13], off offset:2048 nt
	global_load_dwordx2 v[120:121], v[14:15], off offset:2048 nt
	global_load_dwordx4 v[176:179], v[38:39], off
	global_load_dwordx2 v[90:91], v[12:13], off offset:2560 nt
	global_load_dwordx2 v[122:123], v[14:15], off offset:2560 nt
	global_load_dwordx4 v[180:183], v[38:39], off offset:1024
	global_load_dwordx2 v[92:93], v[12:13], off offset:3072 nt
	global_load_dwordx2 v[124:125], v[14:15], off offset:3072 nt
	global_load_dwordx4 v[184:187], v[38:39], off offset:2048
	global_load_dwordx2 v[94:95], v[12:13], off offset:3584 nt
	global_load_dwordx2 v[126:127], v[14:15], off offset:3584 nt
	global_load_dwordx4 v[188:191], v[38:39], off offset:3072
	s_waitcnt vmcnt(45)
	v_lshlrev_b32_e32 v40, 16, v64
	v_and_b32_e32 v41, 0xffff0000, v64
	v_lshlrev_b32_e32 v42, 16, v65
	v_and_b32_e32 v43, 0xffff0000, v65
	v_lshlrev_b32_e32 v44, 16, v96
	v_and_b32_e32 v45, 0xffff0000, v96
	v_lshlrev_b32_e32 v46, 16, v97
	v_and_b32_e32 v47, 0xffff0000, v97
	v_pk_mul_f32 v[40:41], v[18:19], v[40:41]
	v_pk_mul_f32 v[42:43], v[18:19], v[42:43]
	v_pk_fma_f32 v[128:129], v[128:129], v[40:41], v[44:45]
	v_pk_fma_f32 v[130:131], v[130:131], v[42:43], v[46:47]
	global_store_dwordx4 v[16:17], v[128:131], off offset:-4096 nt
	s_waitcnt vmcnt(43)
	v_lshlrev_b32_e32 v48, 16, v66
	v_and_b32_e32 v49, 0xffff0000, v66
	v_lshlrev_b32_e32 v50, 16, v67
	v_and_b32_e32 v51, 0xffff0000, v67
	v_lshlrev_b32_e32 v52, 16, v98
	v_and_b32_e32 v53, 0xffff0000, v98
	v_lshlrev_b32_e32 v54, 16, v99
	v_and_b32_e32 v55, 0xffff0000, v99
	v_pk_mul_f32 v[48:49], v[18:19], v[48:49]
	v_pk_mul_f32 v[50:51], v[18:19], v[50:51]
	v_pk_fma_f32 v[132:133], v[132:133], v[48:49], v[52:53]
	v_pk_fma_f32 v[134:135], v[134:135], v[50:51], v[54:55]
	global_store_dwordx4 v[16:17], v[132:135], off offset:-3072 nt
	s_waitcnt vmcnt(41)
	v_lshlrev_b32_e32 v40, 16, v68
	v_and_b32_e32 v41, 0xffff0000, v68
	v_lshlrev_b32_e32 v42, 16, v69
	v_and_b32_e32 v43, 0xffff0000, v69
	v_lshlrev_b32_e32 v44, 16, v100
	v_and_b32_e32 v45, 0xffff0000, v100
	v_lshlrev_b32_e32 v46, 16, v101
	v_and_b32_e32 v47, 0xffff0000, v101
	v_pk_mul_f32 v[40:41], v[18:19], v[40:41]
	v_pk_mul_f32 v[42:43], v[18:19], v[42:43]
	v_pk_fma_f32 v[136:137], v[136:137], v[40:41], v[44:45]
	v_pk_fma_f32 v[138:139], v[138:139], v[42:43], v[46:47]
	global_store_dwordx4 v[16:17], v[136:139], off offset:-2048 nt
	s_waitcnt vmcnt(39)
	v_lshlrev_b32_e32 v48, 16, v70
	v_and_b32_e32 v49, 0xffff0000, v70
	v_lshlrev_b32_e32 v50, 16, v71
	v_and_b32_e32 v51, 0xffff0000, v71
	v_lshlrev_b32_e32 v52, 16, v102
	v_and_b32_e32 v53, 0xffff0000, v102
	v_lshlrev_b32_e32 v54, 16, v103
	v_and_b32_e32 v55, 0xffff0000, v103
	v_pk_mul_f32 v[48:49], v[18:19], v[48:49]
	v_pk_mul_f32 v[50:51], v[18:19], v[50:51]
	v_pk_fma_f32 v[140:141], v[140:141], v[48:49], v[52:53]
	v_pk_fma_f32 v[142:143], v[142:143], v[50:51], v[54:55]
	global_store_dwordx4 v[16:17], v[140:143], off offset:-1024 nt
	s_waitcnt vmcnt(37)
; __device__ __forceinline__ float bf_lo(unsigned w) { return __uint_as_float(w << 16); }
; __device__ __forceinline__ float bf_hi(unsigned w) { return __uint_as_float(w & 0xffff0000u); }
; __device__ __forceinline__ void phase_final(const Params& p, int gw, int NGW, int lane) {
;     ...
;         const u32x2* dr = (const u32x2*)(DN + (size_t)row * DM) + lane; const u32x2* hr = (const u32x2*)(H1 + (size_t)row * DM) + lane; f32x4* o = (f32x4*)(p.out + (size_t)row * DM) + lane;
;         const f32x4* gp = g + lane;
;         asm volatile("" : "+v"(gp), "+v"(dr), "+v"(hr), "+v"(o));
; #pragma unroll 8
;         for (int j = 0; j < 16; ++j) { const u32x2 dw = dr[64 * j]; const f32x4 dn = {bf_lo(dw.x), bf_hi(dw.x), bf_lo(dw.y), bf_hi(dw.y)}; const u32x2 hw = hr[64 * j]; const f32x4 hh = {bf_lo(hw.x), bf_hi(hw.x), bf_lo(hw.y), bf_hi(hw.y)}; o[64 * j] = hh + dn * r * gp[64 * j]; }
	v_lshlrev_b32_e32 v40, 16, v72
	v_and_b32_e32 v41, 0xffff0000, v72
	v_lshlrev_b32_e32 v42, 16, v73
	v_and_b32_e32 v43, 0xffff0000, v73
	v_lshlrev_b32_e32 v44, 16, v104
	v_and_b32_e32 v45, 0xffff0000, v104
	v_lshlrev_b32_e32 v46, 16, v105
	v_and_b32_e32 v47, 0xffff0000, v105
	v_pk_mul_f32 v[40:41], v[18:19], v[40:41]
	v_pk_mul_f32 v[42:43], v[18:19], v[42:43]
	v_pk_fma_f32 v[144:145], v[144:145], v[40:41], v[44:45]
	v_pk_fma_f32 v[146:147], v[146:147], v[42:43], v[46:47]
	global_store_dwordx4 v[16:17], v[144:147], off nt
	s_waitcnt vmcnt(35)
	v_lshlrev_b32_e32 v48, 16, v74
	v_and_b32_e32 v49, 0xffff0000, v74
	v_lshlrev_b32_e32 v50, 16, v75
	v_and_b32_e32 v51, 0xffff0000, v75
	v_lshlrev_b32_e32 v52, 16, v106
	v_and_b32_e32 v53, 0xffff0000, v106
	v_lshlrev_b32_e32 v54, 16, v107
	v_and_b32_e32 v55, 0xffff0000, v107
	v_pk_mul_f32 v[48:49], v[18:19], v[48:49]
	v_pk_mul_f32 v[50:51], v[18:19], v[50:51]
	v_pk_fma_f32 v[148:149], v[148:149], v[48:49], v[52:53]
	v_pk_fma_f32 v[150:151], v[150:151], v[50:51], v[54:55]
	global_store_dwordx4 v[16:17], v[148:151], off offset:1024 nt
	s_waitcnt vmcnt(33)
	v_lshlrev_b32_e32 v40, 16, v76
	v_and_b32_e32 v41, 0xffff0000, v76
	v_lshlrev_b32_e32 v42, 16, v77
	v_and_b32_e32 v43, 0xffff0000, v77
	v_lshlrev_b32_e32 v44, 16, v108
	v_and_b32_e32 v45, 0xffff0000, v108
	v_lshlrev_b32_e32 v46, 16, v109
	v_and_b32_e32 v47, 0xffff0000, v109
	v_pk_mul_f32 v[40:41], v[18:19], v[40:41]
	v_pk_mul_f32 v[42:43], v[18:19], v[42:43]
	v_pk_fma_f32 v[152:153], v[152:153], v[40:41], v[44:45]
	v_pk_fma_f32 v[154:155], v[154:155], v[42:43], v[46:47]
	global_store_dwordx4 v[16:17], v[152:155], off offset:2048 nt
	s_waitcnt vmcnt(31)
	v_lshlrev_b32_e32 v48, 16, v78
	v_and_b32_e32 v49, 0xffff0000, v78
	v_lshlrev_b32_e32 v50, 16, v79
	v_and_b32_e32 v51, 0xffff0000, v79
	v_lshlrev_b32_e32 v52, 16, v110
	v_and_b32_e32 v53, 0xffff0000, v110
	v_lshlrev_b32_e32 v54, 16, v111
	v_and_b32_e32 v55, 0xffff0000, v111
	v_pk_mul_f32 v[48:49], v[18:19], v[48:49]
	v_pk_mul_f32 v[50:51], v[18:19], v[50:51]
	v_pk_fma_f32 v[156:157], v[156:157], v[48:49], v[52:53]
	v_pk_fma_f32 v[158:159], v[158:159], v[50:51], v[54:55]
	global_store_dwordx4 v[16:17], v[156:159], off offset:3072 nt
	s_waitcnt vmcnt(29)
	v_lshlrev_b32_e32 v40, 16, v80
	v_and_b32_e32 v41, 0xffff0000, v80
	v_lshlrev_b32_e32 v42, 16, v81
	v_and_b32_e32 v43, 0xffff0000, v81
	v_lshlrev_b32_e32 v44, 16, v112
	v_and_b32_e32 v45, 0xffff0000, v112
	v_lshlrev_b32_e32 v46, 16, v113
	v_and_b32_e32 v47, 0xffff0000, v113
	v_pk_mul_f32 v[40:41], v[18:19], v[40:41]
	v_pk_mul_f32 v[42:43], v[18:19], v[42:43]
	v_pk_fma_f32 v[160:161], v[160:161], v[40:41], v[44:45]
	v_pk_fma_f32 v[162:163], v[162:163], v[42:43], v[46:47]
	global_store_dwordx4 v[22:23], v[160:163], off offset:-4096 nt
	s_waitcnt vmcnt(27)
	v_lshlrev_b32_e32 v48, 16, v82
	v_and_b32_e32 v49, 0xffff0000, v82
	v_lshlrev_b32_e32 v50, 16, v83
	v_and_b32_e32 v51, 0xffff0000, v83
	v_lshlrev_b32_e32 v52, 16, v114
	v_and_b32_e32 v53, 0xffff0000, v114
	v_lshlrev_b32_e32 v54, 16, v115
	v_and_b32_e32 v55, 0xffff0000, v115
	v_pk_mul_f32 v[48:49], v[18:19], v[48:49]
	v_pk_mul_f32 v[50:51], v[18:19], v[50:51]
	v_pk_fma_f32 v[164:165], v[164:165], v[48:49], v[52:53]
	v_pk_fma_f32 v[166:167], v[166:167], v[50:51], v[54:55]
	global_store_dwordx4 v[22:23], v[164:167], off offset:-3072 nt
	s_waitcnt vmcnt(25)
	v_lshlrev_b32_e32 v40, 16, v84
	v_and_b32_e32 v41, 0xffff0000, v84
	v_lshlrev_b32_e32 v42, 16, v85
	v_and_b32_e32 v43, 0xffff0000, v85
	v_lshlrev_b32_e32 v44, 16, v116
	v_and_b32_e32 v45, 0xffff0000, v116
	v_lshlrev_b32_e32 v46, 16, v117
	v_and_b32_e32 v47, 0xffff0000, v117
	v_pk_mul_f32 v[40:41], v[18:19], v[40:41]
	v_pk_mul_f32 v[42:43], v[18:19], v[42:43]
	v_pk_fma_f32 v[168:169], v[168:169], v[40:41], v[44:45]
	v_pk_fma_f32 v[170:171], v[170:171], v[42:43], v[46:47]
	global_store_dwordx4 v[22:23], v[168:171], off offset:-2048 nt
	s_waitcnt vmcnt(23)
; __device__ __forceinline__ float bf_lo(unsigned w) { return __uint_as_float(w << 16); }
; __device__ __forceinline__ float bf_hi(unsigned w) { return __uint_as_float(w & 0xffff0000u); }
; __device__ __forceinline__ float wave_sum(float v) {
; #pragma unroll
;     for (int o = 1; o < 64; o <<= 1) v += __shfl_xor(v, o);
;     return v;
; __device__ __forceinline__ void phase_final(const Params& p, int gw, int NGW, int lane) {
;     ...
;         const float r = rsqrtf(wave_sum(SSQ[(size_t)lane * MT + row]) * (1.f / DM) + EPSN);
;         const u32x2* dr = (const u32x2*)(DN + (size_t)row * DM) + lane; const u32x2* hr = (const u32x2*)(H1 + (size_t)row * DM) + lane; f32x4* o = (f32x4*)(p.out + (size_t)row * DM) + lane;
;         const f32x4* gp = g + lane;
;         asm volatile("" : "+v"(gp), "+v"(dr), "+v"(hr), "+v"(o));
; #pragma unroll 8
;         for (int j = 0; j < 16; ++j) { const u32x2 dw = dr[64 * j]; const f32x4 dn = {bf_lo(dw.x), bf_hi(dw.x), bf_lo(dw.y), bf_hi(dw.y)}; const u32x2 hw = hr[64 * j]; const f32x4 hh = {bf_lo(hw.x), bf_hi(hw.x), bf_lo(hw.y), bf_hi(hw.y)}; o[64 * j] = hh + dn * r * gp[64 * j]; }
	v_lshlrev_b32_e32 v48, 16, v86
	v_and_b32_e32 v49, 0xffff0000, v86
	v_lshlrev_b32_e32 v50, 16, v87
	v_and_b32_e32 v51, 0xffff0000, v87
	v_lshlrev_b32_e32 v52, 16, v118
	v_and_b32_e32 v53, 0xffff0000, v118
	v_lshlrev_b32_e32 v54, 16, v119
	v_and_b32_e32 v55, 0xffff0000, v119
	v_pk_mul_f32 v[48:49], v[18:19], v[48:49]
	v_pk_mul_f32 v[50:51], v[18:19], v[50:51]
	v_pk_fma_f32 v[172:173], v[172:173], v[48:49], v[52:53]
	v_pk_fma_f32 v[174:175], v[174:175], v[50:51], v[54:55]
	global_store_dwordx4 v[22:23], v[172:175], off offset:-1024 nt
	s_waitcnt vmcnt(21)
	v_lshlrev_b32_e32 v40, 16, v88
	v_and_b32_e32 v41, 0xffff0000, v88
	v_lshlrev_b32_e32 v42, 16, v89
	v_and_b32_e32 v43, 0xffff0000, v89
	v_lshlrev_b32_e32 v44, 16, v120
	v_and_b32_e32 v45, 0xffff0000, v120
	v_lshlrev_b32_e32 v46, 16, v121
	v_and_b32_e32 v47, 0xffff0000, v121
	v_pk_mul_f32 v[40:41], v[18:19], v[40:41]
	v_pk_mul_f32 v[42:43], v[18:19], v[42:43]
	v_pk_fma_f32 v[176:177], v[176:177], v[40:41], v[44:45]
	v_pk_fma_f32 v[178:179], v[178:179], v[42:43], v[46:47]
	global_store_dwordx4 v[22:23], v[176:179], off nt
	s_waitcnt vmcnt(19)
	v_lshlrev_b32_e32 v48, 16, v90
	v_and_b32_e32 v49, 0xffff0000, v90
	v_lshlrev_b32_e32 v50, 16, v91
	v_and_b32_e32 v51, 0xffff0000, v91
	v_lshlrev_b32_e32 v52, 16, v122
	v_and_b32_e32 v53, 0xffff0000, v122
	v_lshlrev_b32_e32 v54, 16, v123
	v_and_b32_e32 v55, 0xffff0000, v123
	v_pk_mul_f32 v[48:49], v[18:19], v[48:49]
	v_pk_mul_f32 v[50:51], v[18:19], v[50:51]
	v_pk_fma_f32 v[180:181], v[180:181], v[48:49], v[52:53]
	v_pk_fma_f32 v[182:183], v[182:183], v[50:51], v[54:55]
	global_store_dwordx4 v[22:23], v[180:183], off offset:1024 nt
	s_waitcnt vmcnt(17)
	v_lshlrev_b32_e32 v40, 16, v92
	v_and_b32_e32 v41, 0xffff0000, v92
	v_lshlrev_b32_e32 v42, 16, v93
	v_and_b32_e32 v43, 0xffff0000, v93
	v_lshlrev_b32_e32 v44, 16, v124
	v_and_b32_e32 v45, 0xffff0000, v124
	v_lshlrev_b32_e32 v46, 16, v125
	v_and_b32_e32 v47, 0xffff0000, v125
	v_pk_mul_f32 v[40:41], v[18:19], v[40:41]
	v_pk_mul_f32 v[42:43], v[18:19], v[42:43]
	v_pk_fma_f32 v[184:185], v[184:185], v[40:41], v[44:45]
	v_pk_fma_f32 v[186:187], v[186:187], v[42:43], v[46:47]
	global_store_dwordx4 v[22:23], v[184:187], off offset:2048 nt
	s_waitcnt vmcnt(15)
	v_lshlrev_b32_e32 v48, 16, v94
	v_and_b32_e32 v49, 0xffff0000, v94
	v_lshlrev_b32_e32 v50, 16, v95
	v_and_b32_e32 v51, 0xffff0000, v95
	v_lshlrev_b32_e32 v52, 16, v126
	v_and_b32_e32 v53, 0xffff0000, v126
	v_lshlrev_b32_e32 v54, 16, v127
	v_and_b32_e32 v55, 0xffff0000, v127
	v_pk_mul_f32 v[48:49], v[18:19], v[48:49]
	v_pk_mul_f32 v[50:51], v[18:19], v[50:51]
	v_pk_fma_f32 v[188:189], v[188:189], v[48:49], v[52:53]
	v_pk_fma_f32 v[190:191], v[190:191], v[50:51], v[54:55]
	global_store_dwordx4 v[22:23], v[188:191], off offset:3072 nt
	ds_bpermute_b32 v11, v26, v33
	s_waitcnt lgkmcnt(0)
	v_add_f32_e32 v10, v33, v11
	ds_bpermute_b32 v11, v27, v10
	s_waitcnt lgkmcnt(0)
	v_add_f32_e32 v10, v10, v11
	ds_bpermute_b32 v11, v28, v10
	s_waitcnt lgkmcnt(0)
	v_add_f32_e32 v10, v10, v11
	ds_bpermute_b32 v11, v29, v10
	s_waitcnt lgkmcnt(0)
	v_add_f32_e32 v10, v10, v11
	ds_bpermute_b32 v11, v30, v10
	s_waitcnt lgkmcnt(0)
	v_add_f32_e32 v10, v10, v11
	ds_bpermute_b32 v11, v31, v10
	s_waitcnt lgkmcnt(0)
	v_add_f32_e32 v10, v10, v11
	v_fmamk_f32 v14, v10, 0x39800000, v32
	v_mul_f32_e32 v15, 0x4b800000, v14
	v_cmp_gt_f32_e32 vcc, s4, v14
	s_nop 1
	v_cndmask_b32_e32 v14, v14, v15, vcc
	v_rsq_f32_e32 v18, v14
	s_nop 0
	v_mul_f32_e32 v19, 0x45800000, v18
	v_cndmask_b32_e32 v18, v18, v19, vcc
	v_mov_b32_e32 v19, v18
	s_add_i32 s34, s34, s60
	s_cmpk_gt_i32 s34, 0x1fff
	s_cbranch_scc0 .Lfin_row
